# f32->bf16 packs: integer RNE idiom (bfe/add3/lshr/and_or) replaced by v_cvt_pk_bf16_f32 at 323 sites inside the layer loop (same rounding), on top of v28
# speedup vs baseline: 1.0213x; 1.0093x over previous
.LBB0_525:
	s_and_b64 vcc, exec, s[8:9]
	s_cbranch_vccz .LBB0_381
	s_cmpk_gt_u32 s86, 0x317
	s_mov_b64 s[8:9], -1
	s_cbranch_scc1 .LBB0_529
	s_add_u32 s62, s80, 0xee19000
	s_addc_u32 s63, s81, 0
	s_sub_i32 s8, s86, 24
	s_lshr_b32 s72, s8, 8
	s_bfe_u32 s60, s8, 0x30005
	s_lshl_b32 s8, s8, 3
	s_lshl_b32 s84, s72, 1
	s_and_b32 s8, s8, 0xf8
	v_readlane_b32 s9, v253, 15
	s_add_i32 s8, s8, s9
	s_sub_i32 s9, 8, s84
	s_lshr_b32 s75, s8, s9
	s_lshl_b32 s9, -1, s9
	s_andn2_b32 s10, s8, s9
	s_lshl_b32 s85, s10, 5
	v_ashrrev_i32_e32 v2, 4, v172
	v_add_u32_e32 v118, s85, v2
	v_lshlrev_b32_e32 v3, 3, v172
	v_lshlrev_b32_e32 v4, s84, v118
	v_and_b32_e32 v3, 0x78, v3
	v_add_u32_e32 v4, s75, v4
	v_mov_b64_e32 v[28:29], s[62:63]
	v_mad_i64_i32 v[4:5], s[8:9], v4, s83, v[28:29]
	s_lshl_b32 s70, s60, 8
	v_lshlrev_b32_e32 v82, 1, v3
	v_add_lshl_u32 v3, v118, 4, s84
	v_lshl_add_u64 v[4:5], v[4:5], 0, s[70:71]
	v_add_u32_e32 v3, s75, v3
	v_lshl_add_u64 v[4:5], v[4:5], 0, v[82:83]
	v_mad_i64_i32 v[6:7], s[8:9], v3, s83, v[28:29]
	v_add_lshl_u32 v3, v118, 8, s84
	v_add_co_u32_e32 v4, vcc, s82, v4
	v_lshl_add_u64 v[6:7], v[6:7], 0, s[70:71]
	v_add_u32_e32 v3, s75, v3
	v_addc_co_u32_e32 v5, vcc, 0, v5, vcc
	v_lshl_add_u64 v[6:7], v[6:7], 0, v[82:83]
	v_mad_i64_i32 v[12:13], s[8:9], v3, s83, v[28:29]
	v_add_lshl_u32 v3, v118, 12, s84
	v_add_co_u32_e32 v8, vcc, s82, v6
	v_lshl_add_u64 v[12:13], v[12:13], 0, s[70:71]
	v_add_u32_e32 v3, s75, v3
	v_addc_co_u32_e32 v9, vcc, 0, v7, vcc
	v_lshl_add_u64 v[12:13], v[12:13], 0, v[82:83]
	v_mad_i64_i32 v[14:15], s[8:9], v3, s83, v[28:29]
	v_add_lshl_u32 v3, v118, 16, s84
	v_add_co_u32_e32 v12, vcc, s82, v12
	v_lshl_add_u64 v[14:15], v[14:15], 0, s[70:71]
	v_add_u32_e32 v3, s75, v3
	v_addc_co_u32_e32 v13, vcc, 0, v13, vcc
	v_lshl_add_u64 v[14:15], v[14:15], 0, v[82:83]
	v_mad_i64_i32 v[20:21], s[8:9], v3, s83, v[28:29]
	v_add_lshl_u32 v3, v118, 20, s84
	v_add_co_u32_e32 v16, vcc, s82, v14
	v_lshl_add_u64 v[20:21], v[20:21], 0, s[70:71]
	v_add_u32_e32 v3, s75, v3
	v_addc_co_u32_e32 v17, vcc, 0, v15, vcc
	v_lshl_add_u64 v[20:21], v[20:21], 0, v[82:83]
	v_mad_i64_i32 v[22:23], s[8:9], v3, s83, v[28:29]
	v_add_lshl_u32 v3, v118, 24, s84
	v_add_co_u32_e32 v20, vcc, s82, v20
	v_lshl_add_u64 v[22:23], v[22:23], 0, s[70:71]
	v_add_u32_e32 v3, s75, v3
	v_addc_co_u32_e32 v21, vcc, 0, v21, vcc
	v_lshl_add_u64 v[22:23], v[22:23], 0, v[82:83]
	v_mad_i64_i32 v[30:31], s[8:9], v3, s83, v[28:29]
	v_add_lshl_u32 v3, v118, 28, s84
	v_add_co_u32_e32 v24, vcc, s82, v22
	v_lshl_add_u64 v[30:31], v[30:31], 0, s[70:71]
	v_add_u32_e32 v3, s75, v3
	v_addc_co_u32_e32 v25, vcc, 0, v23, vcc
	v_lshl_add_u64 v[30:31], v[30:31], 0, v[82:83]
	v_mad_i64_i32 v[28:29], s[8:9], v3, s83, v[28:29]
	v_add_co_u32_e32 v30, vcc, s82, v30
	v_lshl_add_u64 v[28:29], v[28:29], 0, s[70:71]
	s_nop 0
	v_addc_co_u32_e32 v31, vcc, 0, v31, vcc
	v_lshl_add_u64 v[28:29], v[28:29], 0, v[82:83]
	v_add_co_u32_e32 v32, vcc, s82, v28
	global_load_dwordx4 v[4:7], v[4:5], off offset:2048
	s_nop 0
	global_load_dwordx4 v[8:11], v[8:9], off offset:2048
	v_addc_co_u32_e32 v33, vcc, 0, v29, vcc
	global_load_dwordx4 v[12:15], v[12:13], off offset:2048
	s_nop 0
	global_load_dwordx4 v[16:19], v[16:17], off offset:2048
	s_nop 0
	global_load_dwordx4 v[20:23], v[20:21], off offset:2048
	s_nop 0
	global_load_dwordx4 v[24:27], v[24:25], off offset:2048
	s_nop 0
	global_load_dwordx4 v[28:31], v[30:31], off offset:2048
	s_nop 0
	global_load_dwordx4 v[32:35], v[32:33], off offset:2048
	v_lshlrev_b32_e32 v3, 4, v172
	v_and_b32_e32 v3, 0xf0, v3
	v_add_u32_e32 v3, s94, v3
	v_mul_lo_u32 v36, v2, s5
	v_and_b32_e32 v120, 31, v172
	v_add_u32_e32 v121, v3, v36
	v_ashrrev_i32_e32 v119, 5, v172
	v_mov_b32_e32 v3, s94
	s_waitcnt vmcnt(0)
	ds_write_b128 v121, v[4:7]
	ds_write_b128 v121, v[8:11] offset:1088
	ds_write_b128 v121, v[12:15] offset:2176
	ds_write_b128 v121, v[16:19] offset:3264
	ds_write_b128 v121, v[20:23] offset:4352
	ds_write_b128 v121, v[24:27] offset:5440
	ds_write_b128 v121, v[28:31] offset:6528
	ds_write_b128 v121, v[32:35] offset:7616
	v_mad_u32_u24 v3, v120, s5, v3
	v_lshlrev_b32_e32 v4, 4, v119
	s_waitcnt lgkmcnt(0)
	v_add_u32_e32 v122, v3, v4
	ds_read_b128 v[84:87], v122
	ds_read_b128 v[88:91], v122 offset:32
	ds_read_b128 v[92:95], v122 offset:64
	ds_read_b128 v[96:99], v122 offset:96
	ds_read_b128 v[100:103], v122 offset:128
	ds_read_b128 v[104:107], v122 offset:160
	ds_read_b128 v[108:111], v122 offset:192
	ds_read_b128 v[112:115], v122 offset:224
	v_lshlrev_b32_e32 v67, 2, v119
	v_bfe_u32 v3, v172, 2, 2
	v_or_b32_e32 v5, v3, v67
	v_add_u32_e32 v66, 8, v67
	v_and_b32_e32 v4, 16, v172
	v_mul_lo_u32 v70, v5, s5
	v_lshlrev_b32_e32 v5, 2, v172
	s_waitcnt lgkmcnt(0)
	v_and_or_b32 v74, v5, 12, v4
	v_or_b32_e32 v4, v66, v3
	v_add_u32_e32 v69, 16, v67
	v_add_u32_e32 v68, 24, v67
	s_lshl_b32 s87, s60, 7
	v_mul_lo_u32 v71, v4, s5
	v_or_b32_e32 v4, v69, v3
	v_or_b32_e32 v3, v68, v3
	v_mul_lo_u32 v72, v4, s5
	v_mul_lo_u32 v73, v3, s5
	s_cmp_gt_u32 s10, 3
	s_mov_b64 s[8:9], -1
	s_cbranch_scc0 .LBB0_546
	s_add_i32 s8, s85, 0xffffff80
	v_add_u32_e32 v32, s8, v2
	v_lshlrev_b32_e32 v2, s84, v32
	v_add_u32_e32 v2, s75, v2
	v_mov_b64_e32 v[30:31], s[62:63]
	v_mad_i64_i32 v[2:3], s[8:9], v2, s83, v[30:31]
	s_lshl_b32 s70, s87, 1
	v_add_lshl_u32 v6, v32, 4, s84
	v_lshl_add_u64 v[2:3], v[2:3], 0, s[70:71]
	v_add_u32_e32 v6, s75, v6
	v_lshl_add_u64 v[2:3], v[2:3], 0, v[82:83]
	v_mad_i64_i32 v[6:7], s[8:9], v6, s83, v[30:31]
	v_add_lshl_u32 v10, v32, 8, s84
	v_add_co_u32_e32 v34, vcc, 0x2000, v2
	v_lshl_add_u64 v[6:7], v[6:7], 0, s[70:71]
	v_add_u32_e32 v10, s75, v10
	v_addc_co_u32_e32 v35, vcc, 0, v3, vcc
	v_lshl_add_u64 v[6:7], v[6:7], 0, v[82:83]
	v_mad_i64_i32 v[10:11], s[8:9], v10, s83, v[30:31]
	v_add_lshl_u32 v14, v32, 12, s84
	v_add_co_u32_e32 v38, vcc, 0x2000, v6
	v_lshl_add_u64 v[10:11], v[10:11], 0, s[70:71]
	v_add_u32_e32 v14, s75, v14
	v_addc_co_u32_e32 v39, vcc, 0, v7, vcc
	v_lshl_add_u64 v[10:11], v[10:11], 0, v[82:83]
	v_mad_i64_i32 v[14:15], s[8:9], v14, s83, v[30:31]
	v_add_lshl_u32 v18, v32, 16, s84
	v_add_co_u32_e32 v42, vcc, 0x2000, v10
	v_lshl_add_u64 v[14:15], v[14:15], 0, s[70:71]
	v_add_u32_e32 v18, s75, v18
	v_addc_co_u32_e32 v43, vcc, 0, v11, vcc
	v_lshl_add_u64 v[14:15], v[14:15], 0, v[82:83]
	v_mad_i64_i32 v[18:19], s[8:9], v18, s83, v[30:31]
	v_add_lshl_u32 v22, v32, 20, s84
	v_add_co_u32_e32 v46, vcc, 0x2000, v14
	v_lshl_add_u64 v[18:19], v[18:19], 0, s[70:71]
	v_add_u32_e32 v22, s75, v22
	v_addc_co_u32_e32 v47, vcc, 0, v15, vcc
	v_lshl_add_u64 v[18:19], v[18:19], 0, v[82:83]
	v_mad_i64_i32 v[22:23], s[8:9], v22, s83, v[30:31]
	v_add_lshl_u32 v26, v32, 24, s84
	global_load_dwordx4 v[2:5], v[34:35], off
	global_load_dwordx4 v[6:9], v[38:39], off
	v_add_co_u32_e32 v50, vcc, 0x2000, v18
	v_lshl_add_u64 v[22:23], v[22:23], 0, s[70:71]
	v_add_u32_e32 v26, s75, v26
	v_addc_co_u32_e32 v51, vcc, 0, v19, vcc
	v_lshl_add_u64 v[22:23], v[22:23], 0, v[82:83]
	v_mad_i64_i32 v[26:27], s[8:9], v26, s83, v[30:31]
	v_add_lshl_u32 v32, v32, 28, s84
	global_load_dwordx4 v[10:13], v[42:43], off
	global_load_dwordx4 v[14:17], v[46:47], off
	v_add_co_u32_e32 v54, vcc, 0x2000, v22
	v_lshl_add_u64 v[26:27], v[26:27], 0, s[70:71]
	v_add_u32_e32 v32, s75, v32
	v_addc_co_u32_e32 v55, vcc, 0, v23, vcc
	v_lshl_add_u64 v[26:27], v[26:27], 0, v[82:83]
	v_mad_i64_i32 v[30:31], s[8:9], v32, s83, v[30:31]
	global_load_dwordx4 v[18:21], v[50:51], off
	global_load_dwordx4 v[22:25], v[54:55], off
	v_add_co_u32_e32 v58, vcc, 0x2000, v26
	v_lshl_add_u64 v[30:31], v[30:31], 0, s[70:71]
	s_nop 0
	v_addc_co_u32_e32 v59, vcc, 0, v27, vcc
	v_lshl_add_u64 v[30:31], v[30:31], 0, v[82:83]
	global_load_dwordx4 v[26:29], v[58:59], off
	v_add_co_u32_e32 v62, vcc, 0x2000, v30
	v_or_b32_e32 v75, 2, v67
	s_nop 0
	v_addc_co_u32_e32 v63, vcc, 0, v31, vcc
	global_load_dwordx4 v[30:33], v[62:63], off
	s_nop 0
	global_load_dwordx4 v[34:37], v[34:35], off offset:2048
	s_nop 0
	global_load_dwordx4 v[38:41], v[38:39], off offset:2048
	s_nop 0
	global_load_dwordx4 v[42:45], v[42:43], off offset:2048
	s_nop 0
	global_load_dwordx4 v[46:49], v[46:47], off offset:2048
	s_nop 0
	global_load_dwordx4 v[50:53], v[50:51], off offset:2048
	s_nop 0
	global_load_dwordx4 v[54:57], v[54:55], off offset:2048
	s_nop 0
	global_load_dwordx4 v[58:61], v[58:59], off offset:2048
	s_nop 0
	global_load_dwordx4 v[62:65], v[62:63], off offset:2048
	v_cmp_ge_i32_e32 vcc, v67, v120
	v_add_u32_e32 v80, 17, v67
	s_waitcnt vmcnt(15)
	ds_write_b128 v121, v[2:5]
	s_waitcnt vmcnt(14)
	ds_write_b128 v121, v[6:9] offset:1088
	s_waitcnt vmcnt(13)
	ds_write_b128 v121, v[10:13] offset:2176
	s_waitcnt vmcnt(12)
	ds_write_b128 v121, v[14:17] offset:3264
	s_waitcnt vmcnt(11)
	ds_write_b128 v121, v[18:21] offset:4352
	s_waitcnt vmcnt(10)
	ds_write_b128 v121, v[22:25] offset:5440
	s_waitcnt vmcnt(9)
	ds_write_b128 v121, v[26:29] offset:6528
	s_waitcnt vmcnt(8)
	ds_write_b128 v121, v[30:33] offset:7616
	s_waitcnt lgkmcnt(0)
	ds_read_b128 v[2:5], v122
	ds_read_b128 v[18:21], v122 offset:32
	ds_read_b128 v[22:25], v122 offset:64
	ds_read_b128 v[26:29], v122 offset:96
	ds_read_b128 v[30:33], v122 offset:128
	ds_read_b128 v[76:79], v122 offset:160
	ds_read_b128 v[124:127], v122 offset:192
	ds_read_b128 v[128:131], v122 offset:224
	s_waitcnt lgkmcnt(7)
	v_mfma_f32_32x32x16_bf16 v[2:17], v[2:5], v[84:87], 0
	v_add_u32_e32 v81, 18, v67
	s_mov_b32 s8, 0xff800000
	v_add_u32_e32 v139, 19, v67
	v_add_u32_e32 v140, 25, v67
	v_add_u32_e32 v141, 26, v67
	v_add_u32_e32 v142, 27, v67
	s_waitcnt vmcnt(7)
	ds_write_b128 v121, v[34:37]
	s_waitcnt vmcnt(6)
	ds_write_b128 v121, v[38:41] offset:1088
	s_waitcnt vmcnt(5)
	ds_write_b128 v121, v[42:45] offset:2176
	s_waitcnt vmcnt(4)
	ds_write_b128 v121, v[46:49] offset:3264
	s_waitcnt vmcnt(3)
	ds_write_b128 v121, v[50:53] offset:4352
	s_waitcnt vmcnt(2)
	ds_write_b128 v121, v[54:57] offset:5440
	s_waitcnt vmcnt(1)
	ds_write_b128 v121, v[58:61] offset:6528
	s_waitcnt vmcnt(0)
	ds_write_b128 v121, v[62:65] offset:7616
	s_waitcnt lgkmcnt(14)
	v_mfma_f32_32x32x16_bf16 v[2:17], v[18:21], v[88:91], v[2:17]
	v_or_b32_e32 v18, 1, v67
	v_and_b32_e32 v20, 64, v249
	v_xor_b32_e32 v19, 32, v249
	v_add_u32_e32 v20, 64, v20
	s_waitcnt lgkmcnt(0)
	v_lshl_add_u32 v138, v74, 1, s93
	v_add_u32_e32 v123, v138, v70
	s_waitcnt lgkmcnt(13)
	v_mfma_f32_32x32x16_bf16 v[2:17], v[22:25], v[92:95], v[2:17]
	v_add_u32_e32 v152, 0x80, v138
	v_add_u32_e32 v132, v152, v71
	v_add_u32_e32 v133, v152, v72
	s_waitcnt lgkmcnt(12)
	v_mfma_f32_32x32x16_bf16 v[2:17], v[26:29], v[96:99], v[2:17]
	s_waitcnt lgkmcnt(11)
	v_mfma_f32_32x32x16_bf16 v[2:17], v[30:33], v[100:103], v[2:17]
	s_waitcnt lgkmcnt(10)
	v_mfma_f32_32x32x16_bf16 v[2:17], v[76:79], v[104:107], v[2:17]
	v_or_b32_e32 v76, 3, v67
	v_add_u32_e32 v77, 9, v67
	v_add_u32_e32 v78, 10, v67
	v_add_u32_e32 v79, 11, v67
	s_waitcnt lgkmcnt(9)
	v_mfma_f32_32x32x16_bf16 v[2:17], v[124:127], v[108:111], v[2:17]
	v_add_u32_e32 v124, v138, v71
	v_add_u32_e32 v125, v138, v72
	v_add_u32_e32 v126, v138, v73
	s_waitcnt lgkmcnt(8)
	v_mfma_f32_32x32x16_bf16 v[2:17], v[128:131], v[112:115], v[2:17]
	v_add_u32_e32 v131, v152, v70
	s_nop 10
	v_cndmask_b32_e32 v2, v228, v2, vcc
	v_cmp_ge_i32_e32 vcc, v18, v120
	s_nop 1
	v_cndmask_b32_e32 v3, v228, v3, vcc
	v_cmp_ge_i32_e32 vcc, v75, v120
	v_max3_f32 v18, v2, s8, v3
	s_mov_b32 s8, 0xf149f2ca
	v_cndmask_b32_e32 v4, v228, v4, vcc
	v_cmp_ge_i32_e32 vcc, v76, v120
	s_nop 1
	v_cndmask_b32_e32 v5, v228, v5, vcc
	v_cmp_ge_i32_e32 vcc, v66, v120
	v_max3_f32 v18, v18, v4, v5
	s_nop 0
	v_cndmask_b32_e32 v6, v228, v6, vcc
	v_cmp_ge_i32_e32 vcc, v77, v120
	s_nop 1
	v_cndmask_b32_e32 v7, v228, v7, vcc
	v_cmp_ge_i32_e32 vcc, v78, v120
	v_max3_f32 v18, v18, v6, v7
	s_nop 0
	v_cndmask_b32_e32 v8, v228, v8, vcc
	v_cmp_ge_i32_e32 vcc, v79, v120
	s_nop 1
	v_cndmask_b32_e32 v9, v228, v9, vcc
	v_cmp_ge_i32_e32 vcc, v69, v120
	v_max3_f32 v18, v18, v8, v9
	s_nop 0
	v_cndmask_b32_e32 v10, v228, v10, vcc
	v_cmp_ge_i32_e32 vcc, v80, v120
	s_nop 1
	v_cndmask_b32_e32 v11, v228, v11, vcc
	v_cmp_ge_i32_e32 vcc, v81, v120
	v_max3_f32 v18, v18, v10, v11
	s_nop 0
	v_cndmask_b32_e32 v12, v228, v12, vcc
	v_cmp_ge_i32_e32 vcc, v139, v120
	s_nop 1
	v_cndmask_b32_e32 v13, v228, v13, vcc
	v_cmp_ge_i32_e32 vcc, v68, v120
	v_max3_f32 v18, v18, v12, v13
	s_nop 0
	v_cndmask_b32_e32 v14, v228, v14, vcc
	v_cmp_ge_i32_e32 vcc, v140, v120
	s_nop 1
	v_cndmask_b32_e32 v15, v228, v15, vcc
	v_cmp_ge_i32_e32 vcc, v141, v120
	v_max3_f32 v18, v18, v14, v15
	s_nop 0
	v_cndmask_b32_e32 v16, v228, v16, vcc
	v_cmp_ge_i32_e32 vcc, v142, v120
	s_nop 1
	v_cndmask_b32_e32 v17, v228, v17, vcc
	v_cmp_lt_i32_e32 vcc, v19, v20
	v_max3_f32 v18, v18, v16, v17
	s_nop 0
	v_cndmask_b32_e32 v19, v249, v19, vcc
	v_lshlrev_b32_e32 v19, 2, v19
	ds_bpermute_b32 v20, v19, v18
	s_waitcnt lgkmcnt(0)
	v_max3_f32 v116, v18, v20, s8
	v_sub_f32_e32 v2, v2, v116
	v_exp_f32_e32 v20, v2
	v_sub_f32_e32 v3, v3, v116
	v_exp_f32_e32 v21, v3
	v_sub_f32_e32 v3, v4, v116
	v_exp_f32_e32 v22, v3
	v_sub_f32_e32 v3, v5, v116
	v_exp_f32_e32 v23, v3
	v_sub_f32_e32 v3, v6, v116
	v_add_f32_e32 v2, 0, v20
	v_exp_f32_e32 v24, v3
	v_sub_f32_e32 v3, v7, v116
	v_add_f32_e32 v2, v21, v2
	v_exp_f32_e32 v25, v3
	v_sub_f32_e32 v3, v8, v116
	v_add_f32_e32 v2, v22, v2
	v_exp_f32_e32 v26, v3
	v_sub_f32_e32 v3, v9, v116
	v_add_f32_e32 v2, v23, v2
	v_exp_f32_e32 v27, v3
	v_sub_f32_e32 v3, v10, v116
	v_add_f32_e32 v2, v24, v2
	v_exp_f32_e32 v28, v3
	v_sub_f32_e32 v3, v11, v116
	v_add_f32_e32 v2, v25, v2
	v_exp_f32_e32 v29, v3
	v_sub_f32_e32 v3, v12, v116
	v_add_f32_e32 v2, v26, v2
	v_exp_f32_e32 v30, v3
	v_sub_f32_e32 v3, v13, v116
	v_add_f32_e32 v2, v27, v2
	v_exp_f32_e32 v31, v3
	v_sub_f32_e32 v3, v14, v116
	v_add_f32_e32 v2, v28, v2
	v_exp_f32_e32 v32, v3
	v_sub_f32_e32 v3, v15, v116
	v_add_f32_e32 v2, v29, v2
	v_exp_f32_e32 v33, v3
	v_sub_f32_e32 v3, v16, v116
	v_add_f32_e32 v2, v30, v2
	v_exp_f32_e32 v34, v3
	v_sub_f32_e32 v3, v17, v116
	v_add_f32_e32 v2, v31, v2
	v_exp_f32_e32 v35, v3
	v_add_f32_e32 v2, v32, v2
	v_add_f32_e32 v2, v33, v2
	v_add_f32_e32 v2, v34, v2
	v_sub_f32_e32 v18, 0xf149f2ca, v116
	v_add_f32_e32 v36, v35, v2
	v_exp_f32_e32 v143, v18
	ds_bpermute_b32 v18, v19, v36
	s_nop 0
	v_bfe_u32 v19, v25, 16, 1
	s_nop 0
	v_bfe_u32 v37, v26, 16, 1
	s_waitcnt lgkmcnt(0)
	v_add_f32_e32 v117, v36, v18
	v_bfe_u32 v18, v27, 16, 1
	v_add3_u32 v18, v27, v18, s73
	v_bfe_u32 v36, v24, 16, 1
	v_add3_u32 v19, v25, v19, s73
	v_add3_u32 v26, v26, v37, s73
	v_add3_u32 v24, v24, v36, s73
	v_lshrrev_b32_e32 v24, 16, v24
	v_lshrrev_b32_e32 v25, 16, v26
	v_and_or_b32 v147, v18, s33, v25
	v_and_or_b32 v146, v19, s33, v24
	v_cvt_pk_bf16_f32 v145, v22, v23
	v_mul_f32_e32 v2, 0, v143
	v_cvt_pk_bf16_f32 v144, v20, v21
	v_mov_b32_e32 v3, v2
	v_mov_b32_e32 v4, v2
	v_mov_b32_e32 v5, v2
	v_mov_b32_e32 v6, v2
	v_mov_b32_e32 v7, v2
	v_mov_b32_e32 v8, v2
	v_mov_b32_e32 v9, v2
	v_mov_b32_e32 v10, v2
	v_mov_b32_e32 v11, v2
	v_mov_b32_e32 v12, v2
	v_mov_b32_e32 v13, v2
	v_mov_b32_e32 v14, v2
	v_mov_b32_e32 v15, v2
	v_mov_b32_e32 v16, v2
	v_mov_b32_e32 v17, v2
	v_cvt_pk_bf16_f32 v151, v34, v35
	v_cvt_pk_bf16_f32 v150, v32, v33
	v_cvt_pk_bf16_f32 v149, v30, v31
	v_cvt_pk_bf16_f32 v148, v28, v29
	ds_read_b64_tr_b16 v[18:19], v123
	ds_read_b64_tr_b16 v[20:21], v124
	s_waitcnt lgkmcnt(0)
	v_add_u32_e32 v22, 64, v138
	v_mfma_f32_32x32x16_bf16 v[50:65], v[18:21], v[144:147], v[2:17]
	ds_read_b64_tr_b16 v[18:19], v125
	ds_read_b64_tr_b16 v[20:21], v126
	s_waitcnt lgkmcnt(0)
	v_add_u32_e32 v127, v22, v70
	v_add_u32_e32 v128, v22, v71
	v_add_u32_e32 v129, v22, v72
	v_add_u32_e32 v130, v22, v73
	v_add_u32_e32 v138, 0xc0, v138
	v_fmac_f32_e32 v117, 0, v143
	v_mfma_f32_32x32x16_bf16 v[50:65], v[18:21], v[148:151], v[50:65]
	ds_read_b64_tr_b16 v[18:19], v127
	ds_read_b64_tr_b16 v[20:21], v128
	s_waitcnt lgkmcnt(0)
	s_nop 0
	v_mfma_f32_32x32x16_bf16 v[34:49], v[18:21], v[144:147], v[2:17]
	ds_read_b64_tr_b16 v[18:19], v129
	ds_read_b64_tr_b16 v[20:21], v130
	s_waitcnt lgkmcnt(0)
	ds_read_b64_tr_b16 v[134:135], v131
	ds_read_b64_tr_b16 v[136:137], v132
	s_waitcnt lgkmcnt(0)
	s_nop 0
	v_mfma_f32_32x32x16_bf16 v[34:49], v[18:21], v[148:151], v[34:49]
	v_mfma_f32_32x32x16_bf16 v[18:33], v[134:137], v[144:147], v[2:17]
	v_add_u32_e32 v134, v152, v73
	ds_read_b64_tr_b16 v[152:153], v133
	ds_read_b64_tr_b16 v[154:155], v134
	s_waitcnt lgkmcnt(0)
	v_add_u32_e32 v135, v138, v70
	v_add_u32_e32 v136, v138, v71
	v_add_u32_e32 v137, v138, v72
	v_add_u32_e32 v138, v138, v73
	v_mfma_f32_32x32x16_bf16 v[18:33], v[152:155], v[148:151], v[18:33]
	ds_read_b64_tr_b16 v[152:153], v135
	ds_read_b64_tr_b16 v[154:155], v136
	s_waitcnt lgkmcnt(0)
	s_nop 0
	v_mfma_f32_32x32x16_bf16 v[2:17], v[152:155], v[144:147], v[2:17]
	ds_read_b64_tr_b16 v[144:145], v137
	ds_read_b64_tr_b16 v[146:147], v138
	s_waitcnt lgkmcnt(0)
	s_nop 0
	v_mfma_f32_32x32x16_bf16 v[2:17], v[144:147], v[148:151], v[2:17]
	s_cbranch_execz .LBB0_547
	s_branch .LBB0_548

.LBB0_549:
	v_add_u32_e32 v139, s88, v118
	v_add_u32_e32 v66, 0xffffffa0, v139
	v_lshlrev_b32_e32 v66, s84, v66
	v_add_u32_e32 v66, s75, v66
	v_mov_b64_e32 v[152:153], s[62:63]
	v_add_u32_e32 v70, 0xffffffa4, v139
	v_mad_i64_i32 v[66:67], s[64:65], v66, s83, v[152:153]
	s_lshl_b32 s70, s87, 1
	v_lshlrev_b32_e32 v70, s84, v70
	v_lshl_add_u64 v[66:67], v[66:67], 0, s[70:71]
	v_add_u32_e32 v70, s75, v70
	v_add_u32_e32 v74, 0xffffffa8, v139
	v_lshl_add_u64 v[66:67], v[66:67], 0, v[82:83]
	v_mad_i64_i32 v[70:71], s[64:65], v70, s83, v[152:153]
	v_lshlrev_b32_e32 v74, s84, v74
	v_add_co_u32_e32 v156, vcc, 0x2000, v66
	v_lshl_add_u64 v[70:71], v[70:71], 0, s[70:71]
	v_add_u32_e32 v74, s75, v74
	v_add_u32_e32 v78, 0xffffffac, v139
	v_addc_co_u32_e32 v157, vcc, 0, v67, vcc
	v_lshl_add_u64 v[70:71], v[70:71], 0, v[82:83]
	v_mad_i64_i32 v[74:75], s[64:65], v74, s83, v[152:153]
	v_lshlrev_b32_e32 v78, s84, v78
	v_add_co_u32_e32 v160, vcc, 0x2000, v70
	v_lshl_add_u64 v[74:75], v[74:75], 0, s[70:71]
	v_add_u32_e32 v78, s75, v78
	v_add_u32_e32 v140, 0xffffffb0, v139
	v_addc_co_u32_e32 v161, vcc, 0, v71, vcc
	v_lshl_add_u64 v[74:75], v[74:75], 0, v[82:83]
	v_mad_i64_i32 v[78:79], s[64:65], v78, s83, v[152:153]
	v_lshlrev_b32_e32 v140, s84, v140
	v_add_co_u32_e32 v164, vcc, 0x2000, v74
	v_lshl_add_u64 v[78:79], v[78:79], 0, s[70:71]
	v_add_u32_e32 v140, s75, v140
	v_add_u32_e32 v144, 0xffffffb4, v139
	v_addc_co_u32_e32 v165, vcc, 0, v75, vcc
	v_lshl_add_u64 v[78:79], v[78:79], 0, v[82:83]
	v_mad_i64_i32 v[140:141], s[64:65], v140, s83, v[152:153]
	v_lshlrev_b32_e32 v144, s84, v144
	v_add_co_u32_e32 v168, vcc, 0x2000, v78
	v_lshl_add_u64 v[140:141], v[140:141], 0, s[70:71]
	v_add_u32_e32 v144, s75, v144
	v_add_u32_e32 v148, 0xffffffb8, v139
	v_addc_co_u32_e32 v169, vcc, 0, v79, vcc
	v_lshl_add_u64 v[140:141], v[140:141], 0, v[82:83]
	v_mad_i64_i32 v[144:145], s[64:65], v144, s83, v[152:153]
	v_lshlrev_b32_e32 v148, s84, v148
	global_load_dwordx4 v[66:69], v[156:157], off
	global_load_dwordx4 v[70:73], v[160:161], off
	v_add_co_u32_e32 v174, vcc, 0x2000, v140
	v_lshl_add_u64 v[144:145], v[144:145], 0, s[70:71]
	v_add_u32_e32 v148, s75, v148
	v_add_u32_e32 v139, 0xffffffbc, v139
	v_addc_co_u32_e32 v175, vcc, 0, v141, vcc
	v_lshl_add_u64 v[144:145], v[144:145], 0, v[82:83]
	v_mad_i64_i32 v[148:149], s[64:65], v148, s83, v[152:153]
	v_lshlrev_b32_e32 v139, s84, v139
	global_load_dwordx4 v[74:77], v[164:165], off
	global_load_dwordx4 v[78:81], v[168:169], off
	v_add_co_u32_e32 v178, vcc, 0x2000, v144
	v_lshl_add_u64 v[148:149], v[148:149], 0, s[70:71]
	v_add_u32_e32 v139, s75, v139
	v_addc_co_u32_e32 v179, vcc, 0, v145, vcc
	v_lshl_add_u64 v[148:149], v[148:149], 0, v[82:83]
	v_mad_i64_i32 v[152:153], s[64:65], v139, s83, v[152:153]
	global_load_dwordx4 v[140:143], v[174:175], off
	global_load_dwordx4 v[144:147], v[178:179], off
	v_add_co_u32_e32 v182, vcc, 0x2000, v148
	v_lshl_add_u64 v[152:153], v[152:153], 0, s[70:71]
	s_nop 0
	v_addc_co_u32_e32 v183, vcc, 0, v149, vcc
	v_lshl_add_u64 v[152:153], v[152:153], 0, v[82:83]
	global_load_dwordx4 v[148:151], v[182:183], off
	v_add_co_u32_e32 v186, vcc, 0x2000, v152
	s_cmpk_lg_i32 s88, 0x60
	s_nop 0
	v_addc_co_u32_e32 v187, vcc, 0, v153, vcc
	global_load_dwordx4 v[152:155], v[186:187], off
	s_nop 0
	global_load_dwordx4 v[156:159], v[156:157], off offset:2048
	s_nop 0
	global_load_dwordx4 v[160:163], v[160:161], off offset:2048
	s_nop 0
	global_load_dwordx4 v[164:167], v[164:165], off offset:2048
	s_nop 0
	global_load_dwordx4 v[168:171], v[168:169], off offset:2048
	s_nop 0
	global_load_dwordx4 v[174:177], v[174:175], off offset:2048
	s_nop 0
	global_load_dwordx4 v[178:181], v[178:179], off offset:2048
	s_nop 0
	global_load_dwordx4 v[182:185], v[182:183], off offset:2048
	s_nop 0
	global_load_dwordx4 v[186:189], v[186:187], off offset:2048
	s_waitcnt vmcnt(15)
	ds_write_b128 v121, v[66:69]
	s_waitcnt vmcnt(14)
	ds_write_b128 v121, v[70:73] offset:1088
	s_waitcnt vmcnt(13)
	ds_write_b128 v121, v[74:77] offset:2176
	s_waitcnt vmcnt(12)
	ds_write_b128 v121, v[78:81] offset:3264
	s_waitcnt vmcnt(11)
	ds_write_b128 v121, v[140:143] offset:4352
	s_waitcnt vmcnt(10)
	ds_write_b128 v121, v[144:147] offset:5440
	s_waitcnt vmcnt(9)
	ds_write_b128 v121, v[148:151] offset:6528
	s_waitcnt vmcnt(8)
	ds_write_b128 v121, v[152:155] offset:7616
	s_waitcnt lgkmcnt(0)
	ds_read_b128 v[66:69], v122
	ds_read_b128 v[140:143], v122 offset:32
	s_waitcnt lgkmcnt(1)
	v_mfma_f32_32x32x16_bf16 v[66:81], v[66:69], v[84:87], 0
	s_cselect_b64 s[64:65], -1, 0
	s_or_b64 vcc, s[8:9], s[64:65]
	s_mov_b32 s70, 0xff800000
	s_waitcnt lgkmcnt(0)
	v_mfma_f32_32x32x16_bf16 v[66:81], v[140:143], v[88:91], v[66:81]
	ds_read_b128 v[140:143], v122 offset:64
	ds_read_b128 v[144:147], v122 offset:96
	s_waitcnt lgkmcnt(1)
	v_mfma_f32_32x32x16_bf16 v[66:81], v[140:143], v[92:95], v[66:81]
	s_waitcnt lgkmcnt(0)
	v_mfma_f32_32x32x16_bf16 v[66:81], v[144:147], v[96:99], v[66:81]
	ds_read_b128 v[140:143], v122 offset:128
	ds_read_b128 v[144:147], v122 offset:160
	s_waitcnt lgkmcnt(1)
	v_mfma_f32_32x32x16_bf16 v[66:81], v[140:143], v[100:103], v[66:81]
	s_waitcnt lgkmcnt(0)
	v_mfma_f32_32x32x16_bf16 v[66:81], v[144:147], v[104:107], v[66:81]
	ds_read_b128 v[140:143], v122 offset:192
	ds_read_b128 v[144:147], v122 offset:224
	s_waitcnt vmcnt(7)
	ds_write_b128 v121, v[156:159]
	s_waitcnt vmcnt(6)
	ds_write_b128 v121, v[160:163] offset:1088
	s_waitcnt vmcnt(5)
	ds_write_b128 v121, v[164:167] offset:2176
	s_waitcnt vmcnt(4)
	ds_write_b128 v121, v[168:171] offset:3264
	s_waitcnt vmcnt(3)
	ds_write_b128 v121, v[174:177] offset:4352
	s_waitcnt vmcnt(2)
	ds_write_b128 v121, v[178:181] offset:5440
	s_waitcnt vmcnt(1)
	ds_write_b128 v121, v[182:185] offset:6528
	s_waitcnt vmcnt(0)
	ds_write_b128 v121, v[186:189] offset:7616
	s_waitcnt lgkmcnt(0)
	s_waitcnt lgkmcnt(9)
	v_mfma_f32_32x32x16_bf16 v[66:81], v[140:143], v[108:111], v[66:81]
	v_and_b32_e32 v141, 64, v249
	v_xor_b32_e32 v140, 32, v249
	v_add_u32_e32 v141, 64, v141
	s_waitcnt lgkmcnt(8)
	v_mfma_f32_32x32x16_bf16 v[66:81], v[144:147], v[112:115], v[66:81]
	s_nop 11
	v_cndmask_b32_e32 v139, v228, v66, vcc
	s_or_b64 vcc, s[10:11], s[64:65]
	v_cndmask_b32_e32 v67, v228, v67, vcc
	s_or_b64 vcc, s[12:13], s[64:65]
	v_cndmask_b32_e32 v68, v228, v68, vcc
	s_or_b64 vcc, s[14:15], s[64:65]
	v_cndmask_b32_e32 v69, v228, v69, vcc
	s_or_b64 vcc, s[16:17], s[64:65]
	v_cndmask_b32_e32 v70, v228, v70, vcc
	s_or_b64 vcc, s[18:19], s[64:65]
	v_cndmask_b32_e32 v71, v228, v71, vcc
	s_or_b64 vcc, s[20:21], s[64:65]
	v_cndmask_b32_e32 v72, v228, v72, vcc
	s_or_b64 vcc, s[22:23], s[64:65]
	v_cndmask_b32_e32 v73, v228, v73, vcc
	s_or_b64 vcc, s[24:25], s[64:65]
	v_cndmask_b32_e32 v74, v228, v74, vcc
	s_or_b64 vcc, s[26:27], s[64:65]
	v_cndmask_b32_e32 v75, v228, v75, vcc
	s_or_b64 vcc, s[28:29], s[64:65]
	v_cndmask_b32_e32 v76, v228, v76, vcc
	s_or_b64 vcc, s[30:31], s[64:65]
	v_max3_f32 v66, v139, s70, v67
	v_cndmask_b32_e32 v77, v228, v77, vcc
	s_or_b64 vcc, s[34:35], s[64:65]
	v_max3_f32 v66, v66, v68, v69
	v_cndmask_b32_e32 v78, v228, v78, vcc
	s_or_b64 vcc, s[36:37], s[64:65]
	v_max3_f32 v66, v66, v70, v71
	v_cndmask_b32_e32 v79, v228, v79, vcc
	v_max3_f32 v66, v66, v72, v73
	s_or_b64 vcc, s[38:39], s[64:65]
	v_max3_f32 v66, v66, v74, v75
	v_cndmask_b32_e32 v80, v228, v80, vcc
	s_or_b64 vcc, s[40:41], s[64:65]
	v_max3_f32 v66, v66, v76, v77
	v_cndmask_b32_e32 v81, v228, v81, vcc
	v_cmp_lt_i32_e32 vcc, v140, v141
	v_max3_f32 v66, v66, v78, v79
	v_max3_f32 v66, v66, v80, v81
	v_cndmask_b32_e32 v140, v249, v140, vcc
	v_lshlrev_b32_e32 v140, 2, v140
	ds_bpermute_b32 v141, v140, v66
	s_waitcnt lgkmcnt(0)
	v_max3_f32 v66, v116, v66, v141
	v_sub_f32_e32 v139, v139, v66
	v_exp_f32_e32 v139, v139
	v_sub_f32_e32 v67, v67, v66
	v_exp_f32_e32 v67, v67
	v_sub_f32_e32 v68, v68, v66
	v_exp_f32_e32 v142, v68
	v_sub_f32_e32 v68, v69, v66
	v_exp_f32_e32 v69, v68
	v_sub_f32_e32 v68, v70, v66
	v_add_f32_e32 v141, 0, v139
	v_exp_f32_e32 v70, v68
	v_sub_f32_e32 v71, v71, v66
	v_add_f32_e32 v68, v67, v141
	v_exp_f32_e32 v71, v71
	v_sub_f32_e32 v72, v72, v66
	v_add_f32_e32 v68, v142, v68
	v_exp_f32_e32 v72, v72
	v_sub_f32_e32 v73, v73, v66
	v_add_f32_e32 v68, v69, v68
	v_exp_f32_e32 v73, v73
	v_sub_f32_e32 v74, v74, v66
	v_add_f32_e32 v68, v70, v68
	v_exp_f32_e32 v74, v74
	v_sub_f32_e32 v75, v75, v66
	v_add_f32_e32 v68, v71, v68
	v_exp_f32_e32 v75, v75
	v_sub_f32_e32 v76, v76, v66
	v_add_f32_e32 v68, v72, v68
	v_exp_f32_e32 v76, v76
	v_sub_f32_e32 v77, v77, v66
	v_add_f32_e32 v68, v73, v68
	v_exp_f32_e32 v77, v77
	v_sub_f32_e32 v78, v78, v66
	v_add_f32_e32 v68, v74, v68
	v_exp_f32_e32 v78, v78
	v_add_f32_e32 v68, v75, v68
	v_add_f32_e32 v68, v76, v68
	v_add_f32_e32 v68, v77, v68
	v_add_f32_e32 v141, v78, v68
	v_sub_f32_e32 v68, v79, v66
	v_exp_f32_e32 v79, v68
	v_sub_f32_e32 v68, v80, v66
	v_sub_f32_e32 v116, v116, v66
	v_exp_f32_e32 v80, v68
	v_sub_f32_e32 v68, v81, v66
	v_exp_f32_e32 v81, v68
	v_exp_f32_e32 v68, v116
	v_add_f32_e32 v116, v79, v141
	v_bfe_u32 v141, v73, 16, 1
	v_bfe_u32 v143, v71, 16, 1
	v_bfe_u32 v144, v69, 16, 1
	v_pk_mul_f32 v[64:65], v[64:65], v[68:69] op_sel_hi:[1,0]
	v_pk_mul_f32 v[62:63], v[62:63], v[68:69] op_sel_hi:[1,0]
	v_pk_mul_f32 v[60:61], v[60:61], v[68:69] op_sel_hi:[1,0]
	v_pk_mul_f32 v[58:59], v[58:59], v[68:69] op_sel_hi:[1,0]
	v_pk_mul_f32 v[56:57], v[56:57], v[68:69] op_sel_hi:[1,0]
	v_pk_mul_f32 v[54:55], v[54:55], v[68:69] op_sel_hi:[1,0]
	v_pk_mul_f32 v[52:53], v[52:53], v[68:69] op_sel_hi:[1,0]
	v_pk_mul_f32 v[50:51], v[50:51], v[68:69] op_sel_hi:[1,0]
	v_pk_mul_f32 v[48:49], v[48:49], v[68:69] op_sel_hi:[1,0]
	v_pk_mul_f32 v[46:47], v[46:47], v[68:69] op_sel_hi:[1,0]
	v_pk_mul_f32 v[44:45], v[44:45], v[68:69] op_sel_hi:[1,0]
	v_pk_mul_f32 v[42:43], v[42:43], v[68:69] op_sel_hi:[1,0]
	v_pk_mul_f32 v[40:41], v[40:41], v[68:69] op_sel_hi:[1,0]
	v_pk_mul_f32 v[38:39], v[38:39], v[68:69] op_sel_hi:[1,0]
	v_pk_mul_f32 v[36:37], v[36:37], v[68:69] op_sel_hi:[1,0]
	v_pk_mul_f32 v[34:35], v[34:35], v[68:69] op_sel_hi:[1,0]
	v_pk_mul_f32 v[32:33], v[32:33], v[68:69] op_sel_hi:[1,0]
	v_add3_u32 v69, v69, v144, s73
	v_add3_u32 v71, v71, v143, s73
	v_add3_u32 v73, v73, v141, s73
	v_bfe_u32 v143, v142, 16, 1
	v_bfe_u32 v144, v70, 16, 1
	v_bfe_u32 v145, v72, 16, 1
	v_add3_u32 v72, v72, v145, s73
	v_add3_u32 v70, v70, v144, s73
	v_add3_u32 v142, v142, v143, s73
	v_lshrrev_b32_e32 v141, 16, v142
	v_lshrrev_b32_e32 v70, 16, v70
	v_lshrrev_b32_e32 v72, 16, v72
	v_add_f32_e32 v116, v80, v116
	v_and_or_b32 v73, v73, s33, v72
	v_and_or_b32 v72, v71, s33, v70
	v_and_or_b32 v71, v69, s33, v141
	v_cvt_pk_bf16_f32 v70, v139, v67
	v_bfe_u32 v67, v81, 16, 1
	v_bfe_u32 v69, v79, 16, 1
	v_bfe_u32 v139, v77, 16, 1
	v_bfe_u32 v141, v75, 16, 1
	v_add_f32_e32 v116, v81, v116
	v_add3_u32 v141, v75, v141, s73
	v_add3_u32 v75, v77, v139, s73
	v_add3_u32 v69, v79, v69, s73
	v_add3_u32 v67, v81, v67, s73
	v_bfe_u32 v79, v76, 16, 1
	v_bfe_u32 v81, v78, 16, 1
	v_bfe_u32 v139, v80, 16, 1
	v_bfe_u32 v77, v74, 16, 1
	v_add3_u32 v80, v80, v139, s73
	v_add3_u32 v78, v78, v81, s73
	v_add3_u32 v76, v76, v79, s73
	v_add3_u32 v74, v74, v77, s73
	v_lshrrev_b32_e32 v139, 16, v76
	v_lshrrev_b32_e32 v76, 16, v78
	v_lshrrev_b32_e32 v77, 16, v80
	ds_read_b64_tr_b16 v[78:79], v123
	ds_read_b64_tr_b16 v[80:81], v124
	s_waitcnt lgkmcnt(0)
	v_lshrrev_b32_e32 v74, 16, v74
	v_mfma_f32_32x32x16_bf16 v[50:65], v[78:81], v[70:73], v[50:65]
	v_and_or_b32 v77, v67, s33, v77
	v_and_or_b32 v76, v69, s33, v76
	v_and_or_b32 v75, v75, s33, v139
	v_and_or_b32 v74, v141, s33, v74
	ds_read_b64_tr_b16 v[78:79], v125
	ds_read_b64_tr_b16 v[80:81], v126
	s_waitcnt lgkmcnt(0)
	v_mul_f32_e64 v30, v30, v68
	v_mul_f32_e64 v31, v31, v68
	v_pk_mul_f32 v[28:29], v[28:29], v[68:69] op_sel_hi:[1,0]
	v_mfma_f32_32x32x16_bf16 v[50:65], v[78:81], v[74:77], v[50:65]
	ds_read_b64_tr_b16 v[78:79], v127
	ds_read_b64_tr_b16 v[80:81], v128
	s_waitcnt lgkmcnt(0)
	v_mul_f32_e64 v26, v26, v68
	v_mul_f32_e64 v27, v27, v68
	v_mul_f32_e64 v24, v24, v68
	v_mul_f32_e64 v25, v25, v68
	v_mul_f32_e64 v22, v22, v68
	v_mul_f32_e64 v23, v23, v68
	v_pk_mul_f32 v[20:21], v[20:21], v[68:69] op_sel_hi:[1,0]
	v_pk_mul_f32 v[18:19], v[18:19], v[68:69] op_sel_hi:[1,0]
	v_pk_mul_f32 v[16:17], v[16:17], v[68:69] op_sel_hi:[1,0]
	v_mfma_f32_32x32x16_bf16 v[34:49], v[78:81], v[70:73], v[34:49]
	ds_read_b64_tr_b16 v[78:79], v129
	ds_read_b64_tr_b16 v[80:81], v130
	s_waitcnt lgkmcnt(0)
	v_mul_f32_e64 v14, v14, v68
	v_mul_f32_e64 v15, v15, v68
	v_mul_f32_e64 v12, v12, v68
	v_mul_f32_e64 v13, v13, v68
	v_mul_f32_e64 v10, v10, v68
	v_mul_f32_e64 v11, v11, v68
	v_pk_mul_f32 v[8:9], v[8:9], v[68:69] op_sel_hi:[1,0]
	v_pk_mul_f32 v[6:7], v[6:7], v[68:69] op_sel_hi:[1,0]
	v_pk_mul_f32 v[4:5], v[4:5], v[68:69] op_sel_hi:[1,0]
	v_mfma_f32_32x32x16_bf16 v[34:49], v[78:81], v[74:77], v[34:49]
	ds_read_b64_tr_b16 v[78:79], v131
	ds_read_b64_tr_b16 v[80:81], v132
	s_waitcnt lgkmcnt(0)
	v_mul_f32_e64 v2, v2, v68
	v_mul_f32_e64 v3, v3, v68
	ds_bpermute_b32 v67, v140, v116
	s_waitcnt lgkmcnt(0)
	v_add_f32_e32 v67, v116, v67
	v_mfma_f32_32x32x16_bf16 v[18:33], v[78:81], v[70:73], v[18:33]
	ds_read_b64_tr_b16 v[78:79], v133
	ds_read_b64_tr_b16 v[80:81], v134
	s_waitcnt lgkmcnt(0)
	v_fmac_f32_e32 v67, v117, v68
	v_mov_b32_e32 v116, v66
	v_mov_b32_e32 v117, v67
	v_mfma_f32_32x32x16_bf16 v[18:33], v[78:81], v[74:77], v[18:33]
	ds_read_b64_tr_b16 v[78:79], v135
	ds_read_b64_tr_b16 v[80:81], v136
	s_waitcnt lgkmcnt(0)
	s_nop 0
	v_mfma_f32_32x32x16_bf16 v[2:17], v[78:81], v[70:73], v[2:17]
	ds_read_b64_tr_b16 v[70:71], v137
	ds_read_b64_tr_b16 v[72:73], v138
	s_waitcnt lgkmcnt(0)
	s_nop 0
	v_mfma_f32_32x32x16_bf16 v[2:17], v[70:73], v[74:77], v[2:17]
	s_add_i32 s88, s88, 32
	s_cmpk_eq_i32 s88, 0x80
	s_cbranch_scc1 .LBB0_552

.LBB0_972:
	s_or_b64 exec, exec, s[10:11]
	v_max_f32_e32 v135, v66, v66
	v_max_f32_e32 v135, 0xff800000, v135
	v_cmp_eq_u32_e32 vcc, 0, v109
	v_max_f32_e32 v140, v67, v67
	v_cmp_eq_u32_e64 s[8:9], 0, v111
	v_cndmask_b32_e32 v135, v135, v228, vcc
	v_max_f32_e32 v140, v135, v140
	v_cndmask_b32_e64 v135, v140, v135, s[8:9]
	v_max_f32_e32 v140, v68, v68
	v_max_f32_e32 v140, v135, v140
	v_cmp_eq_u32_e64 s[10:11], 0, v117
	v_cmp_eq_u32_e64 s[12:13], 0, v118
	v_cmp_eq_u32_e64 s[14:15], 0, v120
	v_cndmask_b32_e64 v135, v140, v135, s[10:11]
	v_max_f32_e32 v140, v69, v69
	v_max_f32_e32 v140, v135, v140
	v_cndmask_b32_e64 v135, v140, v135, s[12:13]
	v_max_f32_e32 v140, v70, v70
	v_max_f32_e32 v140, v135, v140
	v_cndmask_b32_e64 v135, v140, v135, s[14:15]
	v_max_f32_e32 v140, v135, v135
	v_max_f32_e32 v141, v71, v71
	v_max_f32_e32 v140, v140, v141
	v_cmp_eq_u32_e64 s[16:17], 0, v121
	v_max_f32_e32 v141, v72, v72
	v_cmp_eq_u32_e64 s[18:19], 0, v122
	v_cndmask_b32_e64 v135, v140, v135, s[16:17]
	v_max_f32_e32 v140, v135, v135
	v_max_f32_e32 v140, v140, v141
	v_cndmask_b32_e64 v135, v140, v135, s[18:19]
	v_max_f32_e32 v140, v135, v135
	v_max_f32_e32 v141, v73, v73
	v_max_f32_e32 v140, v140, v141
	v_cmp_eq_u32_e64 s[20:21], 0, v123
	v_max_f32_e32 v141, v74, v74
	v_cmp_eq_u32_e64 s[22:23], 0, v128
	v_cndmask_b32_e64 v135, v140, v135, s[20:21]
	v_max_f32_e32 v140, v135, v135
	v_max_f32_e32 v140, v140, v141
	v_cndmask_b32_e64 v135, v140, v135, s[22:23]
	v_max_f32_e32 v140, v135, v135
	v_max_f32_e32 v141, v75, v75
	v_max_f32_e32 v140, v140, v141
	v_cmp_eq_u32_e64 s[24:25], 0, v129
	v_max_f32_e32 v141, v76, v76
	v_cmp_eq_u32_e64 s[26:27], 0, v130
	v_cndmask_b32_e64 v135, v140, v135, s[24:25]
	v_max_f32_e32 v140, v135, v135
	v_max_f32_e32 v140, v140, v141
	v_cndmask_b32_e64 v135, v140, v135, s[26:27]
	v_max_f32_e32 v140, v135, v135
	v_max_f32_e32 v141, v77, v77
	v_max_f32_e32 v140, v140, v141
	v_cmp_eq_u32_e64 s[28:29], 0, v131
	v_max_f32_e32 v141, v78, v78
	v_cmp_eq_u32_e64 s[30:31], 0, v132
	v_cndmask_b32_e64 v135, v140, v135, s[28:29]
	v_max_f32_e32 v140, v135, v135
	v_max_f32_e32 v140, v140, v141
	v_cndmask_b32_e64 v135, v140, v135, s[30:31]
	v_max_f32_e32 v140, v135, v135
	v_max_f32_e32 v141, v79, v79
	v_max_f32_e32 v140, v140, v141
	v_cmp_eq_u32_e64 s[34:35], 0, v133
	v_max_f32_e32 v141, v80, v80
	v_cmp_eq_u32_e64 s[36:37], 0, v134
	v_cndmask_b32_e64 v135, v140, v135, s[34:35]
	v_max_f32_e32 v140, v135, v135
	v_max_f32_e32 v140, v140, v141
	v_cmp_eq_u32_e64 s[38:39], 2, v134
	v_cndmask_b32_e64 v135, v140, v135, s[36:37]
	s_nop 0
	v_cndmask_b32_e64 v140, 0, 1.0, s[38:39]
	v_cmp_ne_u32_e64 s[38:39], 3, v134
	s_nop 1
	v_cndmask_b32_e64 v134, v229, v140, s[38:39]
	v_add_f32_e32 v80, v80, v134
	v_cndmask_b32_e64 v134, v80, v228, s[36:37]
	v_cmp_eq_u32_e64 s[36:37], 2, v133
	s_nop 1
	v_cndmask_b32_e64 v80, 0, 1.0, s[36:37]
	v_cmp_ne_u32_e64 s[36:37], 3, v133
	s_nop 1
	v_cndmask_b32_e64 v80, v229, v80, s[36:37]
	v_add_f32_e32 v79, v79, v80
	v_cndmask_b32_e64 v79, v79, v228, s[34:35]
	v_cmp_eq_u32_e64 s[34:35], 2, v132
	s_nop 1
	v_cndmask_b32_e64 v80, 0, 1.0, s[34:35]
	v_cmp_ne_u32_e64 s[34:35], 3, v132
	s_nop 1
	v_cndmask_b32_e64 v80, v229, v80, s[34:35]
	v_add_f32_e32 v78, v78, v80
	v_cndmask_b32_e64 v132, v78, v228, s[30:31]
	v_cmp_eq_u32_e64 s[30:31], 2, v131
	v_and_b32_e32 v80, 64, v249
	v_add_u32_e32 v80, 64, v80
	v_cndmask_b32_e64 v78, 0, 1.0, s[30:31]
	v_cmp_ne_u32_e64 s[30:31], 3, v131
	s_nop 1
	v_cndmask_b32_e64 v78, v229, v78, s[30:31]
	v_add_f32_e32 v77, v77, v78
	v_cndmask_b32_e64 v77, v77, v228, s[28:29]
	v_cmp_eq_u32_e64 s[28:29], 2, v130
	s_nop 1
	v_cndmask_b32_e64 v78, 0, 1.0, s[28:29]
	v_cmp_ne_u32_e64 s[28:29], 3, v130
	s_nop 1
	v_cndmask_b32_e64 v78, v229, v78, s[28:29]
	v_add_f32_e32 v76, v76, v78
	v_cndmask_b32_e64 v76, v76, v228, s[26:27]
	v_cmp_eq_u32_e64 s[26:27], 2, v129
	s_nop 1
	v_cndmask_b32_e64 v78, 0, 1.0, s[26:27]
	v_cmp_ne_u32_e64 s[26:27], 3, v129
	s_nop 1
	v_cndmask_b32_e64 v78, v229, v78, s[26:27]
	v_add_f32_e32 v75, v75, v78
	v_cndmask_b32_e64 v129, v75, v228, s[24:25]
	v_cmp_eq_u32_e64 s[24:25], 2, v128
	s_nop 1
	v_cndmask_b32_e64 v75, 0, 1.0, s[24:25]
	v_cmp_ne_u32_e64 s[24:25], 3, v128
	s_nop 1
	v_cndmask_b32_e64 v75, v229, v75, s[24:25]
	v_add_f32_e32 v74, v74, v75
	v_cndmask_b32_e64 v128, v74, v228, s[22:23]
	v_cmp_eq_u32_e64 s[22:23], 2, v123
	v_xor_b32_e32 v75, 32, v249
	s_nop 0
	v_cndmask_b32_e64 v74, 0, 1.0, s[22:23]
	v_cmp_ne_u32_e64 s[22:23], 3, v123
	s_nop 1
	v_cndmask_b32_e64 v74, v229, v74, s[22:23]
	v_add_f32_e32 v73, v73, v74
	v_cndmask_b32_e64 v73, v73, v228, s[20:21]
	v_cmp_eq_u32_e64 s[20:21], 2, v122
	s_nop 1
	v_cndmask_b32_e64 v74, 0, 1.0, s[20:21]
	v_cmp_ne_u32_e64 s[20:21], 3, v122
	s_nop 1
	v_cndmask_b32_e64 v74, v229, v74, s[20:21]
	v_add_f32_e32 v72, v72, v74
	v_cndmask_b32_e64 v78, v72, v228, s[18:19]
	v_cmp_eq_u32_e64 s[18:19], 2, v121
	s_nop 1
	v_cndmask_b32_e64 v72, 0, 1.0, s[18:19]
	v_cmp_ne_u32_e64 s[18:19], 3, v121
	s_nop 1
	v_cndmask_b32_e64 v72, v229, v72, s[18:19]
	v_add_f32_e32 v71, v71, v72
	v_cndmask_b32_e64 v71, v71, v228, s[16:17]
	v_cmp_eq_u32_e64 s[16:17], 2, v120
	s_nop 1
	v_cndmask_b32_e64 v72, 0, 1.0, s[16:17]
	v_cmp_ne_u32_e64 s[16:17], 3, v120
	s_nop 1
	v_cndmask_b32_e64 v72, v229, v72, s[16:17]
	v_add_f32_e32 v70, v70, v72
	v_cndmask_b32_e64 v74, v70, v228, s[14:15]
	v_cmp_eq_u32_e64 s[14:15], 2, v118
	s_nop 1
	v_cndmask_b32_e64 v70, 0, 1.0, s[14:15]
	v_cmp_ne_u32_e64 s[14:15], 3, v118
	s_nop 1
	v_cndmask_b32_e64 v70, v229, v70, s[14:15]
	v_add_f32_e32 v69, v69, v70
	v_cndmask_b32_e64 v69, v69, v228, s[12:13]
	v_cmp_eq_u32_e64 s[12:13], 2, v117
	s_nop 1
	v_cndmask_b32_e64 v70, 0, 1.0, s[12:13]
	v_cmp_ne_u32_e64 s[12:13], 3, v117
	s_nop 1
	v_cndmask_b32_e64 v70, v229, v70, s[12:13]
	v_add_f32_e32 v68, v68, v70
	v_cndmask_b32_e64 v70, v68, v228, s[10:11]
	v_cmp_eq_u32_e64 s[10:11], 2, v111
	s_nop 1
	v_cndmask_b32_e64 v68, 0, 1.0, s[10:11]
	v_cmp_ne_u32_e64 s[10:11], 3, v111
	s_nop 1
	v_cndmask_b32_e64 v68, v229, v68, s[10:11]
	v_add_f32_e32 v67, v67, v68
	v_cndmask_b32_e64 v72, v67, v228, s[8:9]
	v_cmp_eq_u32_e64 s[8:9], 2, v109
	v_max_f32_e32 v68, v81, v81
	s_nop 0
	v_cndmask_b32_e64 v67, 0, 1.0, s[8:9]
	v_cmp_ne_u32_e64 s[8:9], 3, v109
	s_nop 1
	v_cndmask_b32_e64 v67, v229, v67, s[8:9]
	v_add_f32_e32 v66, v66, v67
	v_max_f32_e32 v67, v135, v135
	v_cmp_eq_u32_e64 s[8:9], 2, v116
	v_max_f32_e32 v67, v67, v68
	v_cndmask_b32_e32 v66, v66, v228, vcc
	v_cndmask_b32_e64 v68, 0, 1.0, s[8:9]
	v_cmp_lt_i32_e64 s[8:9], v75, v80
	v_cmp_eq_u32_e32 vcc, 0, v116
	s_nop 0
	v_cndmask_b32_e64 v75, v249, v75, s[8:9]
	v_cndmask_b32_e32 v67, v67, v135, vcc
	v_lshlrev_b32_e32 v117, 2, v75
	ds_bpermute_b32 v75, v117, v67
	v_cmp_ne_u32_e64 s[8:9], 3, v116
	s_waitcnt lgkmcnt(0)
	v_max3_f32 v67, v246, v67, v75
	v_cndmask_b32_e64 v68, v229, v68, s[8:9]
	v_add_f32_e32 v68, v81, v68
	v_sub_f32_e32 v66, v66, v67
	v_cndmask_b32_e32 v111, v68, v228, vcc
	v_exp_f32_e32 v68, v66
	v_sub_f32_e32 v66, v72, v67
	v_exp_f32_e32 v72, v66
	v_sub_f32_e32 v66, v70, v67
	v_exp_f32_e32 v70, v66
	v_sub_f32_e32 v66, v69, v67
	v_exp_f32_e32 v75, v66
	v_sub_f32_e32 v69, v74, v67
	v_add_f32_e32 v66, 0, v68
	v_exp_f32_e32 v74, v69
	v_sub_f32_e32 v69, v71, v67
	v_add_f32_e32 v66, v72, v66
	v_exp_f32_e32 v80, v69
	v_sub_f32_e32 v69, v78, v67
	v_add_f32_e32 v66, v70, v66
	v_exp_f32_e32 v78, v69
	v_sub_f32_e32 v69, v73, v67
	v_add_f32_e32 v66, v75, v66
	v_exp_f32_e32 v109, v69
	v_sub_f32_e32 v69, v128, v67
	v_add_f32_e32 v66, v74, v66
	v_exp_f32_e32 v69, v69
	v_sub_f32_e32 v71, v129, v67
	v_add_f32_e32 v66, v80, v66
	v_exp_f32_e32 v73, v71
	v_sub_f32_e32 v71, v76, v67
	v_add_f32_e32 v66, v78, v66
	v_exp_f32_e32 v71, v71
	v_sub_f32_e32 v76, v77, v67
	v_add_f32_e32 v66, v109, v66
	v_exp_f32_e32 v77, v76
	v_sub_f32_e32 v76, v132, v67
	v_add_f32_e32 v66, v69, v66
	v_exp_f32_e32 v76, v76
	v_sub_f32_e32 v79, v79, v67
	v_add_f32_e32 v66, v73, v66
	v_exp_f32_e32 v81, v79
	v_sub_f32_e32 v79, v134, v67
	v_add_f32_e32 v66, v71, v66
	v_exp_f32_e32 v79, v79
	v_sub_f32_e32 v111, v111, v67
	v_add_f32_e32 v66, v77, v66
	v_exp_f32_e32 v111, v111
	v_add_f32_e32 v66, v76, v66
	v_add_f32_e32 v66, v81, v66
	v_add_f32_e32 v66, v79, v66
	v_add_f32_e32 v116, v111, v66
	ds_bpermute_b32 v117, v117, v116
	s_andn2_b64 vcc, exec, s[62:63]
	s_cbranch_vccnz .LBB0_974
	s_waitcnt vmcnt(15)
	v_bfe_u32 v118, v84, 16, 1
	v_add3_u32 v84, v84, v118, s73
	v_bfe_u32 v118, v85, 16, 1
	v_lshrrev_b32_e32 v84, 16, v84
	v_add3_u32 v85, v85, v118, s73
	v_lshlrev_b32_e32 v66, 3, v235
	v_and_or_b32 v84, v85, s33, v84
	v_and_b32_e32 v66, 0xf8, v66
	s_nop 0
	s_nop 0
	v_add_u32_e32 v66, s94, v66
	s_nop 0
	s_nop 0
	v_cvt_pk_bf16_f32 v85, v86, v87
	v_mad_u64_u32 v[86:87], s[8:9], v224, s5, v[66:67]
	ds_write_b64 v86, v[84:85]
	v_add_u32_e32 v84, 64, v235
	v_ashrrev_i32_e32 v86, 5, v84
	s_waitcnt vmcnt(14)
	s_nop 0
	s_nop 0
	s_nop 0
	s_nop 0
	s_nop 0
	v_cvt_pk_bf16_f32 v84, v88, v89
	s_nop 0
	s_nop 0
	s_nop 0
	s_nop 0
	s_nop 0
	v_cvt_pk_bf16_f32 v85, v90, v91
	v_mad_u64_u32 v[86:87], s[8:9], v86, s5, v[66:67]
	ds_write_b64 v86, v[84:85]
	v_add_u32_e32 v84, 0x80, v235
	v_ashrrev_i32_e32 v86, 5, v84
	s_waitcnt vmcnt(13)
	s_nop 0
	s_nop 0
	s_nop 0
	s_nop 0
	s_nop 0
	v_cvt_pk_bf16_f32 v84, v92, v93
	s_nop 0
	s_nop 0
	s_nop 0
	s_nop 0
	s_nop 0
	v_cvt_pk_bf16_f32 v85, v94, v95
	v_mad_u64_u32 v[86:87], s[8:9], v86, s5, v[66:67]
	ds_write_b64 v86, v[84:85]
	v_add_u32_e32 v84, 0xc0, v235
	v_ashrrev_i32_e32 v86, 5, v84
	s_waitcnt vmcnt(12)
	s_nop 0
	s_nop 0
	s_nop 0
	s_nop 0
	s_nop 0
	v_cvt_pk_bf16_f32 v84, v96, v97
	s_nop 0
	s_nop 0
	s_nop 0
	s_nop 0
	s_nop 0
	v_cvt_pk_bf16_f32 v85, v98, v99
	v_mad_u64_u32 v[86:87], s[8:9], v86, s5, v[66:67]
	ds_write_b64 v86, v[84:85]
	v_add_u32_e32 v84, 0x100, v235
	v_ashrrev_i32_e32 v86, 5, v84
	s_waitcnt vmcnt(11)
	s_nop 0
	s_nop 0
	s_nop 0
	s_nop 0
	s_nop 0
	v_cvt_pk_bf16_f32 v84, v100, v101
	s_nop 0
	s_nop 0
	s_nop 0
	s_nop 0
	s_nop 0
	v_cvt_pk_bf16_f32 v85, v102, v103
	v_mad_u64_u32 v[86:87], s[8:9], v86, s5, v[66:67]
	ds_write_b64 v86, v[84:85]
	v_add_u32_e32 v84, 0x140, v235
	v_ashrrev_i32_e32 v86, 5, v84
	s_waitcnt vmcnt(10)
	s_nop 0
	s_nop 0
	s_nop 0
	s_nop 0
	s_nop 0
	v_cvt_pk_bf16_f32 v84, v104, v105
	s_nop 0
	s_nop 0
	s_nop 0
	s_nop 0
	s_nop 0
	v_cvt_pk_bf16_f32 v85, v106, v107
	v_mad_u64_u32 v[86:87], s[8:9], v86, s5, v[66:67]
	ds_write_b64 v86, v[84:85]
	v_add_u32_e32 v84, 0x180, v235
	v_ashrrev_i32_e32 v86, 5, v84
	s_waitcnt vmcnt(9)
	s_nop 0
	s_nop 0
	s_nop 0
	s_nop 0
	s_nop 0
	v_cvt_pk_bf16_f32 v84, v112, v113
	s_nop 0
	s_nop 0
	s_nop 0
	s_nop 0
	s_nop 0
	v_cvt_pk_bf16_f32 v85, v114, v115
	v_mad_u64_u32 v[86:87], s[8:9], v86, s5, v[66:67]
	ds_write_b64 v86, v[84:85]
	v_add_u32_e32 v84, 0x1c0, v235
	v_ashrrev_i32_e32 v86, 5, v84
	s_waitcnt vmcnt(8)
	s_nop 0
	s_nop 0
	s_nop 0
	s_nop 0
	s_nop 0
	v_cvt_pk_bf16_f32 v84, v124, v125
	s_nop 0
	s_nop 0
	s_nop 0
	s_nop 0
	s_nop 0
	v_cvt_pk_bf16_f32 v85, v126, v127
	v_mad_u64_u32 v[86:87], s[8:9], v86, s5, v[66:67]
	ds_write_b64 v86, v[84:85]
	v_add_u32_e32 v84, 0x200, v235
	v_ashrrev_i32_e32 v86, 5, v84
	s_waitcnt vmcnt(7)
	s_nop 0
	s_nop 0
	s_nop 0
	s_nop 0
	s_nop 0
	v_cvt_pk_bf16_f32 v84, v136, v137
	s_nop 0
	s_nop 0
	s_nop 0
	s_nop 0
	s_nop 0
	v_cvt_pk_bf16_f32 v85, v138, v139
	v_mad_u64_u32 v[86:87], s[8:9], v86, s5, v[66:67]
	ds_write_b64 v86, v[84:85]
	v_add_u32_e32 v84, 0x240, v235
	v_ashrrev_i32_e32 v86, 5, v84
	s_waitcnt vmcnt(6)
	s_nop 0
	s_nop 0
	s_nop 0
	s_nop 0
	s_nop 0
	v_cvt_pk_bf16_f32 v84, v148, v149
	s_nop 0
	s_nop 0
	s_nop 0
	s_nop 0
	s_nop 0
	v_cvt_pk_bf16_f32 v85, v150, v151
	v_mad_u64_u32 v[86:87], s[8:9], v86, s5, v[66:67]
	ds_write_b64 v86, v[84:85]
	v_add_u32_e32 v84, 0x280, v235
	v_ashrrev_i32_e32 v86, 5, v84
	s_waitcnt vmcnt(5)
	s_nop 0
	s_nop 0
	s_nop 0
	s_nop 0
	s_nop 0
	v_cvt_pk_bf16_f32 v84, v156, v157
	s_nop 0
	s_nop 0
	s_nop 0
	s_nop 0
	s_nop 0
	v_cvt_pk_bf16_f32 v85, v158, v159
	v_mad_u64_u32 v[86:87], s[8:9], v86, s5, v[66:67]
	ds_write_b64 v86, v[84:85]
	v_add_u32_e32 v84, 0x2c0, v235
	v_ashrrev_i32_e32 v86, 5, v84
	s_waitcnt vmcnt(4)
	s_nop 0
	s_nop 0
	s_nop 0
	s_nop 0
	s_nop 0
	v_cvt_pk_bf16_f32 v84, v160, v161
	s_nop 0
	s_nop 0
	s_nop 0
	s_nop 0
	s_nop 0
	v_cvt_pk_bf16_f32 v85, v162, v163
	v_mad_u64_u32 v[86:87], s[8:9], v86, s5, v[66:67]
	ds_write_b64 v86, v[84:85]
	v_add_u32_e32 v84, 0x300, v235
	v_ashrrev_i32_e32 v86, 5, v84
	s_waitcnt vmcnt(3)
	s_nop 0
	s_nop 0
	s_nop 0
	s_nop 0
	s_nop 0
	v_cvt_pk_bf16_f32 v84, v164, v165
	s_nop 0
	s_nop 0
	s_nop 0
	s_nop 0
	s_nop 0
	v_cvt_pk_bf16_f32 v85, v166, v167
	v_mad_u64_u32 v[86:87], s[8:9], v86, s5, v[66:67]
	ds_write_b64 v86, v[84:85]
	v_add_u32_e32 v84, 0x340, v235
	v_ashrrev_i32_e32 v86, 5, v84
	s_waitcnt vmcnt(2)
	s_nop 0
	s_nop 0
	s_nop 0
	s_nop 0
	s_nop 0
	v_cvt_pk_bf16_f32 v84, v168, v169
	s_nop 0
	s_nop 0
	s_nop 0
	s_nop 0
	s_nop 0
	v_cvt_pk_bf16_f32 v85, v170, v171
	v_mad_u64_u32 v[86:87], s[8:9], v86, s5, v[66:67]
	ds_write_b64 v86, v[84:85]
	v_add_u32_e32 v84, 0x380, v235
	v_ashrrev_i32_e32 v86, 5, v84
	s_waitcnt vmcnt(1)
	s_nop 0
	s_nop 0
	s_nop 0
	s_nop 0
	s_nop 0
	v_cvt_pk_bf16_f32 v84, v172, v173
	s_nop 0
	s_nop 0
	s_nop 0
	s_nop 0
	s_nop 0
	v_cvt_pk_bf16_f32 v85, v174, v175
	v_mad_u64_u32 v[86:87], s[8:9], v86, s5, v[66:67]
	ds_write_b64 v86, v[84:85]
	v_add_u32_e32 v84, 0x3c0, v235
	v_ashrrev_i32_e32 v86, 5, v84
	s_waitcnt vmcnt(0)
	s_nop 0
	s_nop 0
	s_nop 0
	s_nop 0
	s_nop 0
	v_cvt_pk_bf16_f32 v84, v176, v177
	s_nop 0
	s_nop 0
	s_nop 0
	s_nop 0
	s_nop 0
	v_cvt_pk_bf16_f32 v85, v178, v179
	v_mad_u64_u32 v[86:87], s[8:9], v86, s5, v[66:67]
	ds_write_b64 v86, v[84:85]
.LBB0_974:
	v_sub_f32_e32 v66, v246, v67
	s_waitcnt vmcnt(15)
	v_exp_f32_e32 v84, v66
	s_nop 0
	s_nop 0
	s_nop 0
	s_nop 0
	v_pk_mul_f32 v[64:65], v[64:65], v[84:85] op_sel_hi:[1,0]
	v_pk_mul_f32 v[62:63], v[62:63], v[84:85] op_sel_hi:[1,0]
	v_pk_mul_f32 v[60:61], v[60:61], v[84:85] op_sel_hi:[1,0]
	v_pk_mul_f32 v[58:59], v[58:59], v[84:85] op_sel_hi:[1,0]
	v_pk_mul_f32 v[56:57], v[56:57], v[84:85] op_sel_hi:[1,0]
	v_pk_mul_f32 v[54:55], v[54:55], v[84:85] op_sel_hi:[1,0]
	v_pk_mul_f32 v[52:53], v[52:53], v[84:85] op_sel_hi:[1,0]
	v_pk_mul_f32 v[50:51], v[50:51], v[84:85] op_sel_hi:[1,0]
	v_pk_mul_f32 v[48:49], v[48:49], v[84:85] op_sel_hi:[1,0]
	v_pk_mul_f32 v[46:47], v[46:47], v[84:85] op_sel_hi:[1,0]
	v_pk_mul_f32 v[44:45], v[44:45], v[84:85] op_sel_hi:[1,0]
	v_pk_mul_f32 v[42:43], v[42:43], v[84:85] op_sel_hi:[1,0]
	v_pk_mul_f32 v[40:41], v[40:41], v[84:85] op_sel_hi:[1,0]
	v_pk_mul_f32 v[38:39], v[38:39], v[84:85] op_sel_hi:[1,0]
	v_pk_mul_f32 v[36:37], v[36:37], v[84:85] op_sel_hi:[1,0]
	v_pk_mul_f32 v[34:35], v[34:35], v[84:85] op_sel_hi:[1,0]
	v_pk_mul_f32 v[32:33], v[32:33], v[84:85] op_sel_hi:[1,0]
	v_pk_mul_f32 v[30:31], v[30:31], v[84:85] op_sel_hi:[1,0]
	v_pk_mul_f32 v[28:29], v[28:29], v[84:85] op_sel_hi:[1,0]
	v_pk_mul_f32 v[26:27], v[26:27], v[84:85] op_sel_hi:[1,0]
	v_pk_mul_f32 v[24:25], v[24:25], v[84:85] op_sel_hi:[1,0]
	v_pk_mul_f32 v[22:23], v[22:23], v[84:85] op_sel_hi:[1,0]
	v_pk_mul_f32 v[20:21], v[20:21], v[84:85] op_sel_hi:[1,0]
	v_pk_mul_f32 v[18:19], v[18:19], v[84:85] op_sel_hi:[1,0]
	v_pk_mul_f32 v[16:17], v[16:17], v[84:85] op_sel_hi:[1,0]
	v_pk_mul_f32 v[14:15], v[14:15], v[84:85] op_sel_hi:[1,0]
	v_pk_mul_f32 v[12:13], v[12:13], v[84:85] op_sel_hi:[1,0]
	v_pk_mul_f32 v[10:11], v[10:11], v[84:85] op_sel_hi:[1,0]
	v_pk_mul_f32 v[8:9], v[8:9], v[84:85] op_sel_hi:[1,0]
	v_pk_mul_f32 v[6:7], v[6:7], v[84:85] op_sel_hi:[1,0]
	v_pk_mul_f32 v[4:5], v[4:5], v[84:85] op_sel_hi:[1,0]
	v_pk_mul_f32 v[2:3], v[2:3], v[84:85] op_sel_hi:[1,0]
	s_waitcnt lgkmcnt(0)
	v_add_f32_e32 v66, v116, v117
	s_waitcnt vmcnt(14)
	v_fmac_f32_e32 v66, v233, v84
	v_cvt_pk_bf16_f32 v86, v74, v80
	v_bfe_u32 v74, v73, 16, 1
	v_cvt_pk_bf16_f32 v85, v70, v75
	v_add3_u32 v73, v73, v74, s73
	v_bfe_u32 v74, v69, 16, 1
	v_bfe_u32 v75, v71, 16, 1
	v_cvt_pk_bf16_f32 v87, v78, v109
	v_cvt_pk_bf16_f32 v84, v68, v72
	v_bfe_u32 v72, v77, 16, 1
	v_add3_u32 v71, v71, v75, s73
	v_add3_u32 v69, v69, v74, s73
	v_add3_u32 v72, v77, v72, s73
	v_lshrrev_b32_e32 v74, 16, v69
	v_lshrrev_b32_e32 v69, 16, v71
	v_bfe_u32 v77, v76, 16, 1
	v_and_or_b32 v69, v72, s33, v69
	v_bfe_u32 v72, v235, 2, 2
	v_add3_u32 v76, v76, v77, s73
	v_cvt_pk_bf16_f32 v71, v79, v111
	v_and_or_b32 v68, v73, s33, v74
	v_or_b32_e32 v74, v72, v82
	v_lshrrev_b32_e32 v75, 16, v76
	v_and_b32_e32 v73, 16, v235
	v_mul_lo_u32 v76, v74, s5
	v_lshlrev_b32_e32 v74, 2, v235
	v_bfe_u32 v70, v81, 16, 1
	v_and_or_b32 v73, v74, 12, v73
	v_or_b32_e32 v74, v108, v72
	v_add3_u32 v70, v81, v70, s73
	s_waitcnt lgkmcnt(0)
	v_mul_lo_u32 v77, v74, s5
	v_or_b32_e32 v74, v110, v72
	v_or_b32_e32 v72, v119, v72
	v_lshl_add_u32 v80, v73, 1, s93
	v_and_or_b32 v70, v70, s33, v75
	v_mul_lo_u32 v78, v74, s5
	v_mul_lo_u32 v79, v72, s5
	v_add_u32_e32 v81, v80, v76
	v_add_u32_e32 v82, v80, v77
	ds_read_b64_tr_b16 v[72:73], v81
	ds_read_b64_tr_b16 v[74:75], v82
	s_waitcnt lgkmcnt(0)
	v_add_u32_e32 v81, v80, v78
	v_mfma_f32_32x32x16_bf16 v[50:65], v[72:75], v[84:87], v[50:65]
	v_add_u32_e32 v82, v80, v79
	ds_read_b64_tr_b16 v[72:73], v81
	ds_read_b64_tr_b16 v[74:75], v82
	s_waitcnt lgkmcnt(0)
	v_add_u32_e32 v81, 64, v80
	v_add_u32_e32 v82, v81, v76
	v_add_u32_e32 v88, v81, v77
	s_add_i32 s60, s60, 8
	s_addk_i32 s55, 0x100
	v_mfma_f32_32x32x16_bf16 v[50:65], v[72:75], v[68:71], v[50:65]
	ds_read_b64_tr_b16 v[72:73], v82
	ds_read_b64_tr_b16 v[74:75], v88
	s_waitcnt lgkmcnt(0)
	v_add_u32_e32 v82, v81, v78
	v_add_u32_e32 v81, v81, v79
	s_addk_i32 s54, 0x200
	s_cmp_gt_u32 s72, 32
	v_mfma_f32_32x32x16_bf16 v[34:49], v[72:75], v[84:87], v[34:49]
	ds_read_b64_tr_b16 v[72:73], v82
	ds_read_b64_tr_b16 v[74:75], v81
	s_waitcnt lgkmcnt(0)
	v_add_u32_e32 v81, 0x80, v80
	v_add_u32_e32 v82, v81, v76
	v_add_u32_e32 v88, v81, v77
	v_add_u32_e32 v80, 0xc0, v80
	v_add_u32_e32 v76, v80, v76
	v_add_u32_e32 v77, v80, v77
	v_mfma_f32_32x32x16_bf16 v[34:49], v[72:75], v[68:71], v[34:49]
	ds_read_b64_tr_b16 v[72:73], v82
	ds_read_b64_tr_b16 v[74:75], v88
	s_waitcnt lgkmcnt(0)
	v_add_u32_e32 v82, v81, v78
	v_add_u32_e32 v81, v81, v79
	v_mfma_f32_32x32x16_bf16 v[18:33], v[72:75], v[84:87], v[18:33]
	ds_read_b64_tr_b16 v[72:73], v82
	ds_read_b64_tr_b16 v[74:75], v81
	s_waitcnt lgkmcnt(0)
	s_nop 0
	v_mfma_f32_32x32x16_bf16 v[18:33], v[72:75], v[68:71], v[18:33]
	ds_read_b64_tr_b16 v[72:73], v76
	ds_read_b64_tr_b16 v[74:75], v77
	s_waitcnt lgkmcnt(0)
	v_add_u32_e32 v76, v80, v78
	v_add_u32_e32 v77, v80, v79
	v_mfma_f32_32x32x16_bf16 v[2:17], v[72:75], v[84:87], v[2:17]
	ds_read_b64_tr_b16 v[72:73], v76
	ds_read_b64_tr_b16 v[74:75], v77
	s_waitcnt lgkmcnt(0)
	s_nop 0
	v_mfma_f32_32x32x16_bf16 v[2:17], v[72:75], v[68:71], v[2:17]
	s_cbranch_scc1 .LBB0_978
	v_mov_b32_e32 v246, v67
	v_mov_b32_e32 v233, v66
	s_branch .LBB0_676

.LBB0_1018:
	v_ashrrev_i32_e32 v4, 7, v6
	v_ashrrev_i32_e32 v5, 31, v4
	v_lshlrev_b64 v[2:3], 6, v[4:5]
	v_lshrrev_b32_e32 v8, 1, v6
	v_and_b32_e32 v82, 56, v8
	v_lshl_add_u64 v[8:9], s[12:13], 0, v[2:3]
	v_lshl_add_u64 v[10:11], s[14:15], 0, v[2:3]
	v_lshl_add_u64 v[2:3], s[16:17], 0, v[2:3]
	v_lshl_add_u64 v[8:9], v[8:9], 0, v[82:83]
	v_lshl_add_u64 v[10:11], v[10:11], 0, v[82:83]
	v_lshl_add_u64 v[2:3], v[2:3], 0, v[82:83]
	global_load_dwordx2 v[8:9], v[8:9], off
	s_nop 0
	global_load_dwordx2 v[10:11], v[10:11], off
	s_nop 0
	global_load_dwordx2 v[2:3], v[2:3], off
	s_waitcnt vmcnt(0)
	v_max3_f32 v12, v8, v10, v2
	v_sub_f32_e32 v8, v8, v12
	v_sub_f32_e32 v10, v10, v12
	v_sub_f32_e32 v2, v2, v12
	v_exp_f32_e32 v8, v8
	v_exp_f32_e32 v13, v10
	v_exp_f32_e32 v12, v2
	v_mov_b32_e32 v10, v3
	v_fma_f32 v2, v9, v8, 0
	v_mul_f32_e32 v14, v9, v8
	v_pk_mul_f32 v[20:21], v[10:11], v[12:13]
	s_nop 0
	v_add_f32_e32 v2, v21, v2
	v_add_f32_e32 v2, v20, v2
	v_div_scale_f32 v3, s[20:21], v2, v2, 1.0
	v_rcp_f32_e32 v8, v3
	s_nop 0
	v_fma_f32 v9, -v3, v8, 1.0
	v_fmac_f32_e32 v8, v9, v8
	v_div_scale_f32 v9, vcc, 1.0, v2, 1.0
	v_mul_f32_e32 v10, v9, v8
	v_fma_f32 v11, -v3, v10, v9
	v_fmac_f32_e32 v10, v11, v8
	v_fma_f32 v3, -v3, v10, v9
	v_div_fmas_f32 v3, v3, v8, v10
	v_div_fixup_f32 v23, v3, v2, 1.0
	v_lshlrev_b64 v[2:3], 11, v[4:5]
	v_lshl_add_u64 v[8:9], s[10:11], 0, v[2:3]
	v_and_b32_e32 v2, 0x3f8, v7
	v_lshlrev_b32_e32 v2, 1, v2
	v_mov_b32_e32 v3, v83
	v_lshl_add_u64 v[16:17], v[8:9], 0, v[2:3]
	v_add_co_u32_e32 v12, vcc, s56, v16
	global_load_dwordx4 v[8:11], v[16:17], off
	s_nop 0
	v_addc_co_u32_e32 v13, vcc, 0, v17, vcc
	v_mul_f32_e32 v22, v14, v23
	global_load_dwordx4 v[12:15], v[12:13], off
	v_add_co_u32_e32 v16, vcc, s57, v16
	v_mul_f32_e32 v24, v21, v23
	s_nop 0
	v_addc_co_u32_e32 v17, vcc, 0, v17, vcc
	global_load_dwordx4 v[16:19], v[16:17], off
	v_mul_f32_e32 v20, v20, v23
	v_lshlrev_b64 v[4:5], 12, v[4:5]
	v_lshl_add_u64 v[4:5], s[88:89], 0, v[4:5]
	v_lshl_add_u64 v[4:5], v[4:5], 0, v[2:3]
	v_add_co_u32_e32 v4, vcc, s62, v4
	v_add_u32_e32 v7, 0x4000, v7
	s_nop 0
	v_addc_co_u32_e32 v5, vcc, 0, v5, vcc
	s_waitcnt vmcnt(2)
	v_lshlrev_b32_e32 v27, 16, v9
	v_lshlrev_b32_e32 v26, 16, v8
	v_and_b32_e32 v9, 0xffff0000, v9
	v_and_b32_e32 v8, 0xffff0000, v8
	v_pk_fma_f32 v[8:9], v[22:23], v[8:9], 0 op_sel_hi:[0,1,0]
	s_waitcnt vmcnt(1)
	v_lshlrev_b32_e32 v29, 16, v13
	v_lshlrev_b32_e32 v28, 16, v12
	v_and_b32_e32 v13, 0xffff0000, v13
	v_and_b32_e32 v12, 0xffff0000, v12
	v_pk_fma_f32 v[8:9], v[24:25], v[12:13], v[8:9] op_sel_hi:[0,1,1]
	s_waitcnt vmcnt(0)
	v_lshlrev_b32_e32 v13, 16, v17
	v_lshlrev_b32_e32 v12, 16, v16
	v_and_b32_e32 v17, 0xffff0000, v17
	v_and_b32_e32 v16, 0xffff0000, v16
	v_pk_fma_f32 v[8:9], v[20:21], v[16:17], v[8:9] op_sel_hi:[0,1,1]
	v_lshlrev_b32_e32 v17, 16, v11
	v_lshlrev_b32_e32 v16, 16, v10
	v_and_b32_e32 v11, 0xffff0000, v11
	v_and_b32_e32 v10, 0xffff0000, v10
	v_pk_fma_f32 v[26:27], v[22:23], v[26:27], 0 op_sel_hi:[0,1,0]
	v_pk_fma_f32 v[16:17], v[22:23], v[16:17], 0 op_sel_hi:[0,1,0]
	v_pk_fma_f32 v[10:11], v[22:23], v[10:11], 0 op_sel_hi:[0,1,0]
	v_lshlrev_b32_e32 v23, 16, v15
	v_lshlrev_b32_e32 v22, 16, v14
	v_and_b32_e32 v15, 0xffff0000, v15
	v_and_b32_e32 v14, 0xffff0000, v14
	v_pk_fma_f32 v[16:17], v[24:25], v[22:23], v[16:17] op_sel_hi:[0,1,1]
	v_pk_fma_f32 v[10:11], v[24:25], v[14:15], v[10:11] op_sel_hi:[0,1,1]
	v_lshlrev_b32_e32 v15, 16, v19
	v_lshlrev_b32_e32 v14, 16, v18
	v_pk_fma_f32 v[14:15], v[20:21], v[14:15], v[16:17] op_sel_hi:[0,1,1]
	v_and_b32_e32 v17, 0xffff0000, v19
	v_and_b32_e32 v16, 0xffff0000, v18
	v_pk_fma_f32 v[26:27], v[24:25], v[28:29], v[26:27] op_sel_hi:[0,1,1]
	v_pk_fma_f32 v[10:11], v[20:21], v[16:17], v[10:11] op_sel_hi:[0,1,1]
	v_pk_fma_f32 v[12:13], v[20:21], v[12:13], v[26:27] op_sel_hi:[0,1,1]
	v_cvt_pk_bf16_f32 v11, v15, v11
	v_cvt_pk_bf16_f32 v10, v14, v10
	v_cvt_pk_bf16_f32 v9, v13, v9
	v_cvt_pk_bf16_f32 v8, v12, v8
	global_store_dwordx4 v[4:5], v[8:11], off offset:2048
	v_add_u32_e32 v4, 0x200, v6
	v_ashrrev_i32_e32 v4, 7, v4
	v_ashrrev_i32_e32 v5, 31, v4
	v_lshlrev_b64 v[8:9], 6, v[4:5]
	v_lshl_add_u64 v[10:11], s[12:13], 0, v[8:9]
	v_lshl_add_u64 v[12:13], s[14:15], 0, v[8:9]
	v_lshl_add_u64 v[8:9], s[16:17], 0, v[8:9]
	v_lshl_add_u64 v[10:11], v[10:11], 0, v[82:83]
	v_lshl_add_u64 v[12:13], v[12:13], 0, v[82:83]
	v_lshl_add_u64 v[8:9], v[8:9], 0, v[82:83]
	global_load_dwordx2 v[10:11], v[10:11], off
	s_nop 0
	global_load_dwordx2 v[12:13], v[12:13], off
	s_nop 0
	global_load_dwordx2 v[8:9], v[8:9], off
	s_waitcnt vmcnt(0)
	v_max3_f32 v14, v10, v12, v8
	v_sub_f32_e32 v10, v10, v14
	v_sub_f32_e32 v12, v12, v14
	v_sub_f32_e32 v8, v8, v14
	v_exp_f32_e32 v10, v10
	v_exp_f32_e32 v15, v12
	v_exp_f32_e32 v14, v8
	v_mov_b32_e32 v12, v9
	v_fma_f32 v8, v11, v10, 0
	v_mul_f32_e32 v18, v11, v10
	v_pk_mul_f32 v[20:21], v[12:13], v[14:15]
	s_nop 0
	v_add_f32_e32 v8, v21, v8
	v_add_f32_e32 v8, v20, v8
	v_div_scale_f32 v9, s[20:21], v8, v8, 1.0
	v_rcp_f32_e32 v10, v9
	s_nop 0
	v_fma_f32 v11, -v9, v10, 1.0
	v_fmac_f32_e32 v10, v11, v10
	v_div_scale_f32 v11, vcc, 1.0, v8, 1.0
	v_mul_f32_e32 v12, v11, v10
	v_fma_f32 v13, -v9, v12, v11
	v_fmac_f32_e32 v12, v13, v10
	v_fma_f32 v9, -v9, v12, v11
	v_div_fmas_f32 v9, v9, v10, v12
	v_div_fixup_f32 v23, v9, v8, 1.0
	v_lshlrev_b64 v[8:9], 11, v[4:5]
	v_lshl_add_u64 v[8:9], s[10:11], 0, v[8:9]
	v_lshl_add_u64 v[16:17], v[8:9], 0, v[2:3]
	v_add_co_u32_e32 v12, vcc, s56, v16
	global_load_dwordx4 v[8:11], v[16:17], off
	s_nop 0
	v_addc_co_u32_e32 v13, vcc, 0, v17, vcc
	global_load_dwordx4 v[12:15], v[12:13], off
	v_add_co_u32_e32 v16, vcc, s57, v16
	v_mul_f32_e32 v22, v18, v23
	s_nop 0
	v_addc_co_u32_e32 v17, vcc, 0, v17, vcc
	global_load_dwordx4 v[16:19], v[16:17], off
	v_mul_f32_e32 v24, v21, v23
	v_mul_f32_e32 v20, v20, v23
	v_lshlrev_b64 v[4:5], 12, v[4:5]
	v_lshl_add_u64 v[4:5], s[88:89], 0, v[4:5]
	v_lshl_add_u64 v[4:5], v[4:5], 0, v[2:3]
	v_add_co_u32_e32 v4, vcc, s62, v4
	s_waitcnt vmcnt(2)
	v_lshlrev_b32_e32 v27, 16, v9
	v_lshlrev_b32_e32 v26, 16, v8
	v_and_b32_e32 v9, 0xffff0000, v9
	v_and_b32_e32 v8, 0xffff0000, v8
	v_pk_fma_f32 v[8:9], v[22:23], v[8:9], 0 op_sel_hi:[0,1,0]
	s_waitcnt vmcnt(1)
	v_lshlrev_b32_e32 v29, 16, v13
	v_lshlrev_b32_e32 v28, 16, v12
	v_and_b32_e32 v13, 0xffff0000, v13
	v_and_b32_e32 v12, 0xffff0000, v12
	v_pk_fma_f32 v[8:9], v[24:25], v[12:13], v[8:9] op_sel_hi:[0,1,1]
	s_waitcnt vmcnt(0)
	v_lshlrev_b32_e32 v13, 16, v17
	v_lshlrev_b32_e32 v12, 16, v16
	v_and_b32_e32 v17, 0xffff0000, v17
	v_and_b32_e32 v16, 0xffff0000, v16
	v_pk_fma_f32 v[8:9], v[20:21], v[16:17], v[8:9] op_sel_hi:[0,1,1]
	v_lshlrev_b32_e32 v17, 16, v11
	v_lshlrev_b32_e32 v16, 16, v10
	v_and_b32_e32 v11, 0xffff0000, v11
	v_and_b32_e32 v10, 0xffff0000, v10
	v_pk_fma_f32 v[26:27], v[22:23], v[26:27], 0 op_sel_hi:[0,1,0]
	v_pk_fma_f32 v[16:17], v[22:23], v[16:17], 0 op_sel_hi:[0,1,0]
	v_pk_fma_f32 v[10:11], v[22:23], v[10:11], 0 op_sel_hi:[0,1,0]
	v_lshlrev_b32_e32 v23, 16, v15
	v_lshlrev_b32_e32 v22, 16, v14
	v_and_b32_e32 v15, 0xffff0000, v15
	v_and_b32_e32 v14, 0xffff0000, v14
	v_pk_fma_f32 v[16:17], v[24:25], v[22:23], v[16:17] op_sel_hi:[0,1,1]
	v_pk_fma_f32 v[10:11], v[24:25], v[14:15], v[10:11] op_sel_hi:[0,1,1]
	v_lshlrev_b32_e32 v15, 16, v19
	v_lshlrev_b32_e32 v14, 16, v18
	v_pk_fma_f32 v[14:15], v[20:21], v[14:15], v[16:17] op_sel_hi:[0,1,1]
	v_and_b32_e32 v17, 0xffff0000, v19
	v_and_b32_e32 v16, 0xffff0000, v18
	v_pk_fma_f32 v[26:27], v[24:25], v[28:29], v[26:27] op_sel_hi:[0,1,1]
	v_pk_fma_f32 v[10:11], v[20:21], v[16:17], v[10:11] op_sel_hi:[0,1,1]
	v_pk_fma_f32 v[12:13], v[20:21], v[12:13], v[26:27] op_sel_hi:[0,1,1]
	v_cvt_pk_bf16_f32 v11, v15, v11
	v_cvt_pk_bf16_f32 v10, v14, v10
	v_cvt_pk_bf16_f32 v9, v13, v9
	v_cvt_pk_bf16_f32 v8, v12, v8
	v_addc_co_u32_e32 v5, vcc, 0, v5, vcc
	global_store_dwordx4 v[4:5], v[8:11], off offset:2048
	v_add_u32_e32 v4, 0x400, v6
	v_ashrrev_i32_e32 v4, 7, v4
	v_ashrrev_i32_e32 v5, 31, v4
	v_lshlrev_b64 v[8:9], 6, v[4:5]
	v_lshl_add_u64 v[10:11], s[12:13], 0, v[8:9]
	v_lshl_add_u64 v[12:13], s[14:15], 0, v[8:9]
	v_lshl_add_u64 v[8:9], s[16:17], 0, v[8:9]
	v_lshl_add_u64 v[10:11], v[10:11], 0, v[82:83]
	v_lshl_add_u64 v[12:13], v[12:13], 0, v[82:83]
	v_lshl_add_u64 v[8:9], v[8:9], 0, v[82:83]
	global_load_dwordx2 v[10:11], v[10:11], off
	s_nop 0
	global_load_dwordx2 v[12:13], v[12:13], off
	s_nop 0
	global_load_dwordx2 v[8:9], v[8:9], off
	s_waitcnt vmcnt(0)
	v_max3_f32 v14, v10, v12, v8
	v_sub_f32_e32 v10, v10, v14
	v_sub_f32_e32 v12, v12, v14
	v_sub_f32_e32 v8, v8, v14
	v_exp_f32_e32 v10, v10
	v_exp_f32_e32 v15, v12
	v_exp_f32_e32 v14, v8
	v_mov_b32_e32 v12, v9
	v_fma_f32 v8, v11, v10, 0
	v_mul_f32_e32 v18, v11, v10
	v_pk_mul_f32 v[20:21], v[12:13], v[14:15]
	s_nop 0
	v_add_f32_e32 v8, v21, v8
	v_add_f32_e32 v8, v20, v8
	v_div_scale_f32 v9, s[20:21], v8, v8, 1.0
	v_rcp_f32_e32 v10, v9
	s_nop 0
	v_fma_f32 v11, -v9, v10, 1.0
	v_fmac_f32_e32 v10, v11, v10
	v_div_scale_f32 v11, vcc, 1.0, v8, 1.0
	v_mul_f32_e32 v12, v11, v10
	v_fma_f32 v13, -v9, v12, v11
	v_fmac_f32_e32 v12, v13, v10
	v_fma_f32 v9, -v9, v12, v11
	v_div_fmas_f32 v9, v9, v10, v12
	v_div_fixup_f32 v23, v9, v8, 1.0
	v_lshlrev_b64 v[8:9], 11, v[4:5]
	v_lshl_add_u64 v[8:9], s[10:11], 0, v[8:9]
	v_lshl_add_u64 v[16:17], v[8:9], 0, v[2:3]
	v_add_co_u32_e32 v12, vcc, s56, v16
	global_load_dwordx4 v[8:11], v[16:17], off
	s_nop 0
	v_addc_co_u32_e32 v13, vcc, 0, v17, vcc
	global_load_dwordx4 v[12:15], v[12:13], off
	v_add_co_u32_e32 v16, vcc, s57, v16
	v_mul_f32_e32 v22, v18, v23
	s_nop 0
	v_addc_co_u32_e32 v17, vcc, 0, v17, vcc
	global_load_dwordx4 v[16:19], v[16:17], off
	v_mul_f32_e32 v24, v21, v23
	v_mul_f32_e32 v20, v20, v23
	v_lshlrev_b64 v[4:5], 12, v[4:5]
	v_lshl_add_u64 v[4:5], s[88:89], 0, v[4:5]
	v_lshl_add_u64 v[4:5], v[4:5], 0, v[2:3]
	v_add_co_u32_e32 v4, vcc, s62, v4
	s_waitcnt vmcnt(2)
	v_lshlrev_b32_e32 v27, 16, v9
	v_lshlrev_b32_e32 v26, 16, v8
	v_and_b32_e32 v9, 0xffff0000, v9
	v_and_b32_e32 v8, 0xffff0000, v8
	v_pk_fma_f32 v[8:9], v[22:23], v[8:9], 0 op_sel_hi:[0,1,0]
	s_waitcnt vmcnt(1)
	v_lshlrev_b32_e32 v29, 16, v13
	v_lshlrev_b32_e32 v28, 16, v12
	v_and_b32_e32 v13, 0xffff0000, v13
	v_and_b32_e32 v12, 0xffff0000, v12
	v_pk_fma_f32 v[8:9], v[24:25], v[12:13], v[8:9] op_sel_hi:[0,1,1]
	s_waitcnt vmcnt(0)
	v_lshlrev_b32_e32 v13, 16, v17
	v_lshlrev_b32_e32 v12, 16, v16
	v_and_b32_e32 v17, 0xffff0000, v17
	v_and_b32_e32 v16, 0xffff0000, v16
	v_pk_fma_f32 v[8:9], v[20:21], v[16:17], v[8:9] op_sel_hi:[0,1,1]
	v_lshlrev_b32_e32 v17, 16, v11
	v_lshlrev_b32_e32 v16, 16, v10
	v_and_b32_e32 v11, 0xffff0000, v11
	v_and_b32_e32 v10, 0xffff0000, v10
	v_pk_fma_f32 v[26:27], v[22:23], v[26:27], 0 op_sel_hi:[0,1,0]
	v_pk_fma_f32 v[16:17], v[22:23], v[16:17], 0 op_sel_hi:[0,1,0]
	v_pk_fma_f32 v[10:11], v[22:23], v[10:11], 0 op_sel_hi:[0,1,0]
	v_lshlrev_b32_e32 v23, 16, v15
	v_lshlrev_b32_e32 v22, 16, v14
	v_and_b32_e32 v15, 0xffff0000, v15
	v_and_b32_e32 v14, 0xffff0000, v14
	v_pk_fma_f32 v[16:17], v[24:25], v[22:23], v[16:17] op_sel_hi:[0,1,1]
	v_pk_fma_f32 v[10:11], v[24:25], v[14:15], v[10:11] op_sel_hi:[0,1,1]
	v_lshlrev_b32_e32 v15, 16, v19
	v_lshlrev_b32_e32 v14, 16, v18
	v_pk_fma_f32 v[14:15], v[20:21], v[14:15], v[16:17] op_sel_hi:[0,1,1]
	v_and_b32_e32 v17, 0xffff0000, v19
	v_and_b32_e32 v16, 0xffff0000, v18
	v_pk_fma_f32 v[26:27], v[24:25], v[28:29], v[26:27] op_sel_hi:[0,1,1]
	v_pk_fma_f32 v[10:11], v[20:21], v[16:17], v[10:11] op_sel_hi:[0,1,1]
	v_pk_fma_f32 v[12:13], v[20:21], v[12:13], v[26:27] op_sel_hi:[0,1,1]
	v_cvt_pk_bf16_f32 v11, v15, v11
	v_cvt_pk_bf16_f32 v10, v14, v10
	v_cvt_pk_bf16_f32 v9, v13, v9
	v_cvt_pk_bf16_f32 v8, v12, v8
	v_addc_co_u32_e32 v5, vcc, 0, v5, vcc
	global_store_dwordx4 v[4:5], v[8:11], off offset:2048
	v_add_u32_e32 v4, 0x600, v6
	v_ashrrev_i32_e32 v4, 7, v4
	v_ashrrev_i32_e32 v5, 31, v4
	v_lshlrev_b64 v[8:9], 6, v[4:5]
	v_lshl_add_u64 v[10:11], s[12:13], 0, v[8:9]
	v_lshl_add_u64 v[12:13], s[14:15], 0, v[8:9]
	v_lshl_add_u64 v[8:9], s[16:17], 0, v[8:9]
	v_lshl_add_u64 v[10:11], v[10:11], 0, v[82:83]
	v_lshl_add_u64 v[12:13], v[12:13], 0, v[82:83]
	v_lshl_add_u64 v[8:9], v[8:9], 0, v[82:83]
	global_load_dwordx2 v[10:11], v[10:11], off
	v_add_u32_e32 v6, 0x800, v6
	global_load_dwordx2 v[12:13], v[12:13], off
	s_nop 0
	global_load_dwordx2 v[8:9], v[8:9], off
	s_waitcnt vmcnt(0)
	v_max3_f32 v14, v10, v12, v8
	v_sub_f32_e32 v10, v10, v14
	v_sub_f32_e32 v12, v12, v14
	v_sub_f32_e32 v8, v8, v14
	v_exp_f32_e32 v10, v10
	v_exp_f32_e32 v15, v12
	v_exp_f32_e32 v14, v8
	v_mov_b32_e32 v12, v9
	v_fma_f32 v8, v11, v10, 0
	v_mul_f32_e32 v18, v11, v10
	v_pk_mul_f32 v[20:21], v[12:13], v[14:15]
	s_nop 0
	v_add_f32_e32 v8, v21, v8
	v_add_f32_e32 v8, v20, v8
	v_div_scale_f32 v9, s[20:21], v8, v8, 1.0
	v_rcp_f32_e32 v10, v9
	s_nop 0
	v_fma_f32 v11, -v9, v10, 1.0
	v_fmac_f32_e32 v10, v11, v10
	v_div_scale_f32 v11, vcc, 1.0, v8, 1.0
	v_mul_f32_e32 v12, v11, v10
	v_fma_f32 v13, -v9, v12, v11
	v_fmac_f32_e32 v12, v13, v10
	v_fma_f32 v9, -v9, v12, v11
	v_div_fmas_f32 v9, v9, v10, v12
	v_div_fixup_f32 v23, v9, v8, 1.0
	v_lshlrev_b64 v[8:9], 11, v[4:5]
	v_lshl_add_u64 v[8:9], s[10:11], 0, v[8:9]
	v_lshl_add_u64 v[16:17], v[8:9], 0, v[2:3]
	v_add_co_u32_e32 v12, vcc, s56, v16
	global_load_dwordx4 v[8:11], v[16:17], off
	s_nop 0
	v_addc_co_u32_e32 v13, vcc, 0, v17, vcc
	global_load_dwordx4 v[12:15], v[12:13], off
	v_add_co_u32_e32 v16, vcc, s57, v16
	v_mul_f32_e32 v22, v18, v23
	s_nop 0
	v_addc_co_u32_e32 v17, vcc, 0, v17, vcc
	global_load_dwordx4 v[16:19], v[16:17], off
	v_mul_f32_e32 v24, v21, v23
	v_mul_f32_e32 v20, v20, v23
	v_lshlrev_b64 v[4:5], 12, v[4:5]
	v_lshl_add_u64 v[4:5], s[88:89], 0, v[4:5]
	v_lshl_add_u64 v[2:3], v[4:5], 0, v[2:3]
	v_add_co_u32_e32 v2, vcc, 0x1b81e000, v2
	s_waitcnt vmcnt(2)
	v_lshlrev_b32_e32 v27, 16, v9
	v_lshlrev_b32_e32 v26, 16, v8
	v_and_b32_e32 v9, 0xffff0000, v9
	v_and_b32_e32 v8, 0xffff0000, v8
	v_pk_fma_f32 v[8:9], v[22:23], v[8:9], 0 op_sel_hi:[0,1,0]
	s_waitcnt vmcnt(1)
	v_lshlrev_b32_e32 v29, 16, v13
	v_lshlrev_b32_e32 v28, 16, v12
	v_and_b32_e32 v13, 0xffff0000, v13
	v_and_b32_e32 v12, 0xffff0000, v12
	v_pk_fma_f32 v[8:9], v[24:25], v[12:13], v[8:9] op_sel_hi:[0,1,1]
	s_waitcnt vmcnt(0)
	v_lshlrev_b32_e32 v13, 16, v17
	v_lshlrev_b32_e32 v12, 16, v16
	v_and_b32_e32 v17, 0xffff0000, v17
	v_and_b32_e32 v16, 0xffff0000, v16
	v_pk_fma_f32 v[8:9], v[20:21], v[16:17], v[8:9] op_sel_hi:[0,1,1]
	v_lshlrev_b32_e32 v17, 16, v11
	v_lshlrev_b32_e32 v16, 16, v10
	v_and_b32_e32 v11, 0xffff0000, v11
	v_and_b32_e32 v10, 0xffff0000, v10
	v_pk_fma_f32 v[26:27], v[22:23], v[26:27], 0 op_sel_hi:[0,1,0]
	v_pk_fma_f32 v[16:17], v[22:23], v[16:17], 0 op_sel_hi:[0,1,0]
	v_pk_fma_f32 v[10:11], v[22:23], v[10:11], 0 op_sel_hi:[0,1,0]
	v_lshlrev_b32_e32 v23, 16, v15
	v_lshlrev_b32_e32 v22, 16, v14
	v_and_b32_e32 v15, 0xffff0000, v15
	v_and_b32_e32 v14, 0xffff0000, v14
	v_pk_fma_f32 v[16:17], v[24:25], v[22:23], v[16:17] op_sel_hi:[0,1,1]
	v_pk_fma_f32 v[10:11], v[24:25], v[14:15], v[10:11] op_sel_hi:[0,1,1]
	v_lshlrev_b32_e32 v15, 16, v19
	v_lshlrev_b32_e32 v14, 16, v18
	v_pk_fma_f32 v[14:15], v[20:21], v[14:15], v[16:17] op_sel_hi:[0,1,1]
	v_and_b32_e32 v17, 0xffff0000, v19
	v_and_b32_e32 v16, 0xffff0000, v18
	v_pk_fma_f32 v[26:27], v[24:25], v[28:29], v[26:27] op_sel_hi:[0,1,1]
	v_pk_fma_f32 v[10:11], v[20:21], v[16:17], v[10:11] op_sel_hi:[0,1,1]
	v_pk_fma_f32 v[12:13], v[20:21], v[12:13], v[26:27] op_sel_hi:[0,1,1]
	v_bfe_u32 v16, v11, 16, 1
	v_bfe_u32 v17, v10, 16, 1
	v_bfe_u32 v18, v9, 16, 1
	v_bfe_u32 v19, v8, 16, 1
	v_add3_u32 v8, v8, v19, s73
	v_add3_u32 v9, v9, v18, s73
	v_add3_u32 v10, v10, v17, s73
	v_add3_u32 v11, v11, v16, s73
	v_bfe_u32 v16, v12, 16, 1
	v_bfe_u32 v17, v13, 16, 1
	v_bfe_u32 v18, v14, 16, 1
	v_bfe_u32 v19, v15, 16, 1
	v_add3_u32 v15, v15, v19, s73
	v_add3_u32 v14, v14, v18, s73
	v_add3_u32 v13, v13, v17, s73
	v_add3_u32 v12, v12, v16, s73
	v_addc_co_u32_e32 v3, vcc, 0, v3, vcc
	v_lshrrev_b32_e32 v12, 16, v12
	v_lshrrev_b32_e32 v13, 16, v13
	v_lshrrev_b32_e32 v14, 16, v14
	v_lshrrev_b32_e32 v15, 16, v15
	v_cmp_le_i32_e32 vcc, s22, v6
	v_and_or_b32 v11, v11, s33, v15
	v_and_or_b32 v10, v10, s33, v14
	v_and_or_b32 v9, v9, s33, v13
	v_and_or_b32 v8, v8, s33, v12
	s_or_b64 s[18:19], vcc, s[18:19]
	global_store_dwordx4 v[2:3], v[8:11], off offset:2048
	s_andn2_b64 exec, exec, s[18:19]
	s_cbranch_execnz .LBB0_1018

.LBB0_1034:
	s_or_b64 exec, exec, s[8:9]
	s_add_u32 s62, s88, 0xee19000
	s_addc_u32 s63, s89, 0
	s_lshl_b32 s8, s96, 2
	v_readlane_b32 s9, v253, 16
	s_add_i32 s8, s9, s8
	s_lshl_b32 s10, s8, 3
	s_and_b32 s55, s10, 0x7fffffc0
	v_readlane_b32 s10, v253, 19
	v_lshlrev_b32_e32 v12, 4, v1
	s_and_b32 s9, s8, 7
	v_add_u32_e32 v7, s10, v1
	v_ashrrev_i32_e32 v10, 4, v7
	v_and_b32_e32 v82, 0xf0, v12
	v_readlane_b32 s10, v253, 18
	v_add_u32_e32 v2, s55, v10
	v_mov_b64_e32 v[8:9], s[62:63]
	v_add_u32_e32 v6, s10, v82
	v_mad_i64_i32 v[2:3], s[10:11], v2, s83, v[8:9]
	s_lshl_b32 s70, s9, 8
	v_lshl_add_u64 v[2:3], v[2:3], 0, s[70:71]
	v_lshl_add_u64 v[2:3], v[2:3], 0, v[82:83]
	s_barrier
	global_load_dwordx4 v[2:5], v[2:3], off offset:2048
	v_mad_u64_u32 v[10:11], s[10:11], v10, s5, v[6:7]
	s_lshl_b32 s54, s9, 7
	s_mov_b32 s9, s71
	s_waitcnt vmcnt(10)
	v_and_b32_e32 v138, 31, v1
	v_readlane_b32 s14, v253, 17
	s_mul_i32 s13, s8, 0x300
	s_load_dwordx2 s[64:65], s[40:41], 0x70
	v_or_b32_e32 v141, s14, v138
	s_mul_hi_u32 s12, s8, 0x300
	v_ashrrev_i32_e32 v143, 5, v1
	v_lshlrev_b32_e32 v134, 2, v143
	s_movk_i32 s61, 0x440
	v_ashrrev_i32_e32 v135, 31, v134
	s_mov_b32 s60, 0
	v_mov_b32_e32 v146, 0
	s_waitcnt vmcnt(0)
	ds_write_b128 v10, v[2:5]
	v_add_u32_e32 v2, 0x80, v7
	v_ashrrev_i32_e32 v10, 4, v2
	v_add_u32_e32 v2, s55, v10
	v_mad_i64_i32 v[2:3], s[10:11], v2, s83, v[8:9]
	v_lshl_add_u64 v[2:3], v[2:3], 0, s[70:71]
	v_lshl_add_u64 v[2:3], v[2:3], 0, v[82:83]
	global_load_dwordx4 v[2:5], v[2:3], off offset:2048
	v_mad_u64_u32 v[10:11], s[10:11], v10, s5, v[6:7]
	s_waitcnt vmcnt(0)
	ds_write_b128 v10, v[2:5]
	v_add_u32_e32 v2, 0x100, v7
	v_ashrrev_i32_e32 v10, 4, v2
	v_add_u32_e32 v2, s55, v10
	v_mad_i64_i32 v[2:3], s[10:11], v2, s83, v[8:9]
	v_lshl_add_u64 v[2:3], v[2:3], 0, s[70:71]
	v_lshl_add_u64 v[2:3], v[2:3], 0, v[82:83]
	global_load_dwordx4 v[2:5], v[2:3], off offset:2048
	v_mad_u64_u32 v[10:11], s[10:11], v10, s5, v[6:7]
	s_waitcnt vmcnt(0)
	ds_write_b128 v10, v[2:5]
	v_add_u32_e32 v2, 0x180, v7
	v_ashrrev_i32_e32 v10, 4, v2
	v_add_u32_e32 v2, s55, v10
	v_mad_i64_i32 v[2:3], s[10:11], v2, s83, v[8:9]
	v_lshl_add_u64 v[2:3], v[2:3], 0, s[70:71]
	v_lshl_add_u64 v[2:3], v[2:3], 0, v[82:83]
	global_load_dwordx4 v[2:5], v[2:3], off offset:2048
	v_mad_u64_u32 v[10:11], s[10:11], v10, s5, v[6:7]
	s_waitcnt vmcnt(0)
	ds_write_b128 v10, v[2:5]
	v_add_u32_e32 v2, 0x200, v7
	v_ashrrev_i32_e32 v10, 4, v2
	v_add_u32_e32 v2, s55, v10
	v_mad_i64_i32 v[2:3], s[10:11], v2, s83, v[8:9]
	v_lshl_add_u64 v[2:3], v[2:3], 0, s[70:71]
	v_lshl_add_u64 v[2:3], v[2:3], 0, v[82:83]
	global_load_dwordx4 v[2:5], v[2:3], off offset:2048
	v_mad_u64_u32 v[10:11], s[10:11], v10, s5, v[6:7]
	s_waitcnt vmcnt(0)
	ds_write_b128 v10, v[2:5]
	v_add_u32_e32 v2, 0x280, v7
	v_ashrrev_i32_e32 v10, 4, v2
	v_add_u32_e32 v2, s55, v10
	v_mad_i64_i32 v[2:3], s[10:11], v2, s83, v[8:9]
	v_lshl_add_u64 v[2:3], v[2:3], 0, s[70:71]
	v_lshl_add_u64 v[2:3], v[2:3], 0, v[82:83]
	global_load_dwordx4 v[2:5], v[2:3], off offset:2048
	v_mad_u64_u32 v[10:11], s[10:11], v10, s5, v[6:7]
	s_waitcnt vmcnt(0)
	ds_write_b128 v10, v[2:5]
	v_add_u32_e32 v2, 0x300, v7
	v_ashrrev_i32_e32 v10, 4, v2
	v_add_u32_e32 v2, s55, v10
	v_mad_i64_i32 v[2:3], s[10:11], v2, s83, v[8:9]
	v_lshl_add_u64 v[2:3], v[2:3], 0, s[70:71]
	v_lshl_add_u64 v[2:3], v[2:3], 0, v[82:83]
	global_load_dwordx4 v[2:5], v[2:3], off offset:2048
	v_mad_u64_u32 v[10:11], s[10:11], v10, s5, v[6:7]
	s_waitcnt vmcnt(0)
	ds_write_b128 v10, v[2:5]
	v_add_u32_e32 v2, 0x380, v7
	v_ashrrev_i32_e32 v7, 4, v2
	v_add_u32_e32 v2, s55, v7
	v_mad_i64_i32 v[2:3], s[10:11], v2, s83, v[8:9]
	v_lshl_add_u64 v[2:3], v[2:3], 0, s[70:71]
	v_lshl_add_u64 v[2:3], v[2:3], 0, v[82:83]
	global_load_dwordx4 v[2:5], v[2:3], off offset:2048
	v_mad_u64_u32 v[6:7], s[10:11], v7, s5, v[6:7]
	s_lshl_b64 s[10:11], s[8:9], 2
	s_add_u32 s10, s88, s10
	s_addc_u32 s11, s89, s11
	s_add_u32 s40, s88, s13
	v_lshlrev_b32_e32 v82, 2, v141
	s_addc_u32 s41, s89, s12
	s_mov_b32 s9, 0x1519d000
	s_waitcnt vmcnt(0)
	ds_write_b128 v6, v[2:5]
	v_mov_b32_e32 v2, 0x1869d000
	global_load_dword v6, v2, s[10:11]
	v_lshl_add_u64 v[2:3], s[40:41], 0, v[82:83]
	s_mov_b64 s[10:11], 0x1519d000
	v_lshl_add_u64 v[4:5], v[2:3], 0, s[10:11]
	v_add_co_u32_e32 v2, vcc, s9, v2
	s_add_u32 s10, s62, s54
	s_nop 0
	v_addc_co_u32_e32 v3, vcc, 0, v3, vcc
	global_load_dword v139, v[2:3], off
	s_nop 0
	global_load_dword v2, v[4:5], off offset:512
	s_addc_u32 s11, s63, 0
	v_and_b32_e32 v82, 0x70, v12
	v_lshl_add_u64 v[132:133], s[10:11], 0, v[82:83]
	v_readlane_b32 s9, v253, 20
	s_waitcnt vmcnt(2)
	v_max_f32_e32 v3, v6, v6
	v_add_u32_e32 v20, s9, v82
	s_waitcnt vmcnt(0)
	v_max_f32_e32 v2, v2, v2
	v_max_f32_e32 v140, v3, v2
	v_sub_f32_e32 v2, v6, v140
	v_mul_f32_e32 v3, 0x3fb8aa3b, v2
	v_ashrrev_i32_e32 v2, 3, v1
	v_add_u32_e32 v142, s55, v2
	v_add_u32_e32 v16, s14, v142
	v_mad_i64_i32 v[4:5], s[10:11], v16, s83, v[132:133]
	v_add_u32_e32 v8, 8, v16
	global_load_dwordx4 v[4:7], v[4:5], off
	v_mad_i64_i32 v[8:9], s[10:11], v8, s83, v[132:133]
	v_add_u32_e32 v12, 16, v16
	global_load_dwordx4 v[8:11], v[8:9], off
	v_mad_i64_i32 v[12:13], s[10:11], v12, s83, v[132:133]
	v_add_u32_e32 v16, 24, v16
	global_load_dwordx4 v[12:15], v[12:13], off
	v_mad_i64_i32 v[16:17], s[10:11], v16, s83, v[132:133]
	global_load_dwordx4 v[16:19], v[16:17], off
	s_movk_i32 s10, 0x90
	v_mul_lo_u32 v21, v2, s10
	v_add_u32_e32 v144, v20, v21
	s_waitcnt vmcnt(3)
	ds_write_b128 v144, v[4:7]
	s_waitcnt vmcnt(2)
	ds_write_b128 v144, v[8:11] offset:1152
	s_waitcnt vmcnt(1)
	ds_write_b128 v144, v[12:15] offset:2304
	s_waitcnt vmcnt(0)
	ds_write_b128 v144, v[16:19] offset:3456
	v_exp_f32_e32 v4, v3
	v_mov_b32_e32 v3, s9
	v_mad_u32_u24 v3, v138, s10, v3
	v_lshlrev_b32_e32 v5, 4, v143
	s_waitcnt lgkmcnt(0)
	v_add_u32_e32 v145, v3, v5
	ds_read_b128 v[96:99], v145
	ds_read_b128 v[104:107], v145 offset:32
	ds_read_b128 v[108:111], v145 offset:64
	ds_read_b128 v[112:115], v145 offset:96
	s_mul_hi_u32 s9, s8, 0x5000
	s_waitcnt lgkmcnt(0)
	v_and_b32_e32 v9, 0xffff0000, v97
	v_and_b32_e32 v8, 0xffff0000, v96
	v_and_b32_e32 v13, 0xffff0000, v99
	v_and_b32_e32 v12, 0xffff0000, v98
	v_lshlrev_b32_e32 v7, 16, v97
	v_lshlrev_b32_e32 v6, 16, v96
	v_pk_mul_f32 v[8:9], v[4:5], v[8:9] op_sel_hi:[0,1]
	v_lshlrev_b32_e32 v11, 16, v99
	v_lshlrev_b32_e32 v10, 16, v98
	v_pk_mul_f32 v[12:13], v[4:5], v[12:13] op_sel_hi:[0,1]
	v_pk_mul_f32 v[6:7], v[4:5], v[6:7] op_sel_hi:[0,1]
	v_pk_mul_f32 v[10:11], v[4:5], v[10:11] op_sel_hi:[0,1]
	v_bfe_u32 v3, v13, 16, 1
	v_bfe_u32 v5, v12, 16, 1
	v_add3_u32 v5, v12, v5, s73
	v_add3_u32 v3, v13, v3, s73
	v_bfe_u32 v14, v10, 16, 1
	v_bfe_u32 v15, v11, 16, 1
	v_add3_u32 v11, v11, v15, s73
	v_add3_u32 v10, v10, v14, s73
	v_lshrrev_b32_e32 v10, 16, v10
	v_lshrrev_b32_e32 v11, 16, v11
	v_and_b32_e32 v13, 0xffff0000, v107
	v_and_b32_e32 v12, 0xffff0000, v106
	v_and_or_b32 v91, v3, s33, v11
	v_and_or_b32 v90, v5, s33, v10
	v_cvt_pk_bf16_f32 v89, v7, v9
	v_cvt_pk_bf16_f32 v88, v6, v8
	v_lshlrev_b32_e32 v7, 16, v105
	v_lshlrev_b32_e32 v6, 16, v104
	v_and_b32_e32 v9, 0xffff0000, v105
	v_and_b32_e32 v8, 0xffff0000, v104
	v_lshlrev_b32_e32 v11, 16, v107
	v_lshlrev_b32_e32 v10, 16, v106
	v_pk_mul_f32 v[12:13], v[4:5], v[12:13] op_sel_hi:[0,1]
	v_pk_mul_f32 v[6:7], v[4:5], v[6:7] op_sel_hi:[0,1]
	v_pk_mul_f32 v[8:9], v[4:5], v[8:9] op_sel_hi:[0,1]
	v_pk_mul_f32 v[10:11], v[4:5], v[10:11] op_sel_hi:[0,1]
	v_bfe_u32 v3, v13, 16, 1
	v_bfe_u32 v5, v12, 16, 1
	v_add3_u32 v5, v12, v5, s73
	v_add3_u32 v3, v13, v3, s73
	v_bfe_u32 v14, v10, 16, 1
	v_bfe_u32 v15, v11, 16, 1
	v_add3_u32 v11, v11, v15, s73
	v_add3_u32 v10, v10, v14, s73
	v_lshrrev_b32_e32 v10, 16, v10
	v_lshrrev_b32_e32 v11, 16, v11
	v_cvt_pk_bf16_f32 v85, v7, v9
	v_cvt_pk_bf16_f32 v84, v6, v8
	v_and_b32_e32 v9, 0xffff0000, v109
	v_and_b32_e32 v8, 0xffff0000, v108
	v_and_b32_e32 v13, 0xffff0000, v111
	v_and_b32_e32 v12, 0xffff0000, v110
	v_and_or_b32 v87, v3, s33, v11
	v_and_or_b32 v86, v5, s33, v10
	v_lshlrev_b32_e32 v7, 16, v109
	v_lshlrev_b32_e32 v6, 16, v108
	v_pk_mul_f32 v[8:9], v[4:5], v[8:9] op_sel_hi:[0,1]
	v_lshlrev_b32_e32 v11, 16, v111
	v_lshlrev_b32_e32 v10, 16, v110
	v_pk_mul_f32 v[12:13], v[4:5], v[12:13] op_sel_hi:[0,1]
	v_pk_mul_f32 v[6:7], v[4:5], v[6:7] op_sel_hi:[0,1]
	v_pk_mul_f32 v[10:11], v[4:5], v[10:11] op_sel_hi:[0,1]
	v_bfe_u32 v3, v13, 16, 1
	v_bfe_u32 v5, v12, 16, 1
	v_add3_u32 v5, v12, v5, s73
	v_add3_u32 v3, v13, v3, s73
	v_bfe_u32 v14, v10, 16, 1
	v_bfe_u32 v15, v11, 16, 1
	v_add3_u32 v11, v11, v15, s73
	v_add3_u32 v10, v10, v14, s73
	v_lshrrev_b32_e32 v10, 16, v10
	v_lshrrev_b32_e32 v11, 16, v11
	v_and_or_b32 v95, v3, s33, v11
	v_and_or_b32 v94, v5, s33, v10
	v_cvt_pk_bf16_f32 v93, v7, v9
	v_cvt_pk_bf16_f32 v92, v6, v8
	v_lshlrev_b32_e32 v7, 16, v113
	v_lshlrev_b32_e32 v6, 16, v112
	v_and_b32_e32 v9, 0xffff0000, v113
	v_and_b32_e32 v8, 0xffff0000, v112
	v_lshlrev_b32_e32 v11, 16, v115
	v_lshlrev_b32_e32 v10, 16, v114
	v_and_b32_e32 v13, 0xffff0000, v115
	v_and_b32_e32 v12, 0xffff0000, v114
	v_pk_mul_f32 v[6:7], v[4:5], v[6:7] op_sel_hi:[0,1]
	v_pk_mul_f32 v[8:9], v[4:5], v[8:9] op_sel_hi:[0,1]
	v_pk_mul_f32 v[10:11], v[4:5], v[10:11] op_sel_hi:[0,1]
	v_pk_mul_f32 v[4:5], v[4:5], v[12:13] op_sel_hi:[0,1]
	v_bfe_u32 v12, v4, 16, 1
	v_bfe_u32 v13, v9, 16, 1
	v_bfe_u32 v14, v8, 16, 1
	v_bfe_u32 v3, v5, 16, 1
	v_add3_u32 v8, v8, v14, s73
	v_add3_u32 v9, v9, v13, s73
	v_add3_u32 v4, v4, v12, s73
	v_bfe_u32 v12, v7, 16, 1
	v_bfe_u32 v13, v10, 16, 1
	v_bfe_u32 v14, v11, 16, 1
	v_add3_u32 v3, v5, v3, s73
	v_bfe_u32 v5, v6, 16, 1
	v_add3_u32 v11, v11, v14, s73
	v_add3_u32 v10, v10, v13, s73
	v_add3_u32 v7, v7, v12, s73
	s_mulk_i32 s8, 0x5000
	v_add3_u32 v5, v6, v5, s73
	v_lshrrev_b32_e32 v6, 16, v7
	v_lshrrev_b32_e32 v7, 16, v10
	v_lshrrev_b32_e32 v10, 16, v11
	s_add_u32 s8, s88, s8
	v_lshrrev_b32_e32 v5, 16, v5
	v_and_or_b32 v103, v3, s33, v10
	s_addc_u32 s9, s89, s9
	v_ashrrev_i32_e32 v3, 31, v2
	v_and_or_b32 v102, v4, s33, v7
	v_and_or_b32 v100, v8, s33, v5
	v_lshl_add_u64 v[4:5], s[8:9], 0, v[82:83]
	v_lshlrev_b64 v[2:3], 7, v[2:3]
	v_lshl_add_u64 v[66:67], v[4:5], 0, v[2:3]
	s_mov_b64 s[8:9], 0x1729d000
	v_lshl_add_u64 v[14:15], v[66:67], 0, s[8:9]
	s_mov_b32 s8, 0x1729e000
	v_add_co_u32_e32 v30, vcc, s8, v66
	v_and_or_b32 v101, v9, s33, v6
	s_nop 0
	v_addc_co_u32_e32 v31, vcc, 0, v67, vcc
	global_load_dwordx4 v[2:5], v[30:31], off offset:-4096
	global_load_dwordx4 v[6:9], v[14:15], off offset:1024
	global_load_dwordx4 v[10:13], v[14:15], off offset:2048
	s_nop 0
	global_load_dwordx4 v[14:17], v[14:15], off offset:3072
	s_waitcnt vmcnt(3)
	ds_write_b128 v144, v[2:5]
	s_waitcnt vmcnt(2)
	ds_write_b128 v144, v[6:9] offset:1152
	s_waitcnt vmcnt(1)
	ds_write_b128 v144, v[10:13] offset:2304
	s_waitcnt vmcnt(0)
	ds_write_b128 v144, v[14:17] offset:3456
	s_waitcnt lgkmcnt(0)
	ds_read_b128 v[2:5], v145
	ds_read_b128 v[18:21], v145 offset:32
	s_waitcnt lgkmcnt(1)
	v_mfma_f32_32x32x16_bf16 v[2:17], v[2:5], v[88:91], 0
	s_mov_b32 s8, 0x1729f000
	v_add_co_u32_e32 v46, vcc, s8, v66
	s_mov_b32 s8, 0x172a0000
	s_nop 0
	v_addc_co_u32_e32 v47, vcc, 0, v67, vcc
	v_add_co_u32_e32 v62, vcc, s8, v66
	s_waitcnt lgkmcnt(0)
	v_mfma_f32_32x32x16_bf16 v[2:17], v[18:21], v[84:87], v[2:17]
	ds_read_b128 v[18:21], v145 offset:64
	v_addc_co_u32_e32 v63, vcc, 0, v67, vcc
	s_mov_b32 s8, 0x172a1000
	v_add_co_u32_e32 v78, vcc, s8, v66
	v_cmp_lt_i32_e64 s[8:9], v134, v138
	s_waitcnt lgkmcnt(0)
	v_mfma_f32_32x32x16_bf16 v[2:17], v[18:21], v[92:95], v[2:17]
	ds_read_b128 v[18:21], v145 offset:96
	v_addc_co_u32_e32 v79, vcc, 0, v67, vcc
	v_cmp_le_i32_e32 vcc, v134, v138
	s_waitcnt lgkmcnt(0)
	v_mfma_f32_32x32x16_bf16 v[2:17], v[18:21], v[100:103], v[2:17]
	global_load_dwordx4 v[18:21], v[30:31], off
	global_load_dwordx4 v[22:25], v[30:31], off offset:1024
	global_load_dwordx4 v[26:29], v[30:31], off offset:2048
	s_nop 0
	global_load_dwordx4 v[30:33], v[30:31], off offset:3072
	s_waitcnt vmcnt(3)
	ds_write_b128 v144, v[18:21]
	s_waitcnt vmcnt(2)
	ds_write_b128 v144, v[22:25] offset:1152
	s_waitcnt vmcnt(1)
	ds_write_b128 v144, v[26:29] offset:2304
	s_waitcnt vmcnt(0)
	ds_write_b128 v144, v[30:33] offset:3456
	s_waitcnt lgkmcnt(0)
	ds_read_b128 v[18:21], v145
	ds_read_b128 v[34:37], v145 offset:32
	s_waitcnt lgkmcnt(1)
	v_mfma_f32_32x32x16_bf16 v[18:33], v[18:21], v[88:91], 0
	s_waitcnt lgkmcnt(0)
	v_mfma_f32_32x32x16_bf16 v[18:33], v[34:37], v[84:87], v[18:33]
	ds_read_b128 v[34:37], v145 offset:64
	s_waitcnt lgkmcnt(0)
	v_mfma_f32_32x32x16_bf16 v[18:33], v[34:37], v[92:95], v[18:33]
	ds_read_b128 v[34:37], v145 offset:96
	s_waitcnt lgkmcnt(0)
	v_mfma_f32_32x32x16_bf16 v[18:33], v[34:37], v[100:103], v[18:33]
	global_load_dwordx4 v[34:37], v[62:63], off offset:-4096
	global_load_dwordx4 v[38:41], v[46:47], off offset:1024
	global_load_dwordx4 v[42:45], v[46:47], off offset:2048
	s_nop 0
	global_load_dwordx4 v[46:49], v[46:47], off offset:3072
	s_waitcnt vmcnt(3)
	ds_write_b128 v144, v[34:37]
	s_waitcnt vmcnt(2)
	ds_write_b128 v144, v[38:41] offset:1152
	s_waitcnt vmcnt(1)
	ds_write_b128 v144, v[42:45] offset:2304
	s_waitcnt vmcnt(0)
	ds_write_b128 v144, v[46:49] offset:3456
	s_waitcnt lgkmcnt(0)
	ds_read_b128 v[34:37], v145
	ds_read_b128 v[50:53], v145 offset:32
	s_waitcnt lgkmcnt(1)
	v_mfma_f32_32x32x16_bf16 v[34:49], v[34:37], v[88:91], 0
	s_waitcnt lgkmcnt(0)
	v_mfma_f32_32x32x16_bf16 v[34:49], v[50:53], v[84:87], v[34:49]
	ds_read_b128 v[50:53], v145 offset:64
	s_waitcnt lgkmcnt(0)
	v_mfma_f32_32x32x16_bf16 v[34:49], v[50:53], v[92:95], v[34:49]
	ds_read_b128 v[50:53], v145 offset:96
	s_waitcnt lgkmcnt(0)
	v_mfma_f32_32x32x16_bf16 v[34:49], v[50:53], v[100:103], v[34:49]
	global_load_dwordx4 v[50:53], v[62:63], off
	global_load_dwordx4 v[54:57], v[62:63], off offset:1024
	global_load_dwordx4 v[58:61], v[62:63], off offset:2048
	s_nop 0
	global_load_dwordx4 v[62:65], v[62:63], off offset:3072
	s_waitcnt vmcnt(3)
	ds_write_b128 v144, v[50:53]
	s_waitcnt vmcnt(2)
	ds_write_b128 v144, v[54:57] offset:1152
	s_waitcnt vmcnt(1)
	ds_write_b128 v144, v[58:61] offset:2304
	s_waitcnt vmcnt(0)
	ds_write_b128 v144, v[62:65] offset:3456
	s_waitcnt lgkmcnt(0)
	ds_read_b128 v[50:53], v145
	ds_read_b128 v[68:71], v145 offset:32
	s_waitcnt lgkmcnt(1)
	v_mfma_f32_32x32x16_bf16 v[50:65], v[50:53], v[88:91], 0
	s_waitcnt lgkmcnt(0)
	v_mfma_f32_32x32x16_bf16 v[50:65], v[68:71], v[84:87], v[50:65]
	ds_read_b128 v[68:71], v145 offset:64
	s_waitcnt lgkmcnt(0)
	v_mfma_f32_32x32x16_bf16 v[50:65], v[68:71], v[92:95], v[50:65]
	ds_read_b128 v[68:71], v145 offset:96
	s_waitcnt lgkmcnt(0)
	v_mfma_f32_32x32x16_bf16 v[50:65], v[68:71], v[100:103], v[50:65]
	global_load_dwordx4 v[66:69], v[78:79], off
	global_load_dwordx4 v[70:73], v[78:79], off offset:1024
	global_load_dwordx4 v[74:77], v[78:79], off offset:2048
	s_nop 0
	global_load_dwordx4 v[78:81], v[78:79], off offset:3072
	s_waitcnt vmcnt(3)
	ds_write_b128 v144, v[66:69]
	s_waitcnt vmcnt(2)
	ds_write_b128 v144, v[70:73] offset:1152
	s_waitcnt vmcnt(1)
	ds_write_b128 v144, v[74:77] offset:2304
	s_waitcnt vmcnt(0)
	ds_write_b128 v144, v[78:81] offset:3456
	v_add_u32_e32 v66, 8, v134
	v_cmp_le_i32_e64 s[14:15], v66, v138
	v_add_u32_e32 v66, 9, v134
	v_cmp_le_i32_e64 s[16:17], v66, v138
	v_add_u32_e32 v66, 10, v134
	v_cmp_le_i32_e64 s[18:19], v66, v138
	v_add_u32_e32 v66, 11, v134
	v_cmp_le_i32_e64 s[20:21], v66, v138
	v_add_u32_e32 v66, 17, v134
	v_cmp_le_i32_e64 s[24:25], v66, v138
	v_add_u32_e32 v66, 18, v134
	v_cmp_le_i32_e64 s[26:27], v66, v138
	v_add_u32_e32 v66, 19, v134
	s_waitcnt lgkmcnt(0)
	v_cmp_le_i32_e64 s[28:29], v66, v138
	v_add_u32_e32 v66, 25, v134
	ds_read_b128 v[128:131], v145
	ds_read_b128 v[124:127], v145 offset:32
	ds_read_b128 v[120:123], v145 offset:64
	ds_read_b128 v[116:119], v145 offset:96
	v_cmp_le_i32_e64 s[34:35], v66, v138
	v_add_u32_e32 v66, 26, v134
	v_bfe_u32 v67, v1, 2, 2
	v_cmp_le_i32_e64 s[36:37], v66, v138
	v_add_u32_e32 v66, 27, v134
	v_cmp_le_i32_e64 s[38:39], v66, v138
	v_mul_lo_u32 v66, v143, s61
	v_mul_u32_u24_e32 v67, 0x110, v67
	v_readlane_b32 s61, v253, 60
	v_or_b32_e32 v70, 2, v134
	v_add_u32_e32 v68, 16, v134
	v_add3_u32 v66, s61, v66, v67
	v_lshlrev_b32_e32 v67, 1, v1
	v_and_b32_e32 v1, 3, v1
	v_and_b32_e32 v67, 32, v67
	v_lshlrev_b32_e32 v1, 3, v1
	v_add_u32_e32 v69, 24, v134
	v_cmp_le_i32_e64 s[10:11], v70, v138
	v_or_b32_e32 v70, 3, v134
	v_add3_u32 v1, v66, v67, v1
	v_lshl_add_u64 v[66:67], v[134:135], 2, s[40:41]
	s_mov_b64 s[40:41], 0x1519d160
	v_cmp_le_i32_e64 s[12:13], v70, v138
	v_cmp_le_i32_e64 s[22:23], v68, v138
	v_cmp_le_i32_e64 s[30:31], v69, v138
	v_lshl_add_u64 v[136:137], v[66:67], 0, s[40:41]
	s_mov_b32 s61, 0
	s_waitcnt lgkmcnt(0)
	s_barrier
.LBB0_1035:
	v_mad_i64_i32 v[66:67], s[40:41], v142, s83, v[132:133]
	v_add_u32_e32 v70, 8, v142
	global_load_dwordx4 v[66:69], v[66:67], off offset:1024
	v_mad_i64_i32 v[70:71], s[40:41], v70, s83, v[132:133]
	v_add_u32_e32 v74, 16, v142
	global_load_dwordx4 v[70:73], v[70:71], off offset:1024
	v_mad_i64_i32 v[74:75], s[40:41], v74, s83, v[132:133]
	v_add_u32_e32 v78, 24, v142
	global_load_dwordx4 v[74:77], v[74:75], off offset:1024
	v_mad_i64_i32 v[78:79], s[40:41], v78, s83, v[132:133]
	global_load_dwordx4 v[78:81], v[78:79], off offset:1024
	s_cmp_lt_u32 s61, s95
	s_cselect_b64 s[74:75], -1, 0
	s_or_b64 s[40:41], s[74:75], vcc
	s_add_i32 s61, s61, 1
	v_add_u32_e32 v142, 32, v142
	s_waitcnt vmcnt(3)
	ds_write_b128 v144, v[66:69]
	s_waitcnt vmcnt(2)
	ds_write_b128 v144, v[70:73] offset:1152
	s_waitcnt vmcnt(1)
	ds_write_b128 v144, v[74:77] offset:2304
	s_waitcnt vmcnt(0)
	ds_write_b128 v144, v[78:81] offset:3456
	s_waitcnt lgkmcnt(0)
	ds_read_b128 v[66:69], v145
	ds_read_b128 v[148:151], v145 offset:32
	s_waitcnt lgkmcnt(1)
	v_mfma_f32_32x32x16_bf16 v[66:81], v[66:69], v[96:99], 0
	s_waitcnt lgkmcnt(0)
	v_mfma_f32_32x32x16_bf16 v[66:81], v[148:151], v[104:107], v[66:81]
	ds_read_b128 v[148:151], v145 offset:64
	s_waitcnt lgkmcnt(0)
	v_mfma_f32_32x32x16_bf16 v[66:81], v[148:151], v[108:111], v[66:81]
	ds_read_b128 v[148:151], v145 offset:96
	s_waitcnt lgkmcnt(0)
	v_mfma_f32_32x32x16_bf16 v[66:81], v[148:151], v[112:115], v[66:81]
	global_load_dwordx4 v[148:151], v[136:137], off offset:-96
	s_waitcnt vmcnt(0)
	v_sub_f32_e32 v82, v148, v140
	v_mul_f32_e32 v82, 0x3fb8aa3b, v82
	v_exp_f32_e32 v82, v82
	s_nop 6
	v_mul_f32_e32 v66, v66, v82
	v_cndmask_b32_e64 v82, 0, v66, s[40:41]
	v_add_f32_e32 v66, v146, v82
	v_sub_f32_e32 v146, v149, v140
	v_mul_f32_e32 v146, 0x3fb8aa3b, v146
	v_exp_f32_e32 v146, v146
	s_or_b64 s[40:41], s[74:75], s[8:9]
	v_mul_f32_e32 v67, v67, v146
	v_cndmask_b32_e64 v146, 0, v67, s[40:41]
	v_sub_f32_e32 v67, v150, v140
	v_mul_f32_e32 v67, 0x3fb8aa3b, v67
	v_exp_f32_e32 v67, v67
	s_or_b64 s[40:41], s[74:75], s[10:11]
	v_add_f32_e32 v66, v146, v66
	v_mul_f32_e32 v67, v68, v67
	v_cndmask_b32_e64 v147, 0, v67, s[40:41]
	v_sub_f32_e32 v67, v151, v140
	v_mul_f32_e32 v67, 0x3fb8aa3b, v67
	v_exp_f32_e32 v67, v67
	s_or_b64 s[40:41], s[74:75], s[12:13]
	v_add_f32_e32 v66, v147, v66
	v_mul_f32_e32 v67, v69, v67
	v_cndmask_b32_e64 v148, 0, v67, s[40:41]
	v_add_f32_e32 v149, v148, v66
	global_load_dwordx4 v[66:69], v[136:137], off offset:-64
	s_or_b64 s[40:41], s[74:75], s[14:15]
	s_waitcnt vmcnt(0)
	v_sub_f32_e32 v66, v66, v140
	v_mul_f32_e32 v66, 0x3fb8aa3b, v66
	v_sub_f32_e32 v67, v67, v140
	v_exp_f32_e32 v66, v66
	v_mul_f32_e32 v67, 0x3fb8aa3b, v67
	v_exp_f32_e32 v67, v67
	v_mul_f32_e32 v66, v70, v66
	v_cndmask_b32_e64 v70, 0, v66, s[40:41]
	s_or_b64 s[40:41], s[74:75], s[16:17]
	v_mul_f32_e32 v67, v71, v67
	v_cndmask_b32_e64 v71, 0, v67, s[40:41]
	v_sub_f32_e32 v67, v68, v140
	v_mul_f32_e32 v67, 0x3fb8aa3b, v67
	v_exp_f32_e32 v67, v67
	s_or_b64 s[40:41], s[74:75], s[18:19]
	v_add_f32_e32 v66, v70, v149
	v_add_f32_e32 v66, v71, v66
	v_mul_f32_e32 v67, v72, v67
	v_cndmask_b32_e64 v72, 0, v67, s[40:41]
	v_sub_f32_e32 v67, v69, v140
	v_mul_f32_e32 v67, 0x3fb8aa3b, v67
	v_exp_f32_e32 v67, v67
	s_or_b64 s[40:41], s[74:75], s[20:21]
	v_add_f32_e32 v66, v72, v66
	v_mul_f32_e32 v67, v73, v67
	v_cndmask_b32_e64 v73, 0, v67, s[40:41]
	v_add_f32_e32 v149, v73, v66
	global_load_dwordx4 v[66:69], v[136:137], off offset:-32
	s_or_b64 s[40:41], s[74:75], s[22:23]
	s_waitcnt vmcnt(0)
	v_sub_f32_e32 v66, v66, v140
	v_mul_f32_e32 v66, 0x3fb8aa3b, v66
	v_sub_f32_e32 v67, v67, v140
	v_exp_f32_e32 v66, v66
	v_mul_f32_e32 v67, 0x3fb8aa3b, v67
	v_exp_f32_e32 v67, v67
	v_mul_f32_e32 v66, v74, v66
	v_cndmask_b32_e64 v74, 0, v66, s[40:41]
	s_or_b64 s[40:41], s[74:75], s[24:25]
	v_mul_f32_e32 v67, v75, v67
	v_cndmask_b32_e64 v75, 0, v67, s[40:41]
	v_sub_f32_e32 v67, v68, v140
	v_mul_f32_e32 v67, 0x3fb8aa3b, v67
	v_exp_f32_e32 v67, v67
	s_or_b64 s[40:41], s[74:75], s[26:27]
	v_add_f32_e32 v66, v74, v149
	v_add_f32_e32 v66, v75, v66
	v_mul_f32_e32 v67, v76, v67
	v_cndmask_b32_e64 v76, 0, v67, s[40:41]
	v_sub_f32_e32 v67, v69, v140
	v_mul_f32_e32 v67, 0x3fb8aa3b, v67
	v_exp_f32_e32 v67, v67
	s_or_b64 s[40:41], s[74:75], s[28:29]
	v_add_f32_e32 v66, v76, v66
	v_mul_f32_e32 v67, v77, v67
	v_cndmask_b32_e64 v77, 0, v67, s[40:41]
	v_add_f32_e32 v149, v77, v66
	global_load_dwordx4 v[66:69], v[136:137], off
	s_or_b64 s[40:41], s[74:75], s[30:31]
	v_lshl_add_u64 v[136:137], v[136:137], 0, s[68:69]
	s_waitcnt vmcnt(0)
	v_sub_f32_e32 v66, v66, v140
	v_mul_f32_e32 v66, 0x3fb8aa3b, v66
	v_sub_f32_e32 v67, v67, v140
	v_exp_f32_e32 v66, v66
	v_mul_f32_e32 v67, 0x3fb8aa3b, v67
	v_exp_f32_e32 v67, v67
	v_mul_f32_e32 v66, v78, v66
	v_cndmask_b32_e64 v150, 0, v66, s[40:41]
	s_or_b64 s[40:41], s[74:75], s[34:35]
	v_mul_f32_e32 v67, v79, v67
	v_add_f32_e32 v66, v150, v149
	v_cndmask_b32_e64 v149, 0, v67, s[40:41]
	v_sub_f32_e32 v67, v68, v140
	v_mul_f32_e32 v67, 0x3fb8aa3b, v67
	v_exp_f32_e32 v67, v67
	s_or_b64 s[40:41], s[74:75], s[36:37]
	v_add_f32_e32 v66, v149, v66
	s_nop 0
	v_mul_f32_e32 v67, v80, v67
	v_cndmask_b32_e64 v80, 0, v67, s[40:41]
	v_add_f32_e32 v78, v80, v66
	v_sub_f32_e32 v66, v69, v140
	v_mul_f32_e32 v66, 0x3fb8aa3b, v66
	v_exp_f32_e32 v66, v66
	s_or_b64 s[40:41], s[74:75], s[38:39]
	s_nop 0
	s_nop 0
	v_mul_f32_e32 v66, v81, v66
	v_cndmask_b32_e64 v79, 0, v66, s[40:41]
	s_nop 0
	s_nop 0
	s_nop 0
	v_cvt_pk_bf16_f32 v66, v82, v146
	s_nop 0
	s_nop 0
	s_nop 0
	s_nop 0
	v_cvt_pk_bf16_f32 v67, v147, v148
	s_nop 0
	s_nop 0
	s_nop 0
	s_nop 0
	s_nop 0
	v_cvt_pk_bf16_f32 v68, v70, v71
	v_cvt_pk_bf16_f32 v69, v72, v73
	v_cvt_pk_bf16_f32 v70, v74, v75
	v_cvt_pk_bf16_f32 v71, v76, v77
	v_cvt_pk_bf16_f32 v72, v150, v149
	v_bfe_u32 v73, v80, 16, 1
	v_add3_u32 v73, v80, v73, s73
	v_bfe_u32 v74, v79, 16, 1
	v_lshrrev_b32_e32 v73, 16, v73
	v_add3_u32 v74, v79, v74, s73
	v_add_u32_e32 v80, s60, v1
	v_and_or_b32 v73, v74, s33, v73
	v_add_u32_e32 v81, 0x880, v80
	ds_read_b64_tr_b16 v[74:75], v80
	ds_read_b64_tr_b16 v[76:77], v81
	s_waitcnt lgkmcnt(0)
	v_add_u32_e32 v81, 0x1100, v80
	v_mfma_f32_32x32x16_bf16 v[2:17], v[74:77], v[66:69], v[2:17]
	v_add_u32_e32 v82, 0x1980, v80
	ds_read_b64_tr_b16 v[74:75], v81
	ds_read_b64_tr_b16 v[76:77], v82
	s_waitcnt lgkmcnt(0)
	v_add_u32_e32 v81, 64, v80
	v_add_u32_e32 v82, 0x8c0, v80
	s_addk_i32 s60, 0x2200
	v_add_f32_e32 v146, v79, v78
	s_cmp_lg_u32 s66, s60
	v_mfma_f32_32x32x16_bf16 v[2:17], v[74:77], v[70:73], v[2:17]
	ds_read_b64_tr_b16 v[74:75], v81
	ds_read_b64_tr_b16 v[76:77], v82
	s_waitcnt lgkmcnt(0)
	v_add_u32_e32 v81, 0x1140, v80
	v_add_u32_e32 v82, 0x19c0, v80
	v_mfma_f32_32x32x16_bf16 v[18:33], v[74:77], v[66:69], v[18:33]
	ds_read_b64_tr_b16 v[74:75], v81
	ds_read_b64_tr_b16 v[76:77], v82
	s_waitcnt lgkmcnt(0)
	v_add_u32_e32 v81, 0x80, v80
	v_add_u32_e32 v82, 0x900, v80
	v_mfma_f32_32x32x16_bf16 v[18:33], v[74:77], v[70:73], v[18:33]
	ds_read_b64_tr_b16 v[74:75], v81
	ds_read_b64_tr_b16 v[76:77], v82
	s_waitcnt lgkmcnt(0)
	v_add_u32_e32 v81, 0x1180, v80
	v_add_u32_e32 v82, 0x1a00, v80
	v_mfma_f32_32x32x16_bf16 v[34:49], v[74:77], v[66:69], v[34:49]
	ds_read_b64_tr_b16 v[74:75], v81
	ds_read_b64_tr_b16 v[76:77], v82
	s_waitcnt lgkmcnt(0)
	v_add_u32_e32 v81, 0xc0, v80
	v_add_u32_e32 v82, 0x940, v80
	v_mfma_f32_32x32x16_bf16 v[34:49], v[74:77], v[70:73], v[34:49]
	ds_read_b64_tr_b16 v[74:75], v81
	ds_read_b64_tr_b16 v[76:77], v82
	s_waitcnt lgkmcnt(0)
	s_nop 0
	v_mfma_f32_32x32x16_bf16 v[50:65], v[74:77], v[66:69], v[50:65]
	v_add_u32_e32 v74, 0x11c0, v80
	v_add_u32_e32 v75, 0x1a40, v80
	ds_read_b64_tr_b16 v[66:67], v74
	ds_read_b64_tr_b16 v[68:69], v75
	s_waitcnt lgkmcnt(0)
	s_nop 0
	v_mfma_f32_32x32x16_bf16 v[50:65], v[66:69], v[70:73], v[50:65]
	s_cbranch_scc1 .LBB0_1035
	v_readlane_b32 s8, v254, 53
	v_readlane_b32 s9, v254, 54
	s_lshl_b64 s[8:9], s[8:9], 2
	s_add_u32 s10, s64, s8
	v_or_b32_e32 v82, s55, v141
	v_mov_b64_e32 v[66:67], s[62:63]
	s_addc_u32 s11, s65, s9
	v_mad_u64_u32 v[66:67], s[8:9], v82, s83, v[66:67]
	s_lshl_b32 s70, s54, 1
	v_lshl_add_u64 v[66:67], v[66:67], 0, s[70:71]
	v_lshl_add_u64 v[96:97], v[134:135], 1, v[66:67]
	v_add_co_u32_e32 v66, vcc, s82, v96
	s_mov_b64 s[8:9], 0x1000
	s_nop 0
	v_addc_co_u32_e32 v67, vcc, 0, v97, vcc
	global_load_dwordx2 v[104:105], v[66:67], off
	v_mfma_f32_32x32x16_bf16 v[66:81], v[128:131], v[88:91], 0
	v_lshl_add_u64 v[88:89], v[96:97], 0, s[8:9]
	global_load_dwordx2 v[98:99], v[88:89], off offset:16
	v_xor_b32_e32 v1, 32, v249
	s_lshl_b32 s8, s54, 2
	s_add_u32 s8, s10, s8
	s_addc_u32 s9, s11, 0
	v_lshlrev_b32_e32 v96, 3, v143
	v_mfma_f32_32x32x16_bf16 v[66:81], v[124:127], v[84:87], v[66:81]
	v_and_b32_e32 v84, 64, v249
	v_add_u32_e32 v86, 64, v84
	v_cmp_lt_i32_e32 vcc, v1, v86
	v_add_f32_e32 v85, v139, v140
	v_or_b32_e32 v87, v84, v138
	v_cndmask_b32_e32 v1, v249, v1, vcc
	v_lshlrev_b32_e32 v1, 2, v1
	v_mfma_f32_32x32x16_bf16 v[66:81], v[120:123], v[92:95], v[66:81]
	v_mul_f32_e32 v90, 0xbfb8aa3b, v85
	v_lshlrev_b64 v[84:85], 12, v[82:83]
	v_lshlrev_b32_e32 v82, 2, v87
	ds_bpermute_b32 v87, v1, v146
	v_exp_f32_e32 v86, v90
	v_lshl_add_u64 v[84:85], s[88:89], 0, v[84:85]
	v_lshl_add_u64 v[94:95], v[84:85], 0, s[70:71]
	v_mfma_f32_32x32x16_bf16 v[66:81], v[116:119], v[100:103], v[66:81]
	s_mov_b32 s62, 0x1b81e000
	s_nop 10
	ds_bpermute_b32 v66, v82, v66
	s_waitcnt lgkmcnt(1)
	v_add_f32_e32 v67, v146, v87
	v_lshl_add_u64 v[74:75], v[134:135], 2, s[8:9]
	s_mov_b32 s8, 0xf800000
	s_waitcnt lgkmcnt(0)
	v_add_f32_e32 v66, v67, v66
	v_max_f32_e64 v66, |v66|, v86
	v_div_scale_f32 v67, s[10:11], v66, v66, 1.0
	v_rcp_f32_e32 v68, v67
	v_div_scale_f32 v69, vcc, 1.0, v66, 1.0
	v_fma_f32 v70, -v67, v68, 1.0
	v_fmac_f32_e32 v68, v70, v68
	v_mul_f32_e32 v70, v69, v68
	v_fma_f32 v71, -v67, v70, v69
	v_fmac_f32_e32 v70, v71, v68
	v_fma_f32 v67, -v67, v70, v69
	v_div_fmas_f32 v67, v67, v68, v70
	v_div_fixup_f32 v82, v67, v66, 1.0
	v_pk_mul_f32 v[68:69], v[64:65], v[82:83] op_sel_hi:[1,0]
	v_pk_mul_f32 v[126:127], v[2:3], v[82:83] op_sel_hi:[1,0]
	v_pk_mul_f32 v[102:103], v[4:5], v[82:83] op_sel_hi:[1,0]
	v_pk_mul_f32 v[128:129], v[126:127], v[126:127]
	v_pk_mul_f32 v[72:73], v[60:61], v[82:83] op_sel_hi:[1,0]
	v_pk_mul_f32 v[70:71], v[62:63], v[82:83] op_sel_hi:[1,0]
	v_pk_mul_f32 v[118:119], v[102:103], v[102:103]
	v_pk_mul_f32 v[122:123], v[8:9], v[82:83] op_sel_hi:[1,0]
	v_pk_mul_f32 v[130:131], v[6:7], v[82:83] op_sel_hi:[1,0]
	v_pk_mul_f32 v[110:111], v[12:13], v[82:83] op_sel_hi:[1,0]
	v_pk_mul_f32 v[100:101], v[16:17], v[82:83] op_sel_hi:[1,0]
	v_pk_mul_f32 v[116:117], v[10:11], v[82:83] op_sel_hi:[1,0]
	v_pk_mul_f32 v[108:109], v[14:15], v[82:83] op_sel_hi:[1,0]
	v_pk_mul_f32 v[90:91], v[20:21], v[82:83] op_sel_hi:[1,0]
	v_pk_mul_f32 v[84:85], v[24:25], v[82:83] op_sel_hi:[1,0]
	v_pk_mul_f32 v[92:93], v[18:19], v[82:83] op_sel_hi:[1,0]
	v_pk_mul_f32 v[86:87], v[22:23], v[82:83] op_sel_hi:[1,0]
	v_pk_mul_f32 v[78:79], v[28:29], v[82:83] op_sel_hi:[1,0]
	v_pk_mul_f32 v[32:33], v[32:33], v[82:83] op_sel_hi:[1,0]
	v_pk_mul_f32 v[80:81], v[26:27], v[82:83] op_sel_hi:[1,0]
	v_pk_mul_f32 v[28:29], v[36:37], v[82:83] op_sel_hi:[1,0]
	v_pk_mul_f32 v[24:25], v[40:41], v[82:83] op_sel_hi:[1,0]
	v_pk_mul_f32 v[26:27], v[38:39], v[82:83] op_sel_hi:[1,0]
	v_pk_mul_f32 v[20:21], v[44:45], v[82:83] op_sel_hi:[1,0]
	s_waitcnt vmcnt(0)
	v_lshlrev_b32_e32 v64, 16, v98
	v_and_b32_e32 v65, 0xffff0000, v98
	v_mul_f32_e32 v64, 0xbfb8aa3b, v64
	v_mul_f32_e32 v65, 0xbfb8aa3b, v65
	v_exp_f32_e32 v76, v64
	v_exp_f32_e32 v77, v65
	v_pk_mul_f32 v[16:17], v[48:49], v[82:83] op_sel_hi:[1,0]
	v_pk_mul_f32 v[22:23], v[42:43], v[82:83] op_sel_hi:[1,0]
	v_add_f32_e32 v76, 1.0, v76
	v_rcp_f32_e32 v120, v76
	v_add_f32_e32 v76, 1.0, v77
	v_rcp_f32_e32 v121, v76
	v_lshlrev_b32_e32 v76, 16, v99
	v_mul_f32_e32 v97, 0xbfb8aa3b, v76
	v_pk_mul_f32 v[76:77], v[30:31], v[82:83] op_sel_hi:[1,0]
	v_pk_mul_f32 v[30:31], v[34:35], v[82:83] op_sel_hi:[1,0]
	v_pk_mul_f32 v[18:19], v[46:47], v[82:83] op_sel_hi:[1,0]
	v_pk_mul_f32 v[12:13], v[52:53], v[82:83] op_sel_hi:[1,0]
	v_pk_mul_f32 v[6:7], v[56:57], v[82:83] op_sel_hi:[1,0]
	v_pk_mul_f32 v[14:15], v[50:51], v[82:83] op_sel_hi:[1,0]
	v_pk_mul_f32 v[8:9], v[54:55], v[82:83] op_sel_hi:[1,0]
	v_pk_mul_f32 v[2:3], v[58:59], v[82:83] op_sel_hi:[1,0]
	v_add_f32_e32 v82, v128, v129
	v_add_f32_e32 v82, v118, v82
	v_pk_mul_f32 v[132:133], v[130:131], v[130:131]
	v_add_f32_e32 v82, v119, v82
	v_add_f32_e32 v82, v132, v82
	v_pk_mul_f32 v[124:125], v[122:123], v[122:123]
	v_add_f32_e32 v82, v133, v82
	v_add_f32_e32 v82, v124, v82
	v_pk_mul_f32 v[10:11], v[116:117], v[116:117]
	v_add_f32_e32 v82, v125, v82
	v_add_f32_e32 v10, v10, v82
	v_pk_mul_f32 v[134:135], v[110:111], v[110:111]
	v_add_f32_e32 v10, v11, v10
	v_add_f32_e32 v10, v134, v10
	v_pk_mul_f32 v[138:139], v[108:109], v[108:109]
	v_add_f32_e32 v10, v135, v10
	v_add_f32_e32 v10, v138, v10
	v_pk_mul_f32 v[136:137], v[100:101], v[100:101]
	v_add_f32_e32 v10, v139, v10
	v_lshlrev_b32_e32 v60, 16, v104
	v_and_b32_e32 v61, 0xffff0000, v104
	v_lshlrev_b32_e32 v62, 16, v105
	v_and_b32_e32 v63, 0xffff0000, v105
	v_add_f32_e32 v10, v136, v10
	v_mul_f32_e32 v60, 0xbfb8aa3b, v60
	v_mul_f32_e32 v61, 0xbfb8aa3b, v61
	v_mul_f32_e32 v62, 0xbfb8aa3b, v62
	v_mul_f32_e32 v63, 0xbfb8aa3b, v63
	v_pk_mul_f32 v[144:145], v[92:93], v[92:93]
	v_add_f32_e32 v10, v137, v10
	v_exp_f32_e32 v60, v60
	v_exp_f32_e32 v61, v61
	v_exp_f32_e32 v62, v62
	v_exp_f32_e32 v63, v63
	v_add_f32_e32 v10, v144, v10
	v_pk_mul_f32 v[140:141], v[90:91], v[90:91]
	v_add_f32_e32 v10, v145, v10
	v_add_f32_e32 v10, v140, v10
	v_pk_mul_f32 v[146:147], v[86:87], v[86:87]
	v_add_f32_e32 v10, v141, v10
	v_add_f32_e32 v60, 1.0, v60
	v_add_f32_e32 v61, 1.0, v61
	v_add_f32_e32 v62, 1.0, v62
	v_add_f32_e32 v63, 1.0, v63
	v_add_f32_e32 v10, v146, v10
	v_rcp_f32_e32 v106, v60
	v_rcp_f32_e32 v107, v61
	v_rcp_f32_e32 v104, v62
	v_rcp_f32_e32 v105, v63
	global_load_dwordx4 v[64:67], v[74:75], off
	global_load_dwordx4 v[60:63], v[74:75], off offset:32
	v_pk_mul_f32 v[142:143], v[84:85], v[84:85]
	v_add_f32_e32 v10, v147, v10
	v_add_f32_e32 v10, v142, v10
	v_pk_mul_f32 v[152:153], v[80:81], v[80:81]
	v_add_f32_e32 v10, v143, v10
	v_add_f32_e32 v10, v152, v10
	v_pk_mul_f32 v[148:149], v[78:79], v[78:79]
	v_add_f32_e32 v10, v153, v10
	v_add_f32_e32 v10, v148, v10
	v_pk_mul_f32 v[154:155], v[76:77], v[76:77]
	v_add_f32_e32 v10, v149, v10
	v_add_f32_e32 v10, v154, v10
	v_pk_mul_f32 v[150:151], v[32:33], v[32:33]
	v_add_f32_e32 v10, v155, v10
	v_add_f32_e32 v10, v150, v10
	v_pk_mul_f32 v[34:35], v[30:31], v[30:31]
	v_add_f32_e32 v10, v151, v10
	v_add_f32_e32 v10, v34, v10
	v_pk_mul_f32 v[36:37], v[28:29], v[28:29]
	v_add_f32_e32 v10, v35, v10
	v_add_f32_e32 v10, v36, v10
	v_pk_mul_f32 v[38:39], v[26:27], v[26:27]
	v_add_f32_e32 v10, v37, v10
	v_add_f32_e32 v10, v38, v10
	v_pk_mul_f32 v[40:41], v[24:25], v[24:25]
	v_add_f32_e32 v10, v39, v10
	v_add_f32_e32 v10, v40, v10
	v_pk_mul_f32 v[42:43], v[22:23], v[22:23]
	v_add_f32_e32 v10, v41, v10
	v_add_f32_e32 v10, v42, v10
	v_pk_mul_f32 v[44:45], v[20:21], v[20:21]
	v_add_f32_e32 v10, v43, v10
	v_add_f32_e32 v10, v44, v10
	v_pk_mul_f32 v[46:47], v[18:19], v[18:19]
	v_add_f32_e32 v10, v45, v10
	v_add_f32_e32 v10, v46, v10
	v_pk_mul_f32 v[48:49], v[16:17], v[16:17]
	v_add_f32_e32 v10, v47, v10
	v_add_f32_e32 v10, v48, v10
	v_pk_mul_f32 v[50:51], v[14:15], v[14:15]
	v_add_f32_e32 v10, v49, v10
	v_add_f32_e32 v10, v50, v10
	v_pk_mul_f32 v[52:53], v[12:13], v[12:13]
	v_add_f32_e32 v10, v51, v10
	v_add_f32_e32 v10, v52, v10
	v_pk_mul_f32 v[54:55], v[8:9], v[8:9]
	v_add_f32_e32 v10, v53, v10
	v_add_f32_e32 v10, v54, v10
	v_pk_mul_f32 v[56:57], v[6:7], v[6:7]
	v_add_f32_e32 v10, v55, v10
	v_add_f32_e32 v10, v56, v10
	v_pk_mul_f32 v[58:59], v[2:3], v[2:3]
	v_add_f32_e32 v10, v57, v10
	v_add_f32_e32 v10, v58, v10
	v_pk_mul_f32 v[114:115], v[72:73], v[72:73]
	v_add_f32_e32 v10, v59, v10
	v_add_f32_e32 v10, v114, v10
	v_pk_mul_f32 v[112:113], v[70:71], v[70:71]
	v_add_f32_e32 v10, v115, v10
	v_add_f32_e32 v10, v112, v10
	v_pk_mul_f32 v[4:5], v[68:69], v[68:69]
	v_add_f32_e32 v10, v113, v10
	v_add_f32_e32 v4, v4, v10
	v_add_f32_e32 v4, v5, v4
	ds_bpermute_b32 v1, v1, v4
	v_and_b32_e32 v10, 0xffff0000, v99
	v_exp_f32_e32 v5, v97
	v_mul_f32_e32 v10, 0xbfb8aa3b, v10
	v_exp_f32_e32 v11, v10
	s_waitcnt lgkmcnt(0)
	v_add_f32_e32 v1, v4, v1
	v_fmamk_f32 v1, v1, 0x3c000000, v245
	v_mul_f32_e32 v4, 0x4f800000, v1
	v_cmp_gt_f32_e32 vcc, s8, v1
	v_add_f32_e32 v5, 1.0, v5
	v_rcp_f32_e32 v10, v5
	v_cndmask_b32_e32 v1, v1, v4, vcc
	v_sqrt_f32_e32 v4, v1
	v_add_f32_e32 v5, 1.0, v11
	v_ashrrev_i32_e32 v97, 31, v96
	v_lshl_add_u64 v[42:43], v[96:97], 1, v[94:95]
	v_add_u32_e32 v11, -1, v4
	v_fma_f32 v34, -v11, v4, v1
	v_cmp_ge_f32_e64 s[8:9], 0, v34
	v_add_u32_e32 v34, 1, v4
	s_nop 0
	v_cndmask_b32_e64 v11, v4, v11, s[8:9]
	v_fma_f32 v4, -v34, v4, v1
	v_cmp_lt_f32_e64 s[8:9], 0, v4
	s_nop 1
	v_cndmask_b32_e64 v4, v11, v34, s[8:9]
	v_mul_f32_e32 v11, 0x37800000, v4
	v_cndmask_b32_e32 v4, v4, v11, vcc
	v_cmp_class_f32_e32 vcc, v1, v251
	v_rcp_f32_e32 v11, v5
	s_nop 0
	v_cndmask_b32_e32 v1, v4, v1, vcc
	v_div_scale_f32 v4, s[8:9], v1, v1, 1.0
	v_rcp_f32_e32 v34, v4
	s_mov_b64 s[8:9], 0x1b81e000
	v_fma_f32 v5, -v4, v34, 1.0
	v_fmac_f32_e32 v34, v5, v34
	v_div_scale_f32 v5, vcc, 1.0, v1, 1.0
	v_mul_f32_e32 v35, v5, v34
	v_fma_f32 v36, -v4, v35, v5
	v_fmac_f32_e32 v35, v36, v34
	v_fma_f32 v4, -v4, v35, v5
	v_div_fmas_f32 v4, v4, v34, v35
	v_div_fixup_f32 v4, v4, v1, 1.0
	v_pk_mul_f32 v[34:35], v[126:127], v[4:5] op_sel_hi:[1,0]
	v_pk_mul_f32 v[36:37], v[102:103], v[4:5] op_sel_hi:[1,0]
	s_waitcnt vmcnt(1)
	v_pk_mul_f32 v[34:35], v[64:65], v[34:35]
	v_pk_mul_f32 v[36:37], v[66:67], v[36:37]
	v_pk_mul_f32 v[34:35], v[106:107], v[34:35]
	v_pk_mul_f32 v[36:37], v[104:105], v[36:37]
	v_and_b32_sdwa v5, v34, v247 dst_sel:DWORD dst_unused:UNUSED_PAD src0_sel:WORD_1 src1_sel:DWORD
	v_and_b32_sdwa v1, v35, v247 dst_sel:DWORD dst_unused:UNUSED_PAD src0_sel:WORD_1 src1_sel:DWORD
	v_add3_u32 v5, v34, v5, s73
	v_add3_u32 v1, v35, v1, s73
	v_lshrrev_b32_e32 v5, 16, v5
	v_and_or_b32 v34, v1, s33, v5
	v_and_b32_sdwa v5, v36, v247 dst_sel:DWORD dst_unused:UNUSED_PAD src0_sel:WORD_1 src1_sel:DWORD
	v_add3_u32 v5, v36, v5, s73
	v_and_b32_sdwa v1, v37, v247 dst_sel:DWORD dst_unused:UNUSED_PAD src0_sel:WORD_1 src1_sel:DWORD
	v_lshrrev_b32_e32 v5, 16, v5
	v_add3_u32 v1, v37, v1, s73
	v_pk_mul_f32 v[36:37], v[130:131], v[4:5] op_sel_hi:[1,0]
	v_and_or_b32 v35, v1, s33, v5
	s_waitcnt vmcnt(0)
	v_pk_mul_f32 v[36:37], v[60:61], v[36:37]
	v_pk_mul_f32 v[38:39], v[122:123], v[4:5] op_sel_hi:[1,0]
	v_pk_mul_f32 v[36:37], v[120:121], v[36:37]
	v_pk_mul_f32 v[38:39], v[62:63], v[38:39]
	v_and_b32_sdwa v5, v36, v247 dst_sel:DWORD dst_unused:UNUSED_PAD src0_sel:WORD_1 src1_sel:DWORD
	v_and_b32_sdwa v1, v37, v247 dst_sel:DWORD dst_unused:UNUSED_PAD src0_sel:WORD_1 src1_sel:DWORD
	v_add3_u32 v5, v36, v5, s73
	v_pk_mul_f32 v[10:11], v[10:11], v[38:39]
	v_add3_u32 v1, v37, v1, s73
	v_lshrrev_b32_e32 v5, 16, v5
	v_and_or_b32 v36, v1, s33, v5
	v_and_b32_sdwa v5, v10, v247 dst_sel:DWORD dst_unused:UNUSED_PAD src0_sel:WORD_1 src1_sel:DWORD
	v_and_b32_sdwa v1, v11, v247 dst_sel:DWORD dst_unused:UNUSED_PAD src0_sel:WORD_1 src1_sel:DWORD
	v_add3_u32 v5, v10, v5, s73
	v_add3_u32 v1, v11, v1, s73
	v_lshrrev_b32_e32 v5, 16, v5
	v_and_or_b32 v37, v1, s33, v5
	v_add_co_u32_e32 v10, vcc, s62, v42
	v_permlane32_swap_b32_e32 v34, v36
	v_permlane32_swap_b32_e32 v35, v37
	v_addc_co_u32_e32 v11, vcc, 0, v43, vcc
	global_store_dwordx4 v[10:11], v[34:37], off
	global_load_dwordx2 v[44:45], v[88:89], off offset:32
	s_nop 0
	global_load_dwordx4 v[34:37], v[74:75], off offset:64
	global_load_dwordx2 v[46:47], v[88:89], off offset:48
	global_load_dwordx4 v[38:41], v[74:75], off offset:96
	v_lshl_add_u64 v[10:11], v[42:43], 0, s[8:9]
	s_mov_b64 s[8:9], 0
	s_waitcnt vmcnt(3)
	v_lshlrev_b32_e32 v1, 16, v44
	v_mul_f32_e32 v1, 0xbfb8aa3b, v1
	v_and_b32_e32 v5, 0xffff0000, v44
	v_exp_f32_e32 v1, v1
	v_mul_f32_e32 v5, 0xbfb8aa3b, v5
	v_exp_f32_e32 v5, v5
	v_and_b32_e32 v43, 0xffff0000, v45
	v_add_f32_e32 v1, 1.0, v1
	v_rcp_f32_e32 v42, v1
	v_pk_mul_f32 v[48:49], v[116:117], v[4:5] op_sel_hi:[1,0]
	v_add_f32_e32 v1, 1.0, v5
	v_lshlrev_b32_e32 v5, 16, v45
	v_mul_f32_e32 v5, 0xbfb8aa3b, v5
	v_exp_f32_e32 v5, v5
	v_mul_f32_e32 v43, 0xbfb8aa3b, v43
	v_exp_f32_e32 v45, v43
	v_rcp_f32_e32 v43, v1
	v_add_f32_e32 v1, 1.0, v5
	v_rcp_f32_e32 v44, v1
	v_add_f32_e32 v1, 1.0, v45
	s_waitcnt vmcnt(2)
	v_pk_mul_f32 v[34:35], v[34:35], v[48:49]
	v_rcp_f32_e32 v45, v1
	v_pk_mul_f32 v[34:35], v[42:43], v[34:35]
	v_pk_mul_f32 v[42:43], v[110:111], v[4:5] op_sel_hi:[1,0]
	v_and_b32_sdwa v5, v34, v247 dst_sel:DWORD dst_unused:UNUSED_PAD src0_sel:WORD_1 src1_sel:DWORD
	v_pk_mul_f32 v[36:37], v[36:37], v[42:43]
	v_and_b32_sdwa v1, v35, v247 dst_sel:DWORD dst_unused:UNUSED_PAD src0_sel:WORD_1 src1_sel:DWORD
	v_add3_u32 v5, v34, v5, s73
	v_pk_mul_f32 v[36:37], v[44:45], v[36:37]
	v_add3_u32 v1, v35, v1, s73
	v_lshrrev_b32_e32 v5, 16, v5
	v_and_or_b32 v34, v1, s33, v5
	v_and_b32_sdwa v5, v36, v247 dst_sel:DWORD dst_unused:UNUSED_PAD src0_sel:WORD_1 src1_sel:DWORD
	v_and_b32_sdwa v1, v37, v247 dst_sel:DWORD dst_unused:UNUSED_PAD src0_sel:WORD_1 src1_sel:DWORD
	s_waitcnt vmcnt(1)
	v_lshlrev_b32_e32 v35, 16, v46
	v_add3_u32 v5, v36, v5, s73
	v_add3_u32 v1, v37, v1, s73
	v_mul_f32_e32 v35, 0xbfb8aa3b, v35
	v_lshrrev_b32_e32 v5, 16, v5
	v_exp_f32_e32 v37, v35
	v_and_or_b32 v35, v1, s33, v5
	v_and_b32_e32 v5, 0xffff0000, v46
	v_mul_f32_e32 v5, 0xbfb8aa3b, v5
	v_exp_f32_e32 v5, v5
	v_add_f32_e32 v1, 1.0, v37
	v_rcp_f32_e32 v36, v1
	v_and_b32_e32 v37, 0xffff0000, v47
	v_pk_mul_f32 v[42:43], v[108:109], v[4:5] op_sel_hi:[1,0]
	v_add_f32_e32 v1, 1.0, v5
	v_lshlrev_b32_e32 v5, 16, v47
	v_mul_f32_e32 v5, 0xbfb8aa3b, v5
	v_exp_f32_e32 v5, v5
	v_mul_f32_e32 v37, 0xbfb8aa3b, v37
	s_waitcnt vmcnt(0)
	v_pk_mul_f32 v[38:39], v[38:39], v[42:43]
	v_exp_f32_e32 v43, v37
	v_rcp_f32_e32 v37, v1
	v_add_f32_e32 v1, 1.0, v5
	v_rcp_f32_e32 v42, v1
	v_add_f32_e32 v1, 1.0, v43
	v_rcp_f32_e32 v43, v1
	v_pk_mul_f32 v[36:37], v[36:37], v[38:39]
	v_pk_mul_f32 v[38:39], v[100:101], v[4:5] op_sel_hi:[1,0]
	v_and_b32_sdwa v5, v36, v247 dst_sel:DWORD dst_unused:UNUSED_PAD src0_sel:WORD_1 src1_sel:DWORD
	v_pk_mul_f32 v[38:39], v[40:41], v[38:39]
	v_and_b32_sdwa v1, v37, v247 dst_sel:DWORD dst_unused:UNUSED_PAD src0_sel:WORD_1 src1_sel:DWORD
	v_add3_u32 v5, v36, v5, s73
	v_pk_mul_f32 v[38:39], v[42:43], v[38:39]
	v_add3_u32 v1, v37, v1, s73
	v_lshrrev_b32_e32 v5, 16, v5
	v_and_or_b32 v36, v1, s33, v5
	v_and_b32_sdwa v5, v38, v247 dst_sel:DWORD dst_unused:UNUSED_PAD src0_sel:WORD_1 src1_sel:DWORD
	v_and_b32_sdwa v1, v39, v247 dst_sel:DWORD dst_unused:UNUSED_PAD src0_sel:WORD_1 src1_sel:DWORD
	v_add3_u32 v5, v38, v5, s73
	v_add3_u32 v1, v39, v1, s73
	v_lshrrev_b32_e32 v5, 16, v5
	v_and_or_b32 v37, v1, s33, v5
	v_permlane32_swap_b32_e32 v34, v36
	s_nop 0
	v_permlane32_swap_b32_e32 v35, v37
	global_store_dwordx4 v[10:11], v[34:37], off offset:32
	global_load_dwordx2 v[42:43], v[88:89], off offset:64
	s_nop 0
	global_load_dwordx4 v[34:37], v[74:75], off offset:128
	global_load_dwordx2 v[44:45], v[88:89], off offset:80
	global_load_dwordx4 v[38:41], v[74:75], off offset:160
	s_waitcnt vmcnt(3)
	v_lshlrev_b32_e32 v1, 16, v42
	v_mul_f32_e32 v1, 0xbfb8aa3b, v1
	v_and_b32_e32 v5, 0xffff0000, v42
	v_exp_f32_e32 v1, v1
	v_mul_f32_e32 v5, 0xbfb8aa3b, v5
	v_exp_f32_e32 v5, v5
	v_add_f32_e32 v1, 1.0, v1
	v_rcp_f32_e32 v42, v1
	v_pk_mul_f32 v[46:47], v[92:93], v[4:5] op_sel_hi:[1,0]
	v_add_f32_e32 v1, 1.0, v5
	v_lshlrev_b32_e32 v5, 16, v43
	v_mul_f32_e32 v5, 0xbfb8aa3b, v5
	v_and_b32_e32 v43, 0xffff0000, v43
	v_exp_f32_e32 v5, v5
	v_mul_f32_e32 v43, 0xbfb8aa3b, v43
	s_waitcnt vmcnt(2)
	v_pk_mul_f32 v[34:35], v[34:35], v[46:47]
	v_exp_f32_e32 v47, v43
	v_rcp_f32_e32 v43, v1
	v_add_f32_e32 v1, 1.0, v5
	v_rcp_f32_e32 v46, v1
	v_add_f32_e32 v1, 1.0, v47
	v_rcp_f32_e32 v47, v1
	v_pk_mul_f32 v[34:35], v[42:43], v[34:35]
	v_pk_mul_f32 v[42:43], v[90:91], v[4:5] op_sel_hi:[1,0]
	v_and_b32_sdwa v5, v34, v247 dst_sel:DWORD dst_unused:UNUSED_PAD src0_sel:WORD_1 src1_sel:DWORD
	v_pk_mul_f32 v[36:37], v[36:37], v[42:43]
	v_and_b32_sdwa v1, v35, v247 dst_sel:DWORD dst_unused:UNUSED_PAD src0_sel:WORD_1 src1_sel:DWORD
	v_add3_u32 v5, v34, v5, s73
	v_pk_mul_f32 v[36:37], v[46:47], v[36:37]
	v_add3_u32 v1, v35, v1, s73
	v_lshrrev_b32_e32 v5, 16, v5
	v_and_or_b32 v34, v1, s33, v5
	v_and_b32_sdwa v5, v36, v247 dst_sel:DWORD dst_unused:UNUSED_PAD src0_sel:WORD_1 src1_sel:DWORD
	v_and_b32_sdwa v1, v37, v247 dst_sel:DWORD dst_unused:UNUSED_PAD src0_sel:WORD_1 src1_sel:DWORD
	s_waitcnt vmcnt(1)
	v_lshlrev_b32_e32 v35, 16, v44
	v_add3_u32 v5, v36, v5, s73
	v_add3_u32 v1, v37, v1, s73
	v_mul_f32_e32 v35, 0xbfb8aa3b, v35
	v_lshrrev_b32_e32 v5, 16, v5
	v_exp_f32_e32 v37, v35
	v_and_or_b32 v35, v1, s33, v5
	v_and_b32_e32 v5, 0xffff0000, v44
	v_mul_f32_e32 v5, 0xbfb8aa3b, v5
	v_exp_f32_e32 v5, v5
	v_add_f32_e32 v1, 1.0, v37
	v_rcp_f32_e32 v36, v1
	v_and_b32_e32 v37, 0xffff0000, v45
	v_pk_mul_f32 v[42:43], v[86:87], v[4:5] op_sel_hi:[1,0]
	v_add_f32_e32 v1, 1.0, v5
	v_lshlrev_b32_e32 v5, 16, v45
	v_mul_f32_e32 v5, 0xbfb8aa3b, v5
	v_exp_f32_e32 v5, v5
	v_mul_f32_e32 v37, 0xbfb8aa3b, v37
	s_waitcnt vmcnt(0)
	v_pk_mul_f32 v[38:39], v[38:39], v[42:43]
	v_exp_f32_e32 v43, v37
	v_rcp_f32_e32 v37, v1
	v_add_f32_e32 v1, 1.0, v5
	v_rcp_f32_e32 v42, v1
	v_add_f32_e32 v1, 1.0, v43
	v_rcp_f32_e32 v43, v1
	v_pk_mul_f32 v[36:37], v[36:37], v[38:39]
	v_pk_mul_f32 v[38:39], v[84:85], v[4:5] op_sel_hi:[1,0]
	v_and_b32_sdwa v5, v36, v247 dst_sel:DWORD dst_unused:UNUSED_PAD src0_sel:WORD_1 src1_sel:DWORD
	v_pk_mul_f32 v[38:39], v[40:41], v[38:39]
	v_and_b32_sdwa v1, v37, v247 dst_sel:DWORD dst_unused:UNUSED_PAD src0_sel:WORD_1 src1_sel:DWORD
	v_add3_u32 v5, v36, v5, s73
	v_pk_mul_f32 v[38:39], v[42:43], v[38:39]
	v_add3_u32 v1, v37, v1, s73
	v_lshrrev_b32_e32 v5, 16, v5
	v_and_or_b32 v36, v1, s33, v5
	v_and_b32_sdwa v5, v38, v247 dst_sel:DWORD dst_unused:UNUSED_PAD src0_sel:WORD_1 src1_sel:DWORD
	v_and_b32_sdwa v1, v39, v247 dst_sel:DWORD dst_unused:UNUSED_PAD src0_sel:WORD_1 src1_sel:DWORD
	v_add3_u32 v5, v38, v5, s73
	v_add3_u32 v1, v39, v1, s73
	v_lshrrev_b32_e32 v5, 16, v5
	v_and_or_b32 v37, v1, s33, v5
	v_permlane32_swap_b32_e32 v34, v36
	s_nop 0
	v_permlane32_swap_b32_e32 v35, v37
	global_store_dwordx4 v[10:11], v[34:37], off offset:64
	global_load_dwordx2 v[42:43], v[88:89], off offset:96
	s_nop 0
	global_load_dwordx4 v[34:37], v[74:75], off offset:192
	global_load_dwordx2 v[44:45], v[88:89], off offset:112
	global_load_dwordx4 v[38:41], v[74:75], off offset:224
	s_waitcnt vmcnt(3)
	v_lshlrev_b32_e32 v1, 16, v42
	v_mul_f32_e32 v1, 0xbfb8aa3b, v1
	v_and_b32_e32 v5, 0xffff0000, v42
	v_exp_f32_e32 v1, v1
	v_mul_f32_e32 v5, 0xbfb8aa3b, v5
	v_exp_f32_e32 v5, v5
	v_add_f32_e32 v1, 1.0, v1
	v_rcp_f32_e32 v42, v1
	v_pk_mul_f32 v[46:47], v[80:81], v[4:5] op_sel_hi:[1,0]
	v_add_f32_e32 v1, 1.0, v5
	v_lshlrev_b32_e32 v5, 16, v43
	v_mul_f32_e32 v5, 0xbfb8aa3b, v5
	v_and_b32_e32 v43, 0xffff0000, v43
	v_exp_f32_e32 v5, v5
	v_mul_f32_e32 v43, 0xbfb8aa3b, v43
	s_waitcnt vmcnt(2)
	v_pk_mul_f32 v[34:35], v[34:35], v[46:47]
	v_exp_f32_e32 v47, v43
	v_rcp_f32_e32 v43, v1
	v_add_f32_e32 v1, 1.0, v5
	v_rcp_f32_e32 v46, v1
	v_add_f32_e32 v1, 1.0, v47
	v_rcp_f32_e32 v47, v1
	v_pk_mul_f32 v[34:35], v[42:43], v[34:35]
	v_pk_mul_f32 v[42:43], v[78:79], v[4:5] op_sel_hi:[1,0]
	v_and_b32_sdwa v5, v34, v247 dst_sel:DWORD dst_unused:UNUSED_PAD src0_sel:WORD_1 src1_sel:DWORD
	v_pk_mul_f32 v[36:37], v[36:37], v[42:43]
	v_and_b32_sdwa v1, v35, v247 dst_sel:DWORD dst_unused:UNUSED_PAD src0_sel:WORD_1 src1_sel:DWORD
	v_add3_u32 v5, v34, v5, s73
	v_pk_mul_f32 v[36:37], v[46:47], v[36:37]
	v_add3_u32 v1, v35, v1, s73
	v_lshrrev_b32_e32 v5, 16, v5
	v_and_or_b32 v34, v1, s33, v5
	v_and_b32_sdwa v5, v36, v247 dst_sel:DWORD dst_unused:UNUSED_PAD src0_sel:WORD_1 src1_sel:DWORD
	v_and_b32_sdwa v1, v37, v247 dst_sel:DWORD dst_unused:UNUSED_PAD src0_sel:WORD_1 src1_sel:DWORD
	s_waitcnt vmcnt(1)
	v_lshlrev_b32_e32 v35, 16, v44
	v_add3_u32 v5, v36, v5, s73
	v_add3_u32 v1, v37, v1, s73
	v_mul_f32_e32 v35, 0xbfb8aa3b, v35
	v_lshrrev_b32_e32 v5, 16, v5
	v_exp_f32_e32 v37, v35
	v_and_or_b32 v35, v1, s33, v5
	v_and_b32_e32 v5, 0xffff0000, v44
	v_mul_f32_e32 v5, 0xbfb8aa3b, v5
	v_exp_f32_e32 v5, v5
	v_add_f32_e32 v1, 1.0, v37
	v_rcp_f32_e32 v36, v1
	v_and_b32_e32 v37, 0xffff0000, v45
	v_pk_mul_f32 v[42:43], v[76:77], v[4:5] op_sel_hi:[1,0]
	v_add_f32_e32 v1, 1.0, v5
	v_lshlrev_b32_e32 v5, 16, v45
	v_mul_f32_e32 v5, 0xbfb8aa3b, v5
	v_exp_f32_e32 v5, v5
	v_mul_f32_e32 v37, 0xbfb8aa3b, v37
	s_waitcnt vmcnt(0)
	v_pk_mul_f32 v[38:39], v[38:39], v[42:43]
	v_exp_f32_e32 v43, v37
	v_rcp_f32_e32 v37, v1
	v_add_f32_e32 v1, 1.0, v5
	v_rcp_f32_e32 v42, v1
	v_add_f32_e32 v1, 1.0, v43
	v_rcp_f32_e32 v43, v1
	v_pk_mul_f32 v[36:37], v[36:37], v[38:39]
	v_pk_mul_f32 v[32:33], v[32:33], v[4:5] op_sel_hi:[1,0]
	v_and_b32_sdwa v5, v36, v247 dst_sel:DWORD dst_unused:UNUSED_PAD src0_sel:WORD_1 src1_sel:DWORD
	v_pk_mul_f32 v[32:33], v[40:41], v[32:33]
	v_and_b32_sdwa v1, v37, v247 dst_sel:DWORD dst_unused:UNUSED_PAD src0_sel:WORD_1 src1_sel:DWORD
	v_add3_u32 v5, v36, v5, s73
	v_pk_mul_f32 v[32:33], v[42:43], v[32:33]
	v_add3_u32 v1, v37, v1, s73
	v_lshrrev_b32_e32 v5, 16, v5
	v_and_or_b32 v36, v1, s33, v5
	v_and_b32_sdwa v5, v32, v247 dst_sel:DWORD dst_unused:UNUSED_PAD src0_sel:WORD_1 src1_sel:DWORD
	v_and_b32_sdwa v1, v33, v247 dst_sel:DWORD dst_unused:UNUSED_PAD src0_sel:WORD_1 src1_sel:DWORD
	v_add3_u32 v5, v32, v5, s73
	v_add3_u32 v1, v33, v1, s73
	v_lshrrev_b32_e32 v5, 16, v5
	v_and_or_b32 v37, v1, s33, v5
	v_permlane32_swap_b32_e32 v34, v36
	s_nop 0
	v_permlane32_swap_b32_e32 v35, v37
	global_store_dwordx4 v[10:11], v[34:37], off offset:96
	global_load_dwordx2 v[40:41], v[88:89], off offset:128
	s_nop 0
	global_load_dwordx4 v[32:35], v[74:75], off offset:256
	global_load_dwordx2 v[42:43], v[88:89], off offset:144
	global_load_dwordx4 v[36:39], v[74:75], off offset:288
	s_waitcnt vmcnt(3)
	v_lshlrev_b32_e32 v1, 16, v40
	v_mul_f32_e32 v1, 0xbfb8aa3b, v1
	v_and_b32_e32 v5, 0xffff0000, v40
	v_exp_f32_e32 v1, v1
	v_mul_f32_e32 v5, 0xbfb8aa3b, v5
	v_exp_f32_e32 v5, v5
	v_add_f32_e32 v1, 1.0, v1
	v_rcp_f32_e32 v40, v1
	v_pk_mul_f32 v[30:31], v[30:31], v[4:5] op_sel_hi:[1,0]
	v_add_f32_e32 v1, 1.0, v5
	v_lshlrev_b32_e32 v5, 16, v41
	s_waitcnt vmcnt(2)
	v_pk_mul_f32 v[30:31], v[32:33], v[30:31]
	v_mul_f32_e32 v5, 0xbfb8aa3b, v5
	v_and_b32_e32 v32, 0xffff0000, v41
	v_exp_f32_e32 v5, v5
	v_mul_f32_e32 v32, 0xbfb8aa3b, v32
	v_exp_f32_e32 v33, v32
	v_rcp_f32_e32 v41, v1
	v_add_f32_e32 v1, 1.0, v5
	v_rcp_f32_e32 v32, v1
	v_add_f32_e32 v1, 1.0, v33
	v_rcp_f32_e32 v33, v1
	v_pk_mul_f32 v[30:31], v[40:41], v[30:31]
	v_pk_mul_f32 v[28:29], v[28:29], v[4:5] op_sel_hi:[1,0]
	v_and_b32_sdwa v5, v30, v247 dst_sel:DWORD dst_unused:UNUSED_PAD src0_sel:WORD_1 src1_sel:DWORD
	v_pk_mul_f32 v[28:29], v[34:35], v[28:29]
	v_and_b32_sdwa v1, v31, v247 dst_sel:DWORD dst_unused:UNUSED_PAD src0_sel:WORD_1 src1_sel:DWORD
	v_add3_u32 v5, v30, v5, s73
	v_pk_mul_f32 v[32:33], v[32:33], v[28:29]
	v_add3_u32 v1, v31, v1, s73
	v_lshrrev_b32_e32 v5, 16, v5
	v_and_or_b32 v28, v1, s33, v5
	v_and_b32_sdwa v5, v32, v247 dst_sel:DWORD dst_unused:UNUSED_PAD src0_sel:WORD_1 src1_sel:DWORD
	v_and_b32_sdwa v1, v33, v247 dst_sel:DWORD dst_unused:UNUSED_PAD src0_sel:WORD_1 src1_sel:DWORD
	s_waitcnt vmcnt(1)
	v_lshlrev_b32_e32 v29, 16, v42
	v_add3_u32 v5, v32, v5, s73
	v_add3_u32 v1, v33, v1, s73
	v_mul_f32_e32 v29, 0xbfb8aa3b, v29
	v_lshrrev_b32_e32 v5, 16, v5
	v_exp_f32_e32 v30, v29
	v_and_or_b32 v29, v1, s33, v5
	v_and_b32_e32 v5, 0xffff0000, v42
	v_mul_f32_e32 v5, 0xbfb8aa3b, v5
	v_exp_f32_e32 v5, v5
	v_add_f32_e32 v1, 1.0, v30
	v_rcp_f32_e32 v30, v1
	v_and_b32_e32 v31, 0xffff0000, v43
	v_pk_mul_f32 v[26:27], v[26:27], v[4:5] op_sel_hi:[1,0]
	v_add_f32_e32 v1, 1.0, v5
	v_lshlrev_b32_e32 v5, 16, v43
	v_mul_f32_e32 v5, 0xbfb8aa3b, v5
	v_exp_f32_e32 v5, v5
	v_mul_f32_e32 v31, 0xbfb8aa3b, v31
	v_exp_f32_e32 v33, v31
	v_rcp_f32_e32 v31, v1
	v_add_f32_e32 v1, 1.0, v5
	v_rcp_f32_e32 v32, v1
	v_add_f32_e32 v1, 1.0, v33
	s_waitcnt vmcnt(0)
	v_pk_mul_f32 v[26:27], v[36:37], v[26:27]
	v_rcp_f32_e32 v33, v1
	v_pk_mul_f32 v[26:27], v[30:31], v[26:27]
	v_pk_mul_f32 v[24:25], v[24:25], v[4:5] op_sel_hi:[1,0]
	v_and_b32_sdwa v5, v26, v247 dst_sel:DWORD dst_unused:UNUSED_PAD src0_sel:WORD_1 src1_sel:DWORD
	v_pk_mul_f32 v[24:25], v[38:39], v[24:25]
	v_and_b32_sdwa v1, v27, v247 dst_sel:DWORD dst_unused:UNUSED_PAD src0_sel:WORD_1 src1_sel:DWORD
	v_add3_u32 v5, v26, v5, s73
	v_pk_mul_f32 v[24:25], v[32:33], v[24:25]
	v_add3_u32 v1, v27, v1, s73
	v_lshrrev_b32_e32 v5, 16, v5
	v_and_or_b32 v30, v1, s33, v5
	v_and_b32_sdwa v5, v24, v247 dst_sel:DWORD dst_unused:UNUSED_PAD src0_sel:WORD_1 src1_sel:DWORD
	v_and_b32_sdwa v1, v25, v247 dst_sel:DWORD dst_unused:UNUSED_PAD src0_sel:WORD_1 src1_sel:DWORD
	v_add3_u32 v5, v24, v5, s73
	v_add3_u32 v1, v25, v1, s73
	v_lshrrev_b32_e32 v5, 16, v5
	v_and_or_b32 v31, v1, s33, v5
	v_permlane32_swap_b32_e32 v28, v30
	s_nop 0
	v_permlane32_swap_b32_e32 v29, v31
	global_store_dwordx4 v[10:11], v[28:31], off offset:128
	global_load_dwordx2 v[32:33], v[88:89], off offset:160
	global_load_dwordx4 v[24:27], v[74:75], off offset:320
	global_load_dwordx2 v[34:35], v[88:89], off offset:176
	s_nop 0
	global_load_dwordx4 v[28:31], v[74:75], off offset:352
	s_waitcnt vmcnt(3)
	v_lshlrev_b32_e32 v1, 16, v32
	v_mul_f32_e32 v1, 0xbfb8aa3b, v1
	v_and_b32_e32 v5, 0xffff0000, v32
	v_exp_f32_e32 v1, v1
	v_mul_f32_e32 v5, 0xbfb8aa3b, v5
	v_exp_f32_e32 v5, v5
	v_add_f32_e32 v1, 1.0, v1
	v_rcp_f32_e32 v32, v1
	v_pk_mul_f32 v[22:23], v[22:23], v[4:5] op_sel_hi:[1,0]
	v_add_f32_e32 v1, 1.0, v5
	v_lshlrev_b32_e32 v5, 16, v33
	s_waitcnt vmcnt(2)
	v_pk_mul_f32 v[22:23], v[24:25], v[22:23]
	v_mul_f32_e32 v5, 0xbfb8aa3b, v5
	v_and_b32_e32 v24, 0xffff0000, v33
	v_exp_f32_e32 v5, v5
	v_mul_f32_e32 v24, 0xbfb8aa3b, v24
	v_exp_f32_e32 v25, v24
	v_rcp_f32_e32 v33, v1
	v_add_f32_e32 v1, 1.0, v5
	v_rcp_f32_e32 v24, v1
	v_add_f32_e32 v1, 1.0, v25
	v_rcp_f32_e32 v25, v1
	v_pk_mul_f32 v[22:23], v[32:33], v[22:23]
	v_pk_mul_f32 v[20:21], v[20:21], v[4:5] op_sel_hi:[1,0]
	v_and_b32_sdwa v5, v22, v247 dst_sel:DWORD dst_unused:UNUSED_PAD src0_sel:WORD_1 src1_sel:DWORD
	v_pk_mul_f32 v[20:21], v[26:27], v[20:21]
	v_and_b32_sdwa v1, v23, v247 dst_sel:DWORD dst_unused:UNUSED_PAD src0_sel:WORD_1 src1_sel:DWORD
	v_add3_u32 v5, v22, v5, s73
	v_pk_mul_f32 v[24:25], v[24:25], v[20:21]
	v_add3_u32 v1, v23, v1, s73
	v_lshrrev_b32_e32 v5, 16, v5
	v_and_or_b32 v20, v1, s33, v5
	v_and_b32_sdwa v5, v24, v247 dst_sel:DWORD dst_unused:UNUSED_PAD src0_sel:WORD_1 src1_sel:DWORD
	v_and_b32_sdwa v1, v25, v247 dst_sel:DWORD dst_unused:UNUSED_PAD src0_sel:WORD_1 src1_sel:DWORD
	s_waitcnt vmcnt(1)
	v_lshlrev_b32_e32 v21, 16, v34
	v_add3_u32 v5, v24, v5, s73
	v_add3_u32 v1, v25, v1, s73
	v_mul_f32_e32 v21, 0xbfb8aa3b, v21
	v_lshrrev_b32_e32 v5, 16, v5
	v_exp_f32_e32 v22, v21
	v_and_or_b32 v21, v1, s33, v5
	v_and_b32_e32 v5, 0xffff0000, v34
	v_mul_f32_e32 v5, 0xbfb8aa3b, v5
	v_exp_f32_e32 v5, v5
	v_add_f32_e32 v1, 1.0, v22
	v_rcp_f32_e32 v22, v1
	v_and_b32_e32 v23, 0xffff0000, v35
	v_pk_mul_f32 v[18:19], v[18:19], v[4:5] op_sel_hi:[1,0]
	v_add_f32_e32 v1, 1.0, v5
	v_lshlrev_b32_e32 v5, 16, v35
	v_mul_f32_e32 v5, 0xbfb8aa3b, v5
	v_exp_f32_e32 v5, v5
	v_mul_f32_e32 v23, 0xbfb8aa3b, v23
	v_exp_f32_e32 v25, v23
	v_rcp_f32_e32 v23, v1
	v_add_f32_e32 v1, 1.0, v5
	v_rcp_f32_e32 v24, v1
	v_add_f32_e32 v1, 1.0, v25
	s_waitcnt vmcnt(0)
	v_pk_mul_f32 v[18:19], v[28:29], v[18:19]
	v_rcp_f32_e32 v25, v1
	v_pk_mul_f32 v[18:19], v[22:23], v[18:19]
	v_pk_mul_f32 v[16:17], v[16:17], v[4:5] op_sel_hi:[1,0]
	v_and_b32_sdwa v5, v18, v247 dst_sel:DWORD dst_unused:UNUSED_PAD src0_sel:WORD_1 src1_sel:DWORD
	v_pk_mul_f32 v[16:17], v[30:31], v[16:17]
	v_and_b32_sdwa v1, v19, v247 dst_sel:DWORD dst_unused:UNUSED_PAD src0_sel:WORD_1 src1_sel:DWORD
	v_add3_u32 v5, v18, v5, s73
	v_pk_mul_f32 v[16:17], v[24:25], v[16:17]
	v_add3_u32 v1, v19, v1, s73
	v_lshrrev_b32_e32 v5, 16, v5
	v_and_or_b32 v22, v1, s33, v5
	v_and_b32_sdwa v5, v16, v247 dst_sel:DWORD dst_unused:UNUSED_PAD src0_sel:WORD_1 src1_sel:DWORD
	v_and_b32_sdwa v1, v17, v247 dst_sel:DWORD dst_unused:UNUSED_PAD src0_sel:WORD_1 src1_sel:DWORD
	v_add3_u32 v5, v16, v5, s73
	v_add3_u32 v1, v17, v1, s73
	v_lshrrev_b32_e32 v5, 16, v5
	v_and_or_b32 v23, v1, s33, v5
	v_permlane32_swap_b32_e32 v20, v22
	s_nop 0
	v_permlane32_swap_b32_e32 v21, v23
	global_store_dwordx4 v[10:11], v[20:23], off offset:160
	global_load_dwordx2 v[24:25], v[88:89], off offset:192
	global_load_dwordx4 v[16:19], v[74:75], off offset:384
	global_load_dwordx2 v[26:27], v[88:89], off offset:208
	s_nop 0
	global_load_dwordx4 v[20:23], v[74:75], off offset:416
	s_waitcnt vmcnt(3)
	v_lshlrev_b32_e32 v1, 16, v24
	v_mul_f32_e32 v1, 0xbfb8aa3b, v1
	v_and_b32_e32 v5, 0xffff0000, v24
	v_exp_f32_e32 v1, v1
	v_mul_f32_e32 v5, 0xbfb8aa3b, v5
	v_exp_f32_e32 v5, v5
	v_add_f32_e32 v1, 1.0, v1
	v_rcp_f32_e32 v24, v1
	v_pk_mul_f32 v[14:15], v[14:15], v[4:5] op_sel_hi:[1,0]
	v_add_f32_e32 v1, 1.0, v5
	v_lshlrev_b32_e32 v5, 16, v25
	s_waitcnt vmcnt(2)
	v_pk_mul_f32 v[14:15], v[16:17], v[14:15]
	v_mul_f32_e32 v5, 0xbfb8aa3b, v5
	v_and_b32_e32 v16, 0xffff0000, v25
	v_exp_f32_e32 v5, v5
	v_mul_f32_e32 v16, 0xbfb8aa3b, v16
	v_exp_f32_e32 v17, v16
	v_rcp_f32_e32 v25, v1
	v_add_f32_e32 v1, 1.0, v5
	v_rcp_f32_e32 v16, v1
	v_add_f32_e32 v1, 1.0, v17
	v_rcp_f32_e32 v17, v1
	v_pk_mul_f32 v[14:15], v[24:25], v[14:15]
	v_pk_mul_f32 v[12:13], v[12:13], v[4:5] op_sel_hi:[1,0]
	v_and_b32_sdwa v5, v14, v247 dst_sel:DWORD dst_unused:UNUSED_PAD src0_sel:WORD_1 src1_sel:DWORD
	v_pk_mul_f32 v[12:13], v[18:19], v[12:13]
	v_and_b32_sdwa v1, v15, v247 dst_sel:DWORD dst_unused:UNUSED_PAD src0_sel:WORD_1 src1_sel:DWORD
	v_add3_u32 v5, v14, v5, s73
	v_pk_mul_f32 v[16:17], v[16:17], v[12:13]
	v_add3_u32 v1, v15, v1, s73
	v_lshrrev_b32_e32 v5, 16, v5
	v_and_or_b32 v12, v1, s33, v5
	v_and_b32_sdwa v5, v16, v247 dst_sel:DWORD dst_unused:UNUSED_PAD src0_sel:WORD_1 src1_sel:DWORD
	v_and_b32_sdwa v1, v17, v247 dst_sel:DWORD dst_unused:UNUSED_PAD src0_sel:WORD_1 src1_sel:DWORD
	s_waitcnt vmcnt(1)
	v_lshlrev_b32_e32 v13, 16, v26
	v_add3_u32 v5, v16, v5, s73
	v_add3_u32 v1, v17, v1, s73
	v_mul_f32_e32 v13, 0xbfb8aa3b, v13
	v_lshrrev_b32_e32 v5, 16, v5
	v_exp_f32_e32 v14, v13
	v_and_or_b32 v13, v1, s33, v5
	v_and_b32_e32 v5, 0xffff0000, v26
	v_mul_f32_e32 v5, 0xbfb8aa3b, v5
	v_exp_f32_e32 v5, v5
	v_add_f32_e32 v1, 1.0, v14
	v_rcp_f32_e32 v14, v1
	v_and_b32_e32 v15, 0xffff0000, v27
	v_pk_mul_f32 v[8:9], v[8:9], v[4:5] op_sel_hi:[1,0]
	v_add_f32_e32 v1, 1.0, v5
	v_lshlrev_b32_e32 v5, 16, v27
	v_mul_f32_e32 v5, 0xbfb8aa3b, v5
	v_exp_f32_e32 v5, v5
	v_mul_f32_e32 v15, 0xbfb8aa3b, v15
	v_exp_f32_e32 v17, v15
	v_rcp_f32_e32 v15, v1
	v_add_f32_e32 v1, 1.0, v5
	v_rcp_f32_e32 v16, v1
	v_add_f32_e32 v1, 1.0, v17
	s_waitcnt vmcnt(0)
	v_pk_mul_f32 v[8:9], v[20:21], v[8:9]
	v_rcp_f32_e32 v17, v1
	v_pk_mul_f32 v[8:9], v[14:15], v[8:9]
	v_pk_mul_f32 v[6:7], v[6:7], v[4:5] op_sel_hi:[1,0]
	v_and_b32_sdwa v5, v8, v247 dst_sel:DWORD dst_unused:UNUSED_PAD src0_sel:WORD_1 src1_sel:DWORD
	v_pk_mul_f32 v[6:7], v[22:23], v[6:7]
	v_and_b32_sdwa v1, v9, v247 dst_sel:DWORD dst_unused:UNUSED_PAD src0_sel:WORD_1 src1_sel:DWORD
	v_add3_u32 v5, v8, v5, s73
	v_pk_mul_f32 v[6:7], v[16:17], v[6:7]
	v_add3_u32 v1, v9, v1, s73
	v_lshrrev_b32_e32 v5, 16, v5
	v_and_or_b32 v14, v1, s33, v5
	v_and_b32_sdwa v5, v6, v247 dst_sel:DWORD dst_unused:UNUSED_PAD src0_sel:WORD_1 src1_sel:DWORD
	v_and_b32_sdwa v1, v7, v247 dst_sel:DWORD dst_unused:UNUSED_PAD src0_sel:WORD_1 src1_sel:DWORD
	v_add3_u32 v5, v6, v5, s73
	v_add3_u32 v1, v7, v1, s73
	v_lshrrev_b32_e32 v5, 16, v5
	v_and_or_b32 v15, v1, s33, v5
	v_permlane32_swap_b32_e32 v12, v14
	s_nop 0
	v_permlane32_swap_b32_e32 v13, v15
	global_store_dwordx4 v[10:11], v[12:15], off offset:192
	global_load_dwordx2 v[16:17], v[88:89], off offset:224
	global_load_dwordx4 v[6:9], v[74:75], off offset:448
	global_load_dwordx2 v[18:19], v[88:89], off offset:240
	s_nop 0
	global_load_dwordx4 v[12:15], v[74:75], off offset:480
	s_waitcnt vmcnt(3)
	v_lshlrev_b32_e32 v1, 16, v16
	v_and_b32_e32 v5, 0xffff0000, v16
	v_mul_f32_e32 v1, 0xbfb8aa3b, v1
	v_mul_f32_e32 v5, 0xbfb8aa3b, v5
	v_exp_f32_e32 v1, v1
	v_exp_f32_e32 v5, v5
	v_add_f32_e32 v1, 1.0, v1
	v_pk_mul_f32 v[2:3], v[2:3], v[4:5] op_sel_hi:[1,0]
	v_add_f32_e32 v5, 1.0, v5
	s_waitcnt vmcnt(2)
	v_pk_mul_f32 v[2:3], v[6:7], v[2:3]
	v_rcp_f32_e32 v6, v1
	v_lshlrev_b32_e32 v1, 16, v17
	v_rcp_f32_e32 v7, v5
	v_mul_f32_e32 v1, 0xbfb8aa3b, v1
	v_and_b32_e32 v5, 0xffff0000, v17
	v_exp_f32_e32 v1, v1
	v_mul_f32_e32 v5, 0xbfb8aa3b, v5
	v_exp_f32_e32 v5, v5
	v_pk_mul_f32 v[2:3], v[6:7], v[2:3]
	v_add_f32_e32 v1, 1.0, v1
	v_rcp_f32_e32 v16, v1
	v_add_f32_e32 v1, 1.0, v5
	v_and_b32_sdwa v5, v2, v247 dst_sel:DWORD dst_unused:UNUSED_PAD src0_sel:WORD_1 src1_sel:DWORD
	v_rcp_f32_e32 v17, v1
	v_and_b32_sdwa v1, v3, v247 dst_sel:DWORD dst_unused:UNUSED_PAD src0_sel:WORD_1 src1_sel:DWORD
	v_add3_u32 v2, v2, v5, s73
	v_add3_u32 v1, v3, v1, s73
	v_lshrrev_b32_e32 v2, 16, v2
	v_and_or_b32 v6, v1, s33, v2
	v_pk_mul_f32 v[2:3], v[72:73], v[4:5] op_sel_hi:[1,0]
	s_nop 0
	v_pk_mul_f32 v[2:3], v[8:9], v[2:3]
	s_nop 0
	v_pk_mul_f32 v[2:3], v[16:17], v[2:3]
	s_nop 0
	v_and_b32_sdwa v1, v3, v247 dst_sel:DWORD dst_unused:UNUSED_PAD src0_sel:WORD_1 src1_sel:DWORD
	v_add3_u32 v1, v3, v1, s73
	s_waitcnt vmcnt(1)
	v_lshlrev_b32_e32 v3, 16, v18
	v_and_b32_sdwa v5, v2, v247 dst_sel:DWORD dst_unused:UNUSED_PAD src0_sel:WORD_1 src1_sel:DWORD
	v_mul_f32_e32 v3, 0xbfb8aa3b, v3
	v_add3_u32 v2, v2, v5, s73
	v_exp_f32_e32 v3, v3
	v_and_b32_e32 v5, 0xffff0000, v18
	v_mul_f32_e32 v5, 0xbfb8aa3b, v5
	v_exp_f32_e32 v5, v5
	v_lshrrev_b32_e32 v2, 16, v2
	v_and_or_b32 v7, v1, s33, v2
	v_add_f32_e32 v1, 1.0, v3
	v_lshlrev_b32_e32 v3, 16, v19
	v_mul_f32_e32 v3, 0xbfb8aa3b, v3
	v_rcp_f32_e32 v2, v1
	v_add_f32_e32 v1, 1.0, v5
	v_exp_f32_e32 v5, v3
	v_and_b32_e32 v3, 0xffff0000, v19
	v_mul_f32_e32 v3, 0xbfb8aa3b, v3
	v_exp_f32_e32 v8, v3
	v_rcp_f32_e32 v3, v1
	v_add_f32_e32 v1, 1.0, v5
	v_rcp_f32_e32 v16, v1
	v_add_f32_e32 v1, 1.0, v8
	v_pk_mul_f32 v[8:9], v[70:71], v[4:5] op_sel_hi:[1,0]
	v_rcp_f32_e32 v17, v1
	s_waitcnt vmcnt(0)
	v_pk_mul_f32 v[8:9], v[12:13], v[8:9]
	s_nop 0
	v_pk_mul_f32 v[2:3], v[2:3], v[8:9]
	s_nop 0
	v_and_b32_sdwa v5, v2, v247 dst_sel:DWORD dst_unused:UNUSED_PAD src0_sel:WORD_1 src1_sel:DWORD
	v_and_b32_sdwa v1, v3, v247 dst_sel:DWORD dst_unused:UNUSED_PAD src0_sel:WORD_1 src1_sel:DWORD
	v_add3_u32 v2, v2, v5, s73
	v_add3_u32 v1, v3, v1, s73
	v_lshrrev_b32_e32 v2, 16, v2
	v_and_or_b32 v8, v1, s33, v2
	v_pk_mul_f32 v[2:3], v[68:69], v[4:5] op_sel_hi:[1,0]
	s_nop 0
	v_permlane32_swap_b32_e32 v6, v8
	v_pk_mul_f32 v[2:3], v[14:15], v[2:3]
	s_nop 0
	v_pk_mul_f32 v[2:3], v[16:17], v[2:3]
	s_nop 0
	v_and_b32_sdwa v4, v2, v247 dst_sel:DWORD dst_unused:UNUSED_PAD src0_sel:WORD_1 src1_sel:DWORD
	v_and_b32_sdwa v1, v3, v247 dst_sel:DWORD dst_unused:UNUSED_PAD src0_sel:WORD_1 src1_sel:DWORD
	v_add3_u32 v2, v2, v4, s73
	v_add3_u32 v1, v3, v1, s73
	v_lshrrev_b32_e32 v2, 16, v2
	v_and_or_b32 v9, v1, s33, v2
	s_nop 1
	v_permlane32_swap_b32_e32 v7, v9
	global_store_dwordx4 v[10:11], v[6:9], off offset:224
	s_barrier
	s_branch .LBB0_619

.LBB0_1140:
	s_mul_i32 s20, s16, 0x3020000
	s_sext_i32_i16 s19, s17
	s_mul_hi_i32 s17, s16, 0x3020000
	s_waitcnt lgkmcnt(0)
	s_add_u32 s20, s8, s20
	s_addc_u32 s21, s9, s17
	s_mul_hi_i32 s17, s16, 0x1800000
	s_mul_i32 s16, s16, 0x1800000
	v_lshl_add_u64 v[14:15], v[12:13], 0, s[16:17]
	s_lshl_b32 s16, s19, 6
	s_ashr_i32 s19, s18, 31
	s_lshl_b64 s[18:19], s[18:19], 2
	s_add_u32 s18, s20, s18
	s_addc_u32 s19, s21, s19
	v_lshlrev_b32_e32 v82, 2, v4
	v_add_u32_e32 v50, s16, v1
	v_lshl_add_u64 v[48:49], s[18:19], 0, v[82:83]
	v_mad_i64_i32 v[20:21], s[18:19], v50, s40, v[48:49]
	v_add_u32_e32 v24, 8, v50
	global_load_dwordx4 v[20:23], v[20:21], off
	v_mad_i64_i32 v[24:25], s[18:19], v24, s40, v[48:49]
	global_load_dwordx4 v[24:27], v[24:25], off
	v_add_u32_e32 v28, 16, v50
	v_mad_i64_i32 v[28:29], s[18:19], v28, s40, v[48:49]
	global_load_dwordx4 v[28:31], v[28:29], off
	v_add_u32_e32 v32, 24, v50
	v_mad_i64_i32 v[32:33], s[18:19], v32, s40, v[48:49]
	global_load_dwordx4 v[32:35], v[32:33], off
	v_add_u32_e32 v36, 32, v50
	v_mad_i64_i32 v[36:37], s[18:19], v36, s40, v[48:49]
	global_load_dwordx4 v[36:39], v[36:37], off
	v_add_u32_e32 v40, 40, v50
	v_mad_i64_i32 v[40:41], s[18:19], v40, s40, v[48:49]
	global_load_dwordx4 v[40:43], v[40:41], off
	v_add_u32_e32 v44, 48, v50
	v_mad_i64_i32 v[44:45], s[18:19], v44, s40, v[48:49]
	global_load_dwordx4 v[44:47], v[44:45], off
	v_add_u32_e32 v50, 56, v50
	v_mad_i64_i32 v[48:49], s[18:19], v50, s40, v[48:49]
	global_load_dwordx4 v[48:51], v[48:49], off
	v_add_u32_e32 v52, v5, v7
	s_ashr_i32 s17, s16, 31
	s_lshl_b64 s[16:17], s[16:17], 1
	v_lshl_add_u64 v[14:15], v[14:15], 0, s[16:17]
	v_lshlrev_b32_e32 v82, 1, v6
	v_lshl_add_u64 v[14:15], v[14:15], 0, v[82:83]
	s_waitcnt vmcnt(7)
	ds_write2_b32 v52, v20, v21 offset1:1
	ds_write2_b32 v52, v22, v23 offset0:2 offset1:3
	v_add_u32_e32 v20, 0x420, v52
	s_waitcnt vmcnt(6)
	ds_write2_b32 v20, v24, v25 offset1:1
	v_add_u32_e32 v20, 0x428, v52
	ds_write2_b32 v20, v26, v27 offset1:1
	v_add_u32_e32 v20, 0x840, v52
	s_waitcnt vmcnt(5)
	ds_write2_b32 v20, v28, v29 offset1:1
	v_add_u32_e32 v20, 0x848, v52
	ds_write2_b32 v20, v30, v31 offset1:1
	v_add_u32_e32 v20, 0xc60, v52
	s_waitcnt vmcnt(4)
	ds_write2_b32 v20, v32, v33 offset1:1
	v_add_u32_e32 v20, 0xc68, v52
	ds_write2_b32 v20, v34, v35 offset1:1
	v_add_u32_e32 v20, 0x1080, v52
	s_waitcnt vmcnt(3)
	ds_write2_b32 v20, v36, v37 offset1:1
	v_add_u32_e32 v20, 0x1088, v52
	ds_write2_b32 v20, v38, v39 offset1:1
	v_add_u32_e32 v20, 0x14a0, v52
	s_waitcnt vmcnt(2)
	ds_write2_b32 v20, v40, v41 offset1:1
	v_add_u32_e32 v20, 0x14a8, v52
	ds_write2_b32 v20, v42, v43 offset1:1
	v_add_u32_e32 v20, 0x18c0, v52
	s_waitcnt vmcnt(1)
	ds_write2_b32 v20, v44, v45 offset1:1
	v_add_u32_e32 v20, 0x18c8, v52
	ds_write2_b32 v20, v46, v47 offset1:1
	v_add_u32_e32 v20, 0x1ce0, v52
	s_waitcnt vmcnt(0)
	ds_write2_b32 v20, v48, v49 offset1:1
	v_add_u32_e32 v20, 0x1ce8, v52
	ds_write2_b32 v20, v50, v51 offset1:1
	s_waitcnt lgkmcnt(0)
	ds_read2_b32 v[24:25], v19 offset0:33 offset1:41
	ds_read2_b32 v[26:27], v19 offset1:8
	ds_read2_b32 v[28:29], v19 offset0:66 offset1:74
	ds_read2_b32 v[30:31], v19 offset0:99 offset1:107
	ds_read2_b32 v[32:33], v19 offset0:132 offset1:140
	ds_read2_b32 v[34:35], v19 offset0:165 offset1:173
	ds_read2_b32 v[36:37], v19 offset0:198 offset1:206
	ds_read2_b32 v[38:39], v19 offset0:231 offset1:239
	s_waitcnt lgkmcnt(7)
	s_waitcnt lgkmcnt(6)
	v_cvt_pk_bf16_f32 v20, v26, v24
	s_waitcnt lgkmcnt(5)
	s_waitcnt lgkmcnt(4)
	v_cvt_pk_bf16_f32 v21, v28, v30
	s_waitcnt lgkmcnt(3)
	s_waitcnt lgkmcnt(2)
	v_cvt_pk_bf16_f32 v22, v32, v34
	s_waitcnt lgkmcnt(1)
	v_add_u32_e32 v40, s25, v1
	s_waitcnt lgkmcnt(0)
	v_ashrrev_i32_e32 v41, 31, v40
	v_lshlrev_b64 v[40:41], 12, v[40:41]
	v_cvt_pk_bf16_f32 v23, v36, v38
	v_lshl_add_u64 v[40:41], v[14:15], 0, v[40:41]
	global_store_dwordx4 v[40:41], v[20:23], off
	s_nop 0
	s_nop 0
	s_nop 0
	s_nop 0
	s_nop 0
	s_nop 0
	s_nop 0
	v_cvt_pk_bf16_f32 v20, v27, v25
	s_nop 0
	s_nop 0
	s_nop 0
	s_nop 0
	s_nop 0
	v_cvt_pk_bf16_f32 v21, v29, v31
	s_nop 0
	s_nop 0
	s_nop 0
	s_nop 0
	s_nop 0
	v_cvt_pk_bf16_f32 v22, v33, v35
	v_cvt_pk_bf16_f32 v23, v37, v39
	v_add_u32_e32 v24, s25, v16
	v_ashrrev_i32_e32 v25, 31, v24
	v_lshlrev_b64 v[24:25], 12, v[24:25]
	v_lshl_add_u64 v[24:25], v[14:15], 0, v[24:25]
	global_store_dwordx4 v[24:25], v[20:23], off
	ds_read2_b32 v[24:25], v19 offset0:49 offset1:57
	ds_read2_b32 v[26:27], v19 offset0:16 offset1:24
	ds_read2_b32 v[28:29], v19 offset0:82 offset1:90
	ds_read2_b32 v[30:31], v19 offset0:115 offset1:123
	ds_read2_b32 v[32:33], v19 offset0:148 offset1:156
	ds_read2_b32 v[34:35], v19 offset0:181 offset1:189
	ds_read2_b32 v[36:37], v19 offset0:214 offset1:222
	ds_read2_b32 v[38:39], v19 offset0:247 offset1:255
	s_waitcnt lgkmcnt(7)
	s_waitcnt lgkmcnt(6)
	v_cvt_pk_bf16_f32 v20, v26, v24
	s_waitcnt lgkmcnt(5)
	s_waitcnt lgkmcnt(4)
	v_cvt_pk_bf16_f32 v21, v28, v30
	s_waitcnt lgkmcnt(3)
	s_waitcnt lgkmcnt(2)
	v_cvt_pk_bf16_f32 v22, v32, v34
	s_waitcnt lgkmcnt(1)
	v_add_u32_e32 v40, s25, v17
	s_waitcnt lgkmcnt(0)
	v_ashrrev_i32_e32 v41, 31, v40
	v_lshlrev_b64 v[40:41], 12, v[40:41]
	v_cvt_pk_bf16_f32 v23, v36, v38
	v_lshl_add_u64 v[40:41], v[14:15], 0, v[40:41]
	global_store_dwordx4 v[40:41], v[20:23], off
	s_nop 0
	s_nop 0
	s_nop 0
	s_nop 0
	s_nop 0
	s_nop 0
	s_nop 0
	v_cvt_pk_bf16_f32 v20, v27, v25
	s_nop 0
	s_nop 0
	s_nop 0
	s_nop 0
	s_nop 0
	v_cvt_pk_bf16_f32 v21, v29, v31
	s_nop 0
	s_nop 0
	s_nop 0
	s_nop 0
	s_nop 0
	v_cvt_pk_bf16_f32 v22, v33, v35
	v_cvt_pk_bf16_f32 v23, v37, v39
	v_add_u32_e32 v24, s25, v18
	v_ashrrev_i32_e32 v25, 31, v24
	v_lshlrev_b64 v[24:25], 12, v[24:25]
	v_lshl_add_u64 v[14:15], v[14:15], 0, v[24:25]
	global_store_dwordx4 v[14:15], v[20:23], off
	s_waitcnt lgkmcnt(0)

.LBB0_1142:
	s_mul_hi_i32 s16, s22, 0x5397829d
	s_lshr_b32 s17, s16, 31
	s_ashr_i32 s16, s16, 13
	s_add_i32 s16, s16, s17
	s_mul_i32 s17, s16, 0xffff9e00
	s_add_i32 s25, s22, s17
	s_cmpk_gt_i32 s25, 0x17ff
	s_mov_b64 s[18:19], -1
	s_cbranch_scc0 .LBB0_1152
	s_cmpk_gt_u32 s25, 0x1fff
	s_cbranch_scc0 .LBB0_1149
	s_mov_b64 s[20:21], -1
	s_cmpk_gt_u32 s25, 0x4bff
	s_mul_hi_i32 s19, s16, 0x2c00000
	s_mul_i32 s18, s16, 0x2c00000
	s_cbranch_scc0 .LBB0_1146
	s_and_b32 s17, s25, 0x7fffffc0
	s_add_i32 s70, s17, 0xffffb400
	s_waitcnt lgkmcnt(0)
	s_add_u32 s26, s14, s18
	s_addc_u32 s27, s15, s19
	s_mul_hi_i32 s21, s16, 0x1600000
	s_mul_i32 s20, s16, 0x1600000
	s_and_b32 s17, s23, 0x7e0
	v_lshl_add_u64 v[14:15], v[2:3], 0, s[20:21]
	s_lshl_b32 s20, s17, 2
	v_add_u32_e32 v20, s70, v1
	s_add_u32 s20, s26, s20
	s_addc_u32 s21, s27, 0
	v_lshlrev_b32_e32 v82, 2, v4
	v_ashrrev_i32_e32 v21, 31, v20
	v_lshl_add_u64 v[22:23], s[20:21], 0, v[82:83]
	v_lshlrev_b64 v[20:21], 13, v[20:21]
	v_lshl_add_u64 v[48:49], v[22:23], 0, v[20:21]
	s_mov_b32 s20, 0x10000
	v_add_co_u32_e32 v24, vcc, s20, v48
	global_load_dwordx4 v[20:23], v[48:49], off
	s_nop 0
	v_addc_co_u32_e32 v25, vcc, 0, v49, vcc
	s_mov_b32 s20, 0x20000
	global_load_dwordx4 v[24:27], v[24:25], off
	v_add_co_u32_e32 v28, vcc, s20, v48
	s_mov_b32 s20, 0x30000
	s_nop 0
	v_addc_co_u32_e32 v29, vcc, 0, v49, vcc
	global_load_dwordx4 v[28:31], v[28:29], off
	v_add_co_u32_e32 v32, vcc, s20, v48
	s_mov_b32 s20, 0x40000
	s_nop 0
	v_addc_co_u32_e32 v33, vcc, 0, v49, vcc
	global_load_dwordx4 v[32:35], v[32:33], off
	v_add_co_u32_e32 v36, vcc, s20, v48
	s_mov_b32 s20, 0x50000
	s_nop 0
	v_addc_co_u32_e32 v37, vcc, 0, v49, vcc
	global_load_dwordx4 v[36:39], v[36:37], off
	v_add_co_u32_e32 v40, vcc, s20, v48
	s_mov_b32 s20, 0x60000
	s_nop 0
	v_addc_co_u32_e32 v41, vcc, 0, v49, vcc
	global_load_dwordx4 v[40:43], v[40:41], off
	v_add_co_u32_e32 v44, vcc, s20, v48
	s_mov_b32 s20, 0x70000
	s_nop 0
	v_addc_co_u32_e32 v45, vcc, 0, v49, vcc
	global_load_dwordx4 v[44:47], v[44:45], off
	v_add_co_u32_e32 v48, vcc, s20, v48
	v_add_u32_e32 v52, v5, v7
	s_nop 0
	v_addc_co_u32_e32 v49, vcc, 0, v49, vcc
	global_load_dwordx4 v[48:51], v[48:49], off
	s_lshl_b64 s[20:21], s[70:71], 1
	v_lshl_add_u64 v[14:15], v[14:15], 0, s[20:21]
	v_lshlrev_b32_e32 v82, 1, v6
	v_lshl_add_u64 v[14:15], v[14:15], 0, v[82:83]
	s_movk_i32 s26, 0x2c00
	s_waitcnt vmcnt(7)
	ds_write2_b32 v52, v20, v21 offset1:1
	ds_write2_b32 v52, v22, v23 offset0:2 offset1:3
	v_add_u32_e32 v20, 0x420, v52
	s_waitcnt vmcnt(6)
	ds_write2_b32 v20, v24, v25 offset1:1
	v_add_u32_e32 v20, 0x428, v52
	ds_write2_b32 v20, v26, v27 offset1:1
	v_add_u32_e32 v20, 0x840, v52
	s_waitcnt vmcnt(5)
	ds_write2_b32 v20, v28, v29 offset1:1
	v_add_u32_e32 v20, 0x848, v52
	ds_write2_b32 v20, v30, v31 offset1:1
	v_add_u32_e32 v20, 0xc60, v52
	s_waitcnt vmcnt(4)
	ds_write2_b32 v20, v32, v33 offset1:1
	v_add_u32_e32 v20, 0xc68, v52
	ds_write2_b32 v20, v34, v35 offset1:1
	v_add_u32_e32 v20, 0x1080, v52
	s_waitcnt vmcnt(3)
	ds_write2_b32 v20, v36, v37 offset1:1
	v_add_u32_e32 v20, 0x1088, v52
	ds_write2_b32 v20, v38, v39 offset1:1
	v_add_u32_e32 v20, 0x14a0, v52
	s_waitcnt vmcnt(2)
	ds_write2_b32 v20, v40, v41 offset1:1
	v_add_u32_e32 v20, 0x14a8, v52
	ds_write2_b32 v20, v42, v43 offset1:1
	v_add_u32_e32 v20, 0x18c0, v52
	s_waitcnt vmcnt(1)
	ds_write2_b32 v20, v44, v45 offset1:1
	v_add_u32_e32 v20, 0x18c8, v52
	ds_write2_b32 v20, v46, v47 offset1:1
	v_add_u32_e32 v20, 0x1ce0, v52
	s_waitcnt vmcnt(0)
	ds_write2_b32 v20, v48, v49 offset1:1
	v_add_u32_e32 v20, 0x1ce8, v52
	ds_write2_b32 v20, v50, v51 offset1:1
	s_waitcnt lgkmcnt(0)
	ds_read2_b32 v[24:25], v19 offset0:33 offset1:41
	ds_read2_b32 v[26:27], v19 offset1:8
	ds_read2_b32 v[28:29], v19 offset0:66 offset1:74
	ds_read2_b32 v[30:31], v19 offset0:99 offset1:107
	ds_read2_b32 v[32:33], v19 offset0:132 offset1:140
	ds_read2_b32 v[34:35], v19 offset0:165 offset1:173
	ds_read2_b32 v[36:37], v19 offset0:198 offset1:206
	ds_read2_b32 v[38:39], v19 offset0:231 offset1:239
	s_waitcnt lgkmcnt(7)
	s_waitcnt lgkmcnt(6)
	v_cvt_pk_bf16_f32 v20, v26, v24
	s_waitcnt lgkmcnt(5)
	s_waitcnt lgkmcnt(4)
	v_cvt_pk_bf16_f32 v21, v28, v30
	s_waitcnt lgkmcnt(3)
	s_waitcnt lgkmcnt(2)
	v_cvt_pk_bf16_f32 v22, v32, v34
	s_waitcnt lgkmcnt(1)
	s_waitcnt lgkmcnt(0)
	s_nop 0
	s_nop 0
	s_nop 0
	v_cvt_pk_bf16_f32 v23, v36, v38
	v_add_u32_e32 v24, s17, v1
	v_mad_i64_i32 v[40:41], s[20:21], v24, s26, v[14:15]
	global_store_dwordx4 v[40:41], v[20:23], off
	s_nop 0
	s_nop 0
	s_nop 0
	s_nop 0
	s_nop 0
	s_nop 0
	s_nop 0
	v_cvt_pk_bf16_f32 v20, v27, v25
	s_nop 0
	s_nop 0
	s_nop 0
	s_nop 0
	s_nop 0
	v_cvt_pk_bf16_f32 v21, v29, v31
	s_nop 0
	s_nop 0
	s_nop 0
	s_nop 0
	s_nop 0
	v_cvt_pk_bf16_f32 v22, v33, v35
	s_nop 0
	s_nop 0
	s_nop 0
	v_cvt_pk_bf16_f32 v23, v37, v39
	v_add_u32_e32 v24, s17, v16
	v_mad_i64_i32 v[24:25], s[20:21], v24, s26, v[14:15]
	global_store_dwordx4 v[24:25], v[20:23], off
	ds_read2_b32 v[24:25], v19 offset0:49 offset1:57
	ds_read2_b32 v[26:27], v19 offset0:16 offset1:24
	ds_read2_b32 v[28:29], v19 offset0:82 offset1:90
	ds_read2_b32 v[30:31], v19 offset0:115 offset1:123
	ds_read2_b32 v[32:33], v19 offset0:148 offset1:156
	ds_read2_b32 v[34:35], v19 offset0:181 offset1:189
	ds_read2_b32 v[36:37], v19 offset0:214 offset1:222
	ds_read2_b32 v[38:39], v19 offset0:247 offset1:255
	s_waitcnt lgkmcnt(7)
	s_waitcnt lgkmcnt(6)
	v_cvt_pk_bf16_f32 v20, v26, v24
	s_waitcnt lgkmcnt(5)
	s_waitcnt lgkmcnt(4)
	v_cvt_pk_bf16_f32 v21, v28, v30
	s_waitcnt lgkmcnt(3)
	s_waitcnt lgkmcnt(2)
	v_cvt_pk_bf16_f32 v22, v32, v34
	s_waitcnt lgkmcnt(1)
	s_waitcnt lgkmcnt(0)
	s_nop 0
	s_nop 0
	s_nop 0
	v_cvt_pk_bf16_f32 v23, v36, v38
	v_add_u32_e32 v24, s17, v17
	v_mad_i64_i32 v[40:41], s[20:21], v24, s26, v[14:15]
	global_store_dwordx4 v[40:41], v[20:23], off
	s_nop 0
	s_nop 0
	s_nop 0
	s_nop 0
	s_nop 0
	s_nop 0
	s_nop 0
	v_cvt_pk_bf16_f32 v20, v27, v25
	s_nop 0
	s_nop 0
	s_nop 0
	s_nop 0
	s_nop 0
	v_cvt_pk_bf16_f32 v21, v29, v31
	s_nop 0
	s_nop 0
	s_nop 0
	s_nop 0
	s_nop 0
	v_cvt_pk_bf16_f32 v22, v33, v35
	s_nop 0
	s_nop 0
	s_nop 0
	v_cvt_pk_bf16_f32 v23, v37, v39
	v_add_u32_e32 v24, s17, v18
	v_mad_i64_i32 v[14:15], s[20:21], v24, s26, v[14:15]
	global_store_dwordx4 v[14:15], v[20:23], off
	s_waitcnt lgkmcnt(0)
	s_mov_b64 s[20:21], 0
.LBB0_1146:
	s_andn2_b64 vcc, exec, s[20:21]
	s_cbranch_vccnz .LBB0_1148
	s_add_i32 s17, s25, 0xe000
	s_and_b32 s20, s17, 0xffff
	s_mul_i32 s20, s20, 0xba2f
	s_lshr_b32 s20, s20, 24
	s_mul_i32 s21, s20, 0x160
	s_sub_i32 s21, s17, s21
	s_and_b32 s26, s21, 0xffff
	s_lshl_b32 s17, s26, 5
	s_mul_i32 s28, s16, 0x5800000
	s_mul_hi_i32 s27, s16, 0x5800000
	s_waitcnt lgkmcnt(0)
	s_add_u32 s28, s12, s28
	s_addc_u32 s27, s13, s27
	v_lshl_add_u64 v[14:15], v[8:9], 0, s[18:19]
	s_bfe_i32 s18, s21, 0x10002
	s_lshl_b32 s19, s26, 4
	s_and_b32 s18, s18, 0x1600
	s_and_b32 s19, s19, 0x1f80
	s_add_i32 s18, s18, s19
	s_and_b32 s19, s17, 0x60
	s_or_b32 s18, s18, s19
	s_lshl_b32 s18, s18, 2
	s_add_u32 s18, s28, s18
	s_addc_u32 s19, s27, 0
	v_lshlrev_b32_e32 v82, 2, v4
	v_lshl_add_u32 v50, s20, 6, v1
	v_lshl_add_u64 v[48:49], s[18:19], 0, v[82:83]
	s_mov_b32 s21, 0xb000
	v_mad_i64_i32 v[20:21], s[18:19], v50, s21, v[48:49]
	v_add_u32_e32 v24, 8, v50
	global_load_dwordx4 v[20:23], v[20:21], off
	v_mad_i64_i32 v[24:25], s[18:19], v24, s21, v[48:49]
	global_load_dwordx4 v[24:27], v[24:25], off
	v_add_u32_e32 v28, 16, v50
	v_mad_i64_i32 v[28:29], s[18:19], v28, s21, v[48:49]
	global_load_dwordx4 v[28:31], v[28:29], off
	v_add_u32_e32 v32, 24, v50
	v_mad_i64_i32 v[32:33], s[18:19], v32, s21, v[48:49]
	global_load_dwordx4 v[32:35], v[32:33], off
	v_add_u32_e32 v36, 32, v50
	v_mad_i64_i32 v[36:37], s[18:19], v36, s21, v[48:49]
	global_load_dwordx4 v[36:39], v[36:37], off
	v_add_u32_e32 v40, 40, v50
	v_mad_i64_i32 v[40:41], s[18:19], v40, s21, v[48:49]
	global_load_dwordx4 v[40:43], v[40:41], off
	v_add_u32_e32 v44, 48, v50
	v_mad_i64_i32 v[44:45], s[18:19], v44, s21, v[48:49]
	global_load_dwordx4 v[44:47], v[44:45], off
	v_add_u32_e32 v50, 56, v50
	v_mad_i64_i32 v[48:49], s[18:19], v50, s21, v[48:49]
	global_load_dwordx4 v[48:51], v[48:49], off
	v_add_u32_e32 v52, v5, v7
	s_lshl_b32 s70, s20, 7
	v_lshl_add_u64 v[14:15], v[14:15], 0, s[70:71]
	v_lshlrev_b32_e32 v82, 1, v6
	v_lshl_add_u64 v[14:15], v[14:15], 0, v[82:83]
	s_waitcnt vmcnt(7)
	ds_write2_b32 v52, v20, v21 offset1:1
	ds_write2_b32 v52, v22, v23 offset0:2 offset1:3
	v_add_u32_e32 v20, 0x420, v52
	s_waitcnt vmcnt(6)
	ds_write2_b32 v20, v24, v25 offset1:1
	v_add_u32_e32 v20, 0x428, v52
	ds_write2_b32 v20, v26, v27 offset1:1
	v_add_u32_e32 v20, 0x840, v52
	s_waitcnt vmcnt(5)
	ds_write2_b32 v20, v28, v29 offset1:1
	v_add_u32_e32 v20, 0x848, v52
	ds_write2_b32 v20, v30, v31 offset1:1
	v_add_u32_e32 v20, 0xc60, v52
	s_waitcnt vmcnt(4)
	ds_write2_b32 v20, v32, v33 offset1:1
	v_add_u32_e32 v20, 0xc68, v52
	ds_write2_b32 v20, v34, v35 offset1:1
	v_add_u32_e32 v20, 0x1080, v52
	s_waitcnt vmcnt(3)
	ds_write2_b32 v20, v36, v37 offset1:1
	v_add_u32_e32 v20, 0x1088, v52
	ds_write2_b32 v20, v38, v39 offset1:1
	v_add_u32_e32 v20, 0x14a0, v52
	s_waitcnt vmcnt(2)
	ds_write2_b32 v20, v40, v41 offset1:1
	v_add_u32_e32 v20, 0x14a8, v52
	ds_write2_b32 v20, v42, v43 offset1:1
	v_add_u32_e32 v20, 0x18c0, v52
	s_waitcnt vmcnt(1)
	ds_write2_b32 v20, v44, v45 offset1:1
	v_add_u32_e32 v20, 0x18c8, v52
	ds_write2_b32 v20, v46, v47 offset1:1
	v_add_u32_e32 v20, 0x1ce0, v52
	s_waitcnt vmcnt(0)
	ds_write2_b32 v20, v48, v49 offset1:1
	v_add_u32_e32 v20, 0x1ce8, v52
	ds_write2_b32 v20, v50, v51 offset1:1
	s_waitcnt lgkmcnt(0)
	ds_read2_b32 v[24:25], v19 offset0:33 offset1:41
	ds_read2_b32 v[26:27], v19 offset1:8
	ds_read2_b32 v[28:29], v19 offset0:66 offset1:74
	ds_read2_b32 v[30:31], v19 offset0:99 offset1:107
	ds_read2_b32 v[32:33], v19 offset0:132 offset1:140
	ds_read2_b32 v[34:35], v19 offset0:165 offset1:173
	ds_read2_b32 v[36:37], v19 offset0:198 offset1:206
	ds_read2_b32 v[38:39], v19 offset0:231 offset1:239
	s_waitcnt lgkmcnt(7)
	s_waitcnt lgkmcnt(6)
	v_cvt_pk_bf16_f32 v20, v26, v24
	s_waitcnt lgkmcnt(5)
	s_waitcnt lgkmcnt(4)
	v_cvt_pk_bf16_f32 v21, v28, v30
	s_waitcnt lgkmcnt(3)
	s_waitcnt lgkmcnt(2)
	v_cvt_pk_bf16_f32 v22, v32, v34
	s_waitcnt lgkmcnt(1)
	v_add_u32_e32 v40, s17, v1
	s_waitcnt lgkmcnt(0)
	v_ashrrev_i32_e32 v41, 31, v40
	v_lshlrev_b64 v[40:41], 12, v[40:41]
	v_cvt_pk_bf16_f32 v23, v36, v38
	v_lshl_add_u64 v[40:41], v[14:15], 0, v[40:41]
	global_store_dwordx4 v[40:41], v[20:23], off
	s_nop 0
	s_nop 0
	s_nop 0
	s_nop 0
	s_nop 0
	s_nop 0
	s_nop 0
	v_cvt_pk_bf16_f32 v20, v27, v25
	s_nop 0
	s_nop 0
	s_nop 0
	s_nop 0
	s_nop 0
	v_cvt_pk_bf16_f32 v21, v29, v31
	s_nop 0
	s_nop 0
	s_nop 0
	s_nop 0
	s_nop 0
	v_cvt_pk_bf16_f32 v22, v33, v35
	v_cvt_pk_bf16_f32 v23, v37, v39
	v_add_u32_e32 v24, s17, v16
	v_ashrrev_i32_e32 v25, 31, v24
	v_lshlrev_b64 v[24:25], 12, v[24:25]
	v_lshl_add_u64 v[24:25], v[14:15], 0, v[24:25]
	global_store_dwordx4 v[24:25], v[20:23], off
	ds_read2_b32 v[24:25], v19 offset0:49 offset1:57
	ds_read2_b32 v[26:27], v19 offset0:16 offset1:24
	ds_read2_b32 v[28:29], v19 offset0:82 offset1:90
	ds_read2_b32 v[30:31], v19 offset0:115 offset1:123
	ds_read2_b32 v[32:33], v19 offset0:148 offset1:156
	ds_read2_b32 v[34:35], v19 offset0:181 offset1:189
	ds_read2_b32 v[36:37], v19 offset0:214 offset1:222
	ds_read2_b32 v[38:39], v19 offset0:247 offset1:255
	s_waitcnt lgkmcnt(7)
	s_waitcnt lgkmcnt(6)
	v_cvt_pk_bf16_f32 v20, v26, v24
	s_waitcnt lgkmcnt(5)
	s_waitcnt lgkmcnt(4)
	v_cvt_pk_bf16_f32 v21, v28, v30
	s_waitcnt lgkmcnt(3)
	s_waitcnt lgkmcnt(2)
	v_cvt_pk_bf16_f32 v22, v32, v34
	s_waitcnt lgkmcnt(1)
	v_add_u32_e32 v40, s17, v17
	s_waitcnt lgkmcnt(0)
	v_ashrrev_i32_e32 v41, 31, v40
	v_lshlrev_b64 v[40:41], 12, v[40:41]
	v_cvt_pk_bf16_f32 v23, v36, v38
	v_lshl_add_u64 v[40:41], v[14:15], 0, v[40:41]
	global_store_dwordx4 v[40:41], v[20:23], off
	s_nop 0
	s_nop 0
	s_nop 0
	s_nop 0
	s_nop 0
	s_nop 0
	s_nop 0
	v_cvt_pk_bf16_f32 v20, v27, v25
	s_nop 0
	s_nop 0
	s_nop 0
	s_nop 0
	s_nop 0
	v_cvt_pk_bf16_f32 v21, v29, v31
	s_nop 0
	s_nop 0
	s_nop 0
	s_nop 0
	s_nop 0
	v_cvt_pk_bf16_f32 v22, v33, v35
	v_cvt_pk_bf16_f32 v23, v37, v39
	v_add_u32_e32 v24, s17, v18
	v_ashrrev_i32_e32 v25, 31, v24
	v_lshlrev_b64 v[24:25], 12, v[24:25]
	v_lshl_add_u64 v[14:15], v[14:15], 0, v[24:25]
	global_store_dwordx4 v[14:15], v[20:23], off
	s_waitcnt lgkmcnt(0)

.LBB0_1149:
	s_andn2_b64 vcc, exec, s[18:19]
	s_cbranch_vccnz .LBB0_1151
	s_and_b32 s17, s25, 0x1fc0
	s_add_i32 s70, s17, 0xffffe800
	s_ashr_i32 s17, s16, 31
	s_lshl_b64 s[18:19], s[16:17], 24
	s_waitcnt lgkmcnt(0)
	s_add_u32 s20, s10, s18
	s_addc_u32 s21, s11, s19
	s_lshl_b64 s[18:19], s[16:17], 23
	s_and_b32 s17, s23, 0x7e0
	v_lshl_add_u64 v[14:15], v[10:11], 0, s[18:19]
	s_lshl_b32 s18, s17, 2
	v_add_u32_e32 v20, s70, v1
	s_add_u32 s18, s20, s18
	s_addc_u32 s19, s21, 0
	v_lshlrev_b32_e32 v82, 2, v4
	v_ashrrev_i32_e32 v21, 31, v20
	v_lshl_add_u64 v[22:23], s[18:19], 0, v[82:83]
	v_lshlrev_b64 v[20:21], 13, v[20:21]
	v_lshl_add_u64 v[48:49], v[22:23], 0, v[20:21]
	s_mov_b32 s18, 0x10000
	v_add_co_u32_e32 v24, vcc, s18, v48
	global_load_dwordx4 v[20:23], v[48:49], off
	s_nop 0
	v_addc_co_u32_e32 v25, vcc, 0, v49, vcc
	s_mov_b32 s18, 0x20000
	global_load_dwordx4 v[24:27], v[24:25], off
	v_add_co_u32_e32 v28, vcc, s18, v48
	s_mov_b32 s18, 0x30000
	s_nop 0
	v_addc_co_u32_e32 v29, vcc, 0, v49, vcc
	global_load_dwordx4 v[28:31], v[28:29], off
	v_add_co_u32_e32 v32, vcc, s18, v48
	s_mov_b32 s18, 0x40000
	s_nop 0
	v_addc_co_u32_e32 v33, vcc, 0, v49, vcc
	global_load_dwordx4 v[32:35], v[32:33], off
	v_add_co_u32_e32 v36, vcc, s18, v48
	s_mov_b32 s18, 0x50000
	s_nop 0
	v_addc_co_u32_e32 v37, vcc, 0, v49, vcc
	global_load_dwordx4 v[36:39], v[36:37], off
	v_add_co_u32_e32 v40, vcc, s18, v48
	s_mov_b32 s18, 0x60000
	s_nop 0
	v_addc_co_u32_e32 v41, vcc, 0, v49, vcc
	global_load_dwordx4 v[40:43], v[40:41], off
	v_add_co_u32_e32 v44, vcc, s18, v48
	s_mov_b32 s18, 0x70000
	s_nop 0
	v_addc_co_u32_e32 v45, vcc, 0, v49, vcc
	global_load_dwordx4 v[44:47], v[44:45], off
	v_add_co_u32_e32 v48, vcc, s18, v48
	v_add_u32_e32 v52, v5, v7
	s_nop 0
	v_addc_co_u32_e32 v49, vcc, 0, v49, vcc
	global_load_dwordx4 v[48:51], v[48:49], off
	s_lshl_b64 s[18:19], s[70:71], 1
	v_lshl_add_u64 v[14:15], v[14:15], 0, s[18:19]
	v_lshlrev_b32_e32 v82, 1, v6
	v_lshl_add_u64 v[14:15], v[14:15], 0, v[82:83]
	s_waitcnt vmcnt(7)
	ds_write2_b32 v52, v20, v21 offset1:1
	ds_write2_b32 v52, v22, v23 offset0:2 offset1:3
	v_add_u32_e32 v20, 0x420, v52
	s_waitcnt vmcnt(6)
	ds_write2_b32 v20, v24, v25 offset1:1
	v_add_u32_e32 v20, 0x428, v52
	ds_write2_b32 v20, v26, v27 offset1:1
	v_add_u32_e32 v20, 0x840, v52
	s_waitcnt vmcnt(5)
	ds_write2_b32 v20, v28, v29 offset1:1
	v_add_u32_e32 v20, 0x848, v52
	ds_write2_b32 v20, v30, v31 offset1:1
	v_add_u32_e32 v20, 0xc60, v52
	s_waitcnt vmcnt(4)
	ds_write2_b32 v20, v32, v33 offset1:1
	v_add_u32_e32 v20, 0xc68, v52
	ds_write2_b32 v20, v34, v35 offset1:1
	v_add_u32_e32 v20, 0x1080, v52
	s_waitcnt vmcnt(3)
	ds_write2_b32 v20, v36, v37 offset1:1
	v_add_u32_e32 v20, 0x1088, v52
	ds_write2_b32 v20, v38, v39 offset1:1
	v_add_u32_e32 v20, 0x14a0, v52
	s_waitcnt vmcnt(2)
	ds_write2_b32 v20, v40, v41 offset1:1
	v_add_u32_e32 v20, 0x14a8, v52
	ds_write2_b32 v20, v42, v43 offset1:1
	v_add_u32_e32 v20, 0x18c0, v52
	v_add_u32_e32 v40, s17, v1
	v_ashrrev_i32_e32 v41, 31, v40
	s_waitcnt vmcnt(1)
	ds_write2_b32 v20, v44, v45 offset1:1
	v_add_u32_e32 v20, 0x18c8, v52
	ds_write2_b32 v20, v46, v47 offset1:1
	v_add_u32_e32 v20, 0x1ce0, v52
	v_lshlrev_b64 v[40:41], 12, v[40:41]
	v_lshl_add_u64 v[40:41], v[14:15], 0, v[40:41]
	s_waitcnt vmcnt(0)
	ds_write2_b32 v20, v48, v49 offset1:1
	v_add_u32_e32 v20, 0x1ce8, v52
	ds_write2_b32 v20, v50, v51 offset1:1
	s_waitcnt lgkmcnt(0)
	ds_read2_b32 v[24:25], v19 offset0:33 offset1:41
	ds_read2_b32 v[26:27], v19 offset1:8
	ds_read2_b32 v[28:29], v19 offset0:66 offset1:74
	ds_read2_b32 v[30:31], v19 offset0:99 offset1:107
	ds_read2_b32 v[32:33], v19 offset0:132 offset1:140
	ds_read2_b32 v[34:35], v19 offset0:165 offset1:173
	ds_read2_b32 v[36:37], v19 offset0:198 offset1:206
	ds_read2_b32 v[38:39], v19 offset0:231 offset1:239
	s_waitcnt lgkmcnt(7)
	s_waitcnt lgkmcnt(6)
	v_cvt_pk_bf16_f32 v20, v26, v24
	s_waitcnt lgkmcnt(5)
	s_waitcnt lgkmcnt(4)
	v_cvt_pk_bf16_f32 v21, v28, v30
	s_waitcnt lgkmcnt(3)
	s_waitcnt lgkmcnt(2)
	v_cvt_pk_bf16_f32 v22, v32, v34
	s_waitcnt lgkmcnt(1)
	s_nop 0
	s_nop 0
	s_waitcnt lgkmcnt(0)
	s_nop 0
	s_nop 0
	s_nop 0
	v_cvt_pk_bf16_f32 v23, v36, v38
	global_store_dwordx4 v[40:41], v[20:23], off
	s_nop 0
	s_nop 0
	s_nop 0
	s_nop 0
	s_nop 0
	s_nop 0
	s_nop 0
	v_cvt_pk_bf16_f32 v20, v27, v25
	s_nop 0
	s_nop 0
	s_nop 0
	s_nop 0
	s_nop 0
	v_cvt_pk_bf16_f32 v21, v29, v31
	s_nop 0
	s_nop 0
	s_nop 0
	s_nop 0
	s_nop 0
	v_cvt_pk_bf16_f32 v22, v33, v35
	v_cvt_pk_bf16_f32 v23, v37, v39
	v_add_u32_e32 v24, s17, v16
	v_ashrrev_i32_e32 v25, 31, v24
	v_lshlrev_b64 v[24:25], 12, v[24:25]
	v_lshl_add_u64 v[24:25], v[14:15], 0, v[24:25]
	global_store_dwordx4 v[24:25], v[20:23], off
	ds_read2_b32 v[24:25], v19 offset0:49 offset1:57
	ds_read2_b32 v[26:27], v19 offset0:16 offset1:24
	ds_read2_b32 v[28:29], v19 offset0:82 offset1:90
	ds_read2_b32 v[30:31], v19 offset0:115 offset1:123
	ds_read2_b32 v[32:33], v19 offset0:148 offset1:156
	ds_read2_b32 v[34:35], v19 offset0:181 offset1:189
	ds_read2_b32 v[36:37], v19 offset0:214 offset1:222
	ds_read2_b32 v[38:39], v19 offset0:247 offset1:255
	s_waitcnt lgkmcnt(7)
	s_waitcnt lgkmcnt(6)
	v_cvt_pk_bf16_f32 v20, v26, v24
	s_waitcnt lgkmcnt(5)
	s_waitcnt lgkmcnt(4)
	v_cvt_pk_bf16_f32 v21, v28, v30
	s_waitcnt lgkmcnt(3)
	s_waitcnt lgkmcnt(2)
	v_cvt_pk_bf16_f32 v22, v32, v34
	s_waitcnt lgkmcnt(1)
	v_add_u32_e32 v40, s17, v17
	s_waitcnt lgkmcnt(0)
	v_ashrrev_i32_e32 v41, 31, v40
	v_lshlrev_b64 v[40:41], 12, v[40:41]
	v_cvt_pk_bf16_f32 v23, v36, v38
	v_lshl_add_u64 v[40:41], v[14:15], 0, v[40:41]
	global_store_dwordx4 v[40:41], v[20:23], off
	s_nop 0
	s_nop 0
	s_nop 0
	s_nop 0
	s_nop 0
	s_nop 0
	s_nop 0
	v_cvt_pk_bf16_f32 v20, v27, v25
	s_nop 0
	s_nop 0
	s_nop 0
	s_nop 0
	s_nop 0
	v_cvt_pk_bf16_f32 v21, v29, v31
	s_nop 0
	s_nop 0
	s_nop 0
	s_nop 0
	s_nop 0
	v_cvt_pk_bf16_f32 v22, v33, v35
	v_cvt_pk_bf16_f32 v23, v37, v39
	v_add_u32_e32 v24, s17, v18
	v_ashrrev_i32_e32 v25, 31, v24
	v_lshlrev_b64 v[24:25], 12, v[24:25]
	v_lshl_add_u64 v[14:15], v[14:15], 0, v[24:25]
	global_store_dwordx4 v[14:15], v[20:23], off
	s_waitcnt lgkmcnt(0)

.LBB0_1218:
	v_pk_add_f32 v[2:3], v[58:59], v[68:69]
	v_pk_add_f32 v[4:5], v[60:61], v[66:67]
	v_pk_add_f32 v[6:7], v[64:65], v[56:57]
	v_pk_add_f32 v[2:3], v[2:3], v[4:5]
	v_add_f32_e32 v14, v20, v21
	v_add_f32_e32 v18, v22, v23
	v_and_b32_e32 v26, 64, v249
	v_pk_add_f32 v[4:5], v[6:7], v[6:7] op_sel:[0,1] op_sel_hi:[1,0]
	v_add_f32_e32 v2, 0, v2
	v_add_f32_e32 v28, v36, v37
	v_add_f32_e32 v32, v40, v41
	v_pk_add_f32 v[34:35], v[14:15], v[18:19]
	v_add_u32_e32 v14, 64, v26
	v_mov_b32_e32 v5, v31
	v_add_f32_e32 v26, v2, v3
	v_pk_add_f32 v[6:7], v[28:29], v[32:33]
	v_pk_add_f32 v[2:3], v[26:27], v[4:5]
	v_pk_add_f32 v[8:9], v[62:63], v[24:25]
	v_pk_add_f32 v[2:3], v[2:3], v[6:7]
	v_pk_add_f32 v[8:9], v[8:9], v[8:9] op_sel:[0,1] op_sel_hi:[1,0]
	v_pk_add_f32 v[2:3], v[2:3], v[2:3] op_sel:[0,1] op_sel_hi:[1,0]
	v_xor_b32_e32 v30, 1, v249
	v_mov_b32_e32 v9, v17
	v_mov_b32_e32 v3, v16
	v_cmp_lt_i32_e32 vcc, v30, v14
	v_pk_add_f32 v[2:3], v[2:3], v[8:9]
	v_xor_b32_e32 v38, 2, v249
	v_cndmask_b32_e32 v18, v249, v30, vcc
	v_pk_add_f32 v[2:3], v[2:3], v[34:35]
	v_lshlrev_b32_e32 v82, 2, v18
	v_add_f32_e32 v26, v2, v3
	ds_bpermute_b32 v84, v82, v26
	v_cmp_lt_i32_e32 vcc, v38, v14
	v_xor_b32_e32 v39, 4, v249
	v_xor_b32_e32 v42, 8, v249
	v_cndmask_b32_e32 v28, v249, v38, vcc
	v_lshlrev_b32_e32 v32, 2, v28
	s_waitcnt lgkmcnt(0)
	v_add_f32_e32 v26, v26, v84
	ds_bpermute_b32 v84, v32, v26
	v_cmp_lt_i32_e32 vcc, v39, v14
	v_xor_b32_e32 v43, 16, v249
	s_add_i32 s28, s8, s60
	v_cndmask_b32_e32 v30, v249, v39, vcc
	v_lshlrev_b32_e32 v30, 2, v30
	s_waitcnt lgkmcnt(0)
	v_add_f32_e32 v26, v26, v84
	ds_bpermute_b32 v84, v30, v26
	v_cmp_lt_i32_e32 vcc, v42, v14
	s_cmpk_lt_i32 s28, 0x2000
	v_xor_b32_e32 v44, 32, v249
	v_cndmask_b32_e32 v38, v249, v42, vcc
	v_lshlrev_b32_e32 v28, 2, v38
	s_waitcnt lgkmcnt(0)
	v_add_f32_e32 v26, v26, v84
	ds_bpermute_b32 v84, v28, v26
	v_cmp_lt_i32_e32 vcc, v43, v14
	s_cselect_b32 s8, s28, s8
	s_ashr_i32 s9, s8, 31
	v_cndmask_b32_e32 v39, v249, v43, vcc
	v_lshlrev_b32_e32 v18, 2, v39
	s_waitcnt lgkmcnt(0)
	v_add_f32_e32 v26, v26, v84
	ds_bpermute_b32 v84, v18, v26
	v_cmp_lt_i32_e32 vcc, v44, v14
	s_lshl_b64 s[8:9], s[8:9], 12
	s_add_u32 s30, s14, s20
	v_cndmask_b32_e32 v14, v249, v44, vcc
	v_lshlrev_b32_e32 v14, 2, v14
	s_waitcnt lgkmcnt(0)
	v_add_f32_e32 v26, v26, v84
	v_mov_b32_e32 v70, v1
	v_lshl_add_u64 v[4:5], v[12:13], 0, s[8:9]
	s_addc_u32 s31, s15, s21
	ds_bpermute_b32 v84, v14, v26
	global_load_dwordx2 v[54:55], v[4:5], off
	global_load_dwordx2 v[52:53], v[4:5], off offset:512
	global_load_dwordx2 v[50:51], v[4:5], off offset:1024
	global_load_dwordx2 v[48:49], v[4:5], off offset:1536
	global_load_dwordx2 v[46:47], v[4:5], off offset:2048
	global_load_dwordx2 v[44:45], v[4:5], off offset:2560
	global_load_dwordx2 v[42:43], v[4:5], off offset:3072
	global_load_dwordx2 v[38:39], v[4:5], off offset:3584
	s_add_u32 s8, s14, s18
	v_lshlrev_b32_e32 v4, 2, v70
	s_addc_u32 s9, s15, s19
	v_ashrrev_i32_e32 v5, 31, v4
	v_lshlrev_b64 v[6:7], 2, v[4:5]
	v_lshl_add_u64 v[4:5], v[4:5], 1, s[8:9]
	v_lshl_add_u64 v[76:77], s[16:17], 0, v[6:7]
	v_add_co_u32_e32 v34, vcc, s61, v4
	v_lshl_add_u64 v[74:75], s[10:11], 0, v[6:7]
	v_lshl_add_u64 v[78:79], s[30:31], 0, v[6:7]
	v_lshl_add_u64 v[72:73], s[24:25], 0, v[6:7]
	v_lshl_add_u64 v[70:71], s[22:23], 0, v[6:7]
	v_addc_co_u32_e32 v35, vcc, 0, v5, vcc
	global_load_dwordx4 v[2:5], v[76:77], off
	global_load_dwordx4 v[6:9], v[74:75], off
	s_waitcnt lgkmcnt(0)
	v_add_f32_e32 v26, v26, v84
	v_fmac_f32_e32 v66, 0xba000000, v26
	v_fmac_f32_e32 v68, 0xba000000, v26
	v_fmac_f32_e32 v67, 0xba000000, v26
	v_fmac_f32_e32 v69, 0xba000000, v26
	v_fmac_f32_e32 v64, 0xba000000, v26
	v_fmac_f32_e32 v57, 0xba000000, v26
	v_fmac_f32_e32 v65, 0xba000000, v26
	v_fmac_f32_e32 v60, 0xba000000, v26
	v_fmac_f32_e32 v58, 0xba000000, v26
	v_fmac_f32_e32 v61, 0xba000000, v26
	v_fmac_f32_e32 v59, 0xba000000, v26
	v_fmac_f32_e32 v56, 0xba000000, v26
	v_mov_b32_e32 v85, v69
	v_mov_b32_e32 v87, v68
	v_pk_mul_f32 v[68:69], v[68:69], v[68:69]
	v_mov_b32_e32 v89, v67
	v_mov_b32_e32 v91, v66
	v_pk_mul_f32 v[66:67], v[66:67], v[66:67]
	v_mov_b32_e32 v92, v65
	v_mov_b32_e32 v93, v57
	v_mov_b32_e32 v57, v64
	v_mov_b32_e32 v84, v59
	v_mov_b32_e32 v86, v58
	v_mov_b32_e32 v88, v61
	v_mov_b32_e32 v90, v60
	v_pk_fma_f32 v[58:59], v[58:59], v[58:59], v[68:69]
	v_pk_fma_f32 v[60:61], v[60:61], v[60:61], v[66:67]
	v_pk_mul_f32 v[66:67], v[92:93], v[92:93]
	v_pk_mul_f32 v[68:69], v[56:57], v[56:57]
	v_fmac_f32_e32 v36, 0xba000000, v26
	v_fmac_f32_e32 v40, 0xba000000, v26
	v_pk_add_f32 v[58:59], v[58:59], v[60:61]
	v_pk_mov_b32 v[60:61], v[68:69], v[66:67] op_sel:[1,0]
	v_mov_b32_e32 v69, v67
	v_fmac_f32_e32 v37, 0xba000000, v26
	v_fmac_f32_e32 v41, 0xba000000, v26
	v_fmac_f32_e32 v33, 0xba000000, v26
	v_fmac_f32_e32 v29, 0xba000000, v26
	v_fmac_f32_e32 v31, 0xba000000, v26
	v_fmac_f32_e32 v27, 0xba000000, v26
	v_fmac_f32_e32 v62, 0xba000000, v26
	v_fmac_f32_e32 v24, 0xba000000, v26
	v_fmac_f32_e32 v25, 0xba000000, v26
	v_fmac_f32_e32 v63, 0xba000000, v26
	v_fmac_f32_e32 v21, 0xba000000, v26
	v_fmac_f32_e32 v20, 0xba000000, v26
	v_fmac_f32_e32 v23, 0xba000000, v26
	v_fmac_f32_e32 v22, 0xba000000, v26
	v_fmac_f32_e32 v19, 0xba000000, v26
	v_fmac_f32_e32 v15, 0xba000000, v26
	v_fmac_f32_e32 v17, 0xba000000, v26
	v_fmac_f32_e32 v16, 0xba000000, v26
	v_mul_f32_e32 v26, v36, v36
	v_mul_f32_e32 v94, v40, v40
	v_pk_add_f32 v[60:61], v[60:61], v[68:69]
	v_mov_b32_e32 v64, v63
	v_mov_b32_e32 v65, v25
	v_mov_b32_e32 v25, v62
	v_pk_fma_f32 v[98:99], v[36:37], v[36:37], v[26:27] op_sel_hi:[1,1,0]
	v_pk_fma_f32 v[94:95], v[40:41], v[40:41], v[94:95] op_sel_hi:[1,1,0]
	v_pk_add_f32 v[58:59], v[58:59], v[58:59] op_sel_hi:[0,1]
	v_pk_add_f32 v[60:61], v[60:61], v[60:61] op_sel_hi:[0,1]
	v_pk_mul_f32 v[100:101], v[64:65], v[64:65]
	v_pk_mul_f32 v[102:103], v[24:25], v[24:25]
	v_mul_f32_e32 v98, v27, v27
	v_mul_f32_e32 v94, v31, v31
	v_mul_f32_e32 v58, v33, v33
	v_mul_f32_e32 v60, v29, v29
	v_pk_mov_b32 v[66:67], v[102:103], v[100:101] op_sel:[1,0]
	v_mov_b32_e32 v103, v101
	v_pk_add_f32 v[68:69], v[98:99], v[94:95]
	v_pk_add_f32 v[58:59], v[60:61], v[58:59]
	v_mul_f32_e32 v62, v20, v20
	v_mul_f32_e32 v96, v22, v22
	v_pk_add_f32 v[66:67], v[66:67], v[102:103]
	v_pk_add_f32 v[58:59], v[68:69], v[58:59]
	v_pk_fma_f32 v[62:63], v[20:21], v[20:21], v[62:63] op_sel_hi:[1,1,0]
	v_pk_fma_f32 v[96:97], v[22:23], v[22:23], v[96:97] op_sel_hi:[1,1,0]
	v_pk_add_f32 v[66:67], v[66:67], v[66:67] op_sel_hi:[0,1]
	v_pk_add_f32 v[58:59], v[58:59], v[58:59] op_sel_hi:[0,1]
	v_mul_f32_e32 v62, v16, v16
	v_mul_f32_e32 v96, v17, v17
	v_mul_f32_e32 v66, v15, v15
	v_mul_f32_e32 v58, v19, v19
	v_pk_add_f32 v[62:63], v[62:63], v[96:97]
	v_pk_add_f32 v[58:59], v[66:67], v[58:59]
	s_mov_b32 s8, 0x21b1e000
	v_pk_add_f32 v[58:59], v[62:63], v[58:59]
	v_add_co_u32_e32 v80, vcc, s8, v78
	v_add_f32_e32 v26, v58, v59
	ds_bpermute_b32 v58, v82, v26
	v_addc_co_u32_e32 v81, vcc, 0, v79, vcc
	v_add_co_u32_e32 v78, vcc, s70, v78
	s_waitcnt lgkmcnt(0)
	v_add_f32_e32 v26, v26, v58
	ds_bpermute_b32 v32, v32, v26
	v_addc_co_u32_e32 v79, vcc, 0, v79, vcc
	s_add_u32 s20, s20, s36
	s_addc_u32 s21, s21, s37
	s_waitcnt lgkmcnt(0)
	v_add_f32_e32 v26, v26, v32
	ds_bpermute_b32 v30, v30, v26
	s_add_u32 s18, s18, s38
	s_addc_u32 s19, s19, s39
	s_cmpk_gt_i32 s28, 0x1fff
	s_waitcnt vmcnt(9)
	v_and_b32_e32 v68, 0xffff0000, v54
	s_waitcnt lgkmcnt(0)
	v_add_f32_e32 v26, v26, v30
	ds_bpermute_b32 v28, v28, v26
	s_waitcnt vmcnt(8)
	v_and_b32_e32 v69, 0xffff0000, v52
	s_waitcnt lgkmcnt(0)
	v_add_f32_e32 v26, v26, v28
	ds_bpermute_b32 v18, v18, v26
	s_waitcnt lgkmcnt(0)
	v_add_f32_e32 v18, v26, v18
	ds_bpermute_b32 v14, v14, v18
	s_waitcnt lgkmcnt(0)
	v_add_f32_e32 v14, v18, v14
	v_fmamk_f32 v14, v14, 0x3a000000, v250
	v_mul_f32_e32 v18, 0x4f800000, v14
	v_cmp_gt_f32_e32 vcc, s96, v14
	s_nop 1
	v_cndmask_b32_e32 v14, v14, v18, vcc
	v_sqrt_f32_e32 v18, v14
	s_nop 0
	v_add_u32_e32 v26, -1, v18
	v_add_u32_e32 v28, 1, v18
	v_fma_f32 v30, -v26, v18, v14
	v_fma_f32 v32, -v28, v18, v14
	v_cmp_ge_f32_e64 s[8:9], 0, v30
	s_nop 1
	v_cndmask_b32_e64 v18, v18, v26, s[8:9]
	v_cmp_lt_f32_e64 s[8:9], 0, v32
	s_nop 1
	v_cndmask_b32_e64 v18, v18, v28, s[8:9]
	v_mul_f32_e32 v26, 0x37800000, v18
	v_cndmask_b32_e32 v18, v18, v26, vcc
	v_cmp_class_f32_e32 vcc, v14, v251
	s_nop 1
	v_cndmask_b32_e32 v14, v18, v14, vcc
	v_div_scale_f32 v18, s[8:9], v14, v14, 1.0
	v_rcp_f32_e32 v28, v18
	v_div_scale_f32 v26, vcc, 1.0, v14, 1.0
	s_mov_b32 s8, s28
	v_fma_f32 v30, -v18, v28, 1.0
	v_fmac_f32_e32 v28, v30, v28
	v_mul_f32_e32 v30, v26, v28
	v_fma_f32 v32, -v18, v30, v26
	v_fmac_f32_e32 v30, v32, v28
	v_fma_f32 v18, -v18, v30, v26
	v_div_fmas_f32 v18, v18, v28, v30
	v_div_fixup_f32 v14, v18, v14, 1.0
	v_pk_mul_f32 v[58:59], v[86:87], v[14:15] op_sel_hi:[1,0]
	v_pk_mul_f32 v[60:61], v[90:91], v[14:15] op_sel_hi:[1,0]
	s_waitcnt vmcnt(0)
	v_pk_fma_f32 v[2:3], v[2:3], v[58:59], v[6:7]
	v_pk_fma_f32 v[4:5], v[4:5], v[60:61], v[8:9]
	global_store_dwordx4 v[78:79], v[2:5], off offset:-4096
	global_load_dwordx4 v[6:9], v[72:73], off
	global_load_dwordx4 v[58:61], v[70:71], off
	v_pk_mul_f32 v[62:63], v[88:89], v[14:15] op_sel_hi:[1,0]
	v_pk_mul_f32 v[66:67], v[84:85], v[14:15] op_sel_hi:[1,0]
	v_pk_mul_f32 v[56:57], v[56:57], v[14:15] op_sel_hi:[1,0]
	v_pk_mul_f32 v[40:41], v[40:41], v[14:15] op_sel_hi:[1,0]
	v_pk_mul_f32 v[36:37], v[36:37], v[14:15] op_sel_hi:[1,0]
	v_mov_b32_e32 v32, v29
	v_mov_b32_e32 v30, v27
	v_pk_mul_f32 v[26:27], v[32:33], v[14:15] op_sel_hi:[1,0]
	v_pk_mul_f32 v[28:29], v[30:31], v[14:15] op_sel_hi:[1,0]
	v_pk_mul_f32 v[24:25], v[24:25], v[14:15] op_sel_hi:[1,0]
	v_pk_mul_f32 v[22:23], v[22:23], v[14:15] op_sel_hi:[1,0]
	v_pk_mul_f32 v[20:21], v[20:21], v[14:15] op_sel_hi:[1,0]
	v_mov_b32_e32 v18, v15
	v_pk_mul_f32 v[18:19], v[18:19], v[14:15] op_sel_hi:[1,0]
	v_lshlrev_b32_e32 v30, 16, v49
	v_and_b32_e32 v32, 0xffff0000, v46
	v_and_b32_e32 v33, 0xffff0000, v47
	v_mov_b32_e32 v31, v32
	s_waitcnt vmcnt(1)
	v_pk_add_f32 v[8:9], v[8:9], 1.0 op_sel_hi:[1,0]
	v_pk_add_f32 v[6:7], v[6:7], 1.0 op_sel_hi:[1,0]
	s_waitcnt vmcnt(0)
	v_pk_fma_f32 v[4:5], v[8:9], v[4:5], v[60:61]
	v_pk_fma_f32 v[2:3], v[6:7], v[2:3], v[58:59]
	v_cvt_pk_bf16_f32 v2, v2, v3
	v_cvt_pk_bf16_f32 v3, v4, v5
	global_store_dwordx2 v[34:35], v[2:3], off
	global_load_dwordx4 v[2:5], v[76:77], off offset:1024
	s_nop 0
	global_load_dwordx4 v[6:9], v[74:75], off offset:1024
	s_waitcnt vmcnt(0)
	v_pk_fma_f32 v[2:3], v[2:3], v[66:67], v[6:7]
	v_pk_fma_f32 v[4:5], v[4:5], v[62:63], v[8:9]
	global_store_dwordx4 v[80:81], v[2:5], off offset:1024
	global_load_dwordx4 v[6:9], v[72:73], off offset:1024
	global_load_dwordx4 v[58:61], v[70:71], off offset:1024
	v_and_b32_e32 v62, 0xffff0000, v44
	v_lshlrev_b32_e32 v63, 16, v45
	v_and_b32_e32 v66, 0xffff0000, v55
	v_and_b32_e32 v67, 0xffff0000, v53
	s_waitcnt vmcnt(1)
	v_pk_add_f32 v[8:9], v[8:9], 1.0 op_sel_hi:[1,0]
	v_pk_add_f32 v[6:7], v[6:7], 1.0 op_sel_hi:[1,0]
	s_waitcnt vmcnt(0)
	v_pk_fma_f32 v[4:5], v[8:9], v[4:5], v[60:61]
	v_pk_fma_f32 v[2:3], v[6:7], v[2:3], v[58:59]
	v_cvt_pk_bf16_f32 v2, v2, v3
	v_cvt_pk_bf16_f32 v3, v4, v5
	global_store_dwordx2 v[34:35], v[2:3], off offset:512
	global_load_dwordx4 v[2:5], v[76:77], off offset:2048
	s_nop 0
	global_load_dwordx4 v[6:9], v[74:75], off offset:2048
	v_pk_mul_f32 v[58:59], v[92:93], v[14:15] op_sel_hi:[1,0]
	v_lshlrev_b32_e32 v60, 16, v55
	v_lshlrev_b32_e32 v61, 16, v53
	s_waitcnt vmcnt(0)
	v_pk_fma_f32 v[2:3], v[2:3], v[56:57], v[6:7]
	v_pk_fma_f32 v[4:5], v[4:5], v[58:59], v[8:9]
	global_store_dwordx4 v[80:81], v[2:5], off offset:2048
	global_load_dwordx4 v[6:9], v[72:73], off offset:2048
	global_load_dwordx4 v[56:59], v[70:71], off offset:2048
	s_waitcnt vmcnt(1)
	v_pk_add_f32 v[8:9], v[8:9], 1.0 op_sel_hi:[1,0]
	v_pk_add_f32 v[6:7], v[6:7], 1.0 op_sel_hi:[1,0]
	s_waitcnt vmcnt(0)
	v_pk_fma_f32 v[4:5], v[4:5], v[8:9], v[58:59]
	v_pk_fma_f32 v[2:3], v[2:3], v[6:7], v[56:57]
	v_cvt_pk_bf16_f32 v2, v2, v3
	v_cvt_pk_bf16_f32 v3, v4, v5
	global_store_dwordx2 v[34:35], v[2:3], off offset:1024
	global_load_dwordx4 v[2:5], v[76:77], off offset:3072
	s_nop 0
	global_load_dwordx4 v[6:9], v[74:75], off offset:3072
	s_waitcnt vmcnt(0)
	v_pk_fma_f32 v[2:3], v[36:37], v[2:3], v[6:7]
	v_pk_fma_f32 v[4:5], v[40:41], v[4:5], v[8:9]
	global_store_dwordx4 v[80:81], v[2:5], off offset:3072
	global_load_dwordx4 v[6:9], v[72:73], off offset:3072
	global_load_dwordx4 v[56:59], v[70:71], off offset:3072
	v_add_co_u32_e32 v36, vcc, s82, v76
	s_waitcnt vmcnt(1)
	v_pk_add_f32 v[8:9], v[8:9], 1.0 op_sel_hi:[1,0]
	v_pk_add_f32 v[6:7], v[6:7], 1.0 op_sel_hi:[1,0]
	s_waitcnt vmcnt(0)
	v_pk_fma_f32 v[4:5], v[4:5], v[8:9], v[58:59]
	v_pk_fma_f32 v[2:3], v[2:3], v[6:7], v[56:57]
	s_nop 0
	s_nop 0
	s_nop 0
	s_nop 0
	s_nop 0
	s_nop 0
	s_nop 0
	s_nop 0
	s_nop 0
	s_nop 0
	v_addc_co_u32_e32 v37, vcc, 0, v77, vcc
	v_cvt_pk_bf16_f32 v2, v2, v3
	v_cvt_pk_bf16_f32 v3, v4, v5
	v_add_co_u32_e32 v40, vcc, s82, v74
	global_store_dwordx2 v[34:35], v[2:3], off offset:1536
	s_nop 0
	v_addc_co_u32_e32 v41, vcc, 0, v75, vcc
	global_load_dwordx4 v[2:5], v[36:37], off
	global_load_dwordx4 v[6:9], v[40:41], off
	v_add_co_u32_e32 v56, vcc, s82, v72
	s_waitcnt vmcnt(0)
	v_pk_fma_f32 v[2:3], v[28:29], v[2:3], v[6:7]
	v_addc_co_u32_e32 v57, vcc, 0, v73, vcc
	v_pk_fma_f32 v[4:5], v[26:27], v[4:5], v[8:9]
	v_add_co_u32_e32 v58, vcc, s82, v70
	global_store_dwordx4 v[78:79], v[2:5], off
	s_nop 0
	v_addc_co_u32_e32 v59, vcc, 0, v71, vcc
	global_load_dwordx4 v[6:9], v[56:57], off
	global_load_dwordx4 v[26:29], v[58:59], off
	s_waitcnt vmcnt(1)
	v_pk_add_f32 v[8:9], v[8:9], 1.0 op_sel_hi:[1,0]
	v_pk_add_f32 v[6:7], v[6:7], 1.0 op_sel_hi:[1,0]
	s_waitcnt vmcnt(0)
	v_pk_fma_f32 v[4:5], v[4:5], v[8:9], v[28:29]
	v_pk_fma_f32 v[2:3], v[2:3], v[6:7], v[26:27]
	v_cvt_pk_bf16_f32 v2, v2, v3
	v_cvt_pk_bf16_f32 v3, v4, v5
	global_store_dwordx2 v[34:35], v[2:3], off offset:2048
	global_load_dwordx4 v[2:5], v[36:37], off offset:1024
	s_nop 0
	global_load_dwordx4 v[6:9], v[40:41], off offset:1024
	v_pk_mul_f32 v[26:27], v[64:65], v[14:15] op_sel_hi:[1,0]
	v_pk_mul_f32 v[14:15], v[16:17], v[14:15] op_sel_hi:[1,0]
	v_and_b32_e32 v28, 0xffff0000, v48
	v_lshlrev_b32_e32 v29, 16, v47
	v_lshlrev_b32_e32 v47, 16, v43
	v_and_b32_e32 v43, 0xffff0000, v43
	v_and_b32_e32 v64, 0xffff0000, v50
	v_lshlrev_b32_e32 v65, 16, v51
	s_waitcnt vmcnt(0)
	v_pk_fma_f32 v[2:3], v[24:25], v[2:3], v[6:7]
	v_pk_fma_f32 v[4:5], v[26:27], v[4:5], v[8:9]
	global_store_dwordx4 v[78:79], v[2:5], off offset:1024
	global_load_dwordx4 v[6:9], v[56:57], off offset:1024
	global_load_dwordx4 v[24:27], v[58:59], off offset:1024
	s_waitcnt vmcnt(1)
	v_pk_add_f32 v[8:9], v[8:9], 1.0 op_sel_hi:[1,0]
	v_pk_add_f32 v[6:7], v[6:7], 1.0 op_sel_hi:[1,0]
	s_waitcnt vmcnt(0)
	v_pk_fma_f32 v[4:5], v[4:5], v[8:9], v[26:27]
	v_pk_fma_f32 v[2:3], v[2:3], v[6:7], v[24:25]
	v_cvt_pk_bf16_f32 v2, v2, v3
	v_cvt_pk_bf16_f32 v3, v4, v5
	global_store_dwordx2 v[34:35], v[2:3], off offset:2560
	global_load_dwordx4 v[2:5], v[36:37], off offset:2048
	s_nop 0
	global_load_dwordx4 v[6:9], v[40:41], off offset:2048
	v_lshlrev_b32_e32 v26, 16, v48
	v_lshlrev_b32_e32 v27, 16, v46
	v_lshlrev_b32_e32 v46, 16, v44
	v_and_b32_e32 v44, 0xffff0000, v45
	v_lshlrev_b32_e32 v45, 16, v42
	v_and_b32_e32 v42, 0xffff0000, v42
	v_lshlrev_b32_e32 v48, 16, v38
	v_and_b32_e32 v38, 0xffff0000, v38
	v_mov_b32_e32 v24, v46
	v_mov_b32_e32 v25, v44
	v_mov_b32_e32 v16, v48
	v_mov_b32_e32 v17, v38
	s_waitcnt vmcnt(0)
	v_pk_fma_f32 v[2:3], v[20:21], v[2:3], v[6:7]
	v_pk_fma_f32 v[4:5], v[22:23], v[4:5], v[8:9]
	global_store_dwordx4 v[78:79], v[2:5], off offset:2048
	global_load_dwordx4 v[6:9], v[56:57], off offset:2048
	global_load_dwordx4 v[20:23], v[58:59], off offset:2048
	s_waitcnt vmcnt(1)
	v_pk_add_f32 v[8:9], v[8:9], 1.0 op_sel_hi:[1,0]
	v_pk_add_f32 v[6:7], v[6:7], 1.0 op_sel_hi:[1,0]
	s_waitcnt vmcnt(0)
	v_pk_fma_f32 v[4:5], v[4:5], v[8:9], v[22:23]
	v_pk_fma_f32 v[2:3], v[2:3], v[6:7], v[20:21]
	v_cvt_pk_bf16_f32 v2, v2, v3
	v_cvt_pk_bf16_f32 v3, v4, v5
	global_store_dwordx2 v[34:35], v[2:3], off offset:3072
	global_load_dwordx4 v[2:5], v[36:37], off offset:3072
	s_nop 0
	global_load_dwordx4 v[6:9], v[40:41], off offset:3072
	v_lshlrev_b32_e32 v40, 16, v39
	v_and_b32_e32 v39, 0xffff0000, v39
	v_and_b32_e32 v41, 0xffff0000, v49
	v_mov_b32_e32 v36, v26
	v_mov_b32_e32 v37, v28
	v_mov_b32_e32 v20, v45
	v_mov_b32_e32 v21, v42
	v_mov_b32_e32 v22, v47
	v_mov_b32_e32 v23, v43
	s_waitcnt vmcnt(0)
	v_pk_fma_f32 v[2:3], v[14:15], v[2:3], v[6:7]
	v_pk_fma_f32 v[4:5], v[18:19], v[4:5], v[8:9]
	global_store_dwordx4 v[78:79], v[2:5], off offset:3072
	global_load_dwordx4 v[6:9], v[56:57], off offset:3072
	global_load_dwordx4 v[70:73], v[58:59], off offset:3072
	v_lshlrev_b32_e32 v58, 16, v54
	v_lshlrev_b32_e32 v59, 16, v52
	v_lshlrev_b32_e32 v56, 16, v50
	v_and_b32_e32 v57, 0xffff0000, v51
	v_mov_b32_e32 v15, v40
	v_mov_b32_e32 v40, v30
	v_mov_b32_e32 v19, v39
	s_waitcnt vmcnt(1)
	v_pk_add_f32 v[8:9], v[8:9], 1.0 op_sel_hi:[1,0]
	v_pk_add_f32 v[6:7], v[6:7], 1.0 op_sel_hi:[1,0]
	s_waitcnt vmcnt(0)
	v_pk_fma_f32 v[4:5], v[4:5], v[8:9], v[72:73]
	v_pk_fma_f32 v[2:3], v[2:3], v[6:7], v[70:71]
	v_bfe_u32 v8, v4, 16, 1
	v_bfe_u32 v6, v2, 16, 1
	v_bfe_u32 v7, v3, 16, 1
	v_bfe_u32 v9, v5, 16, 1
	v_add3_u32 v2, v2, v6, s73
	v_add3_u32 v4, v4, v8, s73
	v_add3_u32 v3, v3, v7, s73
	v_add3_u32 v5, v5, v9, s73
	v_lshrrev_b32_e32 v2, 16, v2
	v_lshrrev_b32_e32 v4, 16, v4
	v_and_or_b32 v2, v3, s33, v2
	v_and_or_b32 v3, v5, s33, v4
	global_store_dwordx2 v[34:35], v[2:3], off offset:3584
	s_cbranch_scc0 .LBB0_1218

.LBB0_1222:
	s_abs_i32 s10, s8
	v_readlane_b32 s11, v253, 56
	s_mul_hi_u32 s11, s10, s11
	v_readlane_b32 s18, v253, 57
	s_mul_i32 s16, s11, s18
	s_ashr_i32 s9, s8, 31
	s_sub_i32 s10, s10, s16
	s_xor_b32 s9, s9, s43
	s_add_i32 s16, s11, 1
	s_sub_i32 s17, s10, s18
	s_cmp_ge_u32 s10, s18
	s_cselect_b32 s11, s16, s11
	s_cselect_b32 s10, s17, s10
	s_add_i32 s16, s11, 1
	s_cmp_ge_u32 s10, s18
	s_cselect_b32 s10, s16, s11
	s_xor_b32 s10, s10, s9
	s_sub_i32 s9, s10, s9
	s_add_i32 s9, s8, s9
	s_and_b32 s9, s9, 7
	v_readlane_b32 s10, v253, 15
	s_cmp_lg_u32 s10, s9
	s_cbranch_scc1 .LBB0_1221
	s_lshr_b32 s9, s8, 3
	s_add_i32 s16, s8, 0x2000
	s_add_i32 s9, s9, 1
	s_cmp_gt_i32 s8, -1
	s_cselect_b32 s9, s9, 0
	s_add_i32 s9, s9, s97
	s_mul_hi_u32 s11, s9, 0xc000
	s_mul_i32 s9, s9, 0xc000
	s_add_u32 s10, s26, s9
	v_lshl_add_u64 v[2:3], s[14:15], 0, v[12:13]
	s_mov_b32 s9, 0x3af5e000
	v_add_co_u32_e32 v8, vcc, s9, v2
	s_mov_b32 s9, 0x3af5f000
	s_nop 0
	v_addc_co_u32_e32 v9, vcc, 0, v3, vcc
	v_add_co_u32_e32 v62, vcc, s9, v2
	s_mov_b32 s9, 0x3b15e000
	s_nop 0
	v_addc_co_u32_e32 v63, vcc, 0, v3, vcc
	global_load_dwordx4 v[4:7], v[62:63], off offset:-4096
	global_load_dwordx4 v[38:41], v[8:9], off offset:1024
	global_load_dwordx4 v[42:45], v[8:9], off offset:2048
	global_load_dwordx4 v[46:49], v[8:9], off offset:3072
	global_load_dwordx4 v[50:53], v[62:63], off
	global_load_dwordx4 v[54:57], v[62:63], off offset:1024
	global_load_dwordx4 v[58:61], v[62:63], off offset:2048
	s_nop 0
	global_load_dwordx4 v[62:65], v[62:63], off offset:3072
	v_add_co_u32_e32 v8, vcc, s9, v2
	s_mov_b32 s9, 0x3b15f000
	s_nop 0
	v_addc_co_u32_e32 v9, vcc, 0, v3, vcc
	v_add_co_u32_e32 v96, vcc, s9, v2
	s_mov_b32 s9, 0x3b35e000
	s_nop 0
	v_addc_co_u32_e32 v97, vcc, 0, v3, vcc
	global_load_dwordx4 v[66:69], v[96:97], off offset:-4096
	global_load_dwordx4 v[70:73], v[8:9], off offset:1024
	global_load_dwordx4 v[74:77], v[8:9], off offset:2048
	global_load_dwordx4 v[78:81], v[8:9], off offset:3072
	global_load_dwordx4 v[84:87], v[96:97], off
	global_load_dwordx4 v[88:91], v[96:97], off offset:1024
	global_load_dwordx4 v[92:95], v[96:97], off offset:2048
	s_nop 0
	global_load_dwordx4 v[96:99], v[96:97], off offset:3072
	v_add_co_u32_e32 v8, vcc, s9, v2
	s_mov_b32 s9, 0x3b35f000
	s_nop 0
	v_addc_co_u32_e32 v9, vcc, 0, v3, vcc
	v_add_co_u32_e32 v128, vcc, s9, v2
	s_mov_b32 s9, 0x3b55e000
	s_nop 0
	v_addc_co_u32_e32 v129, vcc, 0, v3, vcc
	global_load_dwordx4 v[100:103], v[128:129], off offset:-4096
	global_load_dwordx4 v[104:107], v[8:9], off offset:1024
	global_load_dwordx4 v[108:111], v[8:9], off offset:2048
	global_load_dwordx4 v[112:115], v[8:9], off offset:3072
	global_load_dwordx4 v[116:119], v[128:129], off
	global_load_dwordx4 v[120:123], v[128:129], off offset:1024
	global_load_dwordx4 v[124:127], v[128:129], off offset:2048
	s_nop 0
	global_load_dwordx4 v[128:131], v[128:129], off offset:3072
	s_addc_u32 s11, s27, s11
	s_ashr_i32 s17, s16, 31
	s_waitcnt vmcnt(15)
	v_pk_add_f32 v[6:7], v[6:7], v[68:69]
	s_waitcnt vmcnt(14)
	v_pk_add_f32 v[8:9], v[40:41], v[72:73]
	s_waitcnt vmcnt(13)
	v_pk_add_f32 v[42:43], v[42:43], v[74:75]
	v_pk_add_f32 v[40:41], v[44:45], v[76:77]
	s_waitcnt vmcnt(12)
	v_pk_add_f32 v[44:45], v[48:49], v[80:81]
	s_waitcnt vmcnt(11)
	v_pk_add_f32 v[48:49], v[52:53], v[86:87]
	s_waitcnt vmcnt(10)
	v_pk_add_f32 v[52:53], v[56:57], v[90:91]
	s_waitcnt vmcnt(9)
	v_pk_add_f32 v[56:57], v[60:61], v[94:95]
	s_waitcnt vmcnt(8)
	v_pk_add_f32 v[60:61], v[64:65], v[98:99]
	v_pk_add_f32 v[58:59], v[58:59], v[92:93]
	v_pk_add_f32 v[4:5], v[4:5], v[66:67]
	v_pk_add_f32 v[38:39], v[38:39], v[70:71]
	v_pk_add_f32 v[50:51], v[50:51], v[84:85]
	s_waitcnt vmcnt(5)
	v_pk_add_f32 v[74:75], v[42:43], v[108:109]
	v_add_co_u32_e32 v42, vcc, s9, v2
	s_mov_b32 s9, 0x3b55f000
	s_nop 0
	v_addc_co_u32_e32 v43, vcc, 0, v3, vcc
	s_waitcnt vmcnt(0)
	v_pk_add_f32 v[92:93], v[60:61], v[130:131]
	v_add_co_u32_e32 v60, vcc, s9, v2
	v_pk_add_f32 v[54:55], v[54:55], v[88:89]
	v_pk_add_f32 v[62:63], v[62:63], v[96:97]
	v_addc_co_u32_e32 v61, vcc, 0, v3, vcc
	v_pk_add_f32 v[46:47], v[46:47], v[78:79]
	v_pk_add_f32 v[64:65], v[6:7], v[102:103]
	v_pk_add_f32 v[66:67], v[4:5], v[100:101]
	v_pk_add_f32 v[68:69], v[8:9], v[106:107]
	v_pk_add_f32 v[70:71], v[38:39], v[104:105]
	v_pk_add_f32 v[72:73], v[40:41], v[110:111]
	v_pk_add_f32 v[76:77], v[44:45], v[114:115]
	v_pk_add_f32 v[78:79], v[48:49], v[118:119]
	v_pk_add_f32 v[80:81], v[50:51], v[116:117]
	v_pk_add_f32 v[84:85], v[52:53], v[122:123]
	v_pk_add_f32 v[86:87], v[54:55], v[120:121]
	v_pk_add_f32 v[88:89], v[56:57], v[126:127]
	v_pk_add_f32 v[90:91], v[58:59], v[124:125]
	v_pk_add_f32 v[94:95], v[62:63], v[128:129]
	global_load_dwordx4 v[2:5], v[60:61], off offset:-4096
	global_load_dwordx4 v[6:9], v[42:43], off offset:1024
	global_load_dwordx4 v[38:41], v[42:43], off offset:2048
	s_nop 0
	global_load_dwordx4 v[42:45], v[42:43], off offset:3072
	s_nop 0
	global_load_dwordx4 v[48:51], v[60:61], off
	global_load_dwordx4 v[52:55], v[60:61], off offset:1024
	global_load_dwordx4 v[56:59], v[60:61], off offset:2048
	s_nop 0
	global_load_dwordx4 v[60:63], v[60:61], off offset:3072
	s_movk_i32 s9, 0x5000
	v_pk_add_f32 v[46:47], v[46:47], v[112:113]
	s_waitcnt vmcnt(7)
	v_pk_add_f32 v[64:65], v[4:5], v[64:65]
	s_waitcnt vmcnt(6)
	v_pk_add_f32 v[96:97], v[8:9], v[68:69]
	v_pk_add_f32 v[98:99], v[6:7], v[70:71]
	v_pk_add_f32 v[66:67], v[2:3], v[66:67]
	s_waitcnt vmcnt(4)
	v_pk_add_f32 v[44:45], v[44:45], v[76:77]
	s_waitcnt vmcnt(2)
	v_pk_add_f32 v[8:9], v[54:55], v[84:85]
	v_lshl_add_u64 v[54:55], v[10:11], 2, s[10:11]
	v_add_co_u32_e32 v6, vcc, s9, v54
	s_waitcnt vmcnt(1)
	v_pk_add_f32 v[2:3], v[58:59], v[88:89]
	v_addc_co_u32_e32 v7, vcc, 0, v55, vcc
	v_pk_add_f32 v[4:5], v[56:57], v[90:91]
	global_load_dwordx4 v[56:59], v[6:7], off offset:-4096
	v_lshl_add_u64 v[76:77], s[12:13], 0, v[12:13]
	v_pk_add_f32 v[72:73], v[40:41], v[72:73]
	v_pk_add_f32 v[46:47], v[42:43], v[46:47]
	v_pk_add_f32 v[40:41], v[50:51], v[78:79]
	v_pk_add_f32 v[42:43], v[48:49], v[80:81]
	global_load_dwordx4 v[48:51], v[76:77], off
	s_mov_b64 s[10:11], 0x4000
	v_pk_add_f32 v[74:75], v[38:39], v[74:75]
	v_pk_add_f32 v[38:39], v[52:53], v[86:87]
	v_lshl_add_u64 v[52:53], v[54:55], 0, s[10:11]
	s_waitcnt vmcnt(2)
	v_pk_add_f32 v[68:69], v[62:63], v[92:93]
	v_pk_add_f32 v[70:71], v[60:61], v[94:95]
	s_mov_b32 s9, 0x9000
	s_waitcnt vmcnt(1)
	v_pk_add_f32 v[58:59], v[58:59], 1.0 op_sel_hi:[1,0]
	v_pk_add_f32 v[56:57], v[56:57], 1.0 op_sel_hi:[1,0]
	v_pk_mul_f32 v[58:59], v[58:59], v[64:65]
	v_pk_mul_f32 v[56:57], v[56:57], v[66:67]
	s_waitcnt vmcnt(0)
	v_pk_fma_f32 v[64:65], v[50:51], s[92:93], v[58:59] op_sel_hi:[1,0,1]
	v_pk_fma_f32 v[66:67], v[48:49], s[92:93], v[56:57] op_sel_hi:[1,0,1]
	global_load_dwordx4 v[48:51], v[76:77], off offset:1024
	global_load_dwordx4 v[56:59], v[52:53], off offset:1024
	s_waitcnt vmcnt(0)
	v_pk_add_f32 v[58:59], v[58:59], 1.0 op_sel_hi:[1,0]
	v_pk_add_f32 v[56:57], v[56:57], 1.0 op_sel_hi:[1,0]
	v_pk_mul_f32 v[58:59], v[96:97], v[58:59]
	v_pk_mul_f32 v[56:57], v[98:99], v[56:57]
	v_pk_fma_f32 v[60:61], v[50:51], s[92:93], v[58:59] op_sel_hi:[1,0,1]
	v_pk_fma_f32 v[62:63], v[48:49], s[92:93], v[56:57] op_sel_hi:[1,0,1]
	global_load_dwordx4 v[48:51], v[76:77], off offset:2048
	global_load_dwordx4 v[56:59], v[52:53], off offset:2048
	s_waitcnt vmcnt(0)
	v_pk_add_f32 v[58:59], v[58:59], 1.0 op_sel_hi:[1,0]
	v_pk_add_f32 v[56:57], v[56:57], 1.0 op_sel_hi:[1,0]
	v_pk_mul_f32 v[58:59], v[58:59], v[72:73]
	v_pk_mul_f32 v[56:57], v[56:57], v[74:75]
	v_pk_fma_f32 v[58:59], v[50:51], s[92:93], v[58:59] op_sel_hi:[1,0,1]
	v_pk_fma_f32 v[56:57], v[48:49], s[92:93], v[56:57] op_sel_hi:[1,0,1]
	global_load_dwordx4 v[48:51], v[76:77], off offset:3072
	global_load_dwordx4 v[72:75], v[52:53], off offset:3072
	v_add_co_u32_e32 v76, vcc, s82, v76
	s_waitcnt vmcnt(0)
	v_pk_add_f32 v[52:53], v[74:75], 1.0 op_sel_hi:[1,0]
	v_pk_add_f32 v[72:73], v[72:73], 1.0 op_sel_hi:[1,0]
	v_pk_mul_f32 v[44:45], v[44:45], v[52:53]
	v_pk_mul_f32 v[46:47], v[46:47], v[72:73]
	v_addc_co_u32_e32 v77, vcc, 0, v77, vcc
	v_pk_fma_f32 v[52:53], v[50:51], s[92:93], v[44:45] op_sel_hi:[1,0,1]
	v_pk_fma_f32 v[50:51], v[48:49], s[92:93], v[46:47] op_sel_hi:[1,0,1]
	global_load_dwordx4 v[44:47], v[76:77], off
	global_load_dwordx4 v[72:75], v[6:7], off
	s_waitcnt vmcnt(0)
	v_pk_add_f32 v[48:49], v[74:75], 1.0 op_sel_hi:[1,0]
	v_pk_add_f32 v[72:73], v[72:73], 1.0 op_sel_hi:[1,0]
	v_pk_mul_f32 v[40:41], v[48:49], v[40:41]
	v_pk_mul_f32 v[42:43], v[72:73], v[42:43]
	v_pk_fma_f32 v[48:49], v[46:47], s[92:93], v[40:41] op_sel_hi:[1,0,1]
	v_pk_fma_f32 v[46:47], v[44:45], s[92:93], v[42:43] op_sel_hi:[1,0,1]
	global_load_dwordx4 v[40:43], v[76:77], off offset:1024
	global_load_dwordx4 v[72:75], v[6:7], off offset:1024
	s_waitcnt vmcnt(0)
	v_pk_add_f32 v[44:45], v[74:75], 1.0 op_sel_hi:[1,0]
	v_pk_add_f32 v[72:73], v[72:73], 1.0 op_sel_hi:[1,0]
	v_pk_mul_f32 v[8:9], v[8:9], v[44:45]
	v_pk_mul_f32 v[38:39], v[38:39], v[72:73]
	v_pk_fma_f32 v[44:45], v[42:43], s[92:93], v[8:9] op_sel_hi:[1,0,1]
	v_pk_fma_f32 v[42:43], v[40:41], s[92:93], v[38:39] op_sel_hi:[1,0,1]
	global_load_dwordx4 v[38:41], v[76:77], off offset:2048
	global_load_dwordx4 v[72:75], v[6:7], off offset:2048
	s_waitcnt vmcnt(0)
	v_pk_add_f32 v[8:9], v[74:75], 1.0 op_sel_hi:[1,0]
	v_pk_add_f32 v[72:73], v[72:73], 1.0 op_sel_hi:[1,0]
	v_pk_mul_f32 v[2:3], v[8:9], v[2:3]
	v_pk_mul_f32 v[4:5], v[72:73], v[4:5]
	v_pk_fma_f32 v[40:41], v[40:41], s[92:93], v[2:3] op_sel_hi:[1,0,1]
	v_pk_fma_f32 v[38:39], v[38:39], s[92:93], v[4:5] op_sel_hi:[1,0,1]
	global_load_dwordx4 v[2:5], v[76:77], off offset:3072
	s_nop 0
	global_load_dwordx4 v[6:9], v[6:7], off offset:3072
	s_waitcnt vmcnt(0)
	v_pk_add_f32 v[8:9], v[8:9], 1.0 op_sel_hi:[1,0]
	v_pk_add_f32 v[6:7], v[6:7], 1.0 op_sel_hi:[1,0]
	v_pk_mul_f32 v[8:9], v[68:69], v[8:9]
	v_pk_mul_f32 v[6:7], v[70:71], v[6:7]
	v_pk_fma_f32 v[4:5], v[4:5], s[92:93], v[8:9] op_sel_hi:[1,0,1]
	v_pk_fma_f32 v[2:3], v[2:3], s[92:93], v[6:7] op_sel_hi:[1,0,1]
	v_mov_b32_e32 v6, v66
	v_mov_b32_e32 v7, v62
	v_mov_b32_e32 v8, v67
	v_mov_b32_e32 v9, v63
	v_pk_add_f32 v[6:7], v[6:7], v[8:9]
	v_mov_b32_e32 v8, v64
	v_mov_b32_e32 v9, v60
	v_mov_b32_e32 v68, v65
	v_mov_b32_e32 v69, v61
	v_pk_add_f32 v[8:9], v[8:9], v[68:69]
	v_mov_b32_e32 v68, v56
	v_pk_add_f32 v[6:7], v[6:7], v[8:9]
	v_pk_mov_b32 v[8:9], v[56:57], v[58:59] op_sel:[1,0]
	v_mov_b32_e32 v69, v59
	v_pk_add_f32 v[8:9], v[8:9], v[68:69]
	v_add_f32_e32 v1, 0, v6
	v_pk_add_f32 v[8:9], v[8:9], v[8:9] op_sel:[0,1] op_sel_hi:[1,0]
	v_add_f32_e32 v6, v1, v7
	v_add_f32_e32 v68, v50, v51
	v_add_f32_e32 v70, v52, v53
	v_mov_b32_e32 v7, v46
	v_mov_b32_e32 v9, v47
	v_mov_b32_e32 v69, v48
	v_mov_b32_e32 v71, v49
	v_pk_add_f32 v[6:7], v[6:7], v[8:9]
	v_pk_add_f32 v[8:9], v[68:69], v[70:71]
	v_mov_b32_e32 v68, v42
	v_pk_add_f32 v[6:7], v[6:7], v[8:9]
	v_pk_mov_b32 v[8:9], v[42:43], v[44:45] op_sel:[1,0]
	v_mov_b32_e32 v69, v45
	v_pk_add_f32 v[8:9], v[8:9], v[68:69]
	v_pk_add_f32 v[6:7], v[6:7], v[6:7] op_sel:[0,1] op_sel_hi:[1,0]
	v_pk_add_f32 v[8:9], v[8:9], v[8:9] op_sel:[0,1] op_sel_hi:[1,0]
	v_add_f32_e32 v68, v38, v39
	v_add_f32_e32 v70, v40, v41
	v_mov_b32_e32 v7, v2
	v_mov_b32_e32 v9, v3
	v_mov_b32_e32 v69, v4
	v_mov_b32_e32 v71, v5
	v_pk_add_f32 v[6:7], v[6:7], v[8:9]
	v_pk_add_f32 v[8:9], v[68:69], v[70:71]
	s_nop 0
	v_pk_add_f32 v[6:7], v[6:7], v[8:9]
	s_nop 0
	v_add_f32_e32 v1, v6, v7
	v_and_b32_e32 v6, 64, v249
	v_add_u32_e32 v6, 64, v6
	v_xor_b32_e32 v7, 1, v249
	v_cmp_lt_i32_e32 vcc, v7, v6
	s_nop 1
	v_cndmask_b32_e32 v7, v249, v7, vcc
	v_lshlrev_b32_e32 v72, 2, v7
	ds_bpermute_b32 v7, v72, v1
	s_waitcnt lgkmcnt(0)
	v_add_f32_e32 v1, v1, v7
	v_xor_b32_e32 v7, 2, v249
	v_cmp_lt_i32_e32 vcc, v7, v6
	s_nop 1
	v_cndmask_b32_e32 v7, v249, v7, vcc
	v_lshlrev_b32_e32 v73, 2, v7
	ds_bpermute_b32 v7, v73, v1
	s_waitcnt lgkmcnt(0)
	v_add_f32_e32 v1, v1, v7
	v_xor_b32_e32 v7, 4, v249
	v_cmp_lt_i32_e32 vcc, v7, v6
	s_nop 1
	v_cndmask_b32_e32 v7, v249, v7, vcc
	v_lshlrev_b32_e32 v74, 2, v7
	ds_bpermute_b32 v7, v74, v1
	s_waitcnt lgkmcnt(0)
	v_add_f32_e32 v1, v1, v7
	v_xor_b32_e32 v7, 8, v249
	v_cmp_lt_i32_e32 vcc, v7, v6
	s_nop 1
	v_cndmask_b32_e32 v7, v249, v7, vcc
	v_lshlrev_b32_e32 v75, 2, v7
	ds_bpermute_b32 v7, v75, v1
	s_waitcnt lgkmcnt(0)
	v_add_f32_e32 v1, v1, v7
	v_xor_b32_e32 v7, 16, v249
	v_cmp_lt_i32_e32 vcc, v7, v6
	s_nop 1
	v_cndmask_b32_e32 v7, v249, v7, vcc
	v_lshlrev_b32_e32 v76, 2, v7
	ds_bpermute_b32 v7, v76, v1
	s_waitcnt lgkmcnt(0)
	v_add_f32_e32 v1, v1, v7
	v_xor_b32_e32 v7, 32, v249
	v_cmp_lt_i32_e32 vcc, v7, v6
	s_nop 1
	v_cndmask_b32_e32 v6, v249, v7, vcc
	v_lshlrev_b32_e32 v77, 2, v6
	ds_bpermute_b32 v6, v77, v1
	s_waitcnt lgkmcnt(0)
	v_add_f32_e32 v1, v1, v6
	v_fmamk_f32 v67, v1, 0xba000000, v67
	v_fmamk_f32 v63, v1, 0xba000000, v63
	v_fmamk_f32 v65, v1, 0xba000000, v65
	v_fmac_f32_e32 v66, 0xba000000, v1
	v_fmamk_f32 v61, v1, 0xba000000, v61
	v_fmac_f32_e32 v62, 0xba000000, v1
	v_mov_b32_e32 v8, v67
	v_mov_b32_e32 v9, v63
	v_fmac_f32_e32 v64, 0xba000000, v1
	v_fmac_f32_e32 v60, 0xba000000, v1
	v_mov_b32_e32 v6, v66
	v_mov_b32_e32 v7, v62
	v_pk_mul_f32 v[8:9], v[8:9], v[8:9]
	v_mov_b32_e32 v68, v65
	v_mov_b32_e32 v69, v61
	v_pk_fma_f32 v[6:7], v[6:7], v[6:7], v[8:9]
	v_mov_b32_e32 v8, v64
	v_mov_b32_e32 v9, v60
	v_pk_mul_f32 v[68:69], v[68:69], v[68:69]
	v_fmamk_f32 v57, v1, 0xba000000, v57
	v_pk_fma_f32 v[8:9], v[8:9], v[8:9], v[68:69]
	v_fmac_f32_e32 v56, 0xba000000, v1
	v_pk_add_f32 v[6:7], v[6:7], v[8:9]
	v_fmamk_f32 v59, v1, 0xba000000, v59
	v_fmac_f32_e32 v58, 0xba000000, v1
	v_pk_add_f32 v[6:7], v[6:7], v[6:7] op_sel_hi:[0,1]
	v_pk_mul_f32 v[8:9], v[58:59], v[58:59]
	v_pk_mul_f32 v[68:69], v[56:57], v[56:57]
	v_fmac_f32_e32 v50, 0xba000000, v1
	v_pk_mov_b32 v[70:71], v[68:69], v[8:9] op_sel:[1,0]
	v_mov_b32_e32 v69, v9
	v_fmamk_f32 v51, v1, 0xba000000, v51
	v_fmac_f32_e32 v52, 0xba000000, v1
	v_mul_f32_e32 v6, v50, v50
	v_pk_add_f32 v[8:9], v[70:71], v[68:69]
	v_fmamk_f32 v53, v1, 0xba000000, v53
	v_pk_fma_f32 v[68:69], v[50:51], v[50:51], v[6:7] op_sel_hi:[1,1,0]
	v_mul_f32_e32 v6, v52, v52
	v_pk_add_f32 v[8:9], v[8:9], v[8:9] op_sel_hi:[0,1]
	v_pk_fma_f32 v[70:71], v[52:53], v[52:53], v[6:7] op_sel_hi:[1,1,0]
	v_fmamk_f32 v49, v1, 0xba000000, v49
	v_fmac_f32_e32 v48, 0xba000000, v1
	v_fmamk_f32 v47, v1, 0xba000000, v47
	v_fmac_f32_e32 v46, 0xba000000, v1
	v_mul_f32_e32 v68, v46, v46
	v_mul_f32_e32 v70, v47, v47
	v_mul_f32_e32 v8, v48, v48
	v_mul_f32_e32 v6, v49, v49
	v_pk_add_f32 v[68:69], v[68:69], v[70:71]
	v_pk_add_f32 v[6:7], v[8:9], v[6:7]
	v_fmamk_f32 v43, v1, 0xba000000, v43
	v_pk_add_f32 v[6:7], v[68:69], v[6:7]
	v_fmac_f32_e32 v42, 0xba000000, v1
	v_fmamk_f32 v45, v1, 0xba000000, v45
	v_fmac_f32_e32 v44, 0xba000000, v1
	v_pk_add_f32 v[6:7], v[6:7], v[6:7] op_sel_hi:[0,1]
	v_pk_mul_f32 v[8:9], v[44:45], v[44:45]
	v_pk_mul_f32 v[68:69], v[42:43], v[42:43]
	v_fmac_f32_e32 v38, 0xba000000, v1
	v_pk_mov_b32 v[70:71], v[68:69], v[8:9] op_sel:[1,0]
	v_mov_b32_e32 v69, v9
	v_fmamk_f32 v39, v1, 0xba000000, v39
	v_fmac_f32_e32 v40, 0xba000000, v1
	v_mul_f32_e32 v6, v38, v38
	v_pk_add_f32 v[8:9], v[70:71], v[68:69]
	v_fmamk_f32 v41, v1, 0xba000000, v41
	v_pk_fma_f32 v[68:69], v[38:39], v[38:39], v[6:7] op_sel_hi:[1,1,0]
	v_mul_f32_e32 v6, v40, v40
	v_pk_add_f32 v[8:9], v[8:9], v[8:9] op_sel_hi:[0,1]
	v_pk_fma_f32 v[70:71], v[40:41], v[40:41], v[6:7] op_sel_hi:[1,1,0]
	v_fmamk_f32 v5, v1, 0xba000000, v5
	v_fmac_f32_e32 v4, 0xba000000, v1
	v_fmamk_f32 v3, v1, 0xba000000, v3
	v_fmac_f32_e32 v2, 0xba000000, v1
	v_mul_f32_e32 v68, v2, v2
	v_mul_f32_e32 v70, v3, v3
	v_mul_f32_e32 v8, v4, v4
	v_mul_f32_e32 v6, v5, v5
	v_pk_add_f32 v[68:69], v[68:69], v[70:71]
	v_pk_add_f32 v[6:7], v[8:9], v[6:7]
	s_nop 0
	v_pk_add_f32 v[6:7], v[68:69], v[6:7]
	s_nop 0
	v_add_f32_e32 v1, v6, v7
	ds_bpermute_b32 v6, v72, v1
	s_waitcnt lgkmcnt(0)
	v_add_f32_e32 v1, v1, v6
	ds_bpermute_b32 v6, v73, v1
	s_waitcnt lgkmcnt(0)
	v_add_f32_e32 v1, v1, v6
	ds_bpermute_b32 v6, v74, v1
	s_waitcnt lgkmcnt(0)
	v_add_f32_e32 v1, v1, v6
	ds_bpermute_b32 v6, v75, v1
	s_waitcnt lgkmcnt(0)
	v_add_f32_e32 v1, v1, v6
	ds_bpermute_b32 v6, v76, v1
	s_waitcnt lgkmcnt(0)
	v_add_f32_e32 v1, v1, v6
	ds_bpermute_b32 v6, v77, v1
	s_waitcnt lgkmcnt(0)
	v_add_f32_e32 v1, v1, v6
	v_fmamk_f32 v1, v1, 0x3a000000, v250
	v_cmp_gt_f32_e32 vcc, s96, v1
	v_mul_f32_e32 v6, 0x4f800000, v1
	s_nop 0
	v_cndmask_b32_e32 v1, v1, v6, vcc
	v_sqrt_f32_e32 v6, v1
	s_nop 0
	v_add_u32_e32 v7, -1, v6
	v_fma_f32 v8, -v7, v6, v1
	v_cmp_ge_f32_e64 s[10:11], 0, v8
	v_add_u32_e32 v8, 1, v6
	s_nop 0
	v_cndmask_b32_e64 v7, v6, v7, s[10:11]
	v_fma_f32 v6, -v8, v6, v1
	v_cmp_lt_f32_e64 s[10:11], 0, v6
	s_nop 1
	v_cndmask_b32_e64 v6, v7, v8, s[10:11]
	v_mul_f32_e32 v7, 0x37800000, v6
	v_cndmask_b32_e32 v6, v6, v7, vcc
	v_cmp_class_f32_e32 vcc, v1, v251
	s_nop 1
	v_cndmask_b32_e32 v1, v6, v1, vcc
	v_div_scale_f32 v6, s[10:11], v1, v1, 1.0
	v_rcp_f32_e32 v7, v6
	s_lshl_b64 s[10:11], s[16:17], 13
	v_fma_f32 v8, -v6, v7, 1.0
	v_fmac_f32_e32 v7, v8, v7
	v_div_scale_f32 v8, vcc, 1.0, v1, 1.0
	v_mul_f32_e32 v9, v8, v7
	v_fma_f32 v68, -v6, v9, v8
	v_fmac_f32_e32 v9, v68, v7
	global_load_dwordx4 v[68:71], v[14:15], off
	global_load_dwordx4 v[72:75], v[16:17], off
	v_fma_f32 v6, -v6, v9, v8
	v_div_fmas_f32 v6, v6, v7, v9
	v_div_fixup_f32 v6, v6, v1, 1.0
	v_pk_mul_f32 v[64:65], v[64:65], v[6:7] op_sel_hi:[1,0]
	v_pk_mul_f32 v[8:9], v[66:67], v[6:7] op_sel_hi:[1,0]
	v_lshl_add_u64 v[66:67], v[34:35], 0, s[10:11]
	s_mov_b64 s[10:11], 0x8000
	v_lshl_add_u64 v[80:81], v[54:55], 0, s[10:11]
	s_mov_b64 s[10:11], 0x6000
	v_lshl_add_u64 v[84:85], v[54:55], 0, s[10:11]
	s_lshl_b64 s[10:11], s[16:17], 12
	s_waitcnt vmcnt(0)
	v_pk_fma_f32 v[70:71], v[70:71], v[64:65], v[74:75]
	v_add_co_u32_e32 v64, vcc, s9, v54
	v_pk_fma_f32 v[68:69], v[68:69], v[8:9], v[72:73]
	s_nop 0
	v_addc_co_u32_e32 v65, vcc, 0, v55, vcc
	s_movk_i32 s9, 0x7000
	global_store_dwordx4 v[66:67], v[68:71], off
	v_add_co_u32_e32 v54, vcc, s9, v54
	global_load_dwordx4 v[72:75], v[64:65], off offset:-4096
	s_nop 0
	v_addc_co_u32_e32 v55, vcc, 0, v55, vcc
	global_load_dwordx4 v[76:79], v[54:55], off offset:-4096
	s_waitcnt vmcnt(1)
	v_pk_add_f32 v[72:73], v[72:73], 1.0 op_sel_hi:[1,0]
	v_pk_add_f32 v[8:9], v[74:75], 1.0 op_sel_hi:[1,0]
	s_waitcnt vmcnt(0)
	v_pk_fma_f32 v[68:69], v[72:73], v[68:69], v[76:77]
	s_nop 0
	s_nop 0
	s_nop 0
	s_nop 0
	v_pk_fma_f32 v[8:9], v[8:9], v[70:71], v[78:79]
	s_nop 0
	s_nop 0
	v_cvt_pk_bf16_f32 v68, v68, v69
	v_bfe_u32 v1, v8, 16, 1
	v_add3_u32 v1, v8, v1, s73
	v_bfe_u32 v7, v9, 16, 1
	v_lshrrev_b32_e32 v1, 16, v1
	v_add3_u32 v7, v9, v7, s73
	v_and_or_b32 v69, v7, s33, v1
	v_lshl_add_u64 v[8:9], v[36:37], 0, s[10:11]
	global_store_dwordx2 v[8:9], v[68:69], off
	global_load_dwordx4 v[68:71], v[14:15], off offset:1024
	s_nop 0
	global_load_dwordx4 v[72:75], v[16:17], off offset:1024
	v_pk_mul_f32 v[76:77], v[60:61], v[6:7] op_sel_hi:[1,0]
	v_pk_mul_f32 v[60:61], v[62:63], v[6:7] op_sel_hi:[1,0]
	s_waitcnt vmcnt(0)
	v_pk_fma_f32 v[62:63], v[70:71], v[76:77], v[74:75]
	v_pk_fma_f32 v[60:61], v[68:69], v[60:61], v[72:73]
	global_store_dwordx4 v[66:67], v[60:63], off offset:1024
	global_load_dwordx4 v[68:71], v[80:81], off offset:1024
	global_load_dwordx4 v[72:75], v[84:85], off offset:1024
	s_waitcnt vmcnt(1)
	v_pk_add_f32 v[68:69], v[68:69], 1.0 op_sel_hi:[1,0]
	s_waitcnt vmcnt(0)
	v_pk_fma_f32 v[60:61], v[68:69], v[60:61], v[72:73]
	v_pk_add_f32 v[70:71], v[70:71], 1.0 op_sel_hi:[1,0]
	v_pk_fma_f32 v[62:63], v[70:71], v[62:63], v[74:75]
	v_cvt_pk_bf16_f32 v60, v60, v61
	v_bfe_u32 v1, v62, 16, 1
	v_add3_u32 v1, v62, v1, s73
	v_bfe_u32 v7, v63, 16, 1
	v_lshrrev_b32_e32 v1, 16, v1
	v_add3_u32 v7, v63, v7, s73
	v_and_or_b32 v61, v7, s33, v1
	global_store_dwordx2 v[8:9], v[60:61], off offset:512
	global_load_dwordx4 v[60:63], v[14:15], off offset:2048
	s_nop 0
	global_load_dwordx4 v[68:71], v[16:17], off offset:2048
	v_pk_mul_f32 v[58:59], v[58:59], v[6:7] op_sel_hi:[1,0]
	v_pk_mul_f32 v[56:57], v[56:57], v[6:7] op_sel_hi:[1,0]
	s_waitcnt vmcnt(0)
	v_pk_fma_f32 v[58:59], v[62:63], v[58:59], v[70:71]
	v_pk_fma_f32 v[56:57], v[60:61], v[56:57], v[68:69]
	global_store_dwordx4 v[66:67], v[56:59], off offset:2048
	global_load_dwordx4 v[60:63], v[80:81], off offset:2048
	global_load_dwordx4 v[68:71], v[84:85], off offset:2048
	s_waitcnt vmcnt(1)
	v_pk_add_f32 v[60:61], v[60:61], 1.0 op_sel_hi:[1,0]
	s_waitcnt vmcnt(0)
	v_pk_fma_f32 v[56:57], v[56:57], v[60:61], v[68:69]
	v_pk_add_f32 v[62:63], v[62:63], 1.0 op_sel_hi:[1,0]
	v_pk_fma_f32 v[58:59], v[58:59], v[62:63], v[70:71]
	v_cvt_pk_bf16_f32 v56, v56, v57
	v_bfe_u32 v1, v58, 16, 1
	v_add3_u32 v1, v58, v1, s73
	v_bfe_u32 v7, v59, 16, 1
	v_lshrrev_b32_e32 v1, 16, v1
	v_add3_u32 v7, v59, v7, s73
	v_and_or_b32 v57, v7, s33, v1
	global_store_dwordx2 v[8:9], v[56:57], off offset:1024
	global_load_dwordx4 v[56:59], v[14:15], off offset:3072
	s_nop 0
	global_load_dwordx4 v[60:63], v[16:17], off offset:3072
	v_pk_mul_f32 v[52:53], v[52:53], v[6:7] op_sel_hi:[1,0]
	v_pk_mul_f32 v[50:51], v[50:51], v[6:7] op_sel_hi:[1,0]
	s_waitcnt vmcnt(0)
	v_pk_fma_f32 v[52:53], v[52:53], v[58:59], v[62:63]
	v_pk_fma_f32 v[50:51], v[50:51], v[56:57], v[60:61]
	global_store_dwordx4 v[66:67], v[50:53], off offset:3072
	global_load_dwordx4 v[56:59], v[80:81], off offset:3072
	global_load_dwordx4 v[60:63], v[84:85], off offset:3072
	s_waitcnt vmcnt(1)
	v_pk_add_f32 v[56:57], v[56:57], 1.0 op_sel_hi:[1,0]
	s_waitcnt vmcnt(0)
	v_pk_fma_f32 v[50:51], v[50:51], v[56:57], v[60:61]
	v_pk_add_f32 v[58:59], v[58:59], 1.0 op_sel_hi:[1,0]
	v_pk_fma_f32 v[52:53], v[52:53], v[58:59], v[62:63]
	v_cvt_pk_bf16_f32 v50, v50, v51
	v_bfe_u32 v1, v52, 16, 1
	v_add3_u32 v1, v52, v1, s73
	v_bfe_u32 v7, v53, 16, 1
	v_lshrrev_b32_e32 v1, 16, v1
	v_add3_u32 v7, v53, v7, s73
	v_and_or_b32 v51, v7, s33, v1
	global_store_dwordx2 v[8:9], v[50:51], off offset:1536
	global_load_dwordx4 v[50:53], v[18:19], off
	s_nop 0
	global_load_dwordx4 v[56:59], v[20:21], off
	v_pk_mul_f32 v[46:47], v[46:47], v[6:7] op_sel_hi:[1,0]
	v_pk_mul_f32 v[60:61], v[48:49], v[6:7] op_sel_hi:[1,0]
	s_waitcnt vmcnt(0)
	v_pk_fma_f32 v[48:49], v[46:47], v[50:51], v[56:57]
	v_add_co_u32_e32 v46, vcc, s82, v66
	v_pk_fma_f32 v[50:51], v[60:61], v[52:53], v[58:59]
	s_nop 0
	v_addc_co_u32_e32 v47, vcc, 0, v67, vcc
	global_store_dwordx4 v[46:47], v[48:51], off
	global_load_dwordx4 v[56:59], v[64:65], off
	global_load_dwordx4 v[60:63], v[54:55], off
	s_waitcnt vmcnt(1)
	v_pk_add_f32 v[56:57], v[56:57], 1.0 op_sel_hi:[1,0]
	s_waitcnt vmcnt(0)
	v_pk_fma_f32 v[48:49], v[48:49], v[56:57], v[60:61]
	v_pk_add_f32 v[52:53], v[58:59], 1.0 op_sel_hi:[1,0]
	v_pk_fma_f32 v[50:51], v[50:51], v[52:53], v[62:63]
	v_cvt_pk_bf16_f32 v48, v48, v49
	v_bfe_u32 v1, v50, 16, 1
	v_add3_u32 v1, v50, v1, s73
	v_bfe_u32 v7, v51, 16, 1
	v_lshrrev_b32_e32 v1, 16, v1
	v_add3_u32 v7, v51, v7, s73
	v_and_or_b32 v49, v7, s33, v1
	global_store_dwordx2 v[8:9], v[48:49], off offset:2048
	global_load_dwordx4 v[48:51], v[22:23], off
	s_nop 0
	global_load_dwordx4 v[56:59], v[24:25], off
	v_pk_mul_f32 v[44:45], v[44:45], v[6:7] op_sel_hi:[1,0]
	v_pk_mul_f32 v[42:43], v[42:43], v[6:7] op_sel_hi:[1,0]
	s_waitcnt vmcnt(0)
	v_pk_fma_f32 v[44:45], v[44:45], v[50:51], v[58:59]
	v_pk_fma_f32 v[42:43], v[42:43], v[48:49], v[56:57]
	global_store_dwordx4 v[46:47], v[42:45], off offset:1024
	global_load_dwordx4 v[48:51], v[64:65], off offset:1024
	global_load_dwordx4 v[56:59], v[54:55], off offset:1024
	s_waitcnt vmcnt(1)
	v_pk_add_f32 v[48:49], v[48:49], 1.0 op_sel_hi:[1,0]
	s_waitcnt vmcnt(0)
	v_pk_fma_f32 v[42:43], v[42:43], v[48:49], v[56:57]
	v_pk_add_f32 v[50:51], v[50:51], 1.0 op_sel_hi:[1,0]
	v_pk_fma_f32 v[44:45], v[44:45], v[50:51], v[58:59]
	v_cvt_pk_bf16_f32 v42, v42, v43
	v_bfe_u32 v1, v44, 16, 1
	v_add3_u32 v1, v44, v1, s73
	v_bfe_u32 v7, v45, 16, 1
	v_lshrrev_b32_e32 v1, 16, v1
	v_add3_u32 v7, v45, v7, s73
	v_and_or_b32 v43, v7, s33, v1
	global_store_dwordx2 v[8:9], v[42:43], off offset:2560
	global_load_dwordx4 v[42:45], v[26:27], off
	s_nop 0
	global_load_dwordx4 v[48:51], v[28:29], off
	v_pk_mul_f32 v[40:41], v[40:41], v[6:7] op_sel_hi:[1,0]
	v_pk_mul_f32 v[38:39], v[38:39], v[6:7] op_sel_hi:[1,0]
	s_waitcnt vmcnt(0)
	v_pk_fma_f32 v[40:41], v[40:41], v[44:45], v[50:51]
	v_pk_fma_f32 v[38:39], v[38:39], v[42:43], v[48:49]
	global_store_dwordx4 v[46:47], v[38:41], off offset:2048
	global_load_dwordx4 v[42:45], v[64:65], off offset:2048
	global_load_dwordx4 v[48:51], v[54:55], off offset:2048
	s_waitcnt vmcnt(1)
	v_pk_add_f32 v[42:43], v[42:43], 1.0 op_sel_hi:[1,0]
	s_waitcnt vmcnt(0)
	v_pk_fma_f32 v[38:39], v[38:39], v[42:43], v[48:49]
	v_pk_add_f32 v[44:45], v[44:45], 1.0 op_sel_hi:[1,0]
	v_pk_fma_f32 v[40:41], v[40:41], v[44:45], v[50:51]
	v_cvt_pk_bf16_f32 v38, v38, v39
	v_bfe_u32 v1, v40, 16, 1
	v_add3_u32 v1, v40, v1, s73
	v_bfe_u32 v7, v41, 16, 1
	v_lshrrev_b32_e32 v1, 16, v1
	v_add3_u32 v7, v41, v7, s73
	v_and_or_b32 v39, v7, s33, v1
	global_store_dwordx2 v[8:9], v[38:39], off offset:3072
	global_load_dwordx4 v[38:41], v[30:31], off
	s_nop 0
	global_load_dwordx4 v[42:45], v[32:33], off
	v_pk_mul_f32 v[4:5], v[4:5], v[6:7] op_sel_hi:[1,0]
	v_pk_mul_f32 v[2:3], v[2:3], v[6:7] op_sel_hi:[1,0]
	s_waitcnt vmcnt(0)
	v_pk_fma_f32 v[4:5], v[4:5], v[40:41], v[44:45]
	v_pk_fma_f32 v[2:3], v[2:3], v[38:39], v[42:43]
	global_store_dwordx4 v[46:47], v[2:5], off offset:3072
	global_load_dwordx4 v[38:41], v[64:65], off offset:3072
	global_load_dwordx4 v[42:45], v[54:55], off offset:3072
	s_waitcnt vmcnt(1)
	v_pk_add_f32 v[38:39], v[38:39], 1.0 op_sel_hi:[1,0]
	s_waitcnt vmcnt(0)
	v_pk_fma_f32 v[2:3], v[2:3], v[38:39], v[42:43]
	v_pk_add_f32 v[6:7], v[40:41], 1.0 op_sel_hi:[1,0]
	v_pk_fma_f32 v[4:5], v[4:5], v[6:7], v[44:45]
	v_cvt_pk_bf16_f32 v2, v2, v3
	v_bfe_u32 v1, v4, 16, 1
	v_add3_u32 v1, v4, v1, s73
	v_bfe_u32 v3, v5, 16, 1
	v_lshrrev_b32_e32 v1, 16, v1
	v_add3_u32 v3, v5, v3, s73
	v_and_or_b32 v3, v3, s33, v1
	global_store_dwordx2 v[8:9], v[2:3], off offset:3584
	s_branch .LBB0_1221

.LBB0_1513:
	s_mul_i32 s22, s18, 0x3020000
	s_sext_i32_i16 s21, s19
	s_mul_hi_i32 s19, s18, 0x3020000
	s_waitcnt lgkmcnt(0)
	s_add_u32 s22, s10, s22
	s_addc_u32 s23, s11, s19
	s_mul_hi_i32 s19, s18, 0x1800000
	s_mul_i32 s18, s18, 0x1800000
	v_lshl_add_u64 v[14:15], v[12:13], 0, s[18:19]
	s_lshl_b32 s18, s21, 6
	s_ashr_i32 s21, s20, 31
	s_lshl_b64 s[20:21], s[20:21], 2
	s_add_u32 s20, s22, s20
	s_addc_u32 s21, s23, s21
	v_lshlrev_b32_e32 v82, 2, v4
	v_add_u32_e32 v50, s18, v1
	v_lshl_add_u64 v[48:49], s[20:21], 0, v[82:83]
	v_mad_i64_i32 v[20:21], s[20:21], v50, s40, v[48:49]
	v_add_u32_e32 v24, 8, v50
	global_load_dwordx4 v[20:23], v[20:21], off
	v_mad_i64_i32 v[24:25], s[20:21], v24, s40, v[48:49]
	global_load_dwordx4 v[24:27], v[24:25], off
	v_add_u32_e32 v28, 16, v50
	v_mad_i64_i32 v[28:29], s[20:21], v28, s40, v[48:49]
	global_load_dwordx4 v[28:31], v[28:29], off
	v_add_u32_e32 v32, 24, v50
	v_mad_i64_i32 v[32:33], s[20:21], v32, s40, v[48:49]
	global_load_dwordx4 v[32:35], v[32:33], off
	v_add_u32_e32 v36, 32, v50
	v_mad_i64_i32 v[36:37], s[20:21], v36, s40, v[48:49]
	global_load_dwordx4 v[36:39], v[36:37], off
	v_add_u32_e32 v40, 40, v50
	v_mad_i64_i32 v[40:41], s[20:21], v40, s40, v[48:49]
	global_load_dwordx4 v[40:43], v[40:41], off
	v_add_u32_e32 v44, 48, v50
	v_mad_i64_i32 v[44:45], s[20:21], v44, s40, v[48:49]
	global_load_dwordx4 v[44:47], v[44:45], off
	v_add_u32_e32 v50, 56, v50
	v_mad_i64_i32 v[48:49], s[20:21], v50, s40, v[48:49]
	global_load_dwordx4 v[48:51], v[48:49], off
	v_add_u32_e32 v52, v5, v7
	s_ashr_i32 s19, s18, 31
	s_lshl_b64 s[18:19], s[18:19], 1
	v_lshl_add_u64 v[14:15], v[14:15], 0, s[18:19]
	v_lshlrev_b32_e32 v82, 1, v6
	v_lshl_add_u64 v[14:15], v[14:15], 0, v[82:83]
	s_waitcnt vmcnt(7)
	ds_write2_b32 v52, v20, v21 offset1:1
	ds_write2_b32 v52, v22, v23 offset0:2 offset1:3
	v_add_u32_e32 v20, 0x420, v52
	s_waitcnt vmcnt(6)
	ds_write2_b32 v20, v24, v25 offset1:1
	v_add_u32_e32 v20, 0x428, v52
	ds_write2_b32 v20, v26, v27 offset1:1
	v_add_u32_e32 v20, 0x840, v52
	s_waitcnt vmcnt(5)
	ds_write2_b32 v20, v28, v29 offset1:1
	v_add_u32_e32 v20, 0x848, v52
	ds_write2_b32 v20, v30, v31 offset1:1
	v_add_u32_e32 v20, 0xc60, v52
	s_waitcnt vmcnt(4)
	ds_write2_b32 v20, v32, v33 offset1:1
	v_add_u32_e32 v20, 0xc68, v52
	ds_write2_b32 v20, v34, v35 offset1:1
	v_add_u32_e32 v20, 0x1080, v52
	s_waitcnt vmcnt(3)
	ds_write2_b32 v20, v36, v37 offset1:1
	v_add_u32_e32 v20, 0x1088, v52
	ds_write2_b32 v20, v38, v39 offset1:1
	v_add_u32_e32 v20, 0x14a0, v52
	s_waitcnt vmcnt(2)
	ds_write2_b32 v20, v40, v41 offset1:1
	v_add_u32_e32 v20, 0x14a8, v52
	ds_write2_b32 v20, v42, v43 offset1:1
	v_add_u32_e32 v20, 0x18c0, v52
	s_waitcnt vmcnt(1)
	ds_write2_b32 v20, v44, v45 offset1:1
	v_add_u32_e32 v20, 0x18c8, v52
	ds_write2_b32 v20, v46, v47 offset1:1
	v_add_u32_e32 v20, 0x1ce0, v52
	s_waitcnt vmcnt(0)
	ds_write2_b32 v20, v48, v49 offset1:1
	v_add_u32_e32 v20, 0x1ce8, v52
	ds_write2_b32 v20, v50, v51 offset1:1
	s_waitcnt lgkmcnt(0)
	ds_read2_b32 v[24:25], v19 offset0:33 offset1:41
	ds_read2_b32 v[26:27], v19 offset1:8
	ds_read2_b32 v[28:29], v19 offset0:66 offset1:74
	ds_read2_b32 v[30:31], v19 offset0:99 offset1:107
	ds_read2_b32 v[32:33], v19 offset0:132 offset1:140
	ds_read2_b32 v[34:35], v19 offset0:165 offset1:173
	ds_read2_b32 v[36:37], v19 offset0:198 offset1:206
	ds_read2_b32 v[38:39], v19 offset0:231 offset1:239
	s_waitcnt lgkmcnt(7)
	s_waitcnt lgkmcnt(6)
	v_cvt_pk_bf16_f32 v20, v26, v24
	s_waitcnt lgkmcnt(5)
	s_waitcnt lgkmcnt(4)
	v_cvt_pk_bf16_f32 v21, v28, v30
	s_waitcnt lgkmcnt(3)
	s_waitcnt lgkmcnt(2)
	v_cvt_pk_bf16_f32 v22, v32, v34
	s_waitcnt lgkmcnt(1)
	v_add_u32_e32 v40, s26, v1
	s_waitcnt lgkmcnt(0)
	v_ashrrev_i32_e32 v41, 31, v40
	v_lshlrev_b64 v[40:41], 12, v[40:41]
	v_cvt_pk_bf16_f32 v23, v36, v38
	v_lshl_add_u64 v[40:41], v[14:15], 0, v[40:41]
	global_store_dwordx4 v[40:41], v[20:23], off
	s_nop 0
	s_nop 0
	s_nop 0
	s_nop 0
	s_nop 0
	s_nop 0
	s_nop 0
	v_cvt_pk_bf16_f32 v20, v27, v25
	s_nop 0
	s_nop 0
	s_nop 0
	s_nop 0
	s_nop 0
	v_cvt_pk_bf16_f32 v21, v29, v31
	s_nop 0
	s_nop 0
	s_nop 0
	s_nop 0
	s_nop 0
	v_cvt_pk_bf16_f32 v22, v33, v35
	v_cvt_pk_bf16_f32 v23, v37, v39
	v_add_u32_e32 v24, s26, v16
	v_ashrrev_i32_e32 v25, 31, v24
	v_lshlrev_b64 v[24:25], 12, v[24:25]
	v_lshl_add_u64 v[24:25], v[14:15], 0, v[24:25]
	global_store_dwordx4 v[24:25], v[20:23], off
	ds_read2_b32 v[24:25], v19 offset0:49 offset1:57
	ds_read2_b32 v[26:27], v19 offset0:16 offset1:24
	ds_read2_b32 v[28:29], v19 offset0:82 offset1:90
	ds_read2_b32 v[30:31], v19 offset0:115 offset1:123
	ds_read2_b32 v[32:33], v19 offset0:148 offset1:156
	ds_read2_b32 v[34:35], v19 offset0:181 offset1:189
	ds_read2_b32 v[36:37], v19 offset0:214 offset1:222
	ds_read2_b32 v[38:39], v19 offset0:247 offset1:255
	s_waitcnt lgkmcnt(7)
	s_waitcnt lgkmcnt(6)
	v_cvt_pk_bf16_f32 v20, v26, v24
	s_waitcnt lgkmcnt(5)
	s_waitcnt lgkmcnt(4)
	v_cvt_pk_bf16_f32 v21, v28, v30
	s_waitcnt lgkmcnt(3)
	s_waitcnt lgkmcnt(2)
	v_cvt_pk_bf16_f32 v22, v32, v34
	s_waitcnt lgkmcnt(1)
	v_add_u32_e32 v40, s26, v17
	s_waitcnt lgkmcnt(0)
	v_ashrrev_i32_e32 v41, 31, v40
	v_lshlrev_b64 v[40:41], 12, v[40:41]
	v_cvt_pk_bf16_f32 v23, v36, v38
	v_lshl_add_u64 v[40:41], v[14:15], 0, v[40:41]
	global_store_dwordx4 v[40:41], v[20:23], off
	s_nop 0
	s_nop 0
	s_nop 0
	s_nop 0
	s_nop 0
	s_nop 0
	s_nop 0
	v_cvt_pk_bf16_f32 v20, v27, v25
	s_nop 0
	s_nop 0
	s_nop 0
	s_nop 0
	s_nop 0
	v_cvt_pk_bf16_f32 v21, v29, v31
	s_nop 0
	s_nop 0
	s_nop 0
	s_nop 0
	s_nop 0
	v_cvt_pk_bf16_f32 v22, v33, v35
	v_cvt_pk_bf16_f32 v23, v37, v39
	v_add_u32_e32 v24, s26, v18
	v_ashrrev_i32_e32 v25, 31, v24
	v_lshlrev_b64 v[24:25], 12, v[24:25]
	v_lshl_add_u64 v[14:15], v[14:15], 0, v[24:25]
	global_store_dwordx4 v[14:15], v[20:23], off
	s_waitcnt lgkmcnt(0)

.LBB0_1515:
	s_mul_hi_i32 s18, s9, 0x5397829d
	s_lshr_b32 s19, s18, 31
	s_ashr_i32 s18, s18, 13
	s_add_i32 s18, s18, s19
	s_mul_i32 s19, s18, 0xffff9e00
	s_add_i32 s26, s9, s19
	s_cmpk_gt_i32 s26, 0x17ff
	s_mov_b64 s[20:21], -1
	s_cbranch_scc0 .LBB0_1525
	s_cmpk_gt_u32 s26, 0x1fff
	s_cbranch_scc0 .LBB0_1522
	s_mov_b64 s[22:23], -1
	s_cmpk_gt_u32 s26, 0x4bff
	s_mul_hi_i32 s21, s18, 0x2c00000
	s_mul_i32 s20, s18, 0x2c00000
	s_cbranch_scc0 .LBB0_1519
	s_and_b32 s19, s26, 0x7fffffc0
	s_add_i32 s70, s19, 0xffffb400
	s_waitcnt lgkmcnt(0)
	s_add_u32 s27, s16, s20
	s_addc_u32 s28, s17, s21
	s_mul_hi_i32 s23, s18, 0x1600000
	s_mul_i32 s22, s18, 0x1600000
	s_and_b32 s19, s24, 0x7e0
	v_lshl_add_u64 v[14:15], v[2:3], 0, s[22:23]
	s_lshl_b32 s22, s19, 2
	v_add_u32_e32 v20, s70, v1
	s_add_u32 s22, s27, s22
	s_addc_u32 s23, s28, 0
	v_lshlrev_b32_e32 v82, 2, v4
	v_ashrrev_i32_e32 v21, 31, v20
	v_lshl_add_u64 v[22:23], s[22:23], 0, v[82:83]
	v_lshlrev_b64 v[20:21], 13, v[20:21]
	v_lshl_add_u64 v[48:49], v[22:23], 0, v[20:21]
	s_mov_b32 s22, 0x10000
	v_add_co_u32_e32 v24, vcc, s22, v48
	global_load_dwordx4 v[20:23], v[48:49], off
	s_nop 0
	v_addc_co_u32_e32 v25, vcc, 0, v49, vcc
	s_mov_b32 s22, 0x20000
	global_load_dwordx4 v[24:27], v[24:25], off
	v_add_co_u32_e32 v28, vcc, s22, v48
	s_mov_b32 s22, 0x30000
	s_nop 0
	v_addc_co_u32_e32 v29, vcc, 0, v49, vcc
	global_load_dwordx4 v[28:31], v[28:29], off
	v_add_co_u32_e32 v32, vcc, s22, v48
	s_mov_b32 s22, 0x40000
	s_nop 0
	v_addc_co_u32_e32 v33, vcc, 0, v49, vcc
	global_load_dwordx4 v[32:35], v[32:33], off
	v_add_co_u32_e32 v36, vcc, s22, v48
	s_mov_b32 s22, 0x50000
	s_nop 0
	v_addc_co_u32_e32 v37, vcc, 0, v49, vcc
	global_load_dwordx4 v[36:39], v[36:37], off
	v_add_co_u32_e32 v40, vcc, s22, v48
	s_mov_b32 s22, 0x60000
	s_nop 0
	v_addc_co_u32_e32 v41, vcc, 0, v49, vcc
	global_load_dwordx4 v[40:43], v[40:41], off
	v_add_co_u32_e32 v44, vcc, s22, v48
	s_mov_b32 s22, 0x70000
	s_nop 0
	v_addc_co_u32_e32 v45, vcc, 0, v49, vcc
	global_load_dwordx4 v[44:47], v[44:45], off
	v_add_co_u32_e32 v48, vcc, s22, v48
	v_add_u32_e32 v52, v5, v7
	s_nop 0
	v_addc_co_u32_e32 v49, vcc, 0, v49, vcc
	global_load_dwordx4 v[48:51], v[48:49], off
	s_lshl_b64 s[22:23], s[70:71], 1
	v_lshl_add_u64 v[14:15], v[14:15], 0, s[22:23]
	v_lshlrev_b32_e32 v82, 1, v6
	v_lshl_add_u64 v[14:15], v[14:15], 0, v[82:83]
	s_movk_i32 s27, 0x2c00
	s_mov_b32 s70, 0x21b1f000
	s_waitcnt vmcnt(7)
	ds_write2_b32 v52, v20, v21 offset1:1
	ds_write2_b32 v52, v22, v23 offset0:2 offset1:3
	v_add_u32_e32 v20, 0x420, v52
	s_waitcnt vmcnt(6)
	ds_write2_b32 v20, v24, v25 offset1:1
	v_add_u32_e32 v20, 0x428, v52
	ds_write2_b32 v20, v26, v27 offset1:1
	v_add_u32_e32 v20, 0x840, v52
	s_waitcnt vmcnt(5)
	ds_write2_b32 v20, v28, v29 offset1:1
	v_add_u32_e32 v20, 0x848, v52
	ds_write2_b32 v20, v30, v31 offset1:1
	v_add_u32_e32 v20, 0xc60, v52
	s_waitcnt vmcnt(4)
	ds_write2_b32 v20, v32, v33 offset1:1
	v_add_u32_e32 v20, 0xc68, v52
	ds_write2_b32 v20, v34, v35 offset1:1
	v_add_u32_e32 v20, 0x1080, v52
	s_waitcnt vmcnt(3)
	ds_write2_b32 v20, v36, v37 offset1:1
	v_add_u32_e32 v20, 0x1088, v52
	ds_write2_b32 v20, v38, v39 offset1:1
	v_add_u32_e32 v20, 0x14a0, v52
	s_waitcnt vmcnt(2)
	ds_write2_b32 v20, v40, v41 offset1:1
	v_add_u32_e32 v20, 0x14a8, v52
	ds_write2_b32 v20, v42, v43 offset1:1
	v_add_u32_e32 v20, 0x18c0, v52
	s_waitcnt vmcnt(1)
	ds_write2_b32 v20, v44, v45 offset1:1
	v_add_u32_e32 v20, 0x18c8, v52
	ds_write2_b32 v20, v46, v47 offset1:1
	v_add_u32_e32 v20, 0x1ce0, v52
	s_waitcnt vmcnt(0)
	ds_write2_b32 v20, v48, v49 offset1:1
	v_add_u32_e32 v20, 0x1ce8, v52
	ds_write2_b32 v20, v50, v51 offset1:1
	s_waitcnt lgkmcnt(0)
	ds_read2_b32 v[24:25], v19 offset0:33 offset1:41
	ds_read2_b32 v[26:27], v19 offset1:8
	ds_read2_b32 v[28:29], v19 offset0:66 offset1:74
	ds_read2_b32 v[30:31], v19 offset0:99 offset1:107
	ds_read2_b32 v[32:33], v19 offset0:132 offset1:140
	ds_read2_b32 v[34:35], v19 offset0:165 offset1:173
	ds_read2_b32 v[36:37], v19 offset0:198 offset1:206
	ds_read2_b32 v[38:39], v19 offset0:231 offset1:239
	s_waitcnt lgkmcnt(7)
	s_waitcnt lgkmcnt(6)
	v_cvt_pk_bf16_f32 v20, v26, v24
	s_waitcnt lgkmcnt(5)
	s_waitcnt lgkmcnt(4)
	v_cvt_pk_bf16_f32 v21, v28, v30
	s_waitcnt lgkmcnt(3)
	s_waitcnt lgkmcnt(2)
	v_cvt_pk_bf16_f32 v22, v32, v34
	s_waitcnt lgkmcnt(1)
	s_waitcnt lgkmcnt(0)
	s_nop 0
	s_nop 0
	s_nop 0
	v_cvt_pk_bf16_f32 v23, v36, v38
	v_add_u32_e32 v24, s19, v1
	v_mad_i64_i32 v[40:41], s[22:23], v24, s27, v[14:15]
	global_store_dwordx4 v[40:41], v[20:23], off
	s_nop 0
	s_nop 0
	s_nop 0
	s_nop 0
	s_nop 0
	s_nop 0
	s_nop 0
	v_cvt_pk_bf16_f32 v20, v27, v25
	s_nop 0
	s_nop 0
	s_nop 0
	s_nop 0
	s_nop 0
	v_cvt_pk_bf16_f32 v21, v29, v31
	s_nop 0
	s_nop 0
	s_nop 0
	s_nop 0
	s_nop 0
	v_cvt_pk_bf16_f32 v22, v33, v35
	s_nop 0
	s_nop 0
	s_nop 0
	v_cvt_pk_bf16_f32 v23, v37, v39
	v_add_u32_e32 v24, s19, v16
	v_mad_i64_i32 v[24:25], s[22:23], v24, s27, v[14:15]
	global_store_dwordx4 v[24:25], v[20:23], off
	ds_read2_b32 v[24:25], v19 offset0:49 offset1:57
	ds_read2_b32 v[26:27], v19 offset0:16 offset1:24
	ds_read2_b32 v[28:29], v19 offset0:82 offset1:90
	ds_read2_b32 v[30:31], v19 offset0:115 offset1:123
	ds_read2_b32 v[32:33], v19 offset0:148 offset1:156
	ds_read2_b32 v[34:35], v19 offset0:181 offset1:189
	ds_read2_b32 v[36:37], v19 offset0:214 offset1:222
	ds_read2_b32 v[38:39], v19 offset0:247 offset1:255
	s_waitcnt lgkmcnt(7)
	s_waitcnt lgkmcnt(6)
	v_cvt_pk_bf16_f32 v20, v26, v24
	s_waitcnt lgkmcnt(5)
	s_waitcnt lgkmcnt(4)
	v_cvt_pk_bf16_f32 v21, v28, v30
	s_waitcnt lgkmcnt(3)
	s_waitcnt lgkmcnt(2)
	v_cvt_pk_bf16_f32 v22, v32, v34
	s_waitcnt lgkmcnt(1)
	s_waitcnt lgkmcnt(0)
	s_nop 0
	s_nop 0
	s_nop 0
	v_cvt_pk_bf16_f32 v23, v36, v38
	v_add_u32_e32 v24, s19, v17
	v_mad_i64_i32 v[40:41], s[22:23], v24, s27, v[14:15]
	global_store_dwordx4 v[40:41], v[20:23], off
	s_nop 0
	s_nop 0
	s_nop 0
	s_nop 0
	s_nop 0
	s_nop 0
	s_nop 0
	v_cvt_pk_bf16_f32 v20, v27, v25
	s_nop 0
	s_nop 0
	s_nop 0
	s_nop 0
	s_nop 0
	v_cvt_pk_bf16_f32 v21, v29, v31
	s_nop 0
	s_nop 0
	s_nop 0
	s_nop 0
	s_nop 0
	v_cvt_pk_bf16_f32 v22, v33, v35
	s_nop 0
	s_nop 0
	s_nop 0
	v_cvt_pk_bf16_f32 v23, v37, v39
	v_add_u32_e32 v24, s19, v18
	v_mad_i64_i32 v[14:15], s[22:23], v24, s27, v[14:15]
	global_store_dwordx4 v[14:15], v[20:23], off
	s_waitcnt lgkmcnt(0)
	s_mov_b64 s[22:23], 0
.LBB0_1519:
	s_andn2_b64 vcc, exec, s[22:23]
	s_cbranch_vccnz .LBB0_1521
	s_add_i32 s19, s26, 0xe000
	s_and_b32 s22, s19, 0xffff
	s_mul_i32 s22, s22, 0xba2f
	s_lshr_b32 s22, s22, 24
	s_mul_i32 s23, s22, 0x160
	s_sub_i32 s23, s19, s23
	s_and_b32 s27, s23, 0xffff
	s_lshl_b32 s19, s27, 5
	s_mul_i32 s29, s18, 0x5800000
	s_mul_hi_i32 s28, s18, 0x5800000
	s_waitcnt lgkmcnt(0)
	s_add_u32 s29, s14, s29
	s_addc_u32 s28, s15, s28
	v_lshl_add_u64 v[14:15], v[8:9], 0, s[20:21]
	s_bfe_i32 s20, s23, 0x10002
	s_lshl_b32 s21, s27, 4
	s_and_b32 s20, s20, 0x1600
	s_and_b32 s21, s21, 0x1f80
	s_add_i32 s20, s20, s21
	s_and_b32 s21, s19, 0x60
	s_or_b32 s20, s20, s21
	s_lshl_b32 s20, s20, 2
	s_add_u32 s20, s29, s20
	s_addc_u32 s21, s28, 0
	v_lshlrev_b32_e32 v82, 2, v4
	v_lshl_add_u32 v50, s22, 6, v1
	v_lshl_add_u64 v[48:49], s[20:21], 0, v[82:83]
	s_mov_b32 s23, 0xb000
	v_mad_i64_i32 v[20:21], s[20:21], v50, s23, v[48:49]
	v_add_u32_e32 v24, 8, v50
	global_load_dwordx4 v[20:23], v[20:21], off
	v_mad_i64_i32 v[24:25], s[20:21], v24, s23, v[48:49]
	global_load_dwordx4 v[24:27], v[24:25], off
	v_add_u32_e32 v28, 16, v50
	v_mad_i64_i32 v[28:29], s[20:21], v28, s23, v[48:49]
	global_load_dwordx4 v[28:31], v[28:29], off
	v_add_u32_e32 v32, 24, v50
	v_mad_i64_i32 v[32:33], s[20:21], v32, s23, v[48:49]
	global_load_dwordx4 v[32:35], v[32:33], off
	v_add_u32_e32 v36, 32, v50
	v_mad_i64_i32 v[36:37], s[20:21], v36, s23, v[48:49]
	global_load_dwordx4 v[36:39], v[36:37], off
	v_add_u32_e32 v40, 40, v50
	v_mad_i64_i32 v[40:41], s[20:21], v40, s23, v[48:49]
	global_load_dwordx4 v[40:43], v[40:41], off
	v_add_u32_e32 v44, 48, v50
	v_mad_i64_i32 v[44:45], s[20:21], v44, s23, v[48:49]
	global_load_dwordx4 v[44:47], v[44:45], off
	v_add_u32_e32 v50, 56, v50
	v_mad_i64_i32 v[48:49], s[20:21], v50, s23, v[48:49]
	global_load_dwordx4 v[48:51], v[48:49], off
	v_add_u32_e32 v52, v5, v7
	s_lshl_b32 s70, s22, 7
	v_lshl_add_u64 v[14:15], v[14:15], 0, s[70:71]
	v_lshlrev_b32_e32 v82, 1, v6
	v_lshl_add_u64 v[14:15], v[14:15], 0, v[82:83]
	s_mov_b32 s70, 0x21b1f000
	s_waitcnt vmcnt(7)
	ds_write2_b32 v52, v20, v21 offset1:1
	ds_write2_b32 v52, v22, v23 offset0:2 offset1:3
	v_add_u32_e32 v20, 0x420, v52
	s_waitcnt vmcnt(6)
	ds_write2_b32 v20, v24, v25 offset1:1
	v_add_u32_e32 v20, 0x428, v52
	ds_write2_b32 v20, v26, v27 offset1:1
	v_add_u32_e32 v20, 0x840, v52
	s_waitcnt vmcnt(5)
	ds_write2_b32 v20, v28, v29 offset1:1
	v_add_u32_e32 v20, 0x848, v52
	ds_write2_b32 v20, v30, v31 offset1:1
	v_add_u32_e32 v20, 0xc60, v52
	s_waitcnt vmcnt(4)
	ds_write2_b32 v20, v32, v33 offset1:1
	v_add_u32_e32 v20, 0xc68, v52
	ds_write2_b32 v20, v34, v35 offset1:1
	v_add_u32_e32 v20, 0x1080, v52
	s_waitcnt vmcnt(3)
	ds_write2_b32 v20, v36, v37 offset1:1
	v_add_u32_e32 v20, 0x1088, v52
	ds_write2_b32 v20, v38, v39 offset1:1
	v_add_u32_e32 v20, 0x14a0, v52
	s_waitcnt vmcnt(2)
	ds_write2_b32 v20, v40, v41 offset1:1
	v_add_u32_e32 v20, 0x14a8, v52
	ds_write2_b32 v20, v42, v43 offset1:1
	v_add_u32_e32 v20, 0x18c0, v52
	s_waitcnt vmcnt(1)
	ds_write2_b32 v20, v44, v45 offset1:1
	v_add_u32_e32 v20, 0x18c8, v52
	ds_write2_b32 v20, v46, v47 offset1:1
	v_add_u32_e32 v20, 0x1ce0, v52
	s_waitcnt vmcnt(0)
	ds_write2_b32 v20, v48, v49 offset1:1
	v_add_u32_e32 v20, 0x1ce8, v52
	ds_write2_b32 v20, v50, v51 offset1:1
	s_waitcnt lgkmcnt(0)
	ds_read2_b32 v[24:25], v19 offset0:33 offset1:41
	ds_read2_b32 v[26:27], v19 offset1:8
	ds_read2_b32 v[28:29], v19 offset0:66 offset1:74
	ds_read2_b32 v[30:31], v19 offset0:99 offset1:107
	ds_read2_b32 v[32:33], v19 offset0:132 offset1:140
	ds_read2_b32 v[34:35], v19 offset0:165 offset1:173
	ds_read2_b32 v[36:37], v19 offset0:198 offset1:206
	ds_read2_b32 v[38:39], v19 offset0:231 offset1:239
	s_waitcnt lgkmcnt(7)
	s_waitcnt lgkmcnt(6)
	v_cvt_pk_bf16_f32 v20, v26, v24
	s_waitcnt lgkmcnt(5)
	s_waitcnt lgkmcnt(4)
	v_cvt_pk_bf16_f32 v21, v28, v30
	s_waitcnt lgkmcnt(3)
	s_waitcnt lgkmcnt(2)
	v_cvt_pk_bf16_f32 v22, v32, v34
	s_waitcnt lgkmcnt(1)
	v_add_u32_e32 v40, s19, v1
	s_waitcnt lgkmcnt(0)
	v_ashrrev_i32_e32 v41, 31, v40
	v_lshlrev_b64 v[40:41], 12, v[40:41]
	v_cvt_pk_bf16_f32 v23, v36, v38
	v_lshl_add_u64 v[40:41], v[14:15], 0, v[40:41]
	global_store_dwordx4 v[40:41], v[20:23], off
	s_nop 0
	s_nop 0
	s_nop 0
	s_nop 0
	s_nop 0
	s_nop 0
	s_nop 0
	v_cvt_pk_bf16_f32 v20, v27, v25
	s_nop 0
	s_nop 0
	s_nop 0
	s_nop 0
	s_nop 0
	v_cvt_pk_bf16_f32 v21, v29, v31
	s_nop 0
	s_nop 0
	s_nop 0
	s_nop 0
	s_nop 0
	v_cvt_pk_bf16_f32 v22, v33, v35
	v_cvt_pk_bf16_f32 v23, v37, v39
	v_add_u32_e32 v24, s19, v16
	v_ashrrev_i32_e32 v25, 31, v24
	v_lshlrev_b64 v[24:25], 12, v[24:25]
	v_lshl_add_u64 v[24:25], v[14:15], 0, v[24:25]
	global_store_dwordx4 v[24:25], v[20:23], off
	ds_read2_b32 v[24:25], v19 offset0:49 offset1:57
	ds_read2_b32 v[26:27], v19 offset0:16 offset1:24
	ds_read2_b32 v[28:29], v19 offset0:82 offset1:90
	ds_read2_b32 v[30:31], v19 offset0:115 offset1:123
	ds_read2_b32 v[32:33], v19 offset0:148 offset1:156
	ds_read2_b32 v[34:35], v19 offset0:181 offset1:189
	ds_read2_b32 v[36:37], v19 offset0:214 offset1:222
	ds_read2_b32 v[38:39], v19 offset0:247 offset1:255
	s_waitcnt lgkmcnt(7)
	s_waitcnt lgkmcnt(6)
	v_cvt_pk_bf16_f32 v20, v26, v24
	s_waitcnt lgkmcnt(5)
	s_waitcnt lgkmcnt(4)
	v_cvt_pk_bf16_f32 v21, v28, v30
	s_waitcnt lgkmcnt(3)
	s_waitcnt lgkmcnt(2)
	v_cvt_pk_bf16_f32 v22, v32, v34
	s_waitcnt lgkmcnt(1)
	v_add_u32_e32 v40, s19, v17
	s_waitcnt lgkmcnt(0)
	v_ashrrev_i32_e32 v41, 31, v40
	v_lshlrev_b64 v[40:41], 12, v[40:41]
	v_cvt_pk_bf16_f32 v23, v36, v38
	v_lshl_add_u64 v[40:41], v[14:15], 0, v[40:41]
	global_store_dwordx4 v[40:41], v[20:23], off
	s_nop 0
	s_nop 0
	s_nop 0
	s_nop 0
	s_nop 0
	s_nop 0
	s_nop 0
	v_cvt_pk_bf16_f32 v20, v27, v25
	s_nop 0
	s_nop 0
	s_nop 0
	s_nop 0
	s_nop 0
	v_cvt_pk_bf16_f32 v21, v29, v31
	s_nop 0
	s_nop 0
	s_nop 0
	s_nop 0
	s_nop 0
	v_cvt_pk_bf16_f32 v22, v33, v35
	v_cvt_pk_bf16_f32 v23, v37, v39
	v_add_u32_e32 v24, s19, v18
	v_ashrrev_i32_e32 v25, 31, v24
	v_lshlrev_b64 v[24:25], 12, v[24:25]
	v_lshl_add_u64 v[14:15], v[14:15], 0, v[24:25]
	global_store_dwordx4 v[14:15], v[20:23], off
	s_waitcnt lgkmcnt(0)

.LBB0_1522:
	s_andn2_b64 vcc, exec, s[20:21]
	s_cbranch_vccnz .LBB0_1524
	s_and_b32 s19, s26, 0x1fc0
	s_add_i32 s70, s19, 0xffffe800
	s_ashr_i32 s19, s18, 31
	s_lshl_b64 s[20:21], s[18:19], 24
	s_waitcnt lgkmcnt(0)
	s_add_u32 s22, s12, s20
	s_addc_u32 s23, s13, s21
	s_lshl_b64 s[20:21], s[18:19], 23
	s_and_b32 s19, s24, 0x7e0
	v_lshl_add_u64 v[14:15], v[10:11], 0, s[20:21]
	s_lshl_b32 s20, s19, 2
	v_add_u32_e32 v20, s70, v1
	s_add_u32 s20, s22, s20
	s_addc_u32 s21, s23, 0
	v_lshlrev_b32_e32 v82, 2, v4
	v_ashrrev_i32_e32 v21, 31, v20
	v_lshl_add_u64 v[22:23], s[20:21], 0, v[82:83]
	v_lshlrev_b64 v[20:21], 13, v[20:21]
	v_lshl_add_u64 v[48:49], v[22:23], 0, v[20:21]
	s_mov_b32 s20, 0x10000
	v_add_co_u32_e32 v24, vcc, s20, v48
	global_load_dwordx4 v[20:23], v[48:49], off
	s_nop 0
	v_addc_co_u32_e32 v25, vcc, 0, v49, vcc
	s_mov_b32 s20, 0x20000
	global_load_dwordx4 v[24:27], v[24:25], off
	v_add_co_u32_e32 v28, vcc, s20, v48
	s_mov_b32 s20, 0x30000
	s_nop 0
	v_addc_co_u32_e32 v29, vcc, 0, v49, vcc
	global_load_dwordx4 v[28:31], v[28:29], off
	v_add_co_u32_e32 v32, vcc, s20, v48
	s_mov_b32 s20, 0x40000
	s_nop 0
	v_addc_co_u32_e32 v33, vcc, 0, v49, vcc
	global_load_dwordx4 v[32:35], v[32:33], off
	v_add_co_u32_e32 v36, vcc, s20, v48
	s_mov_b32 s20, 0x50000
	s_nop 0
	v_addc_co_u32_e32 v37, vcc, 0, v49, vcc
	global_load_dwordx4 v[36:39], v[36:37], off
	v_add_co_u32_e32 v40, vcc, s20, v48
	s_mov_b32 s20, 0x60000
	s_nop 0
	v_addc_co_u32_e32 v41, vcc, 0, v49, vcc
	global_load_dwordx4 v[40:43], v[40:41], off
	v_add_co_u32_e32 v44, vcc, s20, v48
	s_mov_b32 s20, 0x70000
	s_nop 0
	v_addc_co_u32_e32 v45, vcc, 0, v49, vcc
	global_load_dwordx4 v[44:47], v[44:45], off
	v_add_co_u32_e32 v48, vcc, s20, v48
	v_add_u32_e32 v52, v5, v7
	s_nop 0
	v_addc_co_u32_e32 v49, vcc, 0, v49, vcc
	global_load_dwordx4 v[48:51], v[48:49], off
	s_lshl_b64 s[20:21], s[70:71], 1
	v_lshl_add_u64 v[14:15], v[14:15], 0, s[20:21]
	v_lshlrev_b32_e32 v82, 1, v6
	v_lshl_add_u64 v[14:15], v[14:15], 0, v[82:83]
	s_mov_b32 s70, 0x21b1f000
	s_waitcnt vmcnt(7)
	ds_write2_b32 v52, v20, v21 offset1:1
	ds_write2_b32 v52, v22, v23 offset0:2 offset1:3
	v_add_u32_e32 v20, 0x420, v52
	s_waitcnt vmcnt(6)
	ds_write2_b32 v20, v24, v25 offset1:1
	v_add_u32_e32 v20, 0x428, v52
	ds_write2_b32 v20, v26, v27 offset1:1
	v_add_u32_e32 v20, 0x840, v52
	s_waitcnt vmcnt(5)
	ds_write2_b32 v20, v28, v29 offset1:1
	v_add_u32_e32 v20, 0x848, v52
	ds_write2_b32 v20, v30, v31 offset1:1
	v_add_u32_e32 v20, 0xc60, v52
	s_waitcnt vmcnt(4)
	ds_write2_b32 v20, v32, v33 offset1:1
	v_add_u32_e32 v20, 0xc68, v52
	ds_write2_b32 v20, v34, v35 offset1:1
	v_add_u32_e32 v20, 0x1080, v52
	s_waitcnt vmcnt(3)
	ds_write2_b32 v20, v36, v37 offset1:1
	v_add_u32_e32 v20, 0x1088, v52
	ds_write2_b32 v20, v38, v39 offset1:1
	v_add_u32_e32 v20, 0x14a0, v52
	s_waitcnt vmcnt(2)
	ds_write2_b32 v20, v40, v41 offset1:1
	v_add_u32_e32 v20, 0x14a8, v52
	ds_write2_b32 v20, v42, v43 offset1:1
	v_add_u32_e32 v20, 0x18c0, v52
	v_add_u32_e32 v40, s19, v1
	v_ashrrev_i32_e32 v41, 31, v40
	s_waitcnt vmcnt(1)
	ds_write2_b32 v20, v44, v45 offset1:1
	v_add_u32_e32 v20, 0x18c8, v52
	ds_write2_b32 v20, v46, v47 offset1:1
	v_add_u32_e32 v20, 0x1ce0, v52
	v_lshlrev_b64 v[40:41], 12, v[40:41]
	v_lshl_add_u64 v[40:41], v[14:15], 0, v[40:41]
	s_waitcnt vmcnt(0)
	ds_write2_b32 v20, v48, v49 offset1:1
	v_add_u32_e32 v20, 0x1ce8, v52
	ds_write2_b32 v20, v50, v51 offset1:1
	s_waitcnt lgkmcnt(0)
	ds_read2_b32 v[24:25], v19 offset0:33 offset1:41
	ds_read2_b32 v[26:27], v19 offset1:8
	ds_read2_b32 v[28:29], v19 offset0:66 offset1:74
	ds_read2_b32 v[30:31], v19 offset0:99 offset1:107
	ds_read2_b32 v[32:33], v19 offset0:132 offset1:140
	ds_read2_b32 v[34:35], v19 offset0:165 offset1:173
	ds_read2_b32 v[36:37], v19 offset0:198 offset1:206
	ds_read2_b32 v[38:39], v19 offset0:231 offset1:239
	s_waitcnt lgkmcnt(7)
	s_waitcnt lgkmcnt(6)
	v_cvt_pk_bf16_f32 v20, v26, v24
	s_waitcnt lgkmcnt(5)
	s_waitcnt lgkmcnt(4)
	v_cvt_pk_bf16_f32 v21, v28, v30
	s_waitcnt lgkmcnt(3)
	s_waitcnt lgkmcnt(2)
	v_cvt_pk_bf16_f32 v22, v32, v34
	s_waitcnt lgkmcnt(1)
	s_nop 0
	s_nop 0
	s_waitcnt lgkmcnt(0)
	s_nop 0
	s_nop 0
	s_nop 0
	v_cvt_pk_bf16_f32 v23, v36, v38
	global_store_dwordx4 v[40:41], v[20:23], off
	s_nop 0
	s_nop 0
	s_nop 0
	s_nop 0
	s_nop 0
	s_nop 0
	s_nop 0
	v_cvt_pk_bf16_f32 v20, v27, v25
	s_nop 0
	s_nop 0
	s_nop 0
	s_nop 0
	s_nop 0
	v_cvt_pk_bf16_f32 v21, v29, v31
	s_nop 0
	s_nop 0
	s_nop 0
	s_nop 0
	s_nop 0
	v_cvt_pk_bf16_f32 v22, v33, v35
	v_cvt_pk_bf16_f32 v23, v37, v39
	v_add_u32_e32 v24, s19, v16
	v_ashrrev_i32_e32 v25, 31, v24
	v_lshlrev_b64 v[24:25], 12, v[24:25]
	v_lshl_add_u64 v[24:25], v[14:15], 0, v[24:25]
	global_store_dwordx4 v[24:25], v[20:23], off
	ds_read2_b32 v[24:25], v19 offset0:49 offset1:57
	ds_read2_b32 v[26:27], v19 offset0:16 offset1:24
	ds_read2_b32 v[28:29], v19 offset0:82 offset1:90
	ds_read2_b32 v[30:31], v19 offset0:115 offset1:123
	ds_read2_b32 v[32:33], v19 offset0:148 offset1:156
	ds_read2_b32 v[34:35], v19 offset0:181 offset1:189
	ds_read2_b32 v[36:37], v19 offset0:214 offset1:222
	ds_read2_b32 v[38:39], v19 offset0:247 offset1:255
	s_waitcnt lgkmcnt(7)
	s_waitcnt lgkmcnt(6)
	v_cvt_pk_bf16_f32 v20, v26, v24
	s_waitcnt lgkmcnt(5)
	s_waitcnt lgkmcnt(4)
	v_cvt_pk_bf16_f32 v21, v28, v30
	s_waitcnt lgkmcnt(3)
	s_waitcnt lgkmcnt(2)
	v_cvt_pk_bf16_f32 v22, v32, v34
	s_waitcnt lgkmcnt(1)
	v_add_u32_e32 v40, s19, v17
	s_waitcnt lgkmcnt(0)
	v_ashrrev_i32_e32 v41, 31, v40
	v_lshlrev_b64 v[40:41], 12, v[40:41]
	v_cvt_pk_bf16_f32 v23, v36, v38
	v_lshl_add_u64 v[40:41], v[14:15], 0, v[40:41]
	global_store_dwordx4 v[40:41], v[20:23], off
	s_nop 0
	s_nop 0
	s_nop 0
	s_nop 0
	s_nop 0
	s_nop 0
	s_nop 0
	v_cvt_pk_bf16_f32 v20, v27, v25
	s_nop 0
	s_nop 0
	s_nop 0
	s_nop 0
	s_nop 0
	v_cvt_pk_bf16_f32 v21, v29, v31
	s_nop 0
	s_nop 0
	s_nop 0
	s_nop 0
	s_nop 0
	v_cvt_pk_bf16_f32 v22, v33, v35
	v_cvt_pk_bf16_f32 v23, v37, v39
	v_add_u32_e32 v24, s19, v18
	v_ashrrev_i32_e32 v25, 31, v24
	v_lshlrev_b64 v[24:25], 12, v[24:25]
	v_lshl_add_u64 v[14:15], v[14:15], 0, v[24:25]
	global_store_dwordx4 v[14:15], v[20:23], off
	s_waitcnt lgkmcnt(0)

.LBB0_1631:
	s_mul_i32 s22, s18, 0x3020000
	s_sext_i32_i16 s21, s19
	s_mul_hi_i32 s19, s18, 0x3020000
	s_waitcnt lgkmcnt(0)
	s_add_u32 s22, s10, s22
	s_addc_u32 s23, s11, s19
	s_mul_hi_i32 s19, s18, 0x1800000
	s_mul_i32 s18, s18, 0x1800000
	v_lshl_add_u64 v[14:15], v[12:13], 0, s[18:19]
	s_lshl_b32 s18, s21, 6
	s_ashr_i32 s21, s20, 31
	s_lshl_b64 s[20:21], s[20:21], 2
	s_add_u32 s20, s22, s20
	s_addc_u32 s21, s23, s21
	v_lshlrev_b32_e32 v82, 2, v4
	v_add_u32_e32 v50, s18, v1
	v_lshl_add_u64 v[48:49], s[20:21], 0, v[82:83]
	v_mad_i64_i32 v[20:21], s[20:21], v50, s40, v[48:49]
	v_add_u32_e32 v24, 8, v50
	global_load_dwordx4 v[20:23], v[20:21], off
	v_mad_i64_i32 v[24:25], s[20:21], v24, s40, v[48:49]
	global_load_dwordx4 v[24:27], v[24:25], off
	v_add_u32_e32 v28, 16, v50
	v_mad_i64_i32 v[28:29], s[20:21], v28, s40, v[48:49]
	global_load_dwordx4 v[28:31], v[28:29], off
	v_add_u32_e32 v32, 24, v50
	v_mad_i64_i32 v[32:33], s[20:21], v32, s40, v[48:49]
	global_load_dwordx4 v[32:35], v[32:33], off
	v_add_u32_e32 v36, 32, v50
	v_mad_i64_i32 v[36:37], s[20:21], v36, s40, v[48:49]
	global_load_dwordx4 v[36:39], v[36:37], off
	v_add_u32_e32 v40, 40, v50
	v_mad_i64_i32 v[40:41], s[20:21], v40, s40, v[48:49]
	global_load_dwordx4 v[40:43], v[40:41], off
	v_add_u32_e32 v44, 48, v50
	v_mad_i64_i32 v[44:45], s[20:21], v44, s40, v[48:49]
	global_load_dwordx4 v[44:47], v[44:45], off
	v_add_u32_e32 v50, 56, v50
	v_mad_i64_i32 v[48:49], s[20:21], v50, s40, v[48:49]
	global_load_dwordx4 v[48:51], v[48:49], off
	v_add_u32_e32 v52, v5, v7
	s_ashr_i32 s19, s18, 31
	s_lshl_b64 s[18:19], s[18:19], 1
	v_lshl_add_u64 v[14:15], v[14:15], 0, s[18:19]
	v_lshlrev_b32_e32 v82, 1, v6
	v_lshl_add_u64 v[14:15], v[14:15], 0, v[82:83]
	s_waitcnt vmcnt(7)
	ds_write2_b32 v52, v20, v21 offset1:1
	ds_write2_b32 v52, v22, v23 offset0:2 offset1:3
	v_add_u32_e32 v20, 0x420, v52
	s_waitcnt vmcnt(6)
	ds_write2_b32 v20, v24, v25 offset1:1
	v_add_u32_e32 v20, 0x428, v52
	ds_write2_b32 v20, v26, v27 offset1:1
	v_add_u32_e32 v20, 0x840, v52
	s_waitcnt vmcnt(5)
	ds_write2_b32 v20, v28, v29 offset1:1
	v_add_u32_e32 v20, 0x848, v52
	ds_write2_b32 v20, v30, v31 offset1:1
	v_add_u32_e32 v20, 0xc60, v52
	s_waitcnt vmcnt(4)
	ds_write2_b32 v20, v32, v33 offset1:1
	v_add_u32_e32 v20, 0xc68, v52
	ds_write2_b32 v20, v34, v35 offset1:1
	v_add_u32_e32 v20, 0x1080, v52
	s_waitcnt vmcnt(3)
	ds_write2_b32 v20, v36, v37 offset1:1
	v_add_u32_e32 v20, 0x1088, v52
	ds_write2_b32 v20, v38, v39 offset1:1
	v_add_u32_e32 v20, 0x14a0, v52
	s_waitcnt vmcnt(2)
	ds_write2_b32 v20, v40, v41 offset1:1
	v_add_u32_e32 v20, 0x14a8, v52
	ds_write2_b32 v20, v42, v43 offset1:1
	v_add_u32_e32 v20, 0x18c0, v52
	s_waitcnt vmcnt(1)
	ds_write2_b32 v20, v44, v45 offset1:1
	v_add_u32_e32 v20, 0x18c8, v52
	ds_write2_b32 v20, v46, v47 offset1:1
	v_add_u32_e32 v20, 0x1ce0, v52
	s_waitcnt vmcnt(0)
	ds_write2_b32 v20, v48, v49 offset1:1
	v_add_u32_e32 v20, 0x1ce8, v52
	ds_write2_b32 v20, v50, v51 offset1:1
	s_waitcnt lgkmcnt(0)
	ds_read2_b32 v[24:25], v19 offset0:33 offset1:41
	ds_read2_b32 v[26:27], v19 offset1:8
	ds_read2_b32 v[28:29], v19 offset0:66 offset1:74
	ds_read2_b32 v[30:31], v19 offset0:99 offset1:107
	ds_read2_b32 v[32:33], v19 offset0:132 offset1:140
	ds_read2_b32 v[34:35], v19 offset0:165 offset1:173
	ds_read2_b32 v[36:37], v19 offset0:198 offset1:206
	ds_read2_b32 v[38:39], v19 offset0:231 offset1:239
	s_waitcnt lgkmcnt(7)
	s_waitcnt lgkmcnt(6)
	v_cvt_pk_bf16_f32 v20, v26, v24
	s_waitcnt lgkmcnt(5)
	s_waitcnt lgkmcnt(4)
	v_cvt_pk_bf16_f32 v21, v28, v30
	s_waitcnt lgkmcnt(3)
	s_waitcnt lgkmcnt(2)
	v_cvt_pk_bf16_f32 v22, v32, v34
	s_waitcnt lgkmcnt(1)
	v_add_u32_e32 v40, s25, v1
	s_waitcnt lgkmcnt(0)
	v_ashrrev_i32_e32 v41, 31, v40
	v_lshlrev_b64 v[40:41], 12, v[40:41]
	v_cvt_pk_bf16_f32 v23, v36, v38
	v_lshl_add_u64 v[40:41], v[14:15], 0, v[40:41]
	global_store_dwordx4 v[40:41], v[20:23], off
	s_nop 0
	s_nop 0
	s_nop 0
	s_nop 0
	s_nop 0
	s_nop 0
	s_nop 0
	v_cvt_pk_bf16_f32 v20, v27, v25
	s_nop 0
	s_nop 0
	s_nop 0
	s_nop 0
	s_nop 0
	v_cvt_pk_bf16_f32 v21, v29, v31
	s_nop 0
	s_nop 0
	s_nop 0
	s_nop 0
	s_nop 0
	v_cvt_pk_bf16_f32 v22, v33, v35
	v_cvt_pk_bf16_f32 v23, v37, v39
	v_add_u32_e32 v24, s25, v16
	v_ashrrev_i32_e32 v25, 31, v24
	v_lshlrev_b64 v[24:25], 12, v[24:25]
	v_lshl_add_u64 v[24:25], v[14:15], 0, v[24:25]
	global_store_dwordx4 v[24:25], v[20:23], off
	ds_read2_b32 v[24:25], v19 offset0:49 offset1:57
	ds_read2_b32 v[26:27], v19 offset0:16 offset1:24
	ds_read2_b32 v[28:29], v19 offset0:82 offset1:90
	ds_read2_b32 v[30:31], v19 offset0:115 offset1:123
	ds_read2_b32 v[32:33], v19 offset0:148 offset1:156
	ds_read2_b32 v[34:35], v19 offset0:181 offset1:189
	ds_read2_b32 v[36:37], v19 offset0:214 offset1:222
	ds_read2_b32 v[38:39], v19 offset0:247 offset1:255
	s_waitcnt lgkmcnt(7)
	s_waitcnt lgkmcnt(6)
	v_cvt_pk_bf16_f32 v20, v26, v24
	s_waitcnt lgkmcnt(5)
	s_waitcnt lgkmcnt(4)
	v_cvt_pk_bf16_f32 v21, v28, v30
	s_waitcnt lgkmcnt(3)
	s_waitcnt lgkmcnt(2)
	v_cvt_pk_bf16_f32 v22, v32, v34
	s_waitcnt lgkmcnt(1)
	v_add_u32_e32 v40, s25, v17
	s_waitcnt lgkmcnt(0)
	v_ashrrev_i32_e32 v41, 31, v40
	v_lshlrev_b64 v[40:41], 12, v[40:41]
	v_cvt_pk_bf16_f32 v23, v36, v38
	v_lshl_add_u64 v[40:41], v[14:15], 0, v[40:41]
	global_store_dwordx4 v[40:41], v[20:23], off
	s_nop 0
	s_nop 0
	s_nop 0
	s_nop 0
	s_nop 0
	s_nop 0
	s_nop 0
	v_cvt_pk_bf16_f32 v20, v27, v25
	s_nop 0
	s_nop 0
	s_nop 0
	s_nop 0
	s_nop 0
	v_cvt_pk_bf16_f32 v21, v29, v31
	s_nop 0
	s_nop 0
	s_nop 0
	s_nop 0
	s_nop 0
	v_cvt_pk_bf16_f32 v22, v33, v35
	v_cvt_pk_bf16_f32 v23, v37, v39
	v_add_u32_e32 v24, s25, v18
	v_ashrrev_i32_e32 v25, 31, v24
	v_lshlrev_b64 v[24:25], 12, v[24:25]
	v_lshl_add_u64 v[14:15], v[14:15], 0, v[24:25]
	global_store_dwordx4 v[14:15], v[20:23], off
	s_waitcnt lgkmcnt(0)

.LBB0_1633:
	s_mul_hi_i32 s18, s24, 0x5397829d
	s_lshr_b32 s19, s18, 31
	s_ashr_i32 s18, s18, 13
	s_add_i32 s18, s18, s19
	s_mul_i32 s19, s18, 0xffff9e00
	s_add_i32 s25, s24, s19
	s_cmpk_gt_i32 s25, 0x17ff
	s_mov_b64 s[20:21], -1
	s_cbranch_scc0 .LBB0_1643
	s_cmpk_gt_u32 s25, 0x1fff
	s_cbranch_scc0 .LBB0_1640
	s_mov_b64 s[22:23], -1
	s_cmpk_gt_u32 s25, 0x4bff
	s_mul_hi_i32 s21, s18, 0x2c00000
	s_mul_i32 s20, s18, 0x2c00000
	s_cbranch_scc0 .LBB0_1637
	s_and_b32 s19, s25, 0x7fffffc0
	s_add_i32 s70, s19, 0xffffb400
	s_waitcnt lgkmcnt(0)
	s_add_u32 s26, s16, s20
	s_addc_u32 s27, s17, s21
	s_mul_hi_i32 s23, s18, 0x1600000
	s_mul_i32 s22, s18, 0x1600000
	s_and_b32 s19, s8, 0x7e0
	v_lshl_add_u64 v[14:15], v[2:3], 0, s[22:23]
	s_lshl_b32 s22, s19, 2
	v_add_u32_e32 v20, s70, v1
	s_add_u32 s22, s26, s22
	s_addc_u32 s23, s27, 0
	v_lshlrev_b32_e32 v82, 2, v4
	v_ashrrev_i32_e32 v21, 31, v20
	v_lshl_add_u64 v[22:23], s[22:23], 0, v[82:83]
	v_lshlrev_b64 v[20:21], 13, v[20:21]
	v_lshl_add_u64 v[48:49], v[22:23], 0, v[20:21]
	s_mov_b32 s22, 0x10000
	v_add_co_u32_e32 v24, vcc, s22, v48
	global_load_dwordx4 v[20:23], v[48:49], off
	s_nop 0
	v_addc_co_u32_e32 v25, vcc, 0, v49, vcc
	s_mov_b32 s22, 0x20000
	global_load_dwordx4 v[24:27], v[24:25], off
	v_add_co_u32_e32 v28, vcc, s22, v48
	s_mov_b32 s22, 0x30000
	s_nop 0
	v_addc_co_u32_e32 v29, vcc, 0, v49, vcc
	global_load_dwordx4 v[28:31], v[28:29], off
	v_add_co_u32_e32 v32, vcc, s22, v48
	s_mov_b32 s22, 0x40000
	s_nop 0
	v_addc_co_u32_e32 v33, vcc, 0, v49, vcc
	global_load_dwordx4 v[32:35], v[32:33], off
	v_add_co_u32_e32 v36, vcc, s22, v48
	s_mov_b32 s22, 0x50000
	s_nop 0
	v_addc_co_u32_e32 v37, vcc, 0, v49, vcc
	global_load_dwordx4 v[36:39], v[36:37], off
	v_add_co_u32_e32 v40, vcc, s22, v48
	s_mov_b32 s22, 0x60000
	s_nop 0
	v_addc_co_u32_e32 v41, vcc, 0, v49, vcc
	global_load_dwordx4 v[40:43], v[40:41], off
	v_add_co_u32_e32 v44, vcc, s22, v48
	s_mov_b32 s22, 0x70000
	s_nop 0
	v_addc_co_u32_e32 v45, vcc, 0, v49, vcc
	global_load_dwordx4 v[44:47], v[44:45], off
	v_add_co_u32_e32 v48, vcc, s22, v48
	v_add_u32_e32 v52, v5, v7
	s_nop 0
	v_addc_co_u32_e32 v49, vcc, 0, v49, vcc
	global_load_dwordx4 v[48:51], v[48:49], off
	s_lshl_b64 s[22:23], s[70:71], 1
	v_lshl_add_u64 v[14:15], v[14:15], 0, s[22:23]
	v_lshlrev_b32_e32 v82, 1, v6
	v_lshl_add_u64 v[14:15], v[14:15], 0, v[82:83]
	s_movk_i32 s26, 0x2c00
	s_mov_b32 s70, 0x21b1f000
	s_waitcnt vmcnt(7)
	ds_write2_b32 v52, v20, v21 offset1:1
	ds_write2_b32 v52, v22, v23 offset0:2 offset1:3
	v_add_u32_e32 v20, 0x420, v52
	s_waitcnt vmcnt(6)
	ds_write2_b32 v20, v24, v25 offset1:1
	v_add_u32_e32 v20, 0x428, v52
	ds_write2_b32 v20, v26, v27 offset1:1
	v_add_u32_e32 v20, 0x840, v52
	s_waitcnt vmcnt(5)
	ds_write2_b32 v20, v28, v29 offset1:1
	v_add_u32_e32 v20, 0x848, v52
	ds_write2_b32 v20, v30, v31 offset1:1
	v_add_u32_e32 v20, 0xc60, v52
	s_waitcnt vmcnt(4)
	ds_write2_b32 v20, v32, v33 offset1:1
	v_add_u32_e32 v20, 0xc68, v52
	ds_write2_b32 v20, v34, v35 offset1:1
	v_add_u32_e32 v20, 0x1080, v52
	s_waitcnt vmcnt(3)
	ds_write2_b32 v20, v36, v37 offset1:1
	v_add_u32_e32 v20, 0x1088, v52
	ds_write2_b32 v20, v38, v39 offset1:1
	v_add_u32_e32 v20, 0x14a0, v52
	s_waitcnt vmcnt(2)
	ds_write2_b32 v20, v40, v41 offset1:1
	v_add_u32_e32 v20, 0x14a8, v52
	ds_write2_b32 v20, v42, v43 offset1:1
	v_add_u32_e32 v20, 0x18c0, v52
	s_waitcnt vmcnt(1)
	ds_write2_b32 v20, v44, v45 offset1:1
	v_add_u32_e32 v20, 0x18c8, v52
	ds_write2_b32 v20, v46, v47 offset1:1
	v_add_u32_e32 v20, 0x1ce0, v52
	s_waitcnt vmcnt(0)
	ds_write2_b32 v20, v48, v49 offset1:1
	v_add_u32_e32 v20, 0x1ce8, v52
	ds_write2_b32 v20, v50, v51 offset1:1
	s_waitcnt lgkmcnt(0)
	ds_read2_b32 v[24:25], v19 offset0:33 offset1:41
	ds_read2_b32 v[26:27], v19 offset1:8
	ds_read2_b32 v[28:29], v19 offset0:66 offset1:74
	ds_read2_b32 v[30:31], v19 offset0:99 offset1:107
	ds_read2_b32 v[32:33], v19 offset0:132 offset1:140
	ds_read2_b32 v[34:35], v19 offset0:165 offset1:173
	ds_read2_b32 v[36:37], v19 offset0:198 offset1:206
	ds_read2_b32 v[38:39], v19 offset0:231 offset1:239
	s_waitcnt lgkmcnt(7)
	s_waitcnt lgkmcnt(6)
	v_cvt_pk_bf16_f32 v20, v26, v24
	s_waitcnt lgkmcnt(5)
	s_waitcnt lgkmcnt(4)
	v_cvt_pk_bf16_f32 v21, v28, v30
	s_waitcnt lgkmcnt(3)
	s_waitcnt lgkmcnt(2)
	v_cvt_pk_bf16_f32 v22, v32, v34
	s_waitcnt lgkmcnt(1)
	s_waitcnt lgkmcnt(0)
	s_nop 0
	s_nop 0
	s_nop 0
	v_cvt_pk_bf16_f32 v23, v36, v38
	v_add_u32_e32 v24, s19, v1
	v_mad_i64_i32 v[40:41], s[22:23], v24, s26, v[14:15]
	global_store_dwordx4 v[40:41], v[20:23], off
	s_nop 0
	s_nop 0
	s_nop 0
	s_nop 0
	s_nop 0
	s_nop 0
	s_nop 0
	v_cvt_pk_bf16_f32 v20, v27, v25
	s_nop 0
	s_nop 0
	s_nop 0
	s_nop 0
	s_nop 0
	v_cvt_pk_bf16_f32 v21, v29, v31
	s_nop 0
	s_nop 0
	s_nop 0
	s_nop 0
	s_nop 0
	v_cvt_pk_bf16_f32 v22, v33, v35
	s_nop 0
	s_nop 0
	s_nop 0
	v_cvt_pk_bf16_f32 v23, v37, v39
	v_add_u32_e32 v24, s19, v16
	v_mad_i64_i32 v[24:25], s[22:23], v24, s26, v[14:15]
	global_store_dwordx4 v[24:25], v[20:23], off
	ds_read2_b32 v[24:25], v19 offset0:49 offset1:57
	ds_read2_b32 v[26:27], v19 offset0:16 offset1:24
	ds_read2_b32 v[28:29], v19 offset0:82 offset1:90
	ds_read2_b32 v[30:31], v19 offset0:115 offset1:123
	ds_read2_b32 v[32:33], v19 offset0:148 offset1:156
	ds_read2_b32 v[34:35], v19 offset0:181 offset1:189
	ds_read2_b32 v[36:37], v19 offset0:214 offset1:222
	ds_read2_b32 v[38:39], v19 offset0:247 offset1:255
	s_waitcnt lgkmcnt(7)
	s_waitcnt lgkmcnt(6)
	v_cvt_pk_bf16_f32 v20, v26, v24
	s_waitcnt lgkmcnt(5)
	s_waitcnt lgkmcnt(4)
	v_cvt_pk_bf16_f32 v21, v28, v30
	s_waitcnt lgkmcnt(3)
	s_waitcnt lgkmcnt(2)
	v_cvt_pk_bf16_f32 v22, v32, v34
	s_waitcnt lgkmcnt(1)
	s_waitcnt lgkmcnt(0)
	s_nop 0
	s_nop 0
	s_nop 0
	v_cvt_pk_bf16_f32 v23, v36, v38
	v_add_u32_e32 v24, s19, v17
	v_mad_i64_i32 v[40:41], s[22:23], v24, s26, v[14:15]
	global_store_dwordx4 v[40:41], v[20:23], off
	s_nop 0
	s_nop 0
	s_nop 0
	s_nop 0
	s_nop 0
	s_nop 0
	s_nop 0
	v_cvt_pk_bf16_f32 v20, v27, v25
	s_nop 0
	s_nop 0
	s_nop 0
	s_nop 0
	s_nop 0
	v_cvt_pk_bf16_f32 v21, v29, v31
	s_nop 0
	s_nop 0
	s_nop 0
	s_nop 0
	s_nop 0
	v_cvt_pk_bf16_f32 v22, v33, v35
	s_nop 0
	s_nop 0
	s_nop 0
	v_cvt_pk_bf16_f32 v23, v37, v39
	v_add_u32_e32 v24, s19, v18
	v_mad_i64_i32 v[14:15], s[22:23], v24, s26, v[14:15]
	global_store_dwordx4 v[14:15], v[20:23], off
	s_waitcnt lgkmcnt(0)
	s_mov_b64 s[22:23], 0
.LBB0_1637:
	s_andn2_b64 vcc, exec, s[22:23]
	s_cbranch_vccnz .LBB0_1639
	s_add_i32 s19, s25, 0xe000
	s_and_b32 s22, s19, 0xffff
	s_mul_i32 s22, s22, 0xba2f
	s_lshr_b32 s22, s22, 24
	s_mul_i32 s23, s22, 0x160
	s_sub_i32 s23, s19, s23
	s_and_b32 s26, s23, 0xffff
	s_lshl_b32 s19, s26, 5
	s_mul_i32 s28, s18, 0x5800000
	s_mul_hi_i32 s27, s18, 0x5800000
	s_waitcnt lgkmcnt(0)
	s_add_u32 s28, s14, s28
	s_addc_u32 s27, s15, s27
	v_lshl_add_u64 v[14:15], v[8:9], 0, s[20:21]
	s_bfe_i32 s20, s23, 0x10002
	s_lshl_b32 s21, s26, 4
	s_and_b32 s20, s20, 0x1600
	s_and_b32 s21, s21, 0x1f80
	s_add_i32 s20, s20, s21
	s_and_b32 s21, s19, 0x60
	s_or_b32 s20, s20, s21
	s_lshl_b32 s20, s20, 2
	s_add_u32 s20, s28, s20
	s_addc_u32 s21, s27, 0
	v_lshlrev_b32_e32 v82, 2, v4
	v_lshl_add_u32 v50, s22, 6, v1
	v_lshl_add_u64 v[48:49], s[20:21], 0, v[82:83]
	s_mov_b32 s23, 0xb000
	v_mad_i64_i32 v[20:21], s[20:21], v50, s23, v[48:49]
	v_add_u32_e32 v24, 8, v50
	global_load_dwordx4 v[20:23], v[20:21], off
	v_mad_i64_i32 v[24:25], s[20:21], v24, s23, v[48:49]
	global_load_dwordx4 v[24:27], v[24:25], off
	v_add_u32_e32 v28, 16, v50
	v_mad_i64_i32 v[28:29], s[20:21], v28, s23, v[48:49]
	global_load_dwordx4 v[28:31], v[28:29], off
	v_add_u32_e32 v32, 24, v50
	v_mad_i64_i32 v[32:33], s[20:21], v32, s23, v[48:49]
	global_load_dwordx4 v[32:35], v[32:33], off
	v_add_u32_e32 v36, 32, v50
	v_mad_i64_i32 v[36:37], s[20:21], v36, s23, v[48:49]
	global_load_dwordx4 v[36:39], v[36:37], off
	v_add_u32_e32 v40, 40, v50
	v_mad_i64_i32 v[40:41], s[20:21], v40, s23, v[48:49]
	global_load_dwordx4 v[40:43], v[40:41], off
	v_add_u32_e32 v44, 48, v50
	v_mad_i64_i32 v[44:45], s[20:21], v44, s23, v[48:49]
	global_load_dwordx4 v[44:47], v[44:45], off
	v_add_u32_e32 v50, 56, v50
	v_mad_i64_i32 v[48:49], s[20:21], v50, s23, v[48:49]
	global_load_dwordx4 v[48:51], v[48:49], off
	v_add_u32_e32 v52, v5, v7
	s_lshl_b32 s70, s22, 7
	v_lshl_add_u64 v[14:15], v[14:15], 0, s[70:71]
	v_lshlrev_b32_e32 v82, 1, v6
	v_lshl_add_u64 v[14:15], v[14:15], 0, v[82:83]
	s_mov_b32 s70, 0x21b1f000
	s_waitcnt vmcnt(7)
	ds_write2_b32 v52, v20, v21 offset1:1
	ds_write2_b32 v52, v22, v23 offset0:2 offset1:3
	v_add_u32_e32 v20, 0x420, v52
	s_waitcnt vmcnt(6)
	ds_write2_b32 v20, v24, v25 offset1:1
	v_add_u32_e32 v20, 0x428, v52
	ds_write2_b32 v20, v26, v27 offset1:1
	v_add_u32_e32 v20, 0x840, v52
	s_waitcnt vmcnt(5)
	ds_write2_b32 v20, v28, v29 offset1:1
	v_add_u32_e32 v20, 0x848, v52
	ds_write2_b32 v20, v30, v31 offset1:1
	v_add_u32_e32 v20, 0xc60, v52
	s_waitcnt vmcnt(4)
	ds_write2_b32 v20, v32, v33 offset1:1
	v_add_u32_e32 v20, 0xc68, v52
	ds_write2_b32 v20, v34, v35 offset1:1
	v_add_u32_e32 v20, 0x1080, v52
	s_waitcnt vmcnt(3)
	ds_write2_b32 v20, v36, v37 offset1:1
	v_add_u32_e32 v20, 0x1088, v52
	ds_write2_b32 v20, v38, v39 offset1:1
	v_add_u32_e32 v20, 0x14a0, v52
	s_waitcnt vmcnt(2)
	ds_write2_b32 v20, v40, v41 offset1:1
	v_add_u32_e32 v20, 0x14a8, v52
	ds_write2_b32 v20, v42, v43 offset1:1
	v_add_u32_e32 v20, 0x18c0, v52
	s_waitcnt vmcnt(1)
	ds_write2_b32 v20, v44, v45 offset1:1
	v_add_u32_e32 v20, 0x18c8, v52
	ds_write2_b32 v20, v46, v47 offset1:1
	v_add_u32_e32 v20, 0x1ce0, v52
	s_waitcnt vmcnt(0)
	ds_write2_b32 v20, v48, v49 offset1:1
	v_add_u32_e32 v20, 0x1ce8, v52
	ds_write2_b32 v20, v50, v51 offset1:1
	s_waitcnt lgkmcnt(0)
	ds_read2_b32 v[24:25], v19 offset0:33 offset1:41
	ds_read2_b32 v[26:27], v19 offset1:8
	ds_read2_b32 v[28:29], v19 offset0:66 offset1:74
	ds_read2_b32 v[30:31], v19 offset0:99 offset1:107
	ds_read2_b32 v[32:33], v19 offset0:132 offset1:140
	ds_read2_b32 v[34:35], v19 offset0:165 offset1:173
	ds_read2_b32 v[36:37], v19 offset0:198 offset1:206
	ds_read2_b32 v[38:39], v19 offset0:231 offset1:239
	s_waitcnt lgkmcnt(7)
	s_waitcnt lgkmcnt(6)
	v_cvt_pk_bf16_f32 v20, v26, v24
	s_waitcnt lgkmcnt(5)
	s_waitcnt lgkmcnt(4)
	v_cvt_pk_bf16_f32 v21, v28, v30
	s_waitcnt lgkmcnt(3)
	s_waitcnt lgkmcnt(2)
	v_cvt_pk_bf16_f32 v22, v32, v34
	s_waitcnt lgkmcnt(1)
	v_add_u32_e32 v40, s19, v1
	s_waitcnt lgkmcnt(0)
	v_ashrrev_i32_e32 v41, 31, v40
	v_lshlrev_b64 v[40:41], 12, v[40:41]
	v_cvt_pk_bf16_f32 v23, v36, v38
	v_lshl_add_u64 v[40:41], v[14:15], 0, v[40:41]
	global_store_dwordx4 v[40:41], v[20:23], off
	s_nop 0
	s_nop 0
	s_nop 0
	s_nop 0
	s_nop 0
	s_nop 0
	s_nop 0
	v_cvt_pk_bf16_f32 v20, v27, v25
	s_nop 0
	s_nop 0
	s_nop 0
	s_nop 0
	s_nop 0
	v_cvt_pk_bf16_f32 v21, v29, v31
	s_nop 0
	s_nop 0
	s_nop 0
	s_nop 0
	s_nop 0
	v_cvt_pk_bf16_f32 v22, v33, v35
	v_cvt_pk_bf16_f32 v23, v37, v39
	v_add_u32_e32 v24, s19, v16
	v_ashrrev_i32_e32 v25, 31, v24
	v_lshlrev_b64 v[24:25], 12, v[24:25]
	v_lshl_add_u64 v[24:25], v[14:15], 0, v[24:25]
	global_store_dwordx4 v[24:25], v[20:23], off
	ds_read2_b32 v[24:25], v19 offset0:49 offset1:57
	ds_read2_b32 v[26:27], v19 offset0:16 offset1:24
	ds_read2_b32 v[28:29], v19 offset0:82 offset1:90
	ds_read2_b32 v[30:31], v19 offset0:115 offset1:123
	ds_read2_b32 v[32:33], v19 offset0:148 offset1:156
	ds_read2_b32 v[34:35], v19 offset0:181 offset1:189
	ds_read2_b32 v[36:37], v19 offset0:214 offset1:222
	ds_read2_b32 v[38:39], v19 offset0:247 offset1:255
	s_waitcnt lgkmcnt(7)
	s_waitcnt lgkmcnt(6)
	v_cvt_pk_bf16_f32 v20, v26, v24
	s_waitcnt lgkmcnt(5)
	s_waitcnt lgkmcnt(4)
	v_cvt_pk_bf16_f32 v21, v28, v30
	s_waitcnt lgkmcnt(3)
	s_waitcnt lgkmcnt(2)
	v_cvt_pk_bf16_f32 v22, v32, v34
	s_waitcnt lgkmcnt(1)
	v_add_u32_e32 v40, s19, v17
	s_waitcnt lgkmcnt(0)
	v_ashrrev_i32_e32 v41, 31, v40
	v_lshlrev_b64 v[40:41], 12, v[40:41]
	v_cvt_pk_bf16_f32 v23, v36, v38
	v_lshl_add_u64 v[40:41], v[14:15], 0, v[40:41]
	global_store_dwordx4 v[40:41], v[20:23], off
	s_nop 0
	s_nop 0
	s_nop 0
	s_nop 0
	s_nop 0
	s_nop 0
	s_nop 0
	v_cvt_pk_bf16_f32 v20, v27, v25
	s_nop 0
	s_nop 0
	s_nop 0
	s_nop 0
	s_nop 0
	v_cvt_pk_bf16_f32 v21, v29, v31
	s_nop 0
	s_nop 0
	s_nop 0
	s_nop 0
	s_nop 0
	v_cvt_pk_bf16_f32 v22, v33, v35
	v_cvt_pk_bf16_f32 v23, v37, v39
	v_add_u32_e32 v24, s19, v18
	v_ashrrev_i32_e32 v25, 31, v24
	v_lshlrev_b64 v[24:25], 12, v[24:25]
	v_lshl_add_u64 v[14:15], v[14:15], 0, v[24:25]
	global_store_dwordx4 v[14:15], v[20:23], off
	s_waitcnt lgkmcnt(0)

.LBB0_1640:
	s_andn2_b64 vcc, exec, s[20:21]
	s_cbranch_vccnz .LBB0_1642
	s_and_b32 s19, s25, 0x1fc0
	s_add_i32 s70, s19, 0xffffe800
	s_ashr_i32 s19, s18, 31
	s_lshl_b64 s[20:21], s[18:19], 24
	s_waitcnt lgkmcnt(0)
	s_add_u32 s22, s12, s20
	s_addc_u32 s23, s13, s21
	s_lshl_b64 s[20:21], s[18:19], 23
	s_and_b32 s19, s8, 0x7e0
	v_lshl_add_u64 v[14:15], v[10:11], 0, s[20:21]
	s_lshl_b32 s20, s19, 2
	v_add_u32_e32 v20, s70, v1
	s_add_u32 s20, s22, s20
	s_addc_u32 s21, s23, 0
	v_lshlrev_b32_e32 v82, 2, v4
	v_ashrrev_i32_e32 v21, 31, v20
	v_lshl_add_u64 v[22:23], s[20:21], 0, v[82:83]
	v_lshlrev_b64 v[20:21], 13, v[20:21]
	v_lshl_add_u64 v[48:49], v[22:23], 0, v[20:21]
	s_mov_b32 s20, 0x10000
	v_add_co_u32_e32 v24, vcc, s20, v48
	global_load_dwordx4 v[20:23], v[48:49], off
	s_nop 0
	v_addc_co_u32_e32 v25, vcc, 0, v49, vcc
	s_mov_b32 s20, 0x20000
	global_load_dwordx4 v[24:27], v[24:25], off
	v_add_co_u32_e32 v28, vcc, s20, v48
	s_mov_b32 s20, 0x30000
	s_nop 0
	v_addc_co_u32_e32 v29, vcc, 0, v49, vcc
	global_load_dwordx4 v[28:31], v[28:29], off
	v_add_co_u32_e32 v32, vcc, s20, v48
	s_mov_b32 s20, 0x40000
	s_nop 0
	v_addc_co_u32_e32 v33, vcc, 0, v49, vcc
	global_load_dwordx4 v[32:35], v[32:33], off
	v_add_co_u32_e32 v36, vcc, s20, v48
	s_mov_b32 s20, 0x50000
	s_nop 0
	v_addc_co_u32_e32 v37, vcc, 0, v49, vcc
	global_load_dwordx4 v[36:39], v[36:37], off
	v_add_co_u32_e32 v40, vcc, s20, v48
	s_mov_b32 s20, 0x60000
	s_nop 0
	v_addc_co_u32_e32 v41, vcc, 0, v49, vcc
	global_load_dwordx4 v[40:43], v[40:41], off
	v_add_co_u32_e32 v44, vcc, s20, v48
	s_mov_b32 s20, 0x70000
	s_nop 0
	v_addc_co_u32_e32 v45, vcc, 0, v49, vcc
	global_load_dwordx4 v[44:47], v[44:45], off
	v_add_co_u32_e32 v48, vcc, s20, v48
	v_add_u32_e32 v52, v5, v7
	s_nop 0
	v_addc_co_u32_e32 v49, vcc, 0, v49, vcc
	global_load_dwordx4 v[48:51], v[48:49], off
	s_lshl_b64 s[20:21], s[70:71], 1
	v_lshl_add_u64 v[14:15], v[14:15], 0, s[20:21]
	v_lshlrev_b32_e32 v82, 1, v6
	v_lshl_add_u64 v[14:15], v[14:15], 0, v[82:83]
	s_mov_b32 s70, 0x21b1f000
	s_waitcnt vmcnt(7)
	ds_write2_b32 v52, v20, v21 offset1:1
	ds_write2_b32 v52, v22, v23 offset0:2 offset1:3
	v_add_u32_e32 v20, 0x420, v52
	s_waitcnt vmcnt(6)
	ds_write2_b32 v20, v24, v25 offset1:1
	v_add_u32_e32 v20, 0x428, v52
	ds_write2_b32 v20, v26, v27 offset1:1
	v_add_u32_e32 v20, 0x840, v52
	s_waitcnt vmcnt(5)
	ds_write2_b32 v20, v28, v29 offset1:1
	v_add_u32_e32 v20, 0x848, v52
	ds_write2_b32 v20, v30, v31 offset1:1
	v_add_u32_e32 v20, 0xc60, v52
	s_waitcnt vmcnt(4)
	ds_write2_b32 v20, v32, v33 offset1:1
	v_add_u32_e32 v20, 0xc68, v52
	ds_write2_b32 v20, v34, v35 offset1:1
	v_add_u32_e32 v20, 0x1080, v52
	s_waitcnt vmcnt(3)
	ds_write2_b32 v20, v36, v37 offset1:1
	v_add_u32_e32 v20, 0x1088, v52
	ds_write2_b32 v20, v38, v39 offset1:1
	v_add_u32_e32 v20, 0x14a0, v52
	s_waitcnt vmcnt(2)
	ds_write2_b32 v20, v40, v41 offset1:1
	v_add_u32_e32 v20, 0x14a8, v52
	ds_write2_b32 v20, v42, v43 offset1:1
	v_add_u32_e32 v20, 0x18c0, v52
	v_add_u32_e32 v40, s19, v1
	v_ashrrev_i32_e32 v41, 31, v40
	s_waitcnt vmcnt(1)
	ds_write2_b32 v20, v44, v45 offset1:1
	v_add_u32_e32 v20, 0x18c8, v52
	ds_write2_b32 v20, v46, v47 offset1:1
	v_add_u32_e32 v20, 0x1ce0, v52
	v_lshlrev_b64 v[40:41], 12, v[40:41]
	v_lshl_add_u64 v[40:41], v[14:15], 0, v[40:41]
	s_waitcnt vmcnt(0)
	ds_write2_b32 v20, v48, v49 offset1:1
	v_add_u32_e32 v20, 0x1ce8, v52
	ds_write2_b32 v20, v50, v51 offset1:1
	s_waitcnt lgkmcnt(0)
	ds_read2_b32 v[24:25], v19 offset0:33 offset1:41
	ds_read2_b32 v[26:27], v19 offset1:8
	ds_read2_b32 v[28:29], v19 offset0:66 offset1:74
	ds_read2_b32 v[30:31], v19 offset0:99 offset1:107
	ds_read2_b32 v[32:33], v19 offset0:132 offset1:140
	ds_read2_b32 v[34:35], v19 offset0:165 offset1:173
	ds_read2_b32 v[36:37], v19 offset0:198 offset1:206
	ds_read2_b32 v[38:39], v19 offset0:231 offset1:239
	s_waitcnt lgkmcnt(7)
	s_waitcnt lgkmcnt(6)
	v_cvt_pk_bf16_f32 v20, v26, v24
	s_waitcnt lgkmcnt(5)
	s_waitcnt lgkmcnt(4)
	v_cvt_pk_bf16_f32 v21, v28, v30
	s_waitcnt lgkmcnt(3)
	s_waitcnt lgkmcnt(2)
	v_cvt_pk_bf16_f32 v22, v32, v34
	s_waitcnt lgkmcnt(1)
	s_nop 0
	s_nop 0
	s_waitcnt lgkmcnt(0)
	s_nop 0
	s_nop 0
	s_nop 0
	v_cvt_pk_bf16_f32 v23, v36, v38
	global_store_dwordx4 v[40:41], v[20:23], off
	s_nop 0
	s_nop 0
	s_nop 0
	s_nop 0
	s_nop 0
	s_nop 0
	s_nop 0
	v_cvt_pk_bf16_f32 v20, v27, v25
	s_nop 0
	s_nop 0
	s_nop 0
	s_nop 0
	s_nop 0
	v_cvt_pk_bf16_f32 v21, v29, v31
	s_nop 0
	s_nop 0
	s_nop 0
	s_nop 0
	s_nop 0
	v_cvt_pk_bf16_f32 v22, v33, v35
	v_cvt_pk_bf16_f32 v23, v37, v39
	v_add_u32_e32 v24, s19, v16
	v_ashrrev_i32_e32 v25, 31, v24
	v_lshlrev_b64 v[24:25], 12, v[24:25]
	v_lshl_add_u64 v[24:25], v[14:15], 0, v[24:25]
	global_store_dwordx4 v[24:25], v[20:23], off
	ds_read2_b32 v[24:25], v19 offset0:49 offset1:57
	ds_read2_b32 v[26:27], v19 offset0:16 offset1:24
	ds_read2_b32 v[28:29], v19 offset0:82 offset1:90
	ds_read2_b32 v[30:31], v19 offset0:115 offset1:123
	ds_read2_b32 v[32:33], v19 offset0:148 offset1:156
	ds_read2_b32 v[34:35], v19 offset0:181 offset1:189
	ds_read2_b32 v[36:37], v19 offset0:214 offset1:222
	ds_read2_b32 v[38:39], v19 offset0:247 offset1:255
	s_waitcnt lgkmcnt(7)
	s_waitcnt lgkmcnt(6)
	v_cvt_pk_bf16_f32 v20, v26, v24
	s_waitcnt lgkmcnt(5)
	s_waitcnt lgkmcnt(4)
	v_cvt_pk_bf16_f32 v21, v28, v30
	s_waitcnt lgkmcnt(3)
	s_waitcnt lgkmcnt(2)
	v_cvt_pk_bf16_f32 v22, v32, v34
	s_waitcnt lgkmcnt(1)
	v_add_u32_e32 v40, s19, v17
	s_waitcnt lgkmcnt(0)
	v_ashrrev_i32_e32 v41, 31, v40
	v_lshlrev_b64 v[40:41], 12, v[40:41]
	v_cvt_pk_bf16_f32 v23, v36, v38
	v_lshl_add_u64 v[40:41], v[14:15], 0, v[40:41]
	global_store_dwordx4 v[40:41], v[20:23], off
	s_nop 0
	s_nop 0
	s_nop 0
	s_nop 0
	s_nop 0
	s_nop 0
	s_nop 0
	v_cvt_pk_bf16_f32 v20, v27, v25
	s_nop 0
	s_nop 0
	s_nop 0
	s_nop 0
	s_nop 0
	v_cvt_pk_bf16_f32 v21, v29, v31
	s_nop 0
	s_nop 0
	s_nop 0
	s_nop 0
	s_nop 0
	v_cvt_pk_bf16_f32 v22, v33, v35
	v_cvt_pk_bf16_f32 v23, v37, v39
	v_add_u32_e32 v24, s19, v18
	v_ashrrev_i32_e32 v25, 31, v24
	v_lshlrev_b64 v[24:25], 12, v[24:25]
	v_lshl_add_u64 v[14:15], v[14:15], 0, v[24:25]
	global_store_dwordx4 v[14:15], v[20:23], off
	s_waitcnt lgkmcnt(0)

.LBB0_1743:
	v_mov_b32_e32 v2, v0
	s_mov_b64 s[8:9], s[44:45]
	v_mov_b32_e32 v1, v232
	s_mov_b64 s[34:35], s[46:47]
	s_mov_b64 s[10:11], s[0:1]
	s_add_i32 s8, s60, s30
	v_lshlrev_b32_e32 v2, 2, v1
	s_waitcnt lgkmcnt(0)
	v_ashrrev_i32_e32 v3, 31, v2
	v_lshlrev_b64 v[4:5], 1, v[2:3]
	v_lshl_add_u64 v[6:7], s[34:35], 0, v[4:5]
	v_lshl_add_u64 v[32:33], v[6:7], 0, s[24:25]
	global_load_dwordx2 v[6:7], v[32:33], off offset:-3584
	global_load_dwordx2 v[34:35], v[32:33], off offset:-3072
	global_load_dwordx2 v[44:45], v[32:33], off offset:-2560
	global_load_dwordx2 v[8:9], v[32:33], off offset:-2048
	s_cmpk_lt_i32 s8, 0x2000
	s_cselect_b32 s36, s8, s30
	s_add_u32 s18, s34, 0x28c000
	s_addc_u32 s19, s35, 0
	s_ashr_i32 s37, s36, 31
	s_ashr_i32 s31, s30, 31
	s_lshl_b64 s[8:9], s[36:37], 12
	s_add_u32 s16, s34, s8
	s_addc_u32 s17, s35, s9
	v_lshl_add_u64 v[4:5], s[16:17], 0, v[4:5]
	s_mov_b64 s[8:9], 0x1d91e000
	v_and_b32_e32 v14, 64, v249
	v_add_u32_e32 v14, 64, v14
	v_xor_b32_e32 v20, 1, v249
	v_lshlrev_b64 v[86:87], 2, v[2:3]
	s_add_u32 s20, s34, 0x28e000
	s_addc_u32 s21, s35, 0
	v_lshl_add_u64 v[88:89], s[20:21], 0, v[86:87]
	s_add_u32 s58, s34, 0x1515b000
	s_addc_u32 s59, s35, 0
	s_waitcnt vmcnt(3)
	v_lshlrev_b32_e32 v68, 16, v6
	s_waitcnt vmcnt(2)
	v_lshlrev_b32_e32 v69, 16, v34
	v_and_b32_e32 v75, 0xffff0000, v34
	s_waitcnt vmcnt(0)
	v_lshlrev_b32_e32 v36, 16, v8
	v_and_b32_e32 v37, 0xffff0000, v8
	v_lshlrev_b32_e32 v38, 16, v9
	v_and_b32_e32 v39, 0xffff0000, v9
	global_load_dwordx2 v[8:9], v[32:33], off offset:-1536
	v_and_b32_e32 v74, 0xffff0000, v6
	v_and_b32_e32 v73, 0xffff0000, v35
	v_and_b32_e32 v72, 0xffff0000, v7
	v_lshlrev_b32_e32 v34, 16, v44
	v_add_f32_e32 v66, v36, v37
	v_add_f32_e32 v46, v38, v39
	s_waitcnt vmcnt(0)
	v_lshlrev_b32_e32 v43, 16, v8
	v_and_b32_e32 v41, 0xffff0000, v8
	v_lshlrev_b32_e32 v67, 16, v9
	v_and_b32_e32 v47, 0xffff0000, v9
	global_load_dwordx2 v[70:71], v[32:33], off offset:-1024
	global_load_dwordx2 v[8:9], v[32:33], off offset:-512
	s_waitcnt vmcnt(0)
	v_lshlrev_b32_e32 v48, 16, v8
	v_and_b32_e32 v49, 0xffff0000, v8
	v_lshlrev_b32_e32 v50, 16, v9
	v_and_b32_e32 v51, 0xffff0000, v9
	global_load_dwordx2 v[8:9], v[32:33], off
	v_add_f32_e32 v64, v48, v49
	v_add_f32_e32 v54, v50, v51
	s_waitcnt vmcnt(0)
	v_lshlrev_b32_e32 v52, 16, v8
	v_and_b32_e32 v53, 0xffff0000, v8
	v_lshlrev_b32_e32 v65, 16, v9
	v_and_b32_e32 v55, 0xffff0000, v9
	v_lshl_add_u64 v[8:9], v[4:5], 0, s[8:9]
	s_mov_b32 s8, 0x1d91e000
	v_add_co_u32_e32 v4, vcc, s8, v4
	s_nop 1
	v_addc_co_u32_e32 v5, vcc, 0, v5, vcc
	global_load_dwordx2 v[60:61], v[4:5], off
	global_load_dwordx2 v[62:63], v[8:9], off offset:512
	global_load_dwordx2 v[58:59], v[8:9], off offset:1024
	s_nop 0
	global_load_dwordx2 v[4:5], v[8:9], off offset:1536
	v_cmp_lt_i32_e32 vcc, v20, v14
	s_waitcnt vmcnt(0)
	v_lshlrev_b32_e32 v28, 16, v4
	v_and_b32_e32 v29, 0xffff0000, v4
	v_lshlrev_b32_e32 v30, 16, v5
	v_and_b32_e32 v31, 0xffff0000, v5
	global_load_dwordx2 v[4:5], v[8:9], off offset:2048
	v_cndmask_b32_e32 v20, v249, v20, vcc
	v_lshlrev_b32_e32 v90, 2, v20
	v_add_f32_e32 v26, v28, v29
	v_add_f32_e32 v24, v30, v31
	s_waitcnt vmcnt(0)
	v_lshlrev_b32_e32 v23, 16, v4
	v_and_b32_e32 v21, 0xffff0000, v4
	v_lshlrev_b32_e32 v27, 16, v5
	v_and_b32_e32 v25, 0xffff0000, v5
	global_load_dwordx2 v[56:57], v[8:9], off offset:2560
	global_load_dwordx2 v[4:5], v[8:9], off offset:3072
	s_load_dwordx4 s[12:15], s[10:11], 0xb0
	s_load_dwordx2 s[38:39], s[10:11], 0x68
	s_waitcnt lgkmcnt(0)
	v_lshl_add_u64 v[84:85], s[12:13], 0, v[86:87]
	s_waitcnt vmcnt(0)
	v_lshlrev_b32_e32 v16, 16, v4
	v_and_b32_e32 v17, 0xffff0000, v4
	v_lshlrev_b32_e32 v18, 16, v5
	v_and_b32_e32 v19, 0xffff0000, v5
	global_load_dwordx2 v[4:5], v[8:9], off offset:3584
	v_lshlrev_b32_e32 v9, 16, v35
	v_lshlrev_b32_e32 v8, 16, v7
	v_pk_add_f32 v[6:7], v[8:9], v[72:73]
	v_lshlrev_b32_e32 v35, 16, v45
	s_waitcnt vmcnt(0)
	v_lshlrev_b32_e32 v10, 16, v4
	v_and_b32_e32 v11, 0xffff0000, v4
	v_lshlrev_b32_e32 v15, 16, v5
	v_and_b32_e32 v13, 0xffff0000, v5
	v_pk_add_f32 v[4:5], v[68:69], v[74:75]
	s_nop 0
	v_pk_add_f32 v[4:5], v[4:5], v[6:7]
	v_and_b32_e32 v7, 0xffff0000, v45
	v_add_f32_e32 v4, 0, v4
	v_and_b32_e32 v6, 0xffff0000, v44
	v_add_f32_e32 v42, v4, v5
	v_pk_add_f32 v[4:5], v[34:35], v[6:7]
	v_pk_add_f32 v[44:45], v[66:67], v[46:47]
	v_pk_add_f32 v[4:5], v[4:5], v[4:5] op_sel:[0,1] op_sel_hi:[1,0]
	s_nop 0
	v_mov_b32_e32 v5, v41
	v_pk_add_f32 v[4:5], v[42:43], v[4:5]
	s_nop 0
	v_pk_add_f32 v[76:77], v[4:5], v[44:45]
	v_lshlrev_b32_e32 v45, 16, v71
	v_lshlrev_b32_e32 v44, 16, v70
	v_and_b32_e32 v5, 0xffff0000, v71
	v_and_b32_e32 v4, 0xffff0000, v70
	v_pk_add_f32 v[70:71], v[44:45], v[4:5]
	v_pk_add_f32 v[76:77], v[76:77], v[76:77] op_sel:[0,1] op_sel_hi:[1,0]
	v_pk_add_f32 v[70:71], v[70:71], v[70:71] op_sel:[0,1] op_sel_hi:[1,0]
	v_mov_b32_e32 v77, v52
	v_mov_b32_e32 v71, v53
	v_pk_add_f32 v[70:71], v[76:77], v[70:71]
	v_pk_add_f32 v[76:77], v[64:65], v[54:55]
	s_nop 0
	v_pk_add_f32 v[70:71], v[70:71], v[76:77]
	s_nop 0
	v_add_f32_e32 v12, v70, v71
	ds_bpermute_b32 v20, v90, v12
	s_waitcnt lgkmcnt(0)
	v_add_f32_e32 v12, v12, v20
	v_xor_b32_e32 v20, 2, v249
	v_cmp_lt_i32_e32 vcc, v20, v14
	s_nop 1
	v_cndmask_b32_e32 v20, v249, v20, vcc
	v_lshlrev_b32_e32 v91, 2, v20
	ds_bpermute_b32 v20, v91, v12
	s_waitcnt lgkmcnt(0)
	v_add_f32_e32 v12, v12, v20
	v_xor_b32_e32 v20, 4, v249
	v_cmp_lt_i32_e32 vcc, v20, v14
	s_nop 1
	v_cndmask_b32_e32 v20, v249, v20, vcc
	v_lshlrev_b32_e32 v92, 2, v20
	ds_bpermute_b32 v20, v92, v12
	s_waitcnt lgkmcnt(0)
	v_add_f32_e32 v12, v12, v20
	v_xor_b32_e32 v20, 8, v249
	v_cmp_lt_i32_e32 vcc, v20, v14
	s_nop 1
	v_cndmask_b32_e32 v20, v249, v20, vcc
	v_lshlrev_b32_e32 v93, 2, v20
	ds_bpermute_b32 v20, v93, v12
	s_waitcnt lgkmcnt(0)
	v_add_f32_e32 v12, v12, v20
	v_xor_b32_e32 v20, 16, v249
	v_cmp_lt_i32_e32 vcc, v20, v14
	s_nop 1
	v_cndmask_b32_e32 v20, v249, v20, vcc
	v_lshlrev_b32_e32 v94, 2, v20
	ds_bpermute_b32 v20, v94, v12
	s_waitcnt lgkmcnt(0)
	v_add_f32_e32 v12, v12, v20
	v_xor_b32_e32 v20, 32, v249
	v_cmp_lt_i32_e32 vcc, v20, v14
	s_nop 1
	v_cndmask_b32_e32 v14, v249, v20, vcc
	v_lshlrev_b32_e32 v95, 2, v14
	ds_bpermute_b32 v14, v95, v12
	s_waitcnt lgkmcnt(0)
	v_add_f32_e32 v12, v12, v14
	v_fmac_f32_e32 v74, 0xba000000, v12
	v_fmac_f32_e32 v75, 0xba000000, v12
	v_fmac_f32_e32 v72, 0xba000000, v12
	v_fmac_f32_e32 v68, 0xba000000, v12
	v_fmac_f32_e32 v73, 0xba000000, v12
	v_fmac_f32_e32 v69, 0xba000000, v12
	v_mov_b32_e32 v71, v75
	v_mov_b32_e32 v77, v74
	v_pk_mul_f32 v[74:75], v[74:75], v[74:75]
	v_fmac_f32_e32 v8, 0xba000000, v12
	v_fmac_f32_e32 v9, 0xba000000, v12
	v_mov_b32_e32 v70, v69
	v_mov_b32_e32 v76, v68
	v_pk_fma_f32 v[68:69], v[68:69], v[68:69], v[74:75]
	v_mov_b32_e32 v75, v73
	v_mov_b32_e32 v79, v72
	v_pk_mul_f32 v[72:73], v[72:73], v[72:73]
	v_fmac_f32_e32 v6, 0xba000000, v12
	v_fmac_f32_e32 v7, 0xba000000, v12
	v_fmac_f32_e32 v35, 0xba000000, v12
	v_mov_b32_e32 v74, v9
	v_mov_b32_e32 v78, v8
	v_pk_fma_f32 v[8:9], v[8:9], v[8:9], v[72:73]
	v_fmac_f32_e32 v34, 0xba000000, v12
	v_mov_b32_e32 v72, v35
	v_mov_b32_e32 v73, v7
	v_mov_b32_e32 v35, v6
	v_pk_add_f32 v[8:9], v[68:69], v[8:9]
	v_pk_mul_f32 v[68:69], v[72:73], v[72:73]
	v_pk_mul_f32 v[6:7], v[34:35], v[34:35]
	v_fmac_f32_e32 v36, 0xba000000, v12
	v_pk_mov_b32 v[80:81], v[6:7], v[68:69] op_sel:[1,0]
	v_mov_b32_e32 v7, v69
	v_pk_add_f32 v[6:7], v[80:81], v[6:7]
	v_fmac_f32_e32 v37, 0xba000000, v12
	v_pk_add_f32 v[6:7], v[6:7], v[6:7] op_sel_hi:[0,1]
	v_fmac_f32_e32 v38, 0xba000000, v12
	v_mul_f32_e32 v6, v36, v36
	v_fmac_f32_e32 v39, 0xba000000, v12
	v_pk_fma_f32 v[68:69], v[36:37], v[36:37], v[6:7] op_sel_hi:[1,1,0]
	v_mul_f32_e32 v6, v38, v38
	v_pk_add_f32 v[8:9], v[8:9], v[8:9] op_sel_hi:[0,1]
	v_pk_fma_f32 v[80:81], v[38:39], v[38:39], v[6:7] op_sel_hi:[1,1,0]
	v_fmac_f32_e32 v47, 0xba000000, v12
	v_fmac_f32_e32 v67, 0xba000000, v12
	v_fmac_f32_e32 v41, 0xba000000, v12
	v_fmac_f32_e32 v43, 0xba000000, v12
	v_mul_f32_e32 v68, v43, v43
	v_mul_f32_e32 v80, v41, v41
	v_mul_f32_e32 v6, v67, v67
	v_mul_f32_e32 v8, v47, v47
	v_pk_add_f32 v[68:69], v[68:69], v[80:81]
	v_pk_add_f32 v[6:7], v[6:7], v[8:9]
	v_fmac_f32_e32 v4, 0xba000000, v12
	v_fmac_f32_e32 v5, 0xba000000, v12
	v_fmac_f32_e32 v45, 0xba000000, v12
	v_pk_add_f32 v[6:7], v[68:69], v[6:7]
	v_fmac_f32_e32 v44, 0xba000000, v12
	v_mov_b32_e32 v68, v45
	v_mov_b32_e32 v69, v5
	v_mov_b32_e32 v45, v4
	v_pk_mul_f32 v[8:9], v[68:69], v[68:69]
	v_pk_mul_f32 v[4:5], v[44:45], v[44:45]
	v_fmac_f32_e32 v48, 0xba000000, v12
	v_pk_mov_b32 v[80:81], v[4:5], v[8:9] op_sel:[1,0]
	v_mov_b32_e32 v5, v9
	v_pk_add_f32 v[4:5], v[80:81], v[4:5]
	v_fmac_f32_e32 v49, 0xba000000, v12
	v_pk_add_f32 v[4:5], v[4:5], v[4:5] op_sel_hi:[0,1]
	v_fmac_f32_e32 v50, 0xba000000, v12
	v_mul_f32_e32 v4, v48, v48
	v_fmac_f32_e32 v51, 0xba000000, v12
	v_pk_fma_f32 v[8:9], v[48:49], v[48:49], v[4:5] op_sel_hi:[1,1,0]
	v_mul_f32_e32 v4, v50, v50
	v_pk_add_f32 v[6:7], v[6:7], v[6:7] op_sel_hi:[0,1]
	v_pk_fma_f32 v[80:81], v[50:51], v[50:51], v[4:5] op_sel_hi:[1,1,0]
	v_fmac_f32_e32 v55, 0xba000000, v12
	v_fmac_f32_e32 v65, 0xba000000, v12
	v_fmac_f32_e32 v53, 0xba000000, v12
	v_fmac_f32_e32 v52, 0xba000000, v12
	v_mul_f32_e32 v8, v52, v52
	v_mul_f32_e32 v80, v53, v53
	v_mul_f32_e32 v4, v65, v65
	v_mul_f32_e32 v6, v55, v55
	v_pk_add_f32 v[8:9], v[8:9], v[80:81]
	v_pk_add_f32 v[4:5], v[4:5], v[6:7]
	v_lshl_add_u64 v[80:81], s[14:15], 0, v[86:87]
	v_pk_add_f32 v[4:5], v[8:9], v[4:5]
	v_mov_b32_e32 v46, v67
	v_add_f32_e32 v4, v4, v5
	ds_bpermute_b32 v5, v90, v4
	v_mov_b32_e32 v40, v43
	v_mov_b32_e32 v54, v65
	s_waitcnt lgkmcnt(0)
	v_add_f32_e32 v4, v4, v5
	ds_bpermute_b32 v5, v91, v4
	s_waitcnt lgkmcnt(0)
	v_add_f32_e32 v4, v4, v5
	ds_bpermute_b32 v5, v92, v4
	s_waitcnt lgkmcnt(0)
	v_add_f32_e32 v4, v4, v5
	ds_bpermute_b32 v5, v93, v4
	s_waitcnt lgkmcnt(0)
	v_add_f32_e32 v4, v4, v5
	ds_bpermute_b32 v5, v94, v4
	s_waitcnt lgkmcnt(0)
	v_add_f32_e32 v4, v4, v5
	ds_bpermute_b32 v5, v95, v4
	s_waitcnt lgkmcnt(0)
	v_add_f32_e32 v4, v4, v5
	v_fmamk_f32 v4, v4, 0x3a000000, v250
	v_cmp_gt_f32_e32 vcc, s96, v4
	v_mul_f32_e32 v5, 0x4f800000, v4
	s_nop 0
	v_cndmask_b32_e32 v4, v4, v5, vcc
	v_sqrt_f32_e32 v5, v4
	s_nop 0
	v_add_u32_e32 v6, -1, v5
	v_fma_f32 v7, -v6, v5, v4
	v_cmp_ge_f32_e64 s[10:11], 0, v7
	v_add_u32_e32 v7, 1, v5
	s_nop 0
	v_cndmask_b32_e64 v6, v5, v6, s[10:11]
	v_fma_f32 v5, -v7, v5, v4
	v_cmp_lt_f32_e64 s[10:11], 0, v5
	s_nop 1
	v_cndmask_b32_e64 v5, v6, v7, s[10:11]
	v_mul_f32_e32 v6, 0x37800000, v5
	v_cndmask_b32_e32 v5, v5, v6, vcc
	v_cmp_class_f32_e32 vcc, v4, v251
	s_nop 1
	v_cndmask_b32_e32 v4, v5, v4, vcc
	v_div_scale_f32 v5, s[8:9], v4, v4, 1.0
	v_rcp_f32_e32 v6, v5
	s_movk_i32 s8, 0xf000
	v_fma_f32 v7, -v5, v6, 1.0
	v_fmac_f32_e32 v6, v7, v6
	v_div_scale_f32 v7, vcc, 1.0, v4, 1.0
	v_mul_f32_e32 v8, v7, v6
	v_fma_f32 v9, -v5, v8, v7
	v_fmac_f32_e32 v8, v9, v6
	v_fma_f32 v5, -v5, v8, v7
	v_div_fmas_f32 v5, v5, v6, v8
	v_div_fixup_f32 v12, v5, v4, 1.0
	global_load_dwordx4 v[2:5], v[84:85], off
	global_load_dwordx4 v[6:9], v[80:81], off
	v_pk_mul_f32 v[76:77], v[76:77], v[12:13] op_sel_hi:[1,0]
	v_pk_mul_f32 v[78:79], v[78:79], v[12:13] op_sel_hi:[1,0]
	v_pk_mul_f32 v[70:71], v[70:71], v[12:13] op_sel_hi:[1,0]
	v_pk_mul_f32 v[34:35], v[34:35], v[12:13] op_sel_hi:[1,0]
	v_pk_mul_f32 v[38:39], v[38:39], v[12:13] op_sel_hi:[1,0]
	v_pk_mul_f32 v[36:37], v[36:37], v[12:13] op_sel_hi:[1,0]
	v_pk_mul_f32 v[46:47], v[46:47], v[12:13] op_sel_hi:[1,0]
	v_pk_mul_f32 v[40:41], v[40:41], v[12:13] op_sel_hi:[1,0]
	v_pk_mul_f32 v[44:45], v[44:45], v[12:13] op_sel_hi:[1,0]
	v_pk_mul_f32 v[50:51], v[50:51], v[12:13] op_sel_hi:[1,0]
	v_pk_mul_f32 v[48:49], v[48:49], v[12:13] op_sel_hi:[1,0]
	v_pk_mul_f32 v[54:55], v[54:55], v[12:13] op_sel_hi:[1,0]
	v_pk_mul_f32 v[52:53], v[52:53], v[12:13] op_sel_hi:[1,0]
	s_waitcnt vmcnt(0)
	v_pk_fma_f32 v[6:7], v[2:3], v[76:77], v[6:7]
	v_lshl_add_u64 v[2:3], s[34:35], 0, v[86:87]
	v_lshl_add_u64 v[76:77], v[2:3], 0, s[22:23]
	v_add_co_u32_e32 v104, vcc, s8, v76
	v_pk_fma_f32 v[8:9], v[4:5], v[78:79], v[8:9]
	s_nop 0
	v_addc_co_u32_e32 v105, vcc, -1, v77, vcc
	global_store_dwordx4 v[104:105], v[6:9], off offset:-3072
	global_load_dwordx4 v[2:5], v[88:89], off
	v_lshl_add_u64 v[86:87], s[18:19], 0, v[86:87]
	global_load_dwordx4 v[96:99], v[86:87], off
	s_mov_b32 s8, 0xef2fd000
	s_waitcnt vmcnt(1)
	v_pk_add_f32 v[4:5], v[4:5], 1.0 op_sel_hi:[1,0]
	v_pk_add_f32 v[78:79], v[2:3], 1.0 op_sel_hi:[1,0]
	s_waitcnt vmcnt(0)
	v_pk_fma_f32 v[2:3], v[4:5], v[8:9], v[98:99]
	v_pk_fma_f32 v[4:5], v[78:79], v[6:7], v[96:97]
	s_nop 0
	s_nop 0
	s_nop 0
	s_nop 0
	s_nop 0
	s_nop 0
	v_cvt_pk_bf16_f32 v6, v4, v5
	s_nop 0
	s_nop 0
	s_nop 0
	s_nop 0
	v_add_co_u32_e32 v78, vcc, s8, v32
	v_cvt_pk_bf16_f32 v7, v2, v3
	s_nop 0
	v_addc_co_u32_e32 v79, vcc, -1, v33, vcc
	global_store_dwordx2 v[78:79], v[6:7], off offset:-3584
	global_load_dwordx4 v[6:9], v[84:85], off offset:1024
	s_nop 0
	global_load_dwordx4 v[96:99], v[80:81], off offset:1024
	v_pk_mul_f32 v[32:33], v[74:75], v[12:13] op_sel_hi:[1,0]
	s_lshl_b64 s[8:9], s[36:37], 13
	s_add_u32 s40, s34, s8
	s_addc_u32 s41, s35, s9
	s_waitcnt vmcnt(0)
	v_pk_fma_f32 v[96:97], v[6:7], v[70:71], v[96:97]
	v_pk_fma_f32 v[98:99], v[8:9], v[32:33], v[98:99]
	global_store_dwordx4 v[104:105], v[96:99], off offset:-2048
	global_load_dwordx4 v[6:9], v[88:89], off offset:1024
	global_load_dwordx4 v[100:103], v[86:87], off offset:1024
	s_waitcnt vmcnt(1)
	v_pk_add_f32 v[8:9], v[8:9], 1.0 op_sel_hi:[1,0]
	v_pk_add_f32 v[32:33], v[6:7], 1.0 op_sel_hi:[1,0]
	s_waitcnt vmcnt(0)
	v_pk_fma_f32 v[6:7], v[8:9], v[98:99], v[102:103]
	v_pk_fma_f32 v[8:9], v[32:33], v[96:97], v[100:101]
	s_nop 0
	s_nop 0
	s_nop 0
	s_nop 0
	s_nop 0
	s_nop 0
	v_cvt_pk_bf16_f32 v32, v8, v9
	s_nop 0
	s_nop 0
	s_nop 0
	s_nop 0
	s_nop 0
	v_cvt_pk_bf16_f32 v33, v6, v7
	global_store_dwordx2 v[78:79], v[32:33], off offset:-3072
	global_load_dwordx4 v[96:99], v[84:85], off offset:2048
	global_load_dwordx4 v[100:103], v[80:81], off offset:2048
	v_pk_mul_f32 v[32:33], v[72:73], v[12:13] op_sel_hi:[1,0]
	s_waitcnt vmcnt(0)
	v_pk_fma_f32 v[70:71], v[96:97], v[34:35], v[100:101]
	v_pk_fma_f32 v[72:73], v[98:99], v[32:33], v[102:103]
	global_store_dwordx4 v[104:105], v[70:73], off offset:-1024
	global_load_dwordx4 v[32:35], v[88:89], off offset:2048
	global_load_dwordx4 v[96:99], v[86:87], off offset:2048
	s_waitcnt vmcnt(1)
	v_pk_add_f32 v[34:35], v[34:35], 1.0 op_sel_hi:[1,0]
	v_pk_add_f32 v[74:75], v[32:33], 1.0 op_sel_hi:[1,0]
	s_waitcnt vmcnt(0)
	v_pk_fma_f32 v[32:33], v[34:35], v[72:73], v[98:99]
	v_pk_fma_f32 v[34:35], v[74:75], v[70:71], v[96:97]
	s_nop 0
	s_nop 0
	s_nop 0
	s_nop 0
	s_nop 0
	s_nop 0
	v_cvt_pk_bf16_f32 v70, v34, v35
	s_nop 0
	s_nop 0
	s_nop 0
	s_nop 0
	s_nop 0
	v_cvt_pk_bf16_f32 v71, v32, v33
	global_store_dwordx2 v[78:79], v[70:71], off offset:-2560
	global_load_dwordx4 v[70:73], v[84:85], off offset:3072
	s_nop 0
	global_load_dwordx4 v[96:99], v[80:81], off offset:3072
	s_waitcnt vmcnt(0)
	v_pk_fma_f32 v[70:71], v[70:71], v[36:37], v[96:97]
	v_pk_fma_f32 v[72:73], v[72:73], v[38:39], v[98:99]
	global_store_dwordx4 v[76:77], v[70:73], off offset:-4096
	global_load_dwordx4 v[36:39], v[88:89], off offset:3072
	global_load_dwordx4 v[96:99], v[86:87], off offset:3072
	s_waitcnt vmcnt(1)
	v_pk_add_f32 v[38:39], v[38:39], 1.0 op_sel_hi:[1,0]
	v_pk_add_f32 v[74:75], v[36:37], 1.0 op_sel_hi:[1,0]
	s_waitcnt vmcnt(0)
	v_pk_fma_f32 v[36:37], v[38:39], v[72:73], v[98:99]
	v_pk_fma_f32 v[38:39], v[74:75], v[70:71], v[96:97]
	s_nop 0
	s_nop 0
	s_nop 0
	s_nop 0
	s_nop 0
	s_nop 0
	v_cvt_pk_bf16_f32 v70, v38, v39
	s_nop 0
	s_nop 0
	s_nop 0
	s_nop 0
	s_nop 0
	v_cvt_pk_bf16_f32 v71, v36, v37
	global_store_dwordx2 v[78:79], v[70:71], off offset:-2048
	v_add_co_u32_e32 v70, vcc, s82, v84
	s_nop 1
	v_addc_co_u32_e32 v71, vcc, 0, v85, vcc
	v_add_co_u32_e32 v72, vcc, s82, v80
	global_load_dwordx4 v[96:99], v[70:71], off
	s_nop 0
	v_addc_co_u32_e32 v73, vcc, 0, v81, vcc
	global_load_dwordx4 v[100:103], v[72:73], off
	v_add_co_u32_e32 v66, vcc, s82, v88
	s_waitcnt vmcnt(0)
	v_pk_fma_f32 v[96:97], v[40:41], v[96:97], v[100:101]
	v_pk_fma_f32 v[98:99], v[46:47], v[98:99], v[102:103]
	v_addc_co_u32_e32 v67, vcc, 0, v89, vcc
	global_store_dwordx4 v[76:77], v[96:99], off offset:-3072
	v_add_co_u32_e32 v80, vcc, s82, v86
	global_load_dwordx4 v[40:43], v[66:67], off
	s_nop 0
	v_addc_co_u32_e32 v81, vcc, 0, v87, vcc
	global_load_dwordx4 v[84:87], v[80:81], off
	s_waitcnt vmcnt(1)
	v_pk_add_f32 v[42:43], v[42:43], 1.0 op_sel_hi:[1,0]
	v_pk_add_f32 v[46:47], v[40:41], 1.0 op_sel_hi:[1,0]
	s_waitcnt vmcnt(0)
	v_pk_fma_f32 v[40:41], v[98:99], v[42:43], v[86:87]
	v_pk_fma_f32 v[42:43], v[96:97], v[46:47], v[84:85]
	s_nop 0
	s_nop 0
	s_nop 0
	s_nop 0
	s_nop 0
	s_nop 0
	v_cvt_pk_bf16_f32 v46, v42, v43
	s_nop 0
	s_nop 0
	s_nop 0
	s_nop 0
	s_nop 0
	v_cvt_pk_bf16_f32 v47, v40, v41
	global_store_dwordx2 v[78:79], v[46:47], off offset:-1536
	global_load_dwordx4 v[84:87], v[70:71], off offset:1024
	global_load_dwordx4 v[96:99], v[72:73], off offset:1024
	v_pk_mul_f32 v[46:47], v[68:69], v[12:13] op_sel_hi:[1,0]
	s_waitcnt vmcnt(0)
	v_pk_fma_f32 v[84:85], v[44:45], v[84:85], v[96:97]
	v_pk_fma_f32 v[86:87], v[46:47], v[86:87], v[98:99]
	global_store_dwordx4 v[76:77], v[84:87], off offset:-2048
	global_load_dwordx4 v[44:47], v[66:67], off offset:1024
	global_load_dwordx4 v[96:99], v[80:81], off offset:1024
	s_waitcnt vmcnt(1)
	v_pk_add_f32 v[46:47], v[46:47], 1.0 op_sel_hi:[1,0]
	v_pk_add_f32 v[68:69], v[44:45], 1.0 op_sel_hi:[1,0]
	s_waitcnt vmcnt(0)
	v_pk_fma_f32 v[44:45], v[86:87], v[46:47], v[98:99]
	v_pk_fma_f32 v[46:47], v[84:85], v[68:69], v[96:97]
	s_nop 0
	s_nop 0
	s_nop 0
	s_nop 0
	s_nop 0
	s_nop 0
	v_cvt_pk_bf16_f32 v68, v46, v47
	s_nop 0
	s_nop 0
	s_nop 0
	s_nop 0
	s_nop 0
	v_cvt_pk_bf16_f32 v69, v44, v45
	global_store_dwordx2 v[78:79], v[68:69], off offset:-1024
	global_load_dwordx4 v[84:87], v[70:71], off offset:2048
	global_load_dwordx4 v[96:99], v[72:73], off offset:2048
	s_waitcnt vmcnt(0)
	v_pk_fma_f32 v[84:85], v[48:49], v[84:85], v[96:97]
	v_pk_fma_f32 v[86:87], v[50:51], v[86:87], v[98:99]
	global_store_dwordx4 v[76:77], v[84:87], off offset:-1024
	global_load_dwordx4 v[48:51], v[66:67], off offset:2048
	global_load_dwordx4 v[96:99], v[80:81], off offset:2048
	s_waitcnt vmcnt(1)
	v_pk_add_f32 v[50:51], v[50:51], 1.0 op_sel_hi:[1,0]
	v_pk_add_f32 v[68:69], v[48:49], 1.0 op_sel_hi:[1,0]
	s_waitcnt vmcnt(0)
	v_pk_fma_f32 v[48:49], v[86:87], v[50:51], v[98:99]
	v_pk_fma_f32 v[50:51], v[84:85], v[68:69], v[96:97]
	s_nop 0
	s_nop 0
	s_nop 0
	s_nop 0
	s_nop 0
	s_nop 0
	v_cvt_pk_bf16_f32 v68, v50, v51
	s_nop 0
	s_nop 0
	s_nop 0
	s_nop 0
	s_nop 0
	v_cvt_pk_bf16_f32 v69, v48, v49
	global_store_dwordx2 v[78:79], v[68:69], off offset:-512
	global_load_dwordx4 v[68:71], v[70:71], off offset:3072
	s_nop 0
	global_load_dwordx4 v[72:75], v[72:73], off offset:3072
	s_waitcnt vmcnt(0)
	v_pk_fma_f32 v[68:69], v[52:53], v[68:69], v[72:73]
	v_pk_fma_f32 v[70:71], v[54:55], v[70:71], v[74:75]
	global_store_dwordx4 v[76:77], v[68:71], off
	global_load_dwordx4 v[52:55], v[66:67], off offset:3072
	s_nop 0
	global_load_dwordx4 v[64:67], v[80:81], off offset:3072
	v_and_b32_e32 v77, 0xffff0000, v63
	v_and_b32_e32 v76, 0xffff0000, v61
	v_and_b32_e32 v75, 0xffff0000, v59
	v_and_b32_e32 v74, 0xffff0000, v58
	s_waitcnt vmcnt(1)
	v_pk_add_f32 v[54:55], v[54:55], 1.0 op_sel_hi:[1,0]
	v_pk_add_f32 v[72:73], v[52:53], 1.0 op_sel_hi:[1,0]
	s_waitcnt vmcnt(0)
	v_pk_fma_f32 v[52:53], v[70:71], v[54:55], v[66:67]
	v_pk_fma_f32 v[54:55], v[68:69], v[72:73], v[64:65]
	v_and_b32_e32 v67, 0xffff0000, v62
	v_cvt_pk_bf16_f32 v64, v54, v55
	v_cvt_pk_bf16_f32 v65, v52, v53
	global_store_dwordx2 v[78:79], v[64:65], off
	v_lshlrev_b32_e32 v64, 16, v60
	v_lshlrev_b32_e32 v65, 16, v62
	v_and_b32_e32 v66, 0xffff0000, v60
	v_lshlrev_b32_e32 v70, 16, v61
	v_lshlrev_b32_e32 v71, 16, v63
	v_pk_add_f32 v[60:61], v[64:65], v[66:67]
	v_pk_add_f32 v[62:63], v[70:71], v[76:77]
	v_lshlrev_b32_e32 v69, 16, v59
	v_lshlrev_b32_e32 v68, 16, v58
	v_pk_add_f32 v[60:61], v[60:61], v[62:63]
	v_pk_add_f32 v[58:59], v[68:69], v[74:75]
	v_add_f32_e32 v12, 0, v60
	v_pk_add_f32 v[58:59], v[58:59], v[58:59] op_sel:[0,1] op_sel_hi:[1,0]
	v_add_f32_e32 v22, v12, v61
	v_mov_b32_e32 v59, v21
	v_pk_add_f32 v[58:59], v[22:23], v[58:59]
	v_pk_add_f32 v[60:61], v[26:27], v[24:25]
	v_and_b32_e32 v73, 0xffff0000, v57
	v_pk_add_f32 v[58:59], v[58:59], v[60:61]
	v_lshlrev_b32_e32 v61, 16, v57
	v_lshlrev_b32_e32 v60, 16, v56
	v_and_b32_e32 v72, 0xffff0000, v56
	v_pk_add_f32 v[56:57], v[60:61], v[72:73]
	v_pk_add_f32 v[58:59], v[58:59], v[58:59] op_sel:[0,1] op_sel_hi:[1,0]
	v_pk_add_f32 v[56:57], v[56:57], v[56:57] op_sel:[0,1] op_sel_hi:[1,0]
	v_add_f32_e32 v14, v16, v17
	v_add_f32_e32 v12, v18, v19
	v_mov_b32_e32 v59, v10
	v_mov_b32_e32 v57, v11
	v_pk_add_f32 v[56:57], v[58:59], v[56:57]
	v_pk_add_f32 v[58:59], v[14:15], v[12:13]
	s_nop 0
	v_pk_add_f32 v[56:57], v[56:57], v[58:59]
	s_nop 0
	v_add_f32_e32 v12, v56, v57
	ds_bpermute_b32 v14, v90, v12
	s_waitcnt lgkmcnt(0)
	v_add_f32_e32 v12, v12, v14
	ds_bpermute_b32 v14, v91, v12
	s_waitcnt lgkmcnt(0)
	v_add_f32_e32 v12, v12, v14
	ds_bpermute_b32 v14, v92, v12
	s_waitcnt lgkmcnt(0)
	v_add_f32_e32 v12, v12, v14
	ds_bpermute_b32 v14, v93, v12
	s_waitcnt lgkmcnt(0)
	v_add_f32_e32 v12, v12, v14
	ds_bpermute_b32 v14, v94, v12
	s_waitcnt lgkmcnt(0)
	v_add_f32_e32 v12, v12, v14
	ds_bpermute_b32 v14, v95, v12
	s_waitcnt lgkmcnt(0)
	v_add_f32_e32 v14, v12, v14
	v_fmac_f32_e32 v66, 0xba000000, v14
	v_fmac_f32_e32 v67, 0xba000000, v14
	v_fmac_f32_e32 v76, 0xba000000, v14
	v_fmac_f32_e32 v64, 0xba000000, v14
	v_fmac_f32_e32 v77, 0xba000000, v14
	v_fmac_f32_e32 v65, 0xba000000, v14
	v_pk_mul_f32 v[58:59], v[66:67], v[66:67]
	v_fmac_f32_e32 v70, 0xba000000, v14
	v_fmac_f32_e32 v71, 0xba000000, v14
	v_mov_b32_e32 v62, v65
	v_mov_b32_e32 v63, v67
	v_mov_b32_e32 v56, v64
	v_pk_fma_f32 v[64:65], v[64:65], v[64:65], v[58:59]
	v_mov_b32_e32 v67, v77
	v_mov_b32_e32 v59, v76
	v_pk_mul_f32 v[76:77], v[76:77], v[76:77]
	v_mov_b32_e32 v57, v66
	v_mov_b32_e32 v66, v71
	v_mov_b32_e32 v58, v70
	v_pk_fma_f32 v[70:71], v[70:71], v[70:71], v[76:77]
	v_fmac_f32_e32 v74, 0xba000000, v14
	v_fmac_f32_e32 v75, 0xba000000, v14
	v_fmac_f32_e32 v69, 0xba000000, v14
	v_pk_add_f32 v[64:65], v[64:65], v[70:71]
	v_fmac_f32_e32 v68, 0xba000000, v14
	v_mov_b32_e32 v70, v69
	v_mov_b32_e32 v71, v75
	v_mov_b32_e32 v69, v74
	v_pk_mul_f32 v[76:77], v[70:71], v[70:71]
	v_pk_mul_f32 v[74:75], v[68:69], v[68:69]
	v_fmac_f32_e32 v28, 0xba000000, v14
	v_pk_mov_b32 v[78:79], v[74:75], v[76:77] op_sel:[1,0]
	v_mov_b32_e32 v75, v77
	v_fmac_f32_e32 v29, 0xba000000, v14
	v_fmac_f32_e32 v30, 0xba000000, v14
	v_mul_f32_e32 v12, v28, v28
	v_pk_add_f32 v[74:75], v[78:79], v[74:75]
	v_fmac_f32_e32 v31, 0xba000000, v14
	v_pk_fma_f32 v[76:77], v[28:29], v[28:29], v[12:13] op_sel_hi:[1,1,0]
	v_mul_f32_e32 v12, v30, v30
	v_pk_add_f32 v[64:65], v[64:65], v[64:65] op_sel_hi:[0,1]
	v_pk_add_f32 v[74:75], v[74:75], v[74:75] op_sel_hi:[0,1]
	v_pk_fma_f32 v[78:79], v[30:31], v[30:31], v[12:13] op_sel_hi:[1,1,0]
	v_fmac_f32_e32 v25, 0xba000000, v14
	v_fmac_f32_e32 v27, 0xba000000, v14
	v_fmac_f32_e32 v21, 0xba000000, v14
	v_fmac_f32_e32 v23, 0xba000000, v14
	v_mul_f32_e32 v76, v23, v23
	v_mul_f32_e32 v78, v21, v21
	v_mul_f32_e32 v74, v27, v27
	v_mul_f32_e32 v64, v25, v25
	v_pk_add_f32 v[76:77], v[76:77], v[78:79]
	v_pk_add_f32 v[64:65], v[74:75], v[64:65]
	v_fmac_f32_e32 v72, 0xba000000, v14
	v_pk_add_f32 v[64:65], v[76:77], v[64:65]
	v_fmac_f32_e32 v73, 0xba000000, v14
	v_fmac_f32_e32 v61, 0xba000000, v14
	v_pk_add_f32 v[74:75], v[64:65], v[64:65] op_sel_hi:[0,1]
	v_fmac_f32_e32 v60, 0xba000000, v14
	v_mov_b32_e32 v64, v61
	v_mov_b32_e32 v65, v73
	v_mov_b32_e32 v61, v72
	v_pk_mul_f32 v[76:77], v[64:65], v[64:65]
	v_pk_mul_f32 v[72:73], v[60:61], v[60:61]
	v_fmac_f32_e32 v16, 0xba000000, v14
	v_pk_mov_b32 v[78:79], v[72:73], v[76:77] op_sel:[1,0]
	v_mov_b32_e32 v73, v77
	v_fmac_f32_e32 v17, 0xba000000, v14
	v_fmac_f32_e32 v18, 0xba000000, v14
	v_mul_f32_e32 v12, v16, v16
	v_pk_add_f32 v[72:73], v[78:79], v[72:73]
	v_fmac_f32_e32 v19, 0xba000000, v14
	v_pk_fma_f32 v[76:77], v[16:17], v[16:17], v[12:13] op_sel_hi:[1,1,0]
	v_mul_f32_e32 v12, v18, v18
	v_pk_add_f32 v[72:73], v[72:73], v[72:73] op_sel_hi:[0,1]
	v_pk_fma_f32 v[78:79], v[18:19], v[18:19], v[12:13] op_sel_hi:[1,1,0]
	v_fmac_f32_e32 v13, 0xba000000, v14
	v_fmac_f32_e32 v15, 0xba000000, v14
	v_fmac_f32_e32 v11, 0xba000000, v14
	v_fmac_f32_e32 v10, 0xba000000, v14
	v_mul_f32_e32 v72, v15, v15
	v_mul_f32_e32 v74, v13, v13
	v_mul_f32_e32 v76, v10, v10
	v_mul_f32_e32 v78, v11, v11
	v_pk_add_f32 v[72:73], v[72:73], v[74:75]
	v_lshlrev_b32_e32 v74, 2, v1
	v_pk_add_f32 v[76:77], v[76:77], v[78:79]
	v_ashrrev_i32_e32 v75, 31, v74
	v_pk_add_f32 v[72:73], v[76:77], v[72:73]
	v_lshlrev_b64 v[76:77], 2, v[74:75]
	v_lshl_add_u64 v[80:81], s[12:13], 0, v[76:77]
	v_lshl_add_u64 v[78:79], s[14:15], 0, v[76:77]
	global_load_dwordx4 v[84:87], v[80:81], off
	global_load_dwordx4 v[96:99], v[78:79], off
	v_add_f32_e32 v12, v72, v73
	ds_bpermute_b32 v14, v90, v12
	s_waitcnt lgkmcnt(0)
	v_add_f32_e32 v12, v12, v14
	ds_bpermute_b32 v14, v91, v12
	s_waitcnt lgkmcnt(0)
	v_add_f32_e32 v12, v12, v14
	ds_bpermute_b32 v14, v92, v12
	s_waitcnt lgkmcnt(0)
	v_add_f32_e32 v12, v12, v14
	ds_bpermute_b32 v14, v93, v12
	s_waitcnt lgkmcnt(0)
	v_add_f32_e32 v12, v12, v14
	ds_bpermute_b32 v14, v94, v12
	s_waitcnt lgkmcnt(0)
	v_add_f32_e32 v12, v12, v14
	ds_bpermute_b32 v14, v95, v12
	s_waitcnt lgkmcnt(0)
	v_add_f32_e32 v12, v12, v14
	v_fmamk_f32 v12, v12, 0x3a000000, v250
	v_cmp_gt_f32_e32 vcc, s96, v12
	v_mul_f32_e32 v14, 0x4f800000, v12
	s_nop 0
	v_cndmask_b32_e32 v12, v12, v14, vcc
	v_sqrt_f32_e32 v14, v12
	s_nop 0
	v_add_u32_e32 v20, -1, v14
	v_fma_f32 v22, -v20, v14, v12
	v_cmp_ge_f32_e64 s[10:11], 0, v22
	v_add_u32_e32 v22, 1, v14
	s_nop 0
	v_cndmask_b32_e64 v20, v14, v20, s[10:11]
	v_fma_f32 v14, -v22, v14, v12
	v_cmp_lt_f32_e64 s[10:11], 0, v14
	s_nop 1
	v_cndmask_b32_e64 v14, v20, v22, s[10:11]
	v_mul_f32_e32 v20, 0x37800000, v14
	v_cndmask_b32_e32 v14, v14, v20, vcc
	v_cmp_class_f32_e32 vcc, v12, v251
	s_nop 1
	v_cndmask_b32_e32 v12, v14, v12, vcc
	v_div_scale_f32 v14, s[8:9], v12, v12, 1.0
	v_rcp_f32_e32 v20, v14
	s_mov_b64 s[8:9], 0x25d1e000
	v_fma_f32 v22, -v14, v20, 1.0
	v_fmac_f32_e32 v20, v22, v20
	v_div_scale_f32 v22, vcc, 1.0, v12, 1.0
	v_mul_f32_e32 v24, v22, v20
	v_fma_f32 v26, -v14, v24, v22
	v_fmac_f32_e32 v24, v26, v20
	v_fma_f32 v14, -v14, v24, v22
	v_div_fmas_f32 v14, v14, v20, v24
	v_div_fixup_f32 v14, v14, v12, 1.0
	v_pk_mul_f32 v[56:57], v[56:57], v[14:15] op_sel_hi:[1,0]
	v_pk_mul_f32 v[58:59], v[58:59], v[14:15] op_sel_hi:[1,0]
	s_waitcnt vmcnt(0)
	v_pk_fma_f32 v[96:97], v[84:85], v[56:57], v[96:97]
	v_lshl_add_u64 v[56:57], s[40:41], 0, v[76:77]
	v_pk_fma_f32 v[98:99], v[86:87], v[58:59], v[98:99]
	v_lshl_add_u64 v[86:87], v[56:57], 0, s[8:9]
	s_mov_b32 s8, 0x25d1f000
	v_add_co_u32_e32 v72, vcc, s8, v56
	v_lshl_add_u64 v[84:85], s[20:21], 0, v[76:77]
	s_nop 0
	v_addc_co_u32_e32 v73, vcc, 0, v57, vcc
	global_load_dwordx4 v[56:59], v[84:85], off
	v_lshl_add_u64 v[76:77], s[18:19], 0, v[76:77]
	global_load_dwordx4 v[100:103], v[76:77], off
	s_mov_b64 s[8:9], 0xcc1b000
	global_store_dwordx4 v[72:73], v[96:99], off offset:-4096
	v_pk_mul_f32 v[66:67], v[66:67], v[14:15] op_sel_hi:[1,0]
	v_pk_mul_f32 v[62:63], v[62:63], v[14:15] op_sel_hi:[1,0]
	v_pk_mul_f32 v[70:71], v[70:71], v[14:15] op_sel_hi:[1,0]
	v_pk_mul_f32 v[68:69], v[68:69], v[14:15] op_sel_hi:[1,0]
	v_pk_mul_f32 v[30:31], v[30:31], v[14:15] op_sel_hi:[1,0]
	v_pk_mul_f32 v[28:29], v[28:29], v[14:15] op_sel_hi:[1,0]
	v_mov_b32_e32 v24, v27
	v_pk_mul_f32 v[24:25], v[24:25], v[14:15] op_sel_hi:[1,0]
	v_pk_mul_f32 v[64:65], v[64:65], v[14:15] op_sel_hi:[1,0]
	v_pk_mul_f32 v[60:61], v[60:61], v[14:15] op_sel_hi:[1,0]
	v_pk_mul_f32 v[18:19], v[18:19], v[14:15] op_sel_hi:[1,0]
	v_pk_mul_f32 v[16:17], v[16:17], v[14:15] op_sel_hi:[1,0]
	v_pk_mul_f32 v[10:11], v[10:11], v[14:15] op_sel_hi:[1,0]
	s_waitcnt vmcnt(2)
	v_pk_add_f32 v[58:59], v[58:59], 1.0 op_sel_hi:[1,0]
	v_pk_add_f32 v[88:89], v[56:57], 1.0 op_sel_hi:[1,0]
	s_waitcnt vmcnt(1)
	v_pk_fma_f32 v[56:57], v[58:59], v[98:99], v[102:103]
	v_pk_fma_f32 v[58:59], v[88:89], v[96:97], v[100:101]
	v_lshl_add_u64 v[96:97], v[74:75], 1, s[16:17]
	s_nop 0
	s_nop 0
	s_nop 0
	s_nop 0
	s_nop 0
	v_cvt_pk_bf16_f32 v88, v58, v59
	s_nop 0
	s_nop 0
	s_nop 0
	s_nop 0
	s_nop 0
	v_lshl_add_u64 v[74:75], v[96:97], 0, s[8:9]
	v_add_co_u32_e32 v96, vcc, s61, v96
	v_cvt_pk_bf16_f32 v89, v56, v57
	s_nop 0
	v_addc_co_u32_e32 v97, vcc, 0, v97, vcc
	global_store_dwordx2 v[96:97], v[88:89], off
	global_load_dwordx4 v[96:99], v[80:81], off offset:1024
	s_nop 0
	global_load_dwordx4 v[100:103], v[78:79], off offset:1024
	s_waitcnt vmcnt(0)
	v_pk_fma_f32 v[96:97], v[96:97], v[62:63], v[100:101]
	v_pk_fma_f32 v[98:99], v[98:99], v[66:67], v[102:103]
	global_store_dwordx4 v[86:87], v[96:99], off offset:1024
	global_load_dwordx4 v[100:103], v[84:85], off offset:1024
	global_load_dwordx4 v[104:107], v[76:77], off offset:1024
	s_waitcnt vmcnt(1)
	v_pk_add_f32 v[66:67], v[100:101], 1.0 op_sel_hi:[1,0]
	s_waitcnt vmcnt(0)
	v_pk_fma_f32 v[66:67], v[66:67], v[96:97], v[104:105]
	v_pk_add_f32 v[62:63], v[102:103], 1.0 op_sel_hi:[1,0]
	v_pk_fma_f32 v[62:63], v[62:63], v[98:99], v[106:107]
	v_cvt_pk_bf16_f32 v88, v66, v67
	v_cvt_pk_bf16_f32 v89, v62, v63
	global_store_dwordx2 v[74:75], v[88:89], off offset:512
	global_load_dwordx4 v[96:99], v[80:81], off offset:2048
	global_load_dwordx4 v[100:103], v[78:79], off offset:2048
	s_waitcnt vmcnt(0)
	v_pk_fma_f32 v[96:97], v[96:97], v[68:69], v[100:101]
	v_pk_fma_f32 v[98:99], v[98:99], v[70:71], v[102:103]
	global_store_dwordx4 v[86:87], v[96:99], off offset:2048
	global_load_dwordx4 v[68:71], v[84:85], off offset:2048
	global_load_dwordx4 v[100:103], v[76:77], off offset:2048
	s_waitcnt vmcnt(1)
	v_pk_add_f32 v[70:71], v[70:71], 1.0 op_sel_hi:[1,0]
	v_pk_add_f32 v[88:89], v[68:69], 1.0 op_sel_hi:[1,0]
	s_waitcnt vmcnt(0)
	v_pk_fma_f32 v[68:69], v[70:71], v[98:99], v[102:103]
	v_pk_fma_f32 v[70:71], v[88:89], v[96:97], v[100:101]
	s_nop 0
	s_nop 0
	s_nop 0
	s_nop 0
	s_nop 0
	s_nop 0
	v_cvt_pk_bf16_f32 v88, v70, v71
	s_nop 0
	s_nop 0
	s_nop 0
	s_nop 0
	s_nop 0
	v_cvt_pk_bf16_f32 v89, v68, v69
	global_store_dwordx2 v[74:75], v[88:89], off offset:1024
	global_load_dwordx4 v[96:99], v[80:81], off offset:3072
	global_load_dwordx4 v[100:103], v[78:79], off offset:3072
	v_add_co_u32_e32 v80, vcc, s82, v80
	s_waitcnt vmcnt(0)
	v_pk_fma_f32 v[96:97], v[96:97], v[28:29], v[100:101]
	v_pk_fma_f32 v[98:99], v[98:99], v[30:31], v[102:103]
	global_store_dwordx4 v[86:87], v[96:99], off offset:3072
	global_load_dwordx4 v[28:31], v[84:85], off offset:3072
	s_nop 0
	global_load_dwordx4 v[86:89], v[76:77], off offset:3072
	v_addc_co_u32_e32 v81, vcc, 0, v81, vcc
	v_add_co_u32_e32 v78, vcc, s82, v78
	s_waitcnt vmcnt(1)
	v_pk_add_f32 v[30:31], v[30:31], 1.0 op_sel_hi:[1,0]
	v_pk_add_f32 v[100:101], v[28:29], 1.0 op_sel_hi:[1,0]
	s_waitcnt vmcnt(0)
	v_pk_fma_f32 v[28:29], v[30:31], v[98:99], v[88:89]
	v_pk_fma_f32 v[30:31], v[100:101], v[96:97], v[86:87]
	v_addc_co_u32_e32 v79, vcc, 0, v79, vcc
	s_nop 0
	s_nop 0
	s_nop 0
	s_nop 0
	s_nop 0
	v_cvt_pk_bf16_f32 v86, v30, v31
	s_nop 0
	s_nop 0
	s_nop 0
	s_nop 0
	s_nop 0
	v_cvt_pk_bf16_f32 v87, v28, v29
	global_store_dwordx2 v[74:75], v[86:87], off offset:1536
	global_load_dwordx4 v[86:89], v[80:81], off
	global_load_dwordx4 v[96:99], v[78:79], off
	v_add_co_u32_e32 v84, vcc, s82, v84
	v_mov_b32_e32 v20, v23
	s_nop 0
	v_addc_co_u32_e32 v85, vcc, 0, v85, vcc
	v_pk_mul_f32 v[20:21], v[20:21], v[14:15] op_sel_hi:[1,0]
	v_add_co_u32_e32 v76, vcc, s82, v76
	s_waitcnt vmcnt(0)
	v_pk_fma_f32 v[22:23], v[20:21], v[86:87], v[96:97]
	v_pk_fma_f32 v[24:25], v[24:25], v[88:89], v[98:99]
	global_load_dwordx4 v[86:89], v[84:85], off
	v_addc_co_u32_e32 v77, vcc, 0, v77, vcc
	global_load_dwordx4 v[96:99], v[76:77], off
	s_waitcnt vmcnt(1)
	v_pk_add_f32 v[26:27], v[86:87], 1.0 op_sel_hi:[1,0]
	global_store_dwordx4 v[72:73], v[22:25], off
	v_pk_add_f32 v[20:21], v[88:89], 1.0 op_sel_hi:[1,0]
	s_waitcnt vmcnt(1)
	v_pk_fma_f32 v[22:23], v[22:23], v[26:27], v[96:97]
	v_pk_fma_f32 v[20:21], v[24:25], v[20:21], v[98:99]
	v_cvt_pk_bf16_f32 v24, v22, v23
	v_cvt_pk_bf16_f32 v25, v20, v21
	global_store_dwordx2 v[74:75], v[24:25], off offset:2048
	global_load_dwordx4 v[24:27], v[80:81], off offset:1024
	s_nop 0
	global_load_dwordx4 v[86:89], v[78:79], off offset:1024
	s_waitcnt vmcnt(0)
	v_pk_fma_f32 v[86:87], v[60:61], v[24:25], v[86:87]
	v_pk_fma_f32 v[88:89], v[64:65], v[26:27], v[88:89]
	global_store_dwordx4 v[72:73], v[86:89], off offset:1024
	global_load_dwordx4 v[24:27], v[84:85], off offset:1024
	global_load_dwordx4 v[96:99], v[76:77], off offset:1024
	s_waitcnt vmcnt(1)
	v_pk_add_f32 v[26:27], v[26:27], 1.0 op_sel_hi:[1,0]
	v_pk_add_f32 v[60:61], v[24:25], 1.0 op_sel_hi:[1,0]
	s_waitcnt vmcnt(0)
	v_pk_fma_f32 v[24:25], v[88:89], v[26:27], v[98:99]
	v_pk_fma_f32 v[26:27], v[86:87], v[60:61], v[96:97]
	v_cvt_pk_bf16_f32 v60, v26, v27
	v_cvt_pk_bf16_f32 v61, v24, v25
	global_store_dwordx2 v[74:75], v[60:61], off offset:2560
	global_load_dwordx4 v[86:89], v[80:81], off offset:2048
	global_load_dwordx4 v[96:99], v[78:79], off offset:2048
	s_waitcnt vmcnt(0)
	v_pk_fma_f32 v[86:87], v[16:17], v[86:87], v[96:97]
	v_pk_fma_f32 v[88:89], v[18:19], v[88:89], v[98:99]
	global_store_dwordx4 v[72:73], v[86:89], off offset:2048
	global_load_dwordx4 v[16:19], v[84:85], off offset:2048
	global_load_dwordx4 v[96:99], v[76:77], off offset:2048
	s_waitcnt vmcnt(1)
	v_pk_add_f32 v[18:19], v[18:19], 1.0 op_sel_hi:[1,0]
	v_pk_add_f32 v[60:61], v[16:17], 1.0 op_sel_hi:[1,0]
	s_waitcnt vmcnt(0)
	v_pk_fma_f32 v[16:17], v[88:89], v[18:19], v[98:99]
	v_pk_fma_f32 v[18:19], v[86:87], v[60:61], v[96:97]
	v_cvt_pk_bf16_f32 v60, v18, v19
	v_cvt_pk_bf16_f32 v61, v16, v17
	global_store_dwordx2 v[74:75], v[60:61], off offset:3072
	global_load_dwordx4 v[86:89], v[80:81], off offset:3072
	s_nop 0
	global_load_dwordx4 v[78:81], v[78:79], off offset:3072
	v_mov_b32_e32 v12, v15
	v_pk_mul_f32 v[60:61], v[12:13], v[14:15] op_sel_hi:[1,0]
	s_waitcnt vmcnt(0)
	v_pk_fma_f32 v[12:13], v[10:11], v[86:87], v[78:79]
	v_pk_fma_f32 v[14:15], v[60:61], v[88:89], v[80:81]
	global_store_dwordx4 v[72:73], v[12:15], off offset:3072
	global_load_dwordx4 v[78:81], v[84:85], off offset:3072
	s_nop 0
	global_load_dwordx4 v[84:87], v[76:77], off offset:3072
	s_waitcnt vmcnt(1)
	v_pk_add_f32 v[60:61], v[78:79], 1.0 op_sel_hi:[1,0]
	v_pk_add_f32 v[10:11], v[80:81], 1.0 op_sel_hi:[1,0]
	s_waitcnt vmcnt(0)
	v_pk_fma_f32 v[12:13], v[12:13], v[60:61], v[84:85]
	v_pk_fma_f32 v[10:11], v[14:15], v[10:11], v[86:87]
	v_cvt_pk_bf16_f32 v14, v12, v13
	s_nop 0
	s_nop 0
	s_nop 0
	s_nop 0
	s_nop 0
	v_cvt_pk_bf16_f32 v15, v10, v11
	global_store_dwordx2 v[74:75], v[14:15], off offset:3584
	s_nop 0
	v_lshl_add_u32 v103, v1, 4, 0
	ds_read_b128 v[72:75], v103
	v_add_u32_e32 v80, 0x18400, v103
	s_waitcnt lgkmcnt(0)
	v_pk_fma_f32 v[14:15], v[4:5], v[72:73], 0 op_sel_hi:[1,1,0]
	v_pk_fma_f32 v[60:61], v[58:59], v[72:73], 0 op_sel_hi:[1,1,0]
	v_pk_fma_f32 v[14:15], v[2:3], v[74:75], v[14:15]
	v_pk_fma_f32 v[60:61], v[56:57], v[74:75], v[60:61]
	ds_read_b128 v[72:75], v103 offset:1024
	s_waitcnt lgkmcnt(0)
	v_pk_fma_f32 v[14:15], v[8:9], v[72:73], v[14:15]
	v_pk_fma_f32 v[60:61], v[66:67], v[72:73], v[60:61]
	v_pk_fma_f32 v[14:15], v[6:7], v[74:75], v[14:15]
	v_pk_fma_f32 v[60:61], v[62:63], v[74:75], v[60:61]
	ds_read_b128 v[72:75], v103 offset:2048
	s_waitcnt lgkmcnt(0)
	v_pk_fma_f32 v[14:15], v[34:35], v[72:73], v[14:15]
	v_pk_fma_f32 v[60:61], v[70:71], v[72:73], v[60:61]
	v_pk_fma_f32 v[14:15], v[32:33], v[74:75], v[14:15]
	v_pk_fma_f32 v[60:61], v[68:69], v[74:75], v[60:61]
	ds_read_b128 v[72:75], v103 offset:3072
	s_waitcnt lgkmcnt(0)
	v_pk_fma_f32 v[14:15], v[38:39], v[72:73], v[14:15]
	v_pk_fma_f32 v[60:61], v[30:31], v[72:73], v[60:61]
	v_pk_fma_f32 v[14:15], v[36:37], v[74:75], v[14:15]
	v_pk_fma_f32 v[60:61], v[28:29], v[74:75], v[60:61]
	ds_read_b128 v[72:75], v103 offset:4096
	s_waitcnt lgkmcnt(0)
	v_pk_fma_f32 v[14:15], v[42:43], v[72:73], v[14:15]
	v_pk_fma_f32 v[60:61], v[22:23], v[72:73], v[60:61]
	v_pk_fma_f32 v[14:15], v[40:41], v[74:75], v[14:15]
	v_pk_fma_f32 v[60:61], v[20:21], v[74:75], v[60:61]
	ds_read_b128 v[72:75], v103 offset:5120
	s_waitcnt lgkmcnt(0)
	v_pk_fma_f32 v[14:15], v[46:47], v[72:73], v[14:15]
	v_pk_fma_f32 v[60:61], v[26:27], v[72:73], v[60:61]
	v_pk_fma_f32 v[14:15], v[44:45], v[74:75], v[14:15]
	v_pk_fma_f32 v[60:61], v[24:25], v[74:75], v[60:61]
	ds_read_b128 v[72:75], v103 offset:6144
	s_waitcnt lgkmcnt(0)
	v_pk_fma_f32 v[14:15], v[50:51], v[72:73], v[14:15]
	v_pk_fma_f32 v[60:61], v[18:19], v[72:73], v[60:61]
	v_pk_fma_f32 v[14:15], v[48:49], v[74:75], v[14:15]
	v_pk_fma_f32 v[60:61], v[16:17], v[74:75], v[60:61]
	ds_read_b128 v[72:75], v103 offset:7168
	s_waitcnt lgkmcnt(0)
	v_pk_fma_f32 v[14:15], v[54:55], v[72:73], v[14:15]
	v_pk_fma_f32 v[60:61], v[12:13], v[72:73], v[60:61]
	v_pk_fma_f32 v[14:15], v[52:53], v[74:75], v[14:15]
	v_pk_fma_f32 v[60:61], v[10:11], v[74:75], v[60:61]
	v_add_f32_e32 v81, v14, v15
	v_add_f32_e32 v14, v60, v61
	ds_read_b128 v[72:75], v103 offset:8192
	s_waitcnt lgkmcnt(0)
	v_pk_fma_f32 v[60:61], v[4:5], v[72:73], 0 op_sel_hi:[1,1,0]
	v_pk_fma_f32 v[64:65], v[58:59], v[72:73], 0 op_sel_hi:[1,1,0]
	v_pk_fma_f32 v[60:61], v[2:3], v[74:75], v[60:61]
	v_pk_fma_f32 v[64:65], v[56:57], v[74:75], v[64:65]
	ds_read_b128 v[72:75], v103 offset:9216
	s_waitcnt lgkmcnt(0)
	v_pk_fma_f32 v[60:61], v[8:9], v[72:73], v[60:61]
	v_pk_fma_f32 v[64:65], v[66:67], v[72:73], v[64:65]
	v_pk_fma_f32 v[60:61], v[6:7], v[74:75], v[60:61]
	v_pk_fma_f32 v[64:65], v[62:63], v[74:75], v[64:65]
	ds_read_b128 v[72:75], v103 offset:10240
	s_waitcnt lgkmcnt(0)
	v_pk_fma_f32 v[60:61], v[34:35], v[72:73], v[60:61]
	v_pk_fma_f32 v[64:65], v[70:71], v[72:73], v[64:65]
	v_pk_fma_f32 v[60:61], v[32:33], v[74:75], v[60:61]
	v_pk_fma_f32 v[64:65], v[68:69], v[74:75], v[64:65]
	ds_read_b128 v[72:75], v103 offset:11264
	s_waitcnt lgkmcnt(0)
	v_pk_fma_f32 v[60:61], v[38:39], v[72:73], v[60:61]
	v_pk_fma_f32 v[64:65], v[30:31], v[72:73], v[64:65]
	v_pk_fma_f32 v[60:61], v[36:37], v[74:75], v[60:61]
	v_pk_fma_f32 v[64:65], v[28:29], v[74:75], v[64:65]
	ds_read_b128 v[72:75], v103 offset:12288
	s_waitcnt lgkmcnt(0)
	v_pk_fma_f32 v[60:61], v[42:43], v[72:73], v[60:61]
	v_pk_fma_f32 v[64:65], v[22:23], v[72:73], v[64:65]
	v_pk_fma_f32 v[60:61], v[40:41], v[74:75], v[60:61]
	v_pk_fma_f32 v[64:65], v[20:21], v[74:75], v[64:65]
	ds_read_b128 v[72:75], v103 offset:13312
	s_waitcnt lgkmcnt(0)
	v_pk_fma_f32 v[60:61], v[46:47], v[72:73], v[60:61]
	v_pk_fma_f32 v[64:65], v[26:27], v[72:73], v[64:65]
	v_pk_fma_f32 v[60:61], v[44:45], v[74:75], v[60:61]
	v_pk_fma_f32 v[64:65], v[24:25], v[74:75], v[64:65]
	ds_read_b128 v[72:75], v103 offset:14336
	s_waitcnt lgkmcnt(0)
	v_pk_fma_f32 v[60:61], v[50:51], v[72:73], v[60:61]
	v_pk_fma_f32 v[64:65], v[18:19], v[72:73], v[64:65]
	v_pk_fma_f32 v[60:61], v[48:49], v[74:75], v[60:61]
	v_pk_fma_f32 v[64:65], v[16:17], v[74:75], v[64:65]
	ds_read_b128 v[72:75], v103 offset:15360
	s_waitcnt lgkmcnt(0)
	v_pk_fma_f32 v[60:61], v[54:55], v[72:73], v[60:61]
	v_pk_fma_f32 v[64:65], v[12:13], v[72:73], v[64:65]
	v_pk_fma_f32 v[60:61], v[52:53], v[74:75], v[60:61]
	v_pk_fma_f32 v[64:65], v[10:11], v[74:75], v[64:65]
	v_add_f32_e32 v82, v60, v61
	v_add_f32_e32 v15, v64, v65
	ds_read_b128 v[72:75], v103 offset:16384
	s_waitcnt lgkmcnt(0)
	v_pk_fma_f32 v[60:61], v[4:5], v[72:73], 0 op_sel_hi:[1,1,0]
	v_pk_fma_f32 v[64:65], v[58:59], v[72:73], 0 op_sel_hi:[1,1,0]
	v_pk_fma_f32 v[60:61], v[2:3], v[74:75], v[60:61]
	v_pk_fma_f32 v[64:65], v[56:57], v[74:75], v[64:65]
	ds_read_b128 v[72:75], v103 offset:17408
	s_waitcnt lgkmcnt(0)
	v_pk_fma_f32 v[60:61], v[8:9], v[72:73], v[60:61]
	v_pk_fma_f32 v[64:65], v[66:67], v[72:73], v[64:65]
	v_pk_fma_f32 v[60:61], v[6:7], v[74:75], v[60:61]
	v_pk_fma_f32 v[64:65], v[62:63], v[74:75], v[64:65]
	ds_read_b128 v[72:75], v103 offset:18432
	s_waitcnt lgkmcnt(0)
	v_pk_fma_f32 v[60:61], v[34:35], v[72:73], v[60:61]
	v_pk_fma_f32 v[64:65], v[70:71], v[72:73], v[64:65]
	v_pk_fma_f32 v[60:61], v[32:33], v[74:75], v[60:61]
	v_pk_fma_f32 v[64:65], v[68:69], v[74:75], v[64:65]
	ds_read_b128 v[72:75], v103 offset:19456
	s_waitcnt lgkmcnt(0)
	v_pk_fma_f32 v[60:61], v[38:39], v[72:73], v[60:61]
	v_pk_fma_f32 v[64:65], v[30:31], v[72:73], v[64:65]
	v_pk_fma_f32 v[60:61], v[36:37], v[74:75], v[60:61]
	v_pk_fma_f32 v[64:65], v[28:29], v[74:75], v[64:65]
	ds_read_b128 v[72:75], v103 offset:20480
	s_waitcnt lgkmcnt(0)
	v_pk_fma_f32 v[60:61], v[42:43], v[72:73], v[60:61]
	v_pk_fma_f32 v[64:65], v[22:23], v[72:73], v[64:65]
	v_pk_fma_f32 v[60:61], v[40:41], v[74:75], v[60:61]
	v_pk_fma_f32 v[64:65], v[20:21], v[74:75], v[64:65]
	ds_read_b128 v[72:75], v103 offset:21504
	s_waitcnt lgkmcnt(0)
	v_pk_fma_f32 v[60:61], v[46:47], v[72:73], v[60:61]
	v_pk_fma_f32 v[64:65], v[26:27], v[72:73], v[64:65]
	v_pk_fma_f32 v[60:61], v[44:45], v[74:75], v[60:61]
	v_pk_fma_f32 v[64:65], v[24:25], v[74:75], v[64:65]
	ds_read_b128 v[72:75], v103 offset:22528
	s_waitcnt lgkmcnt(0)
	v_pk_fma_f32 v[60:61], v[50:51], v[72:73], v[60:61]
	v_pk_fma_f32 v[64:65], v[18:19], v[72:73], v[64:65]
	v_pk_fma_f32 v[60:61], v[48:49], v[74:75], v[60:61]
	v_pk_fma_f32 v[64:65], v[16:17], v[74:75], v[64:65]
	ds_read_b128 v[72:75], v103 offset:23552
	s_waitcnt lgkmcnt(0)
	v_pk_fma_f32 v[60:61], v[54:55], v[72:73], v[60:61]
	v_pk_fma_f32 v[64:65], v[12:13], v[72:73], v[64:65]
	v_pk_fma_f32 v[60:61], v[52:53], v[74:75], v[60:61]
	v_pk_fma_f32 v[64:65], v[10:11], v[74:75], v[64:65]
	v_add_f32_e32 v84, v60, v61
	v_add_f32_e32 v60, v64, v65
	ds_read_b128 v[72:75], v103 offset:24576
	s_waitcnt lgkmcnt(0)
	v_pk_fma_f32 v[64:65], v[4:5], v[72:73], 0 op_sel_hi:[1,1,0]
	v_pk_fma_f32 v[72:73], v[58:59], v[72:73], 0 op_sel_hi:[1,1,0]
	v_pk_fma_f32 v[64:65], v[2:3], v[74:75], v[64:65]
	v_pk_fma_f32 v[76:77], v[56:57], v[74:75], v[72:73]
	ds_read_b128 v[72:75], v103 offset:25600
	s_waitcnt lgkmcnt(0)
	v_pk_fma_f32 v[64:65], v[8:9], v[72:73], v[64:65]
	v_pk_fma_f32 v[72:73], v[66:67], v[72:73], v[76:77]
	v_pk_fma_f32 v[64:65], v[6:7], v[74:75], v[64:65]
	v_pk_fma_f32 v[76:77], v[62:63], v[74:75], v[72:73]
	ds_read_b128 v[72:75], v103 offset:26624
	s_waitcnt lgkmcnt(0)
	v_pk_fma_f32 v[64:65], v[34:35], v[72:73], v[64:65]
	v_pk_fma_f32 v[72:73], v[70:71], v[72:73], v[76:77]
	v_pk_fma_f32 v[64:65], v[32:33], v[74:75], v[64:65]
	v_pk_fma_f32 v[76:77], v[68:69], v[74:75], v[72:73]
	ds_read_b128 v[72:75], v103 offset:27648
	s_waitcnt lgkmcnt(0)
	v_pk_fma_f32 v[64:65], v[38:39], v[72:73], v[64:65]
	v_pk_fma_f32 v[72:73], v[30:31], v[72:73], v[76:77]
	v_pk_fma_f32 v[64:65], v[36:37], v[74:75], v[64:65]
	v_pk_fma_f32 v[76:77], v[28:29], v[74:75], v[72:73]
	ds_read_b128 v[72:75], v103 offset:28672
	s_waitcnt lgkmcnt(0)
	v_pk_fma_f32 v[64:65], v[42:43], v[72:73], v[64:65]
	v_pk_fma_f32 v[72:73], v[22:23], v[72:73], v[76:77]
	v_pk_fma_f32 v[64:65], v[40:41], v[74:75], v[64:65]
	v_pk_fma_f32 v[76:77], v[20:21], v[74:75], v[72:73]
	ds_read_b128 v[72:75], v103 offset:29696
	s_waitcnt lgkmcnt(0)
	v_pk_fma_f32 v[64:65], v[46:47], v[72:73], v[64:65]
	v_pk_fma_f32 v[72:73], v[26:27], v[72:73], v[76:77]
	v_pk_fma_f32 v[64:65], v[44:45], v[74:75], v[64:65]
	v_pk_fma_f32 v[76:77], v[24:25], v[74:75], v[72:73]
	ds_read_b128 v[72:75], v103 offset:30720
	s_waitcnt lgkmcnt(0)
	v_pk_fma_f32 v[64:65], v[50:51], v[72:73], v[64:65]
	v_pk_fma_f32 v[72:73], v[18:19], v[72:73], v[76:77]
	v_pk_fma_f32 v[64:65], v[48:49], v[74:75], v[64:65]
	v_pk_fma_f32 v[76:77], v[16:17], v[74:75], v[72:73]
	ds_read_b128 v[72:75], v103 offset:31744
	s_waitcnt lgkmcnt(0)
	v_pk_fma_f32 v[64:65], v[54:55], v[72:73], v[64:65]
	v_pk_fma_f32 v[72:73], v[12:13], v[72:73], v[76:77]
	v_pk_fma_f32 v[64:65], v[52:53], v[74:75], v[64:65]
	v_pk_fma_f32 v[72:73], v[10:11], v[74:75], v[72:73]
	v_add_f32_e32 v85, v64, v65
	v_add_f32_e32 v61, v72, v73
	ds_read_b128 v[72:75], v103 offset:32768
	s_waitcnt lgkmcnt(0)
	v_pk_fma_f32 v[64:65], v[4:5], v[72:73], 0 op_sel_hi:[1,1,0]
	v_pk_fma_f32 v[72:73], v[58:59], v[72:73], 0 op_sel_hi:[1,1,0]
	v_pk_fma_f32 v[64:65], v[2:3], v[74:75], v[64:65]
	v_pk_fma_f32 v[76:77], v[56:57], v[74:75], v[72:73]
	ds_read_b128 v[72:75], v103 offset:33792
	s_waitcnt lgkmcnt(0)
	v_pk_fma_f32 v[64:65], v[8:9], v[72:73], v[64:65]
	v_pk_fma_f32 v[72:73], v[66:67], v[72:73], v[76:77]
	v_pk_fma_f32 v[64:65], v[6:7], v[74:75], v[64:65]
	v_pk_fma_f32 v[76:77], v[62:63], v[74:75], v[72:73]
	ds_read_b128 v[72:75], v103 offset:34816
	s_waitcnt lgkmcnt(0)
	v_pk_fma_f32 v[64:65], v[34:35], v[72:73], v[64:65]
	v_pk_fma_f32 v[72:73], v[70:71], v[72:73], v[76:77]
	v_pk_fma_f32 v[64:65], v[32:33], v[74:75], v[64:65]
	v_pk_fma_f32 v[76:77], v[68:69], v[74:75], v[72:73]
	ds_read_b128 v[72:75], v103 offset:35840
	s_waitcnt lgkmcnt(0)
	v_pk_fma_f32 v[64:65], v[38:39], v[72:73], v[64:65]
	v_pk_fma_f32 v[72:73], v[30:31], v[72:73], v[76:77]
	v_pk_fma_f32 v[64:65], v[36:37], v[74:75], v[64:65]
	v_pk_fma_f32 v[76:77], v[28:29], v[74:75], v[72:73]
	ds_read_b128 v[72:75], v103 offset:36864
	s_waitcnt lgkmcnt(0)
	v_pk_fma_f32 v[64:65], v[42:43], v[72:73], v[64:65]
	v_pk_fma_f32 v[72:73], v[22:23], v[72:73], v[76:77]
	v_pk_fma_f32 v[64:65], v[40:41], v[74:75], v[64:65]
	v_pk_fma_f32 v[76:77], v[20:21], v[74:75], v[72:73]
	ds_read_b128 v[72:75], v103 offset:37888
	s_waitcnt lgkmcnt(0)
	v_pk_fma_f32 v[64:65], v[46:47], v[72:73], v[64:65]
	v_pk_fma_f32 v[72:73], v[26:27], v[72:73], v[76:77]
	v_pk_fma_f32 v[64:65], v[44:45], v[74:75], v[64:65]
	v_pk_fma_f32 v[76:77], v[24:25], v[74:75], v[72:73]
	ds_read_b128 v[72:75], v103 offset:38912
	s_waitcnt lgkmcnt(0)
	v_pk_fma_f32 v[64:65], v[50:51], v[72:73], v[64:65]
	v_pk_fma_f32 v[72:73], v[18:19], v[72:73], v[76:77]
	v_pk_fma_f32 v[64:65], v[48:49], v[74:75], v[64:65]
	v_pk_fma_f32 v[76:77], v[16:17], v[74:75], v[72:73]
	ds_read_b128 v[72:75], v103 offset:39936
	s_waitcnt lgkmcnt(0)
	v_pk_fma_f32 v[64:65], v[54:55], v[72:73], v[64:65]
	v_pk_fma_f32 v[72:73], v[12:13], v[72:73], v[76:77]
	v_pk_fma_f32 v[64:65], v[52:53], v[74:75], v[64:65]
	v_pk_fma_f32 v[72:73], v[10:11], v[74:75], v[72:73]
	v_add_f32_e32 v86, v64, v65
	v_add_f32_e32 v64, v72, v73
	ds_read_b128 v[72:75], v103 offset:40960
	s_waitcnt lgkmcnt(0)
	v_pk_fma_f32 v[76:77], v[4:5], v[72:73], 0 op_sel_hi:[1,1,0]
	v_pk_fma_f32 v[72:73], v[58:59], v[72:73], 0 op_sel_hi:[1,1,0]
	v_pk_fma_f32 v[76:77], v[2:3], v[74:75], v[76:77]
	v_pk_fma_f32 v[78:79], v[56:57], v[74:75], v[72:73]
	ds_read_b128 v[72:75], v103 offset:41984
	s_waitcnt lgkmcnt(0)
	v_pk_fma_f32 v[76:77], v[8:9], v[72:73], v[76:77]
	v_pk_fma_f32 v[72:73], v[66:67], v[72:73], v[78:79]
	v_pk_fma_f32 v[76:77], v[6:7], v[74:75], v[76:77]
	v_pk_fma_f32 v[78:79], v[62:63], v[74:75], v[72:73]
	ds_read_b128 v[72:75], v103 offset:43008
	s_waitcnt lgkmcnt(0)
	v_pk_fma_f32 v[76:77], v[34:35], v[72:73], v[76:77]
	v_pk_fma_f32 v[72:73], v[70:71], v[72:73], v[78:79]
	v_pk_fma_f32 v[76:77], v[32:33], v[74:75], v[76:77]
	v_pk_fma_f32 v[78:79], v[68:69], v[74:75], v[72:73]
	ds_read_b128 v[72:75], v103 offset:44032
	s_waitcnt lgkmcnt(0)
	v_pk_fma_f32 v[76:77], v[38:39], v[72:73], v[76:77]
	v_pk_fma_f32 v[72:73], v[30:31], v[72:73], v[78:79]
	v_pk_fma_f32 v[76:77], v[36:37], v[74:75], v[76:77]
	v_pk_fma_f32 v[78:79], v[28:29], v[74:75], v[72:73]
	ds_read_b128 v[72:75], v103 offset:45056
	s_waitcnt lgkmcnt(0)
	v_pk_fma_f32 v[76:77], v[42:43], v[72:73], v[76:77]
	v_pk_fma_f32 v[72:73], v[22:23], v[72:73], v[78:79]
	v_pk_fma_f32 v[76:77], v[40:41], v[74:75], v[76:77]
	v_pk_fma_f32 v[78:79], v[20:21], v[74:75], v[72:73]
	ds_read_b128 v[72:75], v103 offset:46080
	s_waitcnt lgkmcnt(0)
	v_pk_fma_f32 v[76:77], v[46:47], v[72:73], v[76:77]
	v_pk_fma_f32 v[72:73], v[26:27], v[72:73], v[78:79]
	v_pk_fma_f32 v[76:77], v[44:45], v[74:75], v[76:77]
	v_pk_fma_f32 v[78:79], v[24:25], v[74:75], v[72:73]
	ds_read_b128 v[72:75], v103 offset:47104
	s_waitcnt lgkmcnt(0)
	v_pk_fma_f32 v[76:77], v[50:51], v[72:73], v[76:77]
	v_pk_fma_f32 v[72:73], v[18:19], v[72:73], v[78:79]
	v_pk_fma_f32 v[76:77], v[48:49], v[74:75], v[76:77]
	v_pk_fma_f32 v[78:79], v[16:17], v[74:75], v[72:73]
	ds_read_b128 v[72:75], v103 offset:48128
	s_waitcnt lgkmcnt(0)
	v_pk_fma_f32 v[76:77], v[54:55], v[72:73], v[76:77]
	v_pk_fma_f32 v[72:73], v[12:13], v[72:73], v[78:79]
	v_pk_fma_f32 v[76:77], v[52:53], v[74:75], v[76:77]
	v_pk_fma_f32 v[72:73], v[10:11], v[74:75], v[72:73]
	v_add_f32_e32 v87, v76, v77
	v_add_f32_e32 v65, v72, v73
	ds_read_b128 v[72:75], v103 offset:49152
	s_waitcnt lgkmcnt(0)
	v_pk_fma_f32 v[76:77], v[4:5], v[72:73], 0 op_sel_hi:[1,1,0]
	v_pk_fma_f32 v[72:73], v[58:59], v[72:73], 0 op_sel_hi:[1,1,0]
	v_pk_fma_f32 v[76:77], v[2:3], v[74:75], v[76:77]
	v_pk_fma_f32 v[78:79], v[56:57], v[74:75], v[72:73]
	ds_read_b128 v[72:75], v103 offset:50176
	s_waitcnt lgkmcnt(0)
	v_pk_fma_f32 v[76:77], v[8:9], v[72:73], v[76:77]
	v_pk_fma_f32 v[72:73], v[66:67], v[72:73], v[78:79]
	v_pk_fma_f32 v[76:77], v[6:7], v[74:75], v[76:77]
	v_pk_fma_f32 v[78:79], v[62:63], v[74:75], v[72:73]
	ds_read_b128 v[72:75], v103 offset:51200
	s_waitcnt lgkmcnt(0)
	v_pk_fma_f32 v[76:77], v[34:35], v[72:73], v[76:77]
	v_pk_fma_f32 v[72:73], v[70:71], v[72:73], v[78:79]
	v_pk_fma_f32 v[76:77], v[32:33], v[74:75], v[76:77]
	v_pk_fma_f32 v[78:79], v[68:69], v[74:75], v[72:73]
	ds_read_b128 v[72:75], v103 offset:52224
	s_waitcnt lgkmcnt(0)
	v_pk_fma_f32 v[76:77], v[38:39], v[72:73], v[76:77]
	v_pk_fma_f32 v[72:73], v[30:31], v[72:73], v[78:79]
	v_pk_fma_f32 v[76:77], v[36:37], v[74:75], v[76:77]
	v_pk_fma_f32 v[78:79], v[28:29], v[74:75], v[72:73]
	ds_read_b128 v[72:75], v103 offset:53248
	s_waitcnt lgkmcnt(0)
	v_pk_fma_f32 v[76:77], v[42:43], v[72:73], v[76:77]
	v_pk_fma_f32 v[72:73], v[22:23], v[72:73], v[78:79]
	v_pk_fma_f32 v[76:77], v[40:41], v[74:75], v[76:77]
	v_pk_fma_f32 v[78:79], v[20:21], v[74:75], v[72:73]
	ds_read_b128 v[72:75], v103 offset:54272
	s_waitcnt lgkmcnt(0)
	v_pk_fma_f32 v[76:77], v[46:47], v[72:73], v[76:77]
	v_pk_fma_f32 v[72:73], v[26:27], v[72:73], v[78:79]
	v_pk_fma_f32 v[76:77], v[44:45], v[74:75], v[76:77]
	v_pk_fma_f32 v[78:79], v[24:25], v[74:75], v[72:73]
	ds_read_b128 v[72:75], v103 offset:55296
	s_waitcnt lgkmcnt(0)
	v_pk_fma_f32 v[76:77], v[50:51], v[72:73], v[76:77]
	v_pk_fma_f32 v[72:73], v[18:19], v[72:73], v[78:79]
	v_pk_fma_f32 v[76:77], v[48:49], v[74:75], v[76:77]
	v_pk_fma_f32 v[78:79], v[16:17], v[74:75], v[72:73]
	ds_read_b128 v[72:75], v103 offset:56320
	s_waitcnt lgkmcnt(0)
	v_pk_fma_f32 v[76:77], v[54:55], v[72:73], v[76:77]
	v_pk_fma_f32 v[72:73], v[12:13], v[72:73], v[78:79]
	v_pk_fma_f32 v[76:77], v[52:53], v[74:75], v[76:77]
	v_pk_fma_f32 v[72:73], v[10:11], v[74:75], v[72:73]
	v_add_f32_e32 v88, v76, v77
	v_add_f32_e32 v72, v72, v73
	ds_read_b128 v[74:77], v103 offset:57344
	s_waitcnt lgkmcnt(0)
	v_pk_fma_f32 v[78:79], v[4:5], v[74:75], 0 op_sel_hi:[1,1,0]
	v_pk_fma_f32 v[74:75], v[58:59], v[74:75], 0 op_sel_hi:[1,1,0]
	v_pk_fma_f32 v[78:79], v[2:3], v[76:77], v[78:79]
	v_pk_fma_f32 v[96:97], v[56:57], v[76:77], v[74:75]
	ds_read_b128 v[74:77], v103 offset:58368
	s_waitcnt lgkmcnt(0)
	v_pk_fma_f32 v[78:79], v[8:9], v[74:75], v[78:79]
	v_pk_fma_f32 v[74:75], v[66:67], v[74:75], v[96:97]
	v_pk_fma_f32 v[78:79], v[6:7], v[76:77], v[78:79]
	v_pk_fma_f32 v[96:97], v[62:63], v[76:77], v[74:75]
	ds_read_b128 v[74:77], v103 offset:59392
	s_waitcnt lgkmcnt(0)
	v_pk_fma_f32 v[78:79], v[34:35], v[74:75], v[78:79]
	v_pk_fma_f32 v[74:75], v[70:71], v[74:75], v[96:97]
	v_pk_fma_f32 v[78:79], v[32:33], v[76:77], v[78:79]
	v_pk_fma_f32 v[96:97], v[68:69], v[76:77], v[74:75]
	ds_read_b128 v[74:77], v103 offset:60416
	s_waitcnt lgkmcnt(0)
	v_pk_fma_f32 v[78:79], v[38:39], v[74:75], v[78:79]
	v_pk_fma_f32 v[74:75], v[30:31], v[74:75], v[96:97]
	v_pk_fma_f32 v[78:79], v[36:37], v[76:77], v[78:79]
	v_pk_fma_f32 v[96:97], v[28:29], v[76:77], v[74:75]
	ds_read_b128 v[74:77], v103 offset:61440
	s_waitcnt lgkmcnt(0)
	v_pk_fma_f32 v[78:79], v[42:43], v[74:75], v[78:79]
	v_pk_fma_f32 v[74:75], v[22:23], v[74:75], v[96:97]
	v_pk_fma_f32 v[78:79], v[40:41], v[76:77], v[78:79]
	v_pk_fma_f32 v[96:97], v[20:21], v[76:77], v[74:75]
	ds_read_b128 v[74:77], v103 offset:62464
	s_waitcnt lgkmcnt(0)
	v_pk_fma_f32 v[78:79], v[46:47], v[74:75], v[78:79]
	v_pk_fma_f32 v[74:75], v[26:27], v[74:75], v[96:97]
	v_pk_fma_f32 v[78:79], v[44:45], v[76:77], v[78:79]
	v_pk_fma_f32 v[96:97], v[24:25], v[76:77], v[74:75]
	ds_read_b128 v[74:77], v103 offset:63488
	s_waitcnt lgkmcnt(0)
	v_pk_fma_f32 v[78:79], v[50:51], v[74:75], v[78:79]
	v_pk_fma_f32 v[74:75], v[18:19], v[74:75], v[96:97]
	v_pk_fma_f32 v[78:79], v[48:49], v[76:77], v[78:79]
	v_pk_fma_f32 v[96:97], v[16:17], v[76:77], v[74:75]
	ds_read_b128 v[74:77], v103 offset:64512
	s_waitcnt lgkmcnt(0)
	v_pk_fma_f32 v[78:79], v[54:55], v[74:75], v[78:79]
	v_pk_fma_f32 v[74:75], v[12:13], v[74:75], v[96:97]
	v_pk_fma_f32 v[78:79], v[52:53], v[76:77], v[78:79]
	v_pk_fma_f32 v[74:75], v[10:11], v[76:77], v[74:75]
	v_add_f32_e32 v89, v78, v79
	v_add_f32_e32 v73, v74, v75
	v_add_u32_e32 v74, 0x10000, v103
	ds_read_b128 v[74:77], v74
	s_waitcnt lgkmcnt(0)
	v_pk_fma_f32 v[78:79], v[4:5], v[74:75], 0 op_sel_hi:[1,1,0]
	v_pk_fma_f32 v[74:75], v[58:59], v[74:75], 0 op_sel_hi:[1,1,0]
	v_pk_fma_f32 v[78:79], v[2:3], v[76:77], v[78:79]
	v_pk_fma_f32 v[96:97], v[56:57], v[76:77], v[74:75]
	v_add_u32_e32 v74, 0x10400, v103
	ds_read_b128 v[74:77], v74
	s_waitcnt lgkmcnt(0)
	v_pk_fma_f32 v[78:79], v[8:9], v[74:75], v[78:79]
	v_pk_fma_f32 v[74:75], v[66:67], v[74:75], v[96:97]
	v_pk_fma_f32 v[78:79], v[6:7], v[76:77], v[78:79]
	v_pk_fma_f32 v[96:97], v[62:63], v[76:77], v[74:75]
	v_add_u32_e32 v74, 0x10800, v103
	ds_read_b128 v[74:77], v74
	s_waitcnt lgkmcnt(0)
	v_pk_fma_f32 v[78:79], v[34:35], v[74:75], v[78:79]
	v_pk_fma_f32 v[74:75], v[70:71], v[74:75], v[96:97]
	v_pk_fma_f32 v[78:79], v[32:33], v[76:77], v[78:79]
	v_pk_fma_f32 v[96:97], v[68:69], v[76:77], v[74:75]
	v_add_u32_e32 v74, 0x10c00, v103
	ds_read_b128 v[74:77], v74
	s_waitcnt lgkmcnt(0)
	v_pk_fma_f32 v[78:79], v[38:39], v[74:75], v[78:79]
	v_pk_fma_f32 v[74:75], v[30:31], v[74:75], v[96:97]
	v_pk_fma_f32 v[78:79], v[36:37], v[76:77], v[78:79]
	v_pk_fma_f32 v[96:97], v[28:29], v[76:77], v[74:75]
	v_add_u32_e32 v74, 0x11000, v103
	ds_read_b128 v[74:77], v74
	s_waitcnt lgkmcnt(0)
	v_pk_fma_f32 v[78:79], v[42:43], v[74:75], v[78:79]
	v_pk_fma_f32 v[74:75], v[22:23], v[74:75], v[96:97]
	v_pk_fma_f32 v[78:79], v[40:41], v[76:77], v[78:79]
	v_pk_fma_f32 v[96:97], v[20:21], v[76:77], v[74:75]
	v_add_u32_e32 v74, 0x11400, v103
	ds_read_b128 v[74:77], v74
	s_waitcnt lgkmcnt(0)
	v_pk_fma_f32 v[78:79], v[46:47], v[74:75], v[78:79]
	v_pk_fma_f32 v[74:75], v[26:27], v[74:75], v[96:97]
	v_pk_fma_f32 v[78:79], v[44:45], v[76:77], v[78:79]
	v_pk_fma_f32 v[96:97], v[24:25], v[76:77], v[74:75]
	v_add_u32_e32 v74, 0x11800, v103
	ds_read_b128 v[74:77], v74
	s_waitcnt lgkmcnt(0)
	v_pk_fma_f32 v[78:79], v[50:51], v[74:75], v[78:79]
	v_pk_fma_f32 v[74:75], v[18:19], v[74:75], v[96:97]
	v_pk_fma_f32 v[78:79], v[48:49], v[76:77], v[78:79]
	v_pk_fma_f32 v[96:97], v[16:17], v[76:77], v[74:75]
	v_add_u32_e32 v74, 0x11c00, v103
	ds_read_b128 v[74:77], v74
	s_waitcnt lgkmcnt(0)
	v_pk_fma_f32 v[78:79], v[54:55], v[74:75], v[78:79]
	v_pk_fma_f32 v[74:75], v[12:13], v[74:75], v[96:97]
	v_pk_fma_f32 v[78:79], v[52:53], v[76:77], v[78:79]
	v_pk_fma_f32 v[74:75], v[10:11], v[76:77], v[74:75]
	v_add_f32_e32 v96, v78, v79
	v_add_f32_e32 v74, v74, v75
	v_add_u32_e32 v75, 0x12000, v103
	ds_read_b128 v[76:79], v75
	v_add_u32_e32 v75, 0x12400, v103
	s_waitcnt lgkmcnt(0)
	v_pk_fma_f32 v[98:99], v[4:5], v[76:77], 0 op_sel_hi:[1,1,0]
	v_pk_fma_f32 v[76:77], v[58:59], v[76:77], 0 op_sel_hi:[1,1,0]
	v_pk_fma_f32 v[98:99], v[2:3], v[78:79], v[98:99]
	v_pk_fma_f32 v[100:101], v[56:57], v[78:79], v[76:77]
	ds_read_b128 v[76:79], v75
	v_add_u32_e32 v75, 0x12800, v103
	s_waitcnt lgkmcnt(0)
	v_pk_fma_f32 v[98:99], v[8:9], v[76:77], v[98:99]
	v_pk_fma_f32 v[76:77], v[66:67], v[76:77], v[100:101]
	v_pk_fma_f32 v[98:99], v[6:7], v[78:79], v[98:99]
	v_pk_fma_f32 v[100:101], v[62:63], v[78:79], v[76:77]
	ds_read_b128 v[76:79], v75
	v_add_u32_e32 v75, 0x12c00, v103
	s_waitcnt lgkmcnt(0)
	v_pk_fma_f32 v[98:99], v[34:35], v[76:77], v[98:99]
	v_pk_fma_f32 v[76:77], v[70:71], v[76:77], v[100:101]
	v_pk_fma_f32 v[98:99], v[32:33], v[78:79], v[98:99]
	v_pk_fma_f32 v[100:101], v[68:69], v[78:79], v[76:77]
	ds_read_b128 v[76:79], v75
	v_add_u32_e32 v75, 0x13000, v103
	s_waitcnt lgkmcnt(0)
	v_pk_fma_f32 v[98:99], v[38:39], v[76:77], v[98:99]
	v_pk_fma_f32 v[76:77], v[30:31], v[76:77], v[100:101]
	v_pk_fma_f32 v[98:99], v[36:37], v[78:79], v[98:99]
	v_pk_fma_f32 v[100:101], v[28:29], v[78:79], v[76:77]
	ds_read_b128 v[76:79], v75
	v_add_u32_e32 v75, 0x13400, v103
	s_waitcnt lgkmcnt(0)
	v_pk_fma_f32 v[98:99], v[42:43], v[76:77], v[98:99]
	v_pk_fma_f32 v[76:77], v[22:23], v[76:77], v[100:101]
	v_pk_fma_f32 v[98:99], v[40:41], v[78:79], v[98:99]
	v_pk_fma_f32 v[100:101], v[20:21], v[78:79], v[76:77]
	ds_read_b128 v[76:79], v75
	v_add_u32_e32 v75, 0x13800, v103
	s_waitcnt lgkmcnt(0)
	v_pk_fma_f32 v[98:99], v[46:47], v[76:77], v[98:99]
	v_pk_fma_f32 v[76:77], v[26:27], v[76:77], v[100:101]
	v_pk_fma_f32 v[98:99], v[44:45], v[78:79], v[98:99]
	v_pk_fma_f32 v[100:101], v[24:25], v[78:79], v[76:77]
	ds_read_b128 v[76:79], v75
	v_add_u32_e32 v75, 0x13c00, v103
	s_waitcnt lgkmcnt(0)
	v_pk_fma_f32 v[98:99], v[50:51], v[76:77], v[98:99]
	v_pk_fma_f32 v[76:77], v[18:19], v[76:77], v[100:101]
	v_pk_fma_f32 v[98:99], v[48:49], v[78:79], v[98:99]
	v_pk_fma_f32 v[100:101], v[16:17], v[78:79], v[76:77]
	ds_read_b128 v[76:79], v75
	s_waitcnt lgkmcnt(0)
	v_pk_fma_f32 v[98:99], v[54:55], v[76:77], v[98:99]
	v_pk_fma_f32 v[76:77], v[12:13], v[76:77], v[100:101]
	v_pk_fma_f32 v[98:99], v[52:53], v[78:79], v[98:99]
	v_pk_fma_f32 v[76:77], v[10:11], v[78:79], v[76:77]
	v_add_f32_e32 v97, v98, v99
	v_add_f32_e32 v75, v76, v77
	v_add_u32_e32 v76, 0x14000, v103
	ds_read_b128 v[76:79], v76
	s_waitcnt lgkmcnt(0)
	v_pk_fma_f32 v[98:99], v[4:5], v[76:77], 0 op_sel_hi:[1,1,0]
	v_pk_fma_f32 v[76:77], v[58:59], v[76:77], 0 op_sel_hi:[1,1,0]
	v_pk_fma_f32 v[98:99], v[2:3], v[78:79], v[98:99]
	v_pk_fma_f32 v[100:101], v[56:57], v[78:79], v[76:77]
	v_add_u32_e32 v76, 0x14400, v103
	ds_read_b128 v[76:79], v76
	s_waitcnt lgkmcnt(0)
	v_pk_fma_f32 v[98:99], v[8:9], v[76:77], v[98:99]
	v_pk_fma_f32 v[76:77], v[66:67], v[76:77], v[100:101]
	v_pk_fma_f32 v[98:99], v[6:7], v[78:79], v[98:99]
	v_pk_fma_f32 v[100:101], v[62:63], v[78:79], v[76:77]
	v_add_u32_e32 v76, 0x14800, v103
	ds_read_b128 v[76:79], v76
	s_waitcnt lgkmcnt(0)
	v_pk_fma_f32 v[98:99], v[34:35], v[76:77], v[98:99]
	v_pk_fma_f32 v[76:77], v[70:71], v[76:77], v[100:101]
	v_pk_fma_f32 v[98:99], v[32:33], v[78:79], v[98:99]
	v_pk_fma_f32 v[100:101], v[68:69], v[78:79], v[76:77]
	v_add_u32_e32 v76, 0x14c00, v103
	ds_read_b128 v[76:79], v76
	s_waitcnt lgkmcnt(0)
	v_pk_fma_f32 v[98:99], v[38:39], v[76:77], v[98:99]
	v_pk_fma_f32 v[76:77], v[30:31], v[76:77], v[100:101]
	v_pk_fma_f32 v[98:99], v[36:37], v[78:79], v[98:99]
	v_pk_fma_f32 v[100:101], v[28:29], v[78:79], v[76:77]
	v_add_u32_e32 v76, 0x15000, v103
	ds_read_b128 v[76:79], v76
	s_waitcnt lgkmcnt(0)
	v_pk_fma_f32 v[98:99], v[42:43], v[76:77], v[98:99]
	v_pk_fma_f32 v[76:77], v[22:23], v[76:77], v[100:101]
	v_pk_fma_f32 v[98:99], v[40:41], v[78:79], v[98:99]
	v_pk_fma_f32 v[100:101], v[20:21], v[78:79], v[76:77]
	v_add_u32_e32 v76, 0x15400, v103
	ds_read_b128 v[76:79], v76
	s_waitcnt lgkmcnt(0)
	v_pk_fma_f32 v[98:99], v[46:47], v[76:77], v[98:99]
	v_pk_fma_f32 v[76:77], v[26:27], v[76:77], v[100:101]
	v_pk_fma_f32 v[98:99], v[44:45], v[78:79], v[98:99]
	v_pk_fma_f32 v[100:101], v[24:25], v[78:79], v[76:77]
	v_add_u32_e32 v76, 0x15800, v103
	ds_read_b128 v[76:79], v76
	s_waitcnt lgkmcnt(0)
	v_pk_fma_f32 v[98:99], v[50:51], v[76:77], v[98:99]
	v_pk_fma_f32 v[76:77], v[18:19], v[76:77], v[100:101]
	v_pk_fma_f32 v[98:99], v[48:49], v[78:79], v[98:99]
	v_pk_fma_f32 v[100:101], v[16:17], v[78:79], v[76:77]
	v_add_u32_e32 v76, 0x15c00, v103
	ds_read_b128 v[76:79], v76
	s_waitcnt lgkmcnt(0)
	v_pk_fma_f32 v[98:99], v[54:55], v[76:77], v[98:99]
	v_pk_fma_f32 v[76:77], v[12:13], v[76:77], v[100:101]
	v_pk_fma_f32 v[98:99], v[52:53], v[78:79], v[98:99]
	v_pk_fma_f32 v[76:77], v[10:11], v[78:79], v[76:77]
	v_add_f32_e32 v98, v98, v99
	v_add_f32_e32 v76, v76, v77
	v_add_u32_e32 v77, 0x16000, v103
	ds_read_b128 v[104:107], v77
	v_add_u32_e32 v77, 0x16400, v103
	s_waitcnt lgkmcnt(0)
	v_pk_fma_f32 v[78:79], v[4:5], v[104:105], 0 op_sel_hi:[1,1,0]
	v_pk_fma_f32 v[100:101], v[58:59], v[104:105], 0 op_sel_hi:[1,1,0]
	v_pk_fma_f32 v[78:79], v[2:3], v[106:107], v[78:79]
	v_pk_fma_f32 v[100:101], v[56:57], v[106:107], v[100:101]
	ds_read_b128 v[104:107], v77
	v_add_u32_e32 v77, 0x16800, v103
	s_waitcnt lgkmcnt(0)
	v_pk_fma_f32 v[78:79], v[8:9], v[104:105], v[78:79]
	v_pk_fma_f32 v[100:101], v[66:67], v[104:105], v[100:101]
	v_pk_fma_f32 v[78:79], v[6:7], v[106:107], v[78:79]
	v_pk_fma_f32 v[100:101], v[62:63], v[106:107], v[100:101]
	ds_read_b128 v[104:107], v77
	v_add_u32_e32 v77, 0x16c00, v103
	s_waitcnt lgkmcnt(0)
	v_pk_fma_f32 v[78:79], v[34:35], v[104:105], v[78:79]
	v_pk_fma_f32 v[100:101], v[70:71], v[104:105], v[100:101]
	v_pk_fma_f32 v[78:79], v[32:33], v[106:107], v[78:79]
	v_pk_fma_f32 v[100:101], v[68:69], v[106:107], v[100:101]
	ds_read_b128 v[104:107], v77
	v_add_u32_e32 v77, 0x17000, v103
	s_waitcnt lgkmcnt(0)
	v_pk_fma_f32 v[78:79], v[38:39], v[104:105], v[78:79]
	v_pk_fma_f32 v[100:101], v[30:31], v[104:105], v[100:101]
	v_pk_fma_f32 v[78:79], v[36:37], v[106:107], v[78:79]
	v_pk_fma_f32 v[100:101], v[28:29], v[106:107], v[100:101]
	ds_read_b128 v[104:107], v77
	v_add_u32_e32 v77, 0x17400, v103
	s_waitcnt lgkmcnt(0)
	v_pk_fma_f32 v[78:79], v[42:43], v[104:105], v[78:79]
	v_pk_fma_f32 v[100:101], v[22:23], v[104:105], v[100:101]
	v_pk_fma_f32 v[78:79], v[40:41], v[106:107], v[78:79]
	v_pk_fma_f32 v[100:101], v[20:21], v[106:107], v[100:101]
	ds_read_b128 v[104:107], v77
	v_add_u32_e32 v77, 0x17800, v103
	s_waitcnt lgkmcnt(0)
	v_pk_fma_f32 v[78:79], v[46:47], v[104:105], v[78:79]
	v_pk_fma_f32 v[100:101], v[26:27], v[104:105], v[100:101]
	v_pk_fma_f32 v[78:79], v[44:45], v[106:107], v[78:79]
	v_pk_fma_f32 v[100:101], v[24:25], v[106:107], v[100:101]
	ds_read_b128 v[104:107], v77
	v_add_u32_e32 v77, 0x17c00, v103
	s_waitcnt lgkmcnt(0)
	v_pk_fma_f32 v[78:79], v[50:51], v[104:105], v[78:79]
	v_pk_fma_f32 v[100:101], v[18:19], v[104:105], v[100:101]
	v_pk_fma_f32 v[78:79], v[48:49], v[106:107], v[78:79]
	v_pk_fma_f32 v[100:101], v[16:17], v[106:107], v[100:101]
	ds_read_b128 v[104:107], v77
	s_waitcnt lgkmcnt(0)
	v_pk_fma_f32 v[78:79], v[54:55], v[104:105], v[78:79]
	v_pk_fma_f32 v[100:101], v[12:13], v[104:105], v[100:101]
	v_pk_fma_f32 v[78:79], v[52:53], v[106:107], v[78:79]
	v_pk_fma_f32 v[100:101], v[10:11], v[106:107], v[100:101]
	v_add_f32_e32 v99, v78, v79
	v_add_f32_e32 v77, v100, v101
	v_add_u32_e32 v78, 0x18000, v103
	ds_read_b128 v[104:107], v78
	s_waitcnt lgkmcnt(0)
	v_pk_fma_f32 v[78:79], v[4:5], v[104:105], 0 op_sel_hi:[1,1,0]
	v_pk_fma_f32 v[100:101], v[58:59], v[104:105], 0 op_sel_hi:[1,1,0]
	v_pk_fma_f32 v[78:79], v[2:3], v[106:107], v[78:79]
	v_pk_fma_f32 v[100:101], v[56:57], v[106:107], v[100:101]
	ds_read_b128 v[104:107], v80
	v_add_u32_e32 v80, 0x18800, v103
	s_waitcnt lgkmcnt(0)
	v_pk_fma_f32 v[78:79], v[8:9], v[104:105], v[78:79]
	v_pk_fma_f32 v[100:101], v[66:67], v[104:105], v[100:101]
	v_pk_fma_f32 v[78:79], v[6:7], v[106:107], v[78:79]
	v_pk_fma_f32 v[100:101], v[62:63], v[106:107], v[100:101]
	ds_read_b128 v[104:107], v80
	v_add_u32_e32 v80, 0x18c00, v103
	s_waitcnt lgkmcnt(0)
	v_pk_fma_f32 v[78:79], v[34:35], v[104:105], v[78:79]
	v_pk_fma_f32 v[100:101], v[70:71], v[104:105], v[100:101]
	v_pk_fma_f32 v[78:79], v[32:33], v[106:107], v[78:79]
	v_pk_fma_f32 v[100:101], v[68:69], v[106:107], v[100:101]
	ds_read_b128 v[104:107], v80
	v_add_u32_e32 v80, 0x19000, v103
	s_waitcnt lgkmcnt(0)
	v_pk_fma_f32 v[78:79], v[38:39], v[104:105], v[78:79]
	v_pk_fma_f32 v[100:101], v[30:31], v[104:105], v[100:101]
	v_pk_fma_f32 v[78:79], v[36:37], v[106:107], v[78:79]
	v_pk_fma_f32 v[100:101], v[28:29], v[106:107], v[100:101]
	ds_read_b128 v[104:107], v80
	v_add_u32_e32 v80, 0x19400, v103
	s_waitcnt lgkmcnt(0)
	v_pk_fma_f32 v[78:79], v[42:43], v[104:105], v[78:79]
	v_pk_fma_f32 v[100:101], v[22:23], v[104:105], v[100:101]
	v_pk_fma_f32 v[78:79], v[40:41], v[106:107], v[78:79]
	v_pk_fma_f32 v[100:101], v[20:21], v[106:107], v[100:101]
	ds_read_b128 v[104:107], v80
	v_add_u32_e32 v80, 0x19800, v103
	s_waitcnt lgkmcnt(0)
	v_pk_fma_f32 v[78:79], v[46:47], v[104:105], v[78:79]
	v_pk_fma_f32 v[100:101], v[26:27], v[104:105], v[100:101]
	v_pk_fma_f32 v[78:79], v[44:45], v[106:107], v[78:79]
	v_pk_fma_f32 v[100:101], v[24:25], v[106:107], v[100:101]
	ds_read_b128 v[104:107], v80
	v_add_u32_e32 v80, 0x19c00, v103
	s_waitcnt lgkmcnt(0)
	v_pk_fma_f32 v[78:79], v[50:51], v[104:105], v[78:79]
	v_pk_fma_f32 v[100:101], v[18:19], v[104:105], v[100:101]
	v_pk_fma_f32 v[78:79], v[48:49], v[106:107], v[78:79]
	v_pk_fma_f32 v[100:101], v[16:17], v[106:107], v[100:101]
	ds_read_b128 v[104:107], v80
	v_add_u32_e32 v80, 0x1c000, v103
	s_waitcnt lgkmcnt(0)
	v_pk_fma_f32 v[78:79], v[54:55], v[104:105], v[78:79]
	v_pk_fma_f32 v[100:101], v[12:13], v[104:105], v[100:101]
	v_pk_fma_f32 v[78:79], v[52:53], v[106:107], v[78:79]
	v_pk_fma_f32 v[104:105], v[10:11], v[106:107], v[100:101]
	v_add_f32_e32 v100, v78, v79
	v_add_f32_e32 v78, v104, v105
	v_add_u32_e32 v79, 0x1a000, v103
	ds_read_b128 v[104:107], v79
	v_add_u32_e32 v79, 0x1a400, v103
	s_waitcnt lgkmcnt(0)
	v_pk_fma_f32 v[108:109], v[4:5], v[104:105], 0 op_sel_hi:[1,1,0]
	v_pk_fma_f32 v[104:105], v[58:59], v[104:105], 0 op_sel_hi:[1,1,0]
	v_pk_fma_f32 v[108:109], v[2:3], v[106:107], v[108:109]
	v_pk_fma_f32 v[110:111], v[56:57], v[106:107], v[104:105]
	ds_read_b128 v[104:107], v79
	v_add_u32_e32 v79, 0x1a800, v103
	s_waitcnt lgkmcnt(0)
	v_pk_fma_f32 v[108:109], v[8:9], v[104:105], v[108:109]
	v_pk_fma_f32 v[104:105], v[66:67], v[104:105], v[110:111]
	v_pk_fma_f32 v[108:109], v[6:7], v[106:107], v[108:109]
	v_pk_fma_f32 v[110:111], v[62:63], v[106:107], v[104:105]
	ds_read_b128 v[104:107], v79
	v_add_u32_e32 v79, 0x1ac00, v103
	s_waitcnt lgkmcnt(0)
	v_pk_fma_f32 v[108:109], v[34:35], v[104:105], v[108:109]
	v_pk_fma_f32 v[104:105], v[70:71], v[104:105], v[110:111]
	v_pk_fma_f32 v[108:109], v[32:33], v[106:107], v[108:109]
	v_pk_fma_f32 v[110:111], v[68:69], v[106:107], v[104:105]
	ds_read_b128 v[104:107], v79
	v_add_u32_e32 v79, 0x1b000, v103
	s_waitcnt lgkmcnt(0)
	v_pk_fma_f32 v[108:109], v[38:39], v[104:105], v[108:109]
	v_pk_fma_f32 v[104:105], v[30:31], v[104:105], v[110:111]
	v_pk_fma_f32 v[108:109], v[36:37], v[106:107], v[108:109]
	v_pk_fma_f32 v[110:111], v[28:29], v[106:107], v[104:105]
	ds_read_b128 v[104:107], v79
	v_add_u32_e32 v79, 0x1b400, v103
	s_waitcnt lgkmcnt(0)
	v_pk_fma_f32 v[108:109], v[42:43], v[104:105], v[108:109]
	v_pk_fma_f32 v[104:105], v[22:23], v[104:105], v[110:111]
	v_pk_fma_f32 v[108:109], v[40:41], v[106:107], v[108:109]
	v_pk_fma_f32 v[110:111], v[20:21], v[106:107], v[104:105]
	ds_read_b128 v[104:107], v79
	v_add_u32_e32 v79, 0x1b800, v103
	s_waitcnt lgkmcnt(0)
	v_pk_fma_f32 v[108:109], v[46:47], v[104:105], v[108:109]
	v_pk_fma_f32 v[104:105], v[26:27], v[104:105], v[110:111]
	v_pk_fma_f32 v[108:109], v[44:45], v[106:107], v[108:109]
	v_pk_fma_f32 v[110:111], v[24:25], v[106:107], v[104:105]
	ds_read_b128 v[104:107], v79
	v_add_u32_e32 v79, 0x1bc00, v103
	s_waitcnt lgkmcnt(0)
	v_pk_fma_f32 v[108:109], v[50:51], v[104:105], v[108:109]
	v_pk_fma_f32 v[104:105], v[18:19], v[104:105], v[110:111]
	v_pk_fma_f32 v[108:109], v[48:49], v[106:107], v[108:109]
	v_pk_fma_f32 v[110:111], v[16:17], v[106:107], v[104:105]
	ds_read_b128 v[104:107], v79
	s_waitcnt lgkmcnt(0)
	v_pk_fma_f32 v[108:109], v[54:55], v[104:105], v[108:109]
	v_pk_fma_f32 v[104:105], v[12:13], v[104:105], v[110:111]
	v_pk_fma_f32 v[108:109], v[52:53], v[106:107], v[108:109]
	v_pk_fma_f32 v[104:105], v[10:11], v[106:107], v[104:105]
	v_add_f32_e32 v101, v108, v109
	v_add_f32_e32 v79, v104, v105
	ds_read_b128 v[104:107], v80
	v_add_u32_e32 v80, 0x1c400, v103
	s_waitcnt lgkmcnt(0)
	v_pk_fma_f32 v[108:109], v[4:5], v[104:105], 0 op_sel_hi:[1,1,0]
	v_pk_fma_f32 v[104:105], v[58:59], v[104:105], 0 op_sel_hi:[1,1,0]
	v_pk_fma_f32 v[108:109], v[2:3], v[106:107], v[108:109]
	v_pk_fma_f32 v[110:111], v[56:57], v[106:107], v[104:105]
	ds_read_b128 v[104:107], v80
	v_add_u32_e32 v80, 0x1c800, v103
	s_waitcnt lgkmcnt(0)
	v_pk_fma_f32 v[108:109], v[8:9], v[104:105], v[108:109]
	v_pk_fma_f32 v[104:105], v[66:67], v[104:105], v[110:111]
	v_pk_fma_f32 v[108:109], v[6:7], v[106:107], v[108:109]
	v_pk_fma_f32 v[110:111], v[62:63], v[106:107], v[104:105]
	ds_read_b128 v[104:107], v80
	v_add_u32_e32 v80, 0x1cc00, v103
	s_waitcnt lgkmcnt(0)
	v_pk_fma_f32 v[108:109], v[34:35], v[104:105], v[108:109]
	v_pk_fma_f32 v[104:105], v[70:71], v[104:105], v[110:111]
	v_pk_fma_f32 v[108:109], v[32:33], v[106:107], v[108:109]
	v_pk_fma_f32 v[110:111], v[68:69], v[106:107], v[104:105]
	ds_read_b128 v[104:107], v80
	v_add_u32_e32 v80, 0x1d000, v103
	s_waitcnt lgkmcnt(0)
	v_pk_fma_f32 v[108:109], v[38:39], v[104:105], v[108:109]
	v_pk_fma_f32 v[104:105], v[30:31], v[104:105], v[110:111]
	v_pk_fma_f32 v[108:109], v[36:37], v[106:107], v[108:109]
	v_pk_fma_f32 v[110:111], v[28:29], v[106:107], v[104:105]
	ds_read_b128 v[104:107], v80
	v_add_u32_e32 v80, 0x1d400, v103
	s_waitcnt lgkmcnt(0)
	v_pk_fma_f32 v[108:109], v[42:43], v[104:105], v[108:109]
	v_pk_fma_f32 v[104:105], v[22:23], v[104:105], v[110:111]
	v_pk_fma_f32 v[108:109], v[40:41], v[106:107], v[108:109]
	v_pk_fma_f32 v[110:111], v[20:21], v[106:107], v[104:105]
	ds_read_b128 v[104:107], v80
	v_add_u32_e32 v80, 0x1d800, v103
	s_waitcnt lgkmcnt(0)
	v_pk_fma_f32 v[108:109], v[46:47], v[104:105], v[108:109]
	v_pk_fma_f32 v[104:105], v[26:27], v[104:105], v[110:111]
	v_pk_fma_f32 v[108:109], v[44:45], v[106:107], v[108:109]
	v_pk_fma_f32 v[110:111], v[24:25], v[106:107], v[104:105]
	ds_read_b128 v[104:107], v80
	v_add_u32_e32 v80, 0x1dc00, v103
	s_waitcnt lgkmcnt(0)
	v_pk_fma_f32 v[108:109], v[50:51], v[104:105], v[108:109]
	v_pk_fma_f32 v[104:105], v[18:19], v[104:105], v[110:111]
	v_pk_fma_f32 v[108:109], v[48:49], v[106:107], v[108:109]
	v_pk_fma_f32 v[110:111], v[16:17], v[106:107], v[104:105]
	ds_read_b128 v[104:107], v80
	s_waitcnt lgkmcnt(0)
	v_pk_fma_f32 v[108:109], v[54:55], v[104:105], v[108:109]
	v_pk_fma_f32 v[104:105], v[12:13], v[104:105], v[110:111]
	v_pk_fma_f32 v[108:109], v[52:53], v[106:107], v[108:109]
	v_pk_fma_f32 v[104:105], v[10:11], v[106:107], v[104:105]
	v_add_f32_e32 v102, v108, v109
	v_add_f32_e32 v80, v104, v105
	v_add_u32_e32 v104, 0x1e000, v103
	ds_read_b128 v[104:107], v104
	s_waitcnt lgkmcnt(0)
	v_pk_fma_f32 v[4:5], v[4:5], v[104:105], 0 op_sel_hi:[1,1,0]
	s_nop 0
	v_pk_fma_f32 v[108:109], v[2:3], v[106:107], v[4:5]
	v_pk_fma_f32 v[2:3], v[58:59], v[104:105], 0 op_sel_hi:[1,1,0]
	s_nop 0
	v_pk_fma_f32 v[56:57], v[56:57], v[106:107], v[2:3]
	v_add_u32_e32 v2, 0x1e400, v103
	ds_read_b128 v[2:5], v2
	s_waitcnt lgkmcnt(0)
	v_pk_fma_f32 v[8:9], v[8:9], v[2:3], v[108:109]
	v_pk_fma_f32 v[2:3], v[66:67], v[2:3], v[56:57]
	v_pk_fma_f32 v[6:7], v[6:7], v[4:5], v[8:9]
	v_pk_fma_f32 v[8:9], v[62:63], v[4:5], v[2:3]
	v_add_u32_e32 v2, 0x1e800, v103
	ds_read_b128 v[2:5], v2
	s_waitcnt lgkmcnt(0)
	v_pk_fma_f32 v[6:7], v[34:35], v[2:3], v[6:7]
	v_pk_fma_f32 v[2:3], v[70:71], v[2:3], v[8:9]
	v_pk_fma_f32 v[6:7], v[32:33], v[4:5], v[6:7]
	v_pk_fma_f32 v[8:9], v[68:69], v[4:5], v[2:3]
	v_add_u32_e32 v2, 0x1ec00, v103
	ds_read_b128 v[2:5], v2
	s_waitcnt lgkmcnt(0)
	v_pk_fma_f32 v[6:7], v[38:39], v[2:3], v[6:7]
	v_pk_fma_f32 v[2:3], v[30:31], v[2:3], v[8:9]
	v_pk_fma_f32 v[6:7], v[36:37], v[4:5], v[6:7]
	v_pk_fma_f32 v[8:9], v[28:29], v[4:5], v[2:3]
	v_add_u32_e32 v2, 0x1f000, v103
	ds_read_b128 v[2:5], v2
	s_waitcnt lgkmcnt(0)
	v_pk_fma_f32 v[6:7], v[42:43], v[2:3], v[6:7]
	v_pk_fma_f32 v[2:3], v[22:23], v[2:3], v[8:9]
	v_pk_fma_f32 v[6:7], v[40:41], v[4:5], v[6:7]
	v_pk_fma_f32 v[8:9], v[20:21], v[4:5], v[2:3]
	v_add_u32_e32 v2, 0x1f400, v103
	ds_read_b128 v[2:5], v2
	s_waitcnt lgkmcnt(0)
	v_pk_fma_f32 v[6:7], v[46:47], v[2:3], v[6:7]
	v_pk_fma_f32 v[2:3], v[26:27], v[2:3], v[8:9]
	v_pk_fma_f32 v[6:7], v[44:45], v[4:5], v[6:7]
	v_pk_fma_f32 v[8:9], v[24:25], v[4:5], v[2:3]
	v_add_u32_e32 v2, 0x1f800, v103
	ds_read_b128 v[2:5], v2
	s_waitcnt lgkmcnt(0)
	v_pk_fma_f32 v[6:7], v[50:51], v[2:3], v[6:7]
	v_pk_fma_f32 v[2:3], v[18:19], v[2:3], v[8:9]
	v_pk_fma_f32 v[6:7], v[48:49], v[4:5], v[6:7]
	v_pk_fma_f32 v[8:9], v[16:17], v[4:5], v[2:3]
	v_add_u32_e32 v2, 0x1fc00, v103
	ds_read_b128 v[2:5], v2
	s_waitcnt lgkmcnt(0)
	v_pk_fma_f32 v[6:7], v[54:55], v[2:3], v[6:7]
	v_pk_fma_f32 v[2:3], v[12:13], v[2:3], v[8:9]
	v_pk_fma_f32 v[6:7], v[52:53], v[4:5], v[6:7]
	v_pk_fma_f32 v[4:5], v[10:11], v[4:5], v[2:3]
	v_and_b32_e32 v3, 32, v1
	v_cmp_eq_u32_e32 vcc, 0, v3
	v_add_f32_e32 v4, v4, v5
	v_add_f32_e32 v2, v6, v7
	v_cndmask_b32_e32 v5, v81, v96, vcc
	ds_bpermute_b32 v5, v95, v5
	v_cndmask_b32_e32 v6, v82, v97, vcc
	ds_bpermute_b32 v6, v95, v6
	v_cndmask_b32_e32 v7, v84, v98, vcc
	ds_bpermute_b32 v7, v95, v7
	v_cndmask_b32_e32 v8, v85, v99, vcc
	ds_bpermute_b32 v8, v95, v8
	v_cndmask_b32_e32 v9, v86, v100, vcc
	v_cndmask_b32_e32 v3, v96, v81, vcc
	ds_bpermute_b32 v9, v95, v9
	v_cndmask_b32_e32 v10, v87, v101, vcc
	s_waitcnt lgkmcnt(4)
	v_add_f32_e32 v3, v3, v5
	v_cndmask_b32_e32 v5, v97, v82, vcc
	ds_bpermute_b32 v10, v95, v10
	v_cndmask_b32_e32 v11, v88, v102, vcc
	s_waitcnt lgkmcnt(4)
	v_add_f32_e32 v6, v5, v6
	v_cndmask_b32_e32 v5, v98, v84, vcc
	ds_bpermute_b32 v11, v95, v11
	s_waitcnt lgkmcnt(4)
	v_add_f32_e32 v7, v5, v7
	v_cndmask_b32_e32 v5, v99, v85, vcc
	s_waitcnt lgkmcnt(3)
	v_add_f32_e32 v8, v5, v8
	v_cndmask_b32_e32 v5, v100, v86, vcc
	s_waitcnt lgkmcnt(2)
	v_add_f32_e32 v5, v5, v9
	v_cndmask_b32_e32 v9, v101, v87, vcc
	s_waitcnt lgkmcnt(1)
	v_add_f32_e32 v9, v9, v10
	v_cndmask_b32_e32 v10, v102, v88, vcc
	s_waitcnt lgkmcnt(0)
	v_add_f32_e32 v10, v10, v11
	v_cndmask_b32_e32 v11, v2, v89, vcc
	v_cndmask_b32_e32 v2, v89, v2, vcc
	ds_bpermute_b32 v2, v95, v2
	s_waitcnt lgkmcnt(0)
	v_add_f32_e32 v11, v11, v2
	v_and_b32_e32 v2, 16, v1
	v_cmp_eq_u32_e64 s[10:11], 0, v2
	s_nop 1
	v_cndmask_b32_e64 v2, v5, v3, s[10:11]
	v_cndmask_b32_e64 v3, v3, v5, s[10:11]
	ds_bpermute_b32 v3, v94, v3
	s_waitcnt lgkmcnt(0)
	v_add_f32_e32 v5, v2, v3
	v_cndmask_b32_e64 v3, v6, v9, s[10:11]
	ds_bpermute_b32 v3, v94, v3
	v_cndmask_b32_e64 v2, v9, v6, s[10:11]
	v_cndmask_b32_e64 v6, v7, v10, s[10:11]
	ds_bpermute_b32 v6, v94, v6
	s_waitcnt lgkmcnt(1)
	v_add_f32_e32 v2, v2, v3
	v_cndmask_b32_e64 v3, v10, v7, s[10:11]
	v_cndmask_b32_e64 v7, v8, v11, s[10:11]
	ds_bpermute_b32 v7, v94, v7
	s_waitcnt lgkmcnt(1)
	v_add_f32_e32 v6, v3, v6
	v_cndmask_b32_e64 v3, v11, v8, s[10:11]
	s_waitcnt lgkmcnt(0)
	v_add_f32_e32 v3, v3, v7
	v_and_b32_e32 v7, 8, v1
	v_cmp_eq_u32_e64 s[12:13], 0, v7
	s_nop 1
	v_cndmask_b32_e64 v7, v6, v5, s[12:13]
	v_cndmask_b32_e64 v5, v5, v6, s[12:13]
	v_cndmask_b32_e64 v6, v3, v2, s[12:13]
	v_cndmask_b32_e64 v2, v2, v3, s[12:13]
	ds_bpermute_b32 v5, v93, v5
	ds_bpermute_b32 v2, v93, v2
	v_and_b32_e32 v3, 4, v1
	v_cmp_eq_u32_e64 s[14:15], 0, v3
	s_waitcnt lgkmcnt(1)
	v_add_f32_e32 v5, v7, v5
	s_waitcnt lgkmcnt(0)
	v_add_f32_e32 v2, v6, v2
	v_cndmask_b32_e64 v3, v2, v5, s[14:15]
	v_cndmask_b32_e64 v2, v5, v2, s[14:15]
	ds_bpermute_b32 v2, v92, v2
	v_and_b32_e32 v5, 3, v1
	v_bfe_u32 v1, v1, 2, 4
	v_cmp_eq_u32_e64 s[16:17], 0, v5
	v_lshlrev_b32_e32 v82, 2, v1
	s_waitcnt lgkmcnt(0)
	v_add_f32_e32 v2, v3, v2
	ds_bpermute_b32 v3, v91, v2
	s_waitcnt lgkmcnt(0)
	v_add_f32_e32 v2, v2, v3
	ds_bpermute_b32 v3, v90, v2
	s_and_saveexec_b64 s[40:41], s[16:17]
	s_cbranch_execz .LBB0_1749
	s_waitcnt lgkmcnt(0)
	v_add_f32_e32 v2, v2, v3
	global_load_dword v3, v82, s[38:39] offset:64
	v_cmp_lt_u32_e64 s[18:19], 7, v1
	s_waitcnt vmcnt(0)
	v_add_f32_e32 v5, v2, v3
	s_and_saveexec_b64 s[8:9], s[18:19]
	s_xor_b64 s[54:55], exec, s[8:9]
	s_cbranch_execz .LBB0_1746
	s_mov_b32 s18, 0xbfb8aa3b
	v_mul_f32_e64 v2, |v5|, s18
	v_exp_f32_e32 v6, v2
	s_lshl_b64 s[8:9], s[30:31], 5
	s_add_u32 s8, s58, s8
	s_addc_u32 s9, s59, s9
	v_lshl_add_u64 v[2:3], s[8:9], 0, v[82:83]
	v_add_f32_e32 v6, 1.0, v6
	s_mov_b32 s8, 0x800000
	v_cmp_gt_f32_e64 s[18:19], s8, v6
	s_movk_i32 s8, 0xffe0
	s_mov_b32 s9, -1
	v_cndmask_b32_e64 v7, 0, 32, s[18:19]
	v_ldexp_f32 v6, v6, v7
	v_log_f32_e32 v6, v6
	v_lshl_add_u64 v[2:3], v[2:3], 0, s[8:9]
	s_mov_b32 s8, 0x3f317217
	v_max_f32_e32 v5, v5, v5
	v_mul_f32_e32 v7, 0x3f317217, v6
	v_fma_f32 v7, v6, s8, -v7
	v_fmac_f32_e32 v7, 0x3377d1cf, v6
	s_mov_b32 s8, 0x7f800000
	v_fmac_f32_e32 v7, 0x3f317217, v6
	v_cmp_lt_f32_e64 s[20:21], |v6|, s8
	v_min_f32_e32 v5, 0, v5
	s_nop 0
	v_cndmask_b32_e64 v6, v6, v7, s[20:21]
	v_mov_b32_e32 v7, 0x41b17218
	v_cndmask_b32_e64 v7, 0, v7, s[18:19]
	v_sub_f32_e32 v6, v6, v7
	v_sub_f32_e32 v5, v5, v6

.LBB0_1757:
	s_abs_i32 s9, s28
	v_readlane_b32 s12, v253, 56
	s_mul_hi_u32 s12, s9, s12
	v_readlane_b32 s15, v253, 57
	s_mul_i32 s13, s12, s15
	s_ashr_i32 s8, s28, 31
	s_sub_i32 s9, s9, s13
	s_xor_b32 s8, s8, s43
	s_add_i32 s13, s12, 1
	s_sub_i32 s14, s9, s15
	s_cmp_ge_u32 s9, s15
	s_cselect_b32 s12, s13, s12
	s_cselect_b32 s9, s14, s9
	s_add_i32 s13, s12, 1
	s_cmp_ge_u32 s9, s15
	s_cselect_b32 s9, s13, s12
	s_xor_b32 s9, s9, s8
	s_sub_i32 s8, s9, s8
	s_add_i32 s8, s28, s8
	s_and_b32 s8, s8, 7
	v_readlane_b32 s9, v253, 15
	s_cmp_lg_u32 s9, s8
	s_cbranch_scc1 .LBB0_1756
	s_add_i32 s14, s28, 0x2000
	v_mov_b32_e32 v1, v232
	s_mov_b64 s[12:13], s[46:47]
	s_mov_b64 s[8:9], s[0:1]
	v_mov_b32_e32 v2, v0
	s_mov_b64 s[16:17], s[44:45]
	s_add_u32 s15, s12, 0x25d1e000
	v_readlane_b32 s34, v254, 40
	s_addc_u32 s20, s13, 0
	v_readlane_b32 s35, v254, 41
	s_and_b64 s[18:19], s[34:35], exec
	s_cselect_b32 s27, s20, s17
	s_cselect_b32 s30, s15, s16
	s_add_u32 s15, s12, 0xcc1b000
	s_addc_u32 s18, s13, 0
	s_and_b64 s[16:17], s[34:35], exec
	s_cselect_b32 s26, s18, 0
	s_cselect_b32 s29, s15, 0
	s_add_u32 s16, s12, 0x100000
	s_addc_u32 s17, s13, 0
	s_lshr_b32 s15, s28, 3
	s_add_i32 s15, s15, 1
	s_cmp_gt_i32 s28, -1
	v_lshlrev_b32_e32 v40, 2, v1
	s_cselect_b32 s15, s15, 0
	v_ashrrev_i32_e32 v41, 31, v40
	s_add_i32 s18, s15, 33
	s_waitcnt lgkmcnt(0)
	v_mov_b64_e32 v[2:3], s[16:17]
	v_mov_b32_e32 v4, 0xc000
	s_add_i32 s15, s15, s97
	v_lshlrev_b64 v[42:43], 2, v[40:41]
	v_mad_u64_u32 v[38:39], s[16:17], s18, v4, v[2:3]
	v_mad_u64_u32 v[2:3], s[16:17], s15, v4, v[2:3]
	v_lshl_add_u64 v[4:5], s[12:13], 0, v[42:43]
	v_lshl_add_u64 v[4:5], v[4:5], 0, s[10:11]
	s_mov_b32 s22, 0xfebff000
	v_add_co_u32_e32 v14, vcc, s22, v4
	s_mov_b32 s22, 0xfec00000
	s_nop 0
	v_addc_co_u32_e32 v15, vcc, -1, v5, vcc
	v_add_co_u32_e32 v34, vcc, s22, v4
	s_mov_b32 s22, 0xfedff000
	s_nop 0
	v_addc_co_u32_e32 v35, vcc, -1, v5, vcc
	v_add_co_u32_e32 v52, vcc, s22, v4
	s_mov_b32 s22, 0xfee00000
	s_nop 0
	v_addc_co_u32_e32 v53, vcc, -1, v5, vcc
	v_add_co_u32_e32 v72, vcc, s22, v4
	s_mov_b32 s22, 0xfefff000
	s_nop 0
	v_addc_co_u32_e32 v73, vcc, -1, v5, vcc
	v_add_co_u32_e32 v80, vcc, s22, v4
	global_load_dwordx4 v[6:9], v[14:15], off offset:-3072
	global_load_dwordx4 v[10:13], v[14:15], off offset:-2048
	s_nop 0
	global_load_dwordx4 v[14:17], v[14:15], off offset:-1024
	s_nop 0
	global_load_dwordx4 v[18:21], v[34:35], off offset:-4096
	global_load_dwordx4 v[22:25], v[34:35], off offset:-3072
	global_load_dwordx4 v[26:29], v[34:35], off offset:-2048
	global_load_dwordx4 v[30:33], v[34:35], off offset:-1024
	s_nop 0
	global_load_dwordx4 v[34:37], v[34:35], off
	s_nop 0
	global_load_dwordx4 v[44:47], v[52:53], off offset:-3072
	global_load_dwordx4 v[48:51], v[52:53], off offset:-2048
	s_nop 0
	global_load_dwordx4 v[52:55], v[52:53], off offset:-1024
	v_addc_co_u32_e32 v81, vcc, -1, v5, vcc
	s_mov_b32 s22, 0xff000000
	global_load_dwordx4 v[56:59], v[72:73], off offset:-4096
	global_load_dwordx4 v[60:63], v[72:73], off offset:-3072
	global_load_dwordx4 v[64:67], v[72:73], off offset:-2048
	global_load_dwordx4 v[68:71], v[72:73], off offset:-1024
	s_nop 0
	global_load_dwordx4 v[72:75], v[72:73], off
	s_nop 0
	global_load_dwordx4 v[76:79], v[80:81], off offset:-3072
	global_load_dwordx4 v[84:87], v[80:81], off offset:-2048
	global_load_dwordx4 v[88:91], v[80:81], off offset:-1024
	v_add_co_u32_e32 v80, vcc, s22, v4
	s_mov_b32 s22, 0xff1ff000
	s_nop 0
	v_addc_co_u32_e32 v81, vcc, -1, v5, vcc
	global_load_dwordx4 v[92:95], v[80:81], off offset:-4096
	global_load_dwordx4 v[96:99], v[80:81], off offset:-3072
	global_load_dwordx4 v[100:103], v[80:81], off offset:-2048
	global_load_dwordx4 v[104:107], v[80:81], off offset:-1024
	global_load_dwordx4 v[108:111], v[80:81], off
	s_ashr_i32 s15, s14, 31
	s_lshl_b64 s[16:17], s[14:15], 11
	s_lshl_b64 s[18:19], s[14:15], 13
	s_add_u32 s20, s12, s18
	s_addc_u32 s21, s13, s19
	v_lshl_add_u64 v[2:3], v[2:3], 0, v[42:43]
	s_waitcnt vmcnt(15)
	v_pk_add_f32 v[8:9], v[8:9], v[46:47]
	v_pk_add_f32 v[6:7], v[6:7], v[44:45]
	s_waitcnt vmcnt(13)
	v_pk_add_f32 v[14:15], v[14:15], v[52:53]
	v_pk_add_f32 v[12:13], v[12:13], v[50:51]
	v_pk_add_f32 v[10:11], v[10:11], v[48:49]
	v_pk_add_f32 v[16:17], v[16:17], v[54:55]
	s_waitcnt vmcnt(8)
	v_pk_add_f32 v[34:35], v[34:35], v[72:73]
	s_waitcnt vmcnt(5)
	v_pk_add_f32 v[88:89], v[14:15], v[88:89]
	v_add_co_u32_e32 v14, vcc, s22, v4
	s_mov_b32 s22, 0xff200000
	s_nop 0
	v_addc_co_u32_e32 v15, vcc, -1, v5, vcc
	s_waitcnt vmcnt(0)
	v_pk_add_f32 v[108:109], v[34:35], v[108:109]
	v_add_co_u32_e32 v34, vcc, s22, v4
	s_mov_b32 s22, 0xff3ff000
	s_nop 0
	v_addc_co_u32_e32 v35, vcc, -1, v5, vcc
	v_add_co_u32_e32 v52, vcc, s22, v4
	v_pk_add_f32 v[20:21], v[20:21], v[58:59]
	v_pk_add_f32 v[18:19], v[18:19], v[56:57]
	v_pk_add_f32 v[24:25], v[24:25], v[62:63]
	v_pk_add_f32 v[22:23], v[22:23], v[60:61]
	v_pk_add_f32 v[28:29], v[28:29], v[66:67]
	v_pk_add_f32 v[26:27], v[26:27], v[64:65]
	v_pk_add_f32 v[32:33], v[32:33], v[70:71]
	v_pk_add_f32 v[30:31], v[30:31], v[68:69]
	v_pk_add_f32 v[36:37], v[36:37], v[74:75]
	v_pk_add_f32 v[78:79], v[8:9], v[78:79]
	v_pk_add_f32 v[76:77], v[6:7], v[76:77]
	v_pk_add_f32 v[80:81], v[12:13], v[86:87]
	v_pk_add_f32 v[84:85], v[10:11], v[84:85]
	v_pk_add_f32 v[86:87], v[16:17], v[90:91]
	global_load_dwordx4 v[6:9], v[14:15], off offset:-3072
	global_load_dwordx4 v[10:13], v[14:15], off offset:-2048
	s_nop 0
	global_load_dwordx4 v[14:17], v[14:15], off offset:-1024
	v_addc_co_u32_e32 v53, vcc, -1, v5, vcc
	s_mov_b32 s22, 0xff400000
	v_pk_add_f32 v[90:91], v[20:21], v[94:95]
	v_pk_add_f32 v[92:93], v[18:19], v[92:93]
	v_pk_add_f32 v[94:95], v[24:25], v[98:99]
	v_pk_add_f32 v[96:97], v[22:23], v[96:97]
	v_pk_add_f32 v[98:99], v[28:29], v[102:103]
	v_pk_add_f32 v[100:101], v[26:27], v[100:101]
	v_pk_add_f32 v[102:103], v[32:33], v[106:107]
	v_pk_add_f32 v[104:105], v[30:31], v[104:105]
	v_pk_add_f32 v[106:107], v[36:37], v[110:111]
	global_load_dwordx4 v[18:21], v[34:35], off offset:-4096
	global_load_dwordx4 v[22:25], v[34:35], off offset:-3072
	global_load_dwordx4 v[26:29], v[34:35], off offset:-2048
	global_load_dwordx4 v[30:33], v[34:35], off offset:-1024
	s_nop 0
	global_load_dwordx4 v[34:37], v[34:35], off
	s_nop 0
	global_load_dwordx4 v[44:47], v[52:53], off offset:-3072
	global_load_dwordx4 v[48:51], v[52:53], off offset:-2048
	s_nop 0
	global_load_dwordx4 v[52:55], v[52:53], off offset:-1024
	v_add_co_u32_e32 v72, vcc, s22, v4
	s_mov_b32 s22, 0xff5ff000
	s_nop 0
	v_addc_co_u32_e32 v73, vcc, -1, v5, vcc
	global_load_dwordx4 v[56:59], v[72:73], off offset:-4096
	global_load_dwordx4 v[60:63], v[72:73], off offset:-3072
	global_load_dwordx4 v[64:67], v[72:73], off offset:-2048
	global_load_dwordx4 v[68:71], v[72:73], off offset:-1024
	s_nop 0
	global_load_dwordx4 v[72:75], v[72:73], off
	s_waitcnt vmcnt(15)
	v_pk_add_f32 v[8:9], v[78:79], v[8:9]
	s_waitcnt vmcnt(14)
	v_pk_add_f32 v[12:13], v[80:81], v[12:13]
	s_waitcnt vmcnt(13)
	v_pk_add_f32 v[16:17], v[86:87], v[16:17]
	v_pk_add_f32 v[80:81], v[88:89], v[14:15]
	v_pk_add_f32 v[78:79], v[84:85], v[10:11]
	v_pk_add_f32 v[76:77], v[76:77], v[6:7]
	s_waitcnt vmcnt(12)
	v_pk_add_f32 v[84:85], v[92:93], v[18:19]
	v_pk_add_f32 v[20:21], v[90:91], v[20:21]
	s_waitcnt vmcnt(11)
	v_pk_add_f32 v[24:25], v[94:95], v[24:25]
	s_waitcnt vmcnt(7)
	v_pk_add_f32 v[6:7], v[8:9], v[46:47]
	v_pk_add_f32 v[36:37], v[106:107], v[36:37]
	s_waitcnt vmcnt(5)
	v_pk_add_f32 v[14:15], v[16:17], v[54:55]
	v_pk_add_f32 v[16:17], v[80:81], v[52:53]
	v_add_co_u32_e32 v52, vcc, s22, v4
	v_pk_add_f32 v[92:93], v[108:109], v[34:35]
	s_nop 0
	v_addc_co_u32_e32 v53, vcc, -1, v5, vcc
	s_mov_b32 s22, 0xff600000
	s_waitcnt vmcnt(0)
	v_pk_add_f32 v[34:35], v[36:37], v[74:75]
	v_pk_add_f32 v[36:37], v[92:93], v[72:73]
	v_add_co_u32_e32 v72, vcc, s22, v4
	v_pk_add_f32 v[8:9], v[76:77], v[44:45]
	v_pk_add_f32 v[10:11], v[12:13], v[50:51]
	v_pk_add_f32 v[12:13], v[78:79], v[48:49]
	global_load_dwordx4 v[44:47], v[52:53], off offset:-3072
	global_load_dwordx4 v[48:51], v[52:53], off offset:-2048
	s_nop 0
	global_load_dwordx4 v[52:55], v[52:53], off offset:-1024
	v_addc_co_u32_e32 v73, vcc, -1, v5, vcc
	s_mov_b32 s22, 0xff7ff000
	v_pk_add_f32 v[86:87], v[96:97], v[22:23]
	v_pk_add_f32 v[28:29], v[98:99], v[28:29]
	v_pk_add_f32 v[88:89], v[100:101], v[26:27]
	v_pk_add_f32 v[32:33], v[102:103], v[32:33]
	v_pk_add_f32 v[90:91], v[104:105], v[30:31]
	v_add_co_u32_e32 v80, vcc, s22, v4
	v_pk_add_f32 v[18:19], v[20:21], v[58:59]
	v_pk_add_f32 v[20:21], v[84:85], v[56:57]
	v_pk_add_f32 v[22:23], v[24:25], v[62:63]
	v_pk_add_f32 v[24:25], v[86:87], v[60:61]
	v_pk_add_f32 v[26:27], v[28:29], v[66:67]
	v_pk_add_f32 v[28:29], v[88:89], v[64:65]
	v_pk_add_f32 v[30:31], v[32:33], v[70:71]
	v_pk_add_f32 v[32:33], v[90:91], v[68:69]
	global_load_dwordx4 v[56:59], v[72:73], off offset:-4096
	global_load_dwordx4 v[60:63], v[72:73], off offset:-3072
	global_load_dwordx4 v[64:67], v[72:73], off offset:-2048
	global_load_dwordx4 v[68:71], v[72:73], off offset:-1024
	s_nop 0
	global_load_dwordx4 v[72:75], v[72:73], off
	v_addc_co_u32_e32 v81, vcc, -1, v5, vcc
	s_mov_b32 s22, 0xff800000
	global_load_dwordx4 v[76:79], v[80:81], off offset:-3072
	global_load_dwordx4 v[84:87], v[80:81], off offset:-2048
	global_load_dwordx4 v[88:91], v[80:81], off offset:-1024
	v_add_co_u32_e32 v80, vcc, s22, v4
	s_mov_b32 s22, 0xff9ff000
	s_nop 0
	v_addc_co_u32_e32 v81, vcc, -1, v5, vcc
	global_load_dwordx4 v[92:95], v[80:81], off offset:-4096
	global_load_dwordx4 v[96:99], v[80:81], off offset:-3072
	global_load_dwordx4 v[100:103], v[80:81], off offset:-2048
	global_load_dwordx4 v[104:107], v[80:81], off offset:-1024
	global_load_dwordx4 v[108:111], v[80:81], off
	s_waitcnt vmcnt(15)
	v_pk_add_f32 v[6:7], v[6:7], v[46:47]
	v_pk_add_f32 v[8:9], v[8:9], v[44:45]
	s_waitcnt vmcnt(13)
	v_pk_add_f32 v[16:17], v[16:17], v[52:53]
	v_add_co_u32_e32 v52, vcc, s22, v4
	s_mov_b32 s22, 0xffa00000
	s_nop 0
	v_addc_co_u32_e32 v53, vcc, -1, v5, vcc
	v_pk_add_f32 v[10:11], v[10:11], v[50:51]
	v_pk_add_f32 v[12:13], v[12:13], v[48:49]
	v_pk_add_f32 v[14:15], v[14:15], v[54:55]
	s_waitcnt vmcnt(12)
	v_pk_add_f32 v[18:19], v[18:19], v[58:59]
	v_pk_add_f32 v[20:21], v[20:21], v[56:57]
	s_waitcnt vmcnt(11)
	v_pk_add_f32 v[22:23], v[22:23], v[62:63]
	v_pk_add_f32 v[24:25], v[24:25], v[60:61]
	s_waitcnt vmcnt(8)
	v_pk_add_f32 v[46:47], v[36:37], v[72:73]
	v_add_co_u32_e32 v72, vcc, s22, v4
	s_mov_b32 s22, 0xffbff000
	s_nop 0
	v_addc_co_u32_e32 v73, vcc, -1, v5, vcc
	v_pk_add_f32 v[26:27], v[26:27], v[66:67]
	v_pk_add_f32 v[28:29], v[28:29], v[64:65]
	v_pk_add_f32 v[30:31], v[30:31], v[70:71]
	v_pk_add_f32 v[32:33], v[32:33], v[68:69]
	v_pk_add_f32 v[44:45], v[34:35], v[74:75]
	v_add_co_u32_e32 v80, vcc, s22, v4
	s_waitcnt vmcnt(7)
	v_pk_add_f32 v[34:35], v[6:7], v[78:79]
	v_pk_add_f32 v[36:37], v[8:9], v[76:77]
	s_waitcnt vmcnt(6)
	v_pk_add_f32 v[6:7], v[10:11], v[86:87]
	v_pk_add_f32 v[8:9], v[12:13], v[84:85]
	s_waitcnt vmcnt(5)
	v_pk_add_f32 v[10:11], v[14:15], v[90:91]
	v_pk_add_f32 v[12:13], v[16:17], v[88:89]
	s_waitcnt vmcnt(4)
	v_pk_add_f32 v[14:15], v[18:19], v[94:95]
	v_pk_add_f32 v[16:17], v[20:21], v[92:93]
	s_waitcnt vmcnt(3)
	v_pk_add_f32 v[18:19], v[22:23], v[98:99]
	v_pk_add_f32 v[20:21], v[24:25], v[96:97]
	s_waitcnt vmcnt(2)
	v_pk_add_f32 v[22:23], v[26:27], v[102:103]
	v_pk_add_f32 v[24:25], v[28:29], v[100:101]
	s_waitcnt vmcnt(1)
	v_pk_add_f32 v[26:27], v[30:31], v[106:107]
	v_pk_add_f32 v[28:29], v[32:33], v[104:105]
	s_waitcnt vmcnt(0)
	v_pk_add_f32 v[30:31], v[44:45], v[110:111]
	v_pk_add_f32 v[32:33], v[46:47], v[108:109]
	global_load_dwordx4 v[44:47], v[52:53], off offset:-3072
	global_load_dwordx4 v[48:51], v[52:53], off offset:-2048
	s_nop 0
	global_load_dwordx4 v[52:55], v[52:53], off offset:-1024
	v_addc_co_u32_e32 v81, vcc, -1, v5, vcc
	global_load_dwordx4 v[56:59], v[72:73], off offset:-4096
	global_load_dwordx4 v[60:63], v[72:73], off offset:-3072
	global_load_dwordx4 v[64:67], v[72:73], off offset:-2048
	global_load_dwordx4 v[68:71], v[72:73], off offset:-1024
	s_nop 0
	global_load_dwordx4 v[72:75], v[72:73], off
	s_nop 0
	global_load_dwordx4 v[76:79], v[80:81], off offset:-3072
	global_load_dwordx4 v[84:87], v[80:81], off offset:-2048
	global_load_dwordx4 v[88:91], v[80:81], off offset:-1024
	s_mov_b32 s22, 0xffc00000
	v_add_co_u32_e32 v80, vcc, s22, v4
	s_mov_b32 s22, 0xffdff000
	s_nop 0
	v_addc_co_u32_e32 v81, vcc, -1, v5, vcc
	global_load_dwordx4 v[92:95], v[80:81], off offset:-4096
	global_load_dwordx4 v[96:99], v[80:81], off offset:-3072
	global_load_dwordx4 v[100:103], v[80:81], off offset:-2048
	global_load_dwordx4 v[104:107], v[80:81], off offset:-1024
	global_load_dwordx4 v[108:111], v[80:81], off
	s_waitcnt vmcnt(15)
	v_pk_add_f32 v[34:35], v[34:35], v[46:47]
	s_waitcnt vmcnt(14)
	v_pk_add_f32 v[6:7], v[6:7], v[50:51]
	s_waitcnt vmcnt(13)
	v_pk_add_f32 v[10:11], v[10:11], v[54:55]
	s_waitcnt vmcnt(12)
	v_pk_add_f32 v[14:15], v[14:15], v[58:59]
	s_waitcnt vmcnt(7)
	v_pk_add_f32 v[78:79], v[34:35], v[78:79]
	s_waitcnt vmcnt(6)
	v_pk_add_f32 v[80:81], v[6:7], v[86:87]
	s_waitcnt vmcnt(5)
	v_pk_add_f32 v[86:87], v[10:11], v[90:91]
	v_pk_add_f32 v[36:37], v[36:37], v[44:45]
	v_pk_add_f32 v[8:9], v[8:9], v[48:49]
	s_waitcnt vmcnt(4)
	v_pk_add_f32 v[90:91], v[14:15], v[94:95]
	v_add_co_u32_e32 v14, vcc, s22, v4
	s_mov_b32 s22, 0xffe00000
	s_nop 0
	v_addc_co_u32_e32 v15, vcc, -1, v5, vcc
	v_add_co_u32_e32 v34, vcc, s22, v4
	v_pk_add_f32 v[12:13], v[12:13], v[52:53]
	s_nop 0
	v_addc_co_u32_e32 v35, vcc, -1, v5, vcc
	v_pk_add_f32 v[16:17], v[16:17], v[56:57]
	v_pk_add_f32 v[18:19], v[18:19], v[62:63]
	v_pk_add_f32 v[20:21], v[20:21], v[60:61]
	v_pk_add_f32 v[22:23], v[22:23], v[66:67]
	v_pk_add_f32 v[24:25], v[24:25], v[64:65]
	v_pk_add_f32 v[26:27], v[26:27], v[70:71]
	v_pk_add_f32 v[28:29], v[28:29], v[68:69]
	v_pk_add_f32 v[30:31], v[30:31], v[74:75]
	v_pk_add_f32 v[32:33], v[32:33], v[72:73]
	v_add_co_u32_e32 v52, vcc, s31, v4
	v_pk_add_f32 v[76:77], v[36:37], v[76:77]
	v_pk_add_f32 v[84:85], v[8:9], v[84:85]
	v_pk_add_f32 v[88:89], v[12:13], v[88:89]
	v_pk_add_f32 v[92:93], v[16:17], v[92:93]
	s_waitcnt vmcnt(3)
	v_pk_add_f32 v[94:95], v[18:19], v[98:99]
	v_pk_add_f32 v[96:97], v[20:21], v[96:97]
	s_waitcnt vmcnt(2)
	v_pk_add_f32 v[98:99], v[22:23], v[102:103]
	v_pk_add_f32 v[100:101], v[24:25], v[100:101]
	s_waitcnt vmcnt(1)
	v_pk_add_f32 v[102:103], v[26:27], v[106:107]
	v_pk_add_f32 v[104:105], v[28:29], v[104:105]
	s_waitcnt vmcnt(0)
	v_pk_add_f32 v[106:107], v[30:31], v[110:111]
	v_pk_add_f32 v[108:109], v[32:33], v[108:109]
	global_load_dwordx4 v[6:9], v[14:15], off offset:-3072
	global_load_dwordx4 v[10:13], v[14:15], off offset:-2048
	s_nop 0
	global_load_dwordx4 v[14:17], v[14:15], off offset:-1024
	s_nop 0
	global_load_dwordx4 v[18:21], v[34:35], off offset:-4096
	global_load_dwordx4 v[22:25], v[34:35], off offset:-3072
	global_load_dwordx4 v[26:29], v[34:35], off offset:-2048
	global_load_dwordx4 v[30:33], v[34:35], off offset:-1024
	s_nop 0
	global_load_dwordx4 v[34:37], v[34:35], off
	v_addc_co_u32_e32 v53, vcc, -1, v5, vcc
	global_load_dwordx4 v[44:47], v[52:53], off offset:-3072
	global_load_dwordx4 v[48:51], v[52:53], off offset:-2048
	s_nop 0
	global_load_dwordx4 v[52:55], v[52:53], off offset:-1024
	s_nop 0
	global_load_dwordx4 v[56:59], v[4:5], off offset:-4096
	global_load_dwordx4 v[60:63], v[4:5], off offset:-3072
	global_load_dwordx4 v[64:67], v[4:5], off offset:-2048
	global_load_dwordx4 v[68:71], v[4:5], off offset:-1024
	global_load_dwordx4 v[72:75], v[4:5], off
	s_waitcnt vmcnt(15)
	v_pk_add_f32 v[4:5], v[78:79], v[8:9]
	s_waitcnt vmcnt(14)
	v_pk_add_f32 v[10:11], v[84:85], v[10:11]
	v_pk_add_f32 v[6:7], v[76:77], v[6:7]
	v_pk_add_f32 v[8:9], v[80:81], v[12:13]
	s_waitcnt vmcnt(13)
	v_pk_add_f32 v[12:13], v[86:87], v[16:17]
	s_waitcnt vmcnt(8)
	v_pk_add_f32 v[36:37], v[106:107], v[36:37]
	s_waitcnt vmcnt(6)
	v_pk_add_f32 v[16:17], v[10:11], v[48:49]
	v_lshl_add_u64 v[10:11], s[20:21], 0, v[42:43]
	s_mov_b64 s[20:21], 0x21b1e000
	v_pk_add_f32 v[76:77], v[88:89], v[14:15]
	v_pk_add_f32 v[80:81], v[92:93], v[18:19]
	v_pk_add_f32 v[86:87], v[96:97], v[22:23]
	v_pk_add_f32 v[96:97], v[6:7], v[44:45]
	v_pk_add_f32 v[14:15], v[8:9], v[50:51]
	s_waitcnt vmcnt(0)
	v_pk_add_f32 v[44:45], v[36:37], v[74:75]
	v_lshl_add_u64 v[36:37], v[10:11], 0, s[20:21]
	v_add_co_u32_e32 v50, vcc, s70, v10
	s_mov_b64 s[20:21], 0xa000
	v_pk_add_f32 v[84:85], v[94:95], v[24:25]
	v_pk_add_f32 v[24:25], v[80:81], v[56:57]
	v_addc_co_u32_e32 v51, vcc, 0, v11, vcc
	v_lshl_add_u64 v[56:57], v[2:3], 0, s[20:21]
	s_mov_b32 s20, 0xb000
	v_add_co_u32_e32 v48, vcc, s20, v2
	v_pk_add_f32 v[32:33], v[102:103], v[32:33]
	v_pk_add_f32 v[34:35], v[108:109], v[34:35]
	v_addc_co_u32_e32 v49, vcc, 0, v3, vcc
	v_pk_add_f32 v[94:95], v[4:5], v[46:47]
	v_pk_add_f32 v[18:19], v[12:13], v[54:55]
	v_pk_add_f32 v[4:5], v[32:33], v[70:71]
	v_pk_add_f32 v[46:47], v[34:35], v[72:73]
	global_load_dwordx4 v[32:35], v[50:51], off offset:-4096
	global_load_dwordx4 v[10:13], v[48:49], off offset:-4096
	v_pk_add_f32 v[78:79], v[90:91], v[20:21]
	v_pk_add_f32 v[20:21], v[76:77], v[52:53]
	v_pk_add_f32 v[22:23], v[78:79], v[58:59]
	v_pk_add_f32 v[88:89], v[98:99], v[28:29]
	v_pk_add_f32 v[90:91], v[100:101], v[26:27]
	v_pk_add_f32 v[26:27], v[84:85], v[62:63]
	v_pk_add_f32 v[28:29], v[86:87], v[60:61]
	v_pk_add_f32 v[8:9], v[88:89], v[66:67]
	v_pk_add_f32 v[92:93], v[104:105], v[30:31]
	v_pk_add_f32 v[30:31], v[90:91], v[64:65]
	v_pk_add_f32 v[6:7], v[92:93], v[68:69]
	s_waitcnt vmcnt(0)
	v_pk_add_f32 v[2:3], v[12:13], 1.0 op_sel_hi:[1,0]
	v_pk_add_f32 v[10:11], v[10:11], 1.0 op_sel_hi:[1,0]
	v_pk_mul_f32 v[2:3], v[94:95], v[2:3]
	v_pk_mul_f32 v[12:13], v[96:97], v[10:11]
	v_pk_fma_f32 v[10:11], v[34:35], s[92:93], v[2:3] op_sel_hi:[1,0,1]
	v_pk_fma_f32 v[12:13], v[32:33], s[92:93], v[12:13] op_sel_hi:[1,0,1]
	global_load_dwordx4 v[32:35], v[36:37], off offset:1024
	global_load_dwordx4 v[52:55], v[56:57], off offset:1024
	s_waitcnt vmcnt(0)
	v_pk_add_f32 v[2:3], v[54:55], 1.0 op_sel_hi:[1,0]
	v_pk_add_f32 v[52:53], v[52:53], 1.0 op_sel_hi:[1,0]
	v_pk_mul_f32 v[2:3], v[14:15], v[2:3]
	v_pk_mul_f32 v[16:17], v[16:17], v[52:53]
	v_pk_fma_f32 v[14:15], v[34:35], s[92:93], v[2:3] op_sel_hi:[1,0,1]
	v_pk_fma_f32 v[16:17], v[32:33], s[92:93], v[16:17] op_sel_hi:[1,0,1]
	global_load_dwordx4 v[32:35], v[36:37], off offset:2048
	global_load_dwordx4 v[52:55], v[56:57], off offset:2048
	s_waitcnt vmcnt(0)
	v_pk_add_f32 v[2:3], v[54:55], 1.0 op_sel_hi:[1,0]
	v_pk_add_f32 v[52:53], v[52:53], 1.0 op_sel_hi:[1,0]
	v_pk_mul_f32 v[2:3], v[18:19], v[2:3]
	v_pk_mul_f32 v[20:21], v[20:21], v[52:53]
	v_pk_fma_f32 v[18:19], v[34:35], s[92:93], v[2:3] op_sel_hi:[1,0,1]
	v_pk_fma_f32 v[20:21], v[32:33], s[92:93], v[20:21] op_sel_hi:[1,0,1]
	global_load_dwordx4 v[32:35], v[36:37], off offset:3072
	global_load_dwordx4 v[52:55], v[56:57], off offset:3072
	s_waitcnt vmcnt(0)
	v_pk_add_f32 v[2:3], v[54:55], 1.0 op_sel_hi:[1,0]
	v_pk_add_f32 v[36:37], v[52:53], 1.0 op_sel_hi:[1,0]
	v_pk_mul_f32 v[2:3], v[22:23], v[2:3]
	v_pk_mul_f32 v[24:25], v[24:25], v[36:37]
	v_pk_fma_f32 v[22:23], v[34:35], s[92:93], v[2:3] op_sel_hi:[1,0,1]
	v_pk_fma_f32 v[24:25], v[32:33], s[92:93], v[24:25] op_sel_hi:[1,0,1]
	global_load_dwordx4 v[32:35], v[50:51], off
	global_load_dwordx4 v[52:55], v[48:49], off
	s_waitcnt vmcnt(0)
	v_pk_add_f32 v[2:3], v[54:55], 1.0 op_sel_hi:[1,0]
	v_pk_add_f32 v[36:37], v[52:53], 1.0 op_sel_hi:[1,0]
	v_pk_mul_f32 v[2:3], v[26:27], v[2:3]
	v_pk_mul_f32 v[28:29], v[28:29], v[36:37]
	v_pk_fma_f32 v[26:27], v[34:35], s[92:93], v[2:3] op_sel_hi:[1,0,1]
	v_pk_fma_f32 v[28:29], v[32:33], s[92:93], v[28:29] op_sel_hi:[1,0,1]
	global_load_dwordx4 v[32:35], v[50:51], off offset:1024
	global_load_dwordx4 v[52:55], v[48:49], off offset:1024
	s_waitcnt vmcnt(0)
	v_pk_add_f32 v[2:3], v[54:55], 1.0 op_sel_hi:[1,0]
	v_pk_add_f32 v[36:37], v[52:53], 1.0 op_sel_hi:[1,0]
	v_pk_mul_f32 v[2:3], v[8:9], v[2:3]
	v_pk_mul_f32 v[8:9], v[30:31], v[36:37]
	v_pk_fma_f32 v[30:31], v[34:35], s[92:93], v[2:3] op_sel_hi:[1,0,1]
	global_load_dwordx4 v[52:55], v[50:51], off offset:2048
	global_load_dwordx4 v[34:37], v[48:49], off offset:2048
	v_pk_fma_f32 v[32:33], v[32:33], s[92:93], v[8:9] op_sel_hi:[1,0,1]
	s_waitcnt vmcnt(0)
	v_pk_add_f32 v[2:3], v[36:37], 1.0 op_sel_hi:[1,0]
	v_pk_add_f32 v[8:9], v[34:35], 1.0 op_sel_hi:[1,0]
	v_pk_mul_f32 v[2:3], v[4:5], v[2:3]
	v_pk_mul_f32 v[4:5], v[6:7], v[8:9]
	v_pk_fma_f32 v[34:35], v[54:55], s[92:93], v[2:3] op_sel_hi:[1,0,1]
	v_pk_fma_f32 v[36:37], v[52:53], s[92:93], v[4:5] op_sel_hi:[1,0,1]
	global_load_dwordx4 v[2:5], v[50:51], off offset:3072
	global_load_dwordx4 v[6:9], v[48:49], off offset:3072
	v_add_f32_e32 v48, v22, v23
	v_mov_b32_e32 v49, v27
	s_load_dwordx4 s[36:39], s[8:9], 0xb0
	s_waitcnt lgkmcnt(0)
	s_add_u32 s22, s36, s40
	s_addc_u32 s23, s37, s41
	s_add_u32 s24, s38, s40
	s_addc_u32 s25, s39, s41
	s_add_u32 s18, s30, s18
	s_addc_u32 s19, s27, s19
	s_and_b64 s[20:21], s[34:35], exec
	s_cselect_b32 s17, s17, 0
	s_cselect_b32 s16, s16, 0
	s_lshl_b64 s[16:17], s[16:17], 1
	s_add_u32 s20, s29, s16
	s_addc_u32 s21, s26, s17
	s_load_dwordx2 s[16:17], s[8:9], 0x68
	s_waitcnt vmcnt(0)
	v_pk_add_f32 v[8:9], v[8:9], 1.0 op_sel_hi:[1,0]
	v_pk_add_f32 v[6:7], v[6:7], 1.0 op_sel_hi:[1,0]
	v_pk_mul_f32 v[8:9], v[44:45], v[8:9]
	v_pk_mul_f32 v[6:7], v[46:47], v[6:7]
	v_pk_fma_f32 v[44:45], v[4:5], s[92:93], v[8:9] op_sel_hi:[1,0,1]
	v_pk_fma_f32 v[8:9], v[2:3], s[92:93], v[6:7] op_sel_hi:[1,0,1]
	v_mov_b32_e32 v2, v12
	v_mov_b32_e32 v3, v16
	v_mov_b32_e32 v4, v13
	v_mov_b32_e32 v5, v17
	v_pk_add_f32 v[2:3], v[2:3], v[4:5]
	v_mov_b32_e32 v4, v10
	v_mov_b32_e32 v5, v14
	v_mov_b32_e32 v46, v11
	v_mov_b32_e32 v47, v15
	v_pk_add_f32 v[4:5], v[4:5], v[46:47]
	v_mov_b32_e32 v46, v20
	v_pk_add_f32 v[2:3], v[2:3], v[4:5]
	v_pk_mov_b32 v[4:5], v[20:21], v[18:19] op_sel:[1,0]
	v_mov_b32_e32 v47, v19
	v_pk_add_f32 v[4:5], v[4:5], v[46:47]
	v_add_f32_e32 v2, 0, v2
	v_pk_add_f32 v[4:5], v[4:5], v[4:5] op_sel:[0,1] op_sel_hi:[1,0]
	v_add_f32_e32 v2, v2, v3
	v_add_f32_e32 v46, v24, v25
	v_mov_b32_e32 v3, v28
	v_mov_b32_e32 v5, v29
	v_mov_b32_e32 v47, v26
	v_pk_add_f32 v[2:3], v[2:3], v[4:5]
	v_pk_add_f32 v[4:5], v[46:47], v[48:49]
	v_mov_b32_e32 v46, v32
	v_pk_add_f32 v[2:3], v[2:3], v[4:5]
	v_pk_mov_b32 v[4:5], v[32:33], v[30:31] op_sel:[1,0]
	v_mov_b32_e32 v47, v31
	v_pk_add_f32 v[4:5], v[4:5], v[46:47]
	v_pk_add_f32 v[2:3], v[2:3], v[2:3] op_sel:[0,1] op_sel_hi:[1,0]
	v_pk_add_f32 v[4:5], v[4:5], v[4:5] op_sel:[0,1] op_sel_hi:[1,0]
	v_add_f32_e32 v46, v36, v37
	v_add_f32_e32 v48, v34, v35
	v_mov_b32_e32 v3, v8
	v_mov_b32_e32 v5, v9
	v_mov_b32_e32 v47, v44
	v_mov_b32_e32 v49, v45
	v_pk_add_f32 v[2:3], v[2:3], v[4:5]
	v_pk_add_f32 v[4:5], v[46:47], v[48:49]
	v_lshl_add_u64 v[6:7], v[38:39], 0, s[6:7]
	v_pk_add_f32 v[2:3], v[2:3], v[4:5]
	v_xor_b32_e32 v4, 1, v249
	v_add_f32_e32 v2, v2, v3
	v_and_b32_e32 v3, 64, v249
	v_add_u32_e32 v3, 64, v3
	v_cmp_lt_i32_e32 vcc, v4, v3
	s_nop 1
	v_cndmask_b32_e32 v4, v249, v4, vcc
	v_lshlrev_b32_e32 v58, 2, v4
	ds_bpermute_b32 v4, v58, v2
	s_waitcnt lgkmcnt(0)
	v_add_f32_e32 v2, v2, v4
	v_xor_b32_e32 v4, 2, v249
	v_cmp_lt_i32_e32 vcc, v4, v3
	s_nop 1
	v_cndmask_b32_e32 v4, v249, v4, vcc
	v_lshlrev_b32_e32 v59, 2, v4
	ds_bpermute_b32 v4, v59, v2
	s_waitcnt lgkmcnt(0)
	v_add_f32_e32 v2, v2, v4
	v_xor_b32_e32 v4, 4, v249
	v_cmp_lt_i32_e32 vcc, v4, v3
	s_nop 1
	v_cndmask_b32_e32 v4, v249, v4, vcc
	v_lshlrev_b32_e32 v60, 2, v4
	ds_bpermute_b32 v4, v60, v2
	s_waitcnt lgkmcnt(0)
	v_add_f32_e32 v2, v2, v4
	v_xor_b32_e32 v4, 8, v249
	v_cmp_lt_i32_e32 vcc, v4, v3
	s_nop 1
	v_cndmask_b32_e32 v4, v249, v4, vcc
	v_lshlrev_b32_e32 v61, 2, v4
	ds_bpermute_b32 v4, v61, v2
	s_waitcnt lgkmcnt(0)
	v_add_f32_e32 v2, v2, v4
	v_xor_b32_e32 v4, 16, v249
	v_cmp_lt_i32_e32 vcc, v4, v3
	s_nop 1
	v_cndmask_b32_e32 v4, v249, v4, vcc
	v_lshlrev_b32_e32 v62, 2, v4
	ds_bpermute_b32 v4, v62, v2
	s_waitcnt lgkmcnt(0)
	v_add_f32_e32 v2, v2, v4
	v_xor_b32_e32 v4, 32, v249
	v_cmp_lt_i32_e32 vcc, v4, v3
	s_nop 1
	v_cndmask_b32_e32 v3, v249, v4, vcc
	v_lshlrev_b32_e32 v63, 2, v3
	ds_bpermute_b32 v3, v63, v2
	s_waitcnt lgkmcnt(0)
	v_add_f32_e32 v50, v2, v3
	v_fmamk_f32 v13, v50, 0xba000000, v13
	v_fmamk_f32 v17, v50, 0xba000000, v17
	v_fmamk_f32 v11, v50, 0xba000000, v11
	v_fmac_f32_e32 v12, 0xba000000, v50
	v_fmamk_f32 v15, v50, 0xba000000, v15
	v_fmac_f32_e32 v16, 0xba000000, v50
	v_mov_b32_e32 v4, v13
	v_mov_b32_e32 v5, v17
	v_fmac_f32_e32 v10, 0xba000000, v50
	v_fmac_f32_e32 v14, 0xba000000, v50
	v_mov_b32_e32 v2, v12
	v_mov_b32_e32 v3, v16
	v_pk_mul_f32 v[4:5], v[4:5], v[4:5]
	v_mov_b32_e32 v46, v11
	v_mov_b32_e32 v47, v15
	v_pk_fma_f32 v[2:3], v[2:3], v[2:3], v[4:5]
	v_mov_b32_e32 v4, v10
	v_mov_b32_e32 v5, v14
	v_pk_mul_f32 v[46:47], v[46:47], v[46:47]
	v_fmamk_f32 v21, v50, 0xba000000, v21
	v_pk_fma_f32 v[4:5], v[4:5], v[4:5], v[46:47]
	v_fmac_f32_e32 v20, 0xba000000, v50
	v_pk_add_f32 v[2:3], v[2:3], v[4:5]
	v_fmamk_f32 v19, v50, 0xba000000, v19
	v_fmac_f32_e32 v18, 0xba000000, v50
	v_pk_add_f32 v[2:3], v[2:3], v[2:3] op_sel_hi:[0,1]
	v_pk_mul_f32 v[4:5], v[18:19], v[18:19]
	v_pk_mul_f32 v[46:47], v[20:21], v[20:21]
	v_fmac_f32_e32 v24, 0xba000000, v50
	v_pk_mov_b32 v[48:49], v[46:47], v[4:5] op_sel:[1,0]
	v_mov_b32_e32 v47, v5
	v_fmamk_f32 v25, v50, 0xba000000, v25
	v_fmac_f32_e32 v22, 0xba000000, v50
	v_mul_f32_e32 v2, v24, v24
	v_pk_add_f32 v[4:5], v[48:49], v[46:47]
	v_fmamk_f32 v23, v50, 0xba000000, v23
	v_pk_fma_f32 v[46:47], v[24:25], v[24:25], v[2:3] op_sel_hi:[1,1,0]
	v_mul_f32_e32 v2, v22, v22
	v_pk_add_f32 v[4:5], v[4:5], v[4:5] op_sel_hi:[0,1]
	v_pk_fma_f32 v[48:49], v[22:23], v[22:23], v[2:3] op_sel_hi:[1,1,0]
	v_fmamk_f32 v27, v50, 0xba000000, v27
	v_fmac_f32_e32 v26, 0xba000000, v50
	v_fmamk_f32 v29, v50, 0xba000000, v29
	v_fmac_f32_e32 v28, 0xba000000, v50
	v_mul_f32_e32 v46, v28, v28
	v_mul_f32_e32 v48, v29, v29
	v_mul_f32_e32 v4, v26, v26
	v_mul_f32_e32 v2, v27, v27
	v_pk_add_f32 v[46:47], v[46:47], v[48:49]
	v_pk_add_f32 v[2:3], v[4:5], v[2:3]
	v_fmamk_f32 v33, v50, 0xba000000, v33
	v_pk_add_f32 v[2:3], v[46:47], v[2:3]
	v_fmac_f32_e32 v32, 0xba000000, v50
	v_fmamk_f32 v31, v50, 0xba000000, v31
	v_fmac_f32_e32 v30, 0xba000000, v50
	v_pk_add_f32 v[2:3], v[2:3], v[2:3] op_sel_hi:[0,1]
	v_pk_mul_f32 v[4:5], v[30:31], v[30:31]
	v_pk_mul_f32 v[46:47], v[32:33], v[32:33]
	v_fmac_f32_e32 v36, 0xba000000, v50
	v_pk_mov_b32 v[48:49], v[46:47], v[4:5] op_sel:[1,0]
	v_mov_b32_e32 v47, v5
	v_fmamk_f32 v37, v50, 0xba000000, v37
	v_fmac_f32_e32 v34, 0xba000000, v50
	v_mul_f32_e32 v2, v36, v36
	v_pk_add_f32 v[4:5], v[48:49], v[46:47]
	v_fmamk_f32 v35, v50, 0xba000000, v35
	v_pk_fma_f32 v[46:47], v[36:37], v[36:37], v[2:3] op_sel_hi:[1,1,0]
	v_mul_f32_e32 v2, v34, v34
	v_pk_add_f32 v[4:5], v[4:5], v[4:5] op_sel_hi:[0,1]
	v_pk_fma_f32 v[48:49], v[34:35], v[34:35], v[2:3] op_sel_hi:[1,1,0]
	v_fmamk_f32 v45, v50, 0xba000000, v45
	v_fmac_f32_e32 v44, 0xba000000, v50
	v_fmamk_f32 v9, v50, 0xba000000, v9
	v_fmac_f32_e32 v8, 0xba000000, v50
	v_mul_f32_e32 v46, v8, v8
	v_mul_f32_e32 v48, v9, v9
	v_mul_f32_e32 v4, v44, v44
	v_mul_f32_e32 v2, v45, v45
	v_pk_add_f32 v[46:47], v[46:47], v[48:49]
	v_pk_add_f32 v[2:3], v[4:5], v[2:3]
	v_lshl_add_u64 v[50:51], s[22:23], 0, v[42:43]
	v_pk_add_f32 v[2:3], v[46:47], v[2:3]
	v_lshl_add_u64 v[48:49], s[24:25], 0, v[42:43]
	v_add_f32_e32 v2, v2, v3
	ds_bpermute_b32 v3, v58, v2
	global_load_dwordx4 v[52:55], v[48:49], off
	s_waitcnt lgkmcnt(0)
	v_add_f32_e32 v2, v2, v3
	ds_bpermute_b32 v3, v59, v2
	s_waitcnt lgkmcnt(0)
	v_add_f32_e32 v2, v2, v3
	ds_bpermute_b32 v3, v60, v2
	s_waitcnt lgkmcnt(0)
	v_add_f32_e32 v2, v2, v3
	ds_bpermute_b32 v3, v61, v2
	s_waitcnt lgkmcnt(0)
	v_add_f32_e32 v2, v2, v3
	ds_bpermute_b32 v3, v62, v2
	s_waitcnt lgkmcnt(0)
	v_add_f32_e32 v2, v2, v3
	ds_bpermute_b32 v3, v63, v2
	s_waitcnt lgkmcnt(0)
	v_add_f32_e32 v2, v2, v3
	v_fmamk_f32 v2, v2, 0x3a000000, v250
	v_cmp_gt_f32_e32 vcc, s96, v2
	v_mul_f32_e32 v3, 0x4f800000, v2
	s_nop 0
	v_cndmask_b32_e32 v2, v2, v3, vcc
	v_sqrt_f32_e32 v3, v2
	s_nop 0
	v_add_u32_e32 v4, -1, v3
	v_fma_f32 v5, -v4, v3, v2
	v_cmp_ge_f32_e64 s[8:9], 0, v5
	v_add_u32_e32 v5, 1, v3
	s_nop 0
	v_cndmask_b32_e64 v4, v3, v4, s[8:9]
	v_fma_f32 v3, -v5, v3, v2
	v_cmp_lt_f32_e64 s[8:9], 0, v3
	s_nop 1
	v_cndmask_b32_e64 v3, v4, v5, s[8:9]
	v_mul_f32_e32 v4, 0x37800000, v3
	v_cndmask_b32_e32 v3, v3, v4, vcc
	v_cmp_class_f32_e32 vcc, v2, v251
	s_nop 1
	v_cndmask_b32_e32 v2, v3, v2, vcc
	v_div_scale_f32 v3, s[8:9], v2, v2, 1.0
	v_rcp_f32_e32 v4, v3
	s_nop 0
	v_fma_f32 v5, -v3, v4, 1.0
	v_fmac_f32_e32 v4, v5, v4
	v_div_scale_f32 v5, vcc, 1.0, v2, 1.0
	v_mul_f32_e32 v46, v5, v4
	v_fma_f32 v47, -v3, v46, v5
	v_fmac_f32_e32 v46, v47, v4
	v_fma_f32 v3, -v3, v46, v5
	v_div_fmas_f32 v3, v3, v4, v46
	v_div_fixup_f32 v46, v3, v2, 1.0
	global_load_dwordx4 v[2:5], v[50:51], off
	v_pk_mul_f32 v[56:57], v[12:13], v[46:47] op_sel_hi:[1,0]
	v_pk_mul_f32 v[64:65], v[10:11], v[46:47] op_sel_hi:[1,0]
	v_cndmask_b32_e64 v47, 0, 1, s[34:35]
	v_cmp_ne_u32_e64 s[8:9], 1, v47
	s_andn2_b64 vcc, exec, s[34:35]
	s_waitcnt vmcnt(0)
	v_pk_fma_f32 v[4:5], v[4:5], v[64:65], v[54:55]
	v_pk_fma_f32 v[2:3], v[2:3], v[56:57], v[52:53]
	v_lshl_add_u64 v[54:55], s[18:19], 0, v[42:43]
	v_lshl_add_u64 v[52:53], v[40:41], 1, s[20:21]
	global_store_dwordx4 v[54:55], v[2:5], off
	s_cbranch_vccnz .LBB0_1760
	v_lshl_add_u64 v[10:11], v[6:7], 0, v[42:43]
	global_load_dwordx4 v[10:13], v[10:11], off
	v_lshl_add_u64 v[42:43], v[38:39], 0, v[42:43]
	global_load_dwordx4 v[64:67], v[42:43], off
	s_waitcnt vmcnt(1)
	v_pk_add_f32 v[12:13], v[12:13], 1.0 op_sel_hi:[1,0]
	v_pk_add_f32 v[42:43], v[10:11], 1.0 op_sel_hi:[1,0]
	s_waitcnt vmcnt(0)
	v_pk_fma_f32 v[10:11], v[4:5], v[12:13], v[66:67]
	v_pk_fma_f32 v[12:13], v[2:3], v[42:43], v[64:65]
	v_bfe_u32 v4, v10, 16, 1
	v_bfe_u32 v5, v11, 16, 1
	v_add3_u32 v4, v10, v4, s73
	v_add3_u32 v5, v11, v5, s73
	v_lshrrev_b32_e32 v4, 16, v4
	v_cvt_pk_bf16_f32 v2, v12, v13
	v_and_or_b32 v3, v5, s33, v4
	global_store_dwordx2 v[52:53], v[2:3], off
.LBB0_1760:
	global_load_dwordx4 v[2:5], v[50:51], off offset:1024
	s_nop 0
	global_load_dwordx4 v[64:67], v[48:49], off offset:1024
	v_mov_b32_e32 v47, v46
	v_mov_b32_e32 v42, v46
	v_mov_b32_e32 v43, v46
	v_pk_mul_f32 v[42:43], v[42:43], v[14:15]
	v_pk_mul_f32 v[56:57], v[46:47], v[16:17]
	s_and_b64 vcc, exec, s[8:9]
	s_waitcnt vmcnt(0)
	v_pk_fma_f32 v[4:5], v[4:5], v[42:43], v[66:67]
	v_pk_fma_f32 v[2:3], v[2:3], v[56:57], v[64:65]
	v_lshl_add_u64 v[42:43], v[40:41], 2, v[38:39]
	global_store_dwordx4 v[54:55], v[2:5], off offset:1024
	s_cbranch_vccnz .LBB0_1762
	v_lshl_add_u64 v[14:15], v[40:41], 2, v[6:7]
	global_load_dwordx4 v[14:17], v[14:15], off offset:1024
	s_nop 0
	global_load_dwordx4 v[64:67], v[42:43], off offset:1024
	s_waitcnt vmcnt(1)
	v_pk_add_f32 v[16:17], v[16:17], 1.0 op_sel_hi:[1,0]
	v_pk_add_f32 v[56:57], v[14:15], 1.0 op_sel_hi:[1,0]
	s_waitcnt vmcnt(0)
	v_pk_fma_f32 v[14:15], v[4:5], v[16:17], v[66:67]
	v_pk_fma_f32 v[16:17], v[2:3], v[56:57], v[64:65]
	v_bfe_u32 v4, v14, 16, 1
	v_bfe_u32 v5, v15, 16, 1
	v_add3_u32 v4, v14, v4, s73
	v_add3_u32 v5, v15, v5, s73
	v_lshrrev_b32_e32 v4, 16, v4
	v_cvt_pk_bf16_f32 v2, v16, v17
	v_and_or_b32 v3, v5, s33, v4
	global_store_dwordx2 v[52:53], v[2:3], off offset:512
.LBB0_1762:
	global_load_dwordx4 v[2:5], v[50:51], off offset:2048
	s_nop 0
	global_load_dwordx4 v[64:67], v[48:49], off offset:2048
	v_mov_b32_e32 v56, v46
	v_mov_b32_e32 v57, v46
	v_pk_mul_f32 v[68:69], v[46:47], v[20:21]
	v_pk_mul_f32 v[70:71], v[56:57], v[18:19]
	s_and_b64 vcc, exec, s[8:9]
	s_waitcnt vmcnt(0)
	v_pk_fma_f32 v[4:5], v[4:5], v[70:71], v[66:67]
	v_pk_fma_f32 v[2:3], v[2:3], v[68:69], v[64:65]
	global_store_dwordx4 v[54:55], v[2:5], off offset:2048
	s_cbranch_vccnz .LBB0_1764
	v_lshl_add_u64 v[18:19], v[40:41], 2, v[6:7]
	global_load_dwordx4 v[18:21], v[18:19], off offset:2048
	s_nop 0
	global_load_dwordx4 v[64:67], v[42:43], off offset:2048
	s_waitcnt vmcnt(1)
	v_pk_add_f32 v[20:21], v[20:21], 1.0 op_sel_hi:[1,0]
	v_pk_add_f32 v[68:69], v[18:19], 1.0 op_sel_hi:[1,0]
	s_waitcnt vmcnt(0)
	v_pk_fma_f32 v[18:19], v[4:5], v[20:21], v[66:67]
	v_pk_fma_f32 v[20:21], v[2:3], v[68:69], v[64:65]
	v_bfe_u32 v4, v18, 16, 1
	v_bfe_u32 v5, v19, 16, 1
	v_add3_u32 v4, v18, v4, s73
	v_add3_u32 v5, v19, v5, s73
	v_lshrrev_b32_e32 v4, 16, v4
	v_cvt_pk_bf16_f32 v2, v20, v21
	v_and_or_b32 v3, v5, s33, v4
	global_store_dwordx2 v[52:53], v[2:3], off offset:1024
.LBB0_1764:
	global_load_dwordx4 v[2:5], v[50:51], off offset:3072
	s_nop 0
	global_load_dwordx4 v[64:67], v[48:49], off offset:3072
	v_pk_mul_f32 v[56:57], v[56:57], v[22:23]
	v_pk_mul_f32 v[68:69], v[46:47], v[24:25]
	s_and_b64 vcc, exec, s[8:9]
	s_waitcnt vmcnt(0)
	v_pk_fma_f32 v[4:5], v[4:5], v[56:57], v[66:67]
	v_pk_fma_f32 v[2:3], v[2:3], v[68:69], v[64:65]
	global_store_dwordx4 v[54:55], v[2:5], off offset:3072
	s_cbranch_vccnz .LBB0_1766
	v_lshl_add_u64 v[22:23], v[40:41], 2, v[6:7]
	global_load_dwordx4 v[22:25], v[22:23], off offset:3072
	s_nop 0
	global_load_dwordx4 v[64:67], v[42:43], off offset:3072
	s_waitcnt vmcnt(1)
	v_pk_add_f32 v[24:25], v[24:25], 1.0 op_sel_hi:[1,0]
	v_pk_add_f32 v[42:43], v[22:23], 1.0 op_sel_hi:[1,0]
	s_waitcnt vmcnt(0)
	v_pk_fma_f32 v[22:23], v[4:5], v[24:25], v[66:67]
	v_pk_fma_f32 v[24:25], v[2:3], v[42:43], v[64:65]
	v_bfe_u32 v4, v22, 16, 1
	v_bfe_u32 v5, v23, 16, 1
	v_add3_u32 v4, v22, v4, s73
	v_add3_u32 v5, v23, v5, s73
	v_lshrrev_b32_e32 v4, 16, v4
	v_cvt_pk_bf16_f32 v2, v24, v25
	v_and_or_b32 v3, v5, s33, v4
	global_store_dwordx2 v[52:53], v[2:3], off offset:1536
.LBB0_1766:
	s_nop 0
	v_add_co_u32_e32 v2, vcc, 0x1000, v50
	v_pk_mul_f32 v[68:69], v[46:47], v[28:29]
	s_nop 0
	v_addc_co_u32_e32 v3, vcc, 0, v51, vcc
	v_add_co_u32_e32 v42, vcc, 0x1000, v48
	global_load_dwordx4 v[2:5], v[2:3], off
	s_nop 0
	v_addc_co_u32_e32 v43, vcc, 0, v49, vcc
	global_load_dwordx4 v[64:67], v[42:43], off
	v_mov_b32_e32 v42, v46
	v_mov_b32_e32 v43, v46
	v_pk_mul_f32 v[56:57], v[42:43], v[26:27]
	s_waitcnt vmcnt(0)
	v_pk_fma_f32 v[2:3], v[2:3], v[68:69], v[64:65]
	v_pk_fma_f32 v[4:5], v[4:5], v[56:57], v[66:67]
	v_add_co_u32_e32 v56, vcc, 0x1000, v54
	s_nop 1
	v_addc_co_u32_e32 v57, vcc, 0, v55, vcc
	s_and_b64 vcc, exec, s[8:9]
	global_store_dwordx4 v[56:57], v[2:5], off
	s_cbranch_vccnz .LBB0_1768
	v_mov_b64_e32 v[26:27], 0x1000
	v_lshl_add_u64 v[56:57], v[40:41], 2, v[26:27]
	v_lshl_add_u64 v[26:27], v[6:7], 0, v[56:57]
	global_load_dwordx4 v[26:29], v[26:27], off
	v_lshl_add_u64 v[56:57], v[38:39], 0, v[56:57]
	global_load_dwordx4 v[64:67], v[56:57], off
	s_waitcnt vmcnt(1)
	v_pk_add_f32 v[28:29], v[28:29], 1.0 op_sel_hi:[1,0]
	v_pk_add_f32 v[56:57], v[26:27], 1.0 op_sel_hi:[1,0]
	s_waitcnt vmcnt(0)
	v_pk_fma_f32 v[26:27], v[4:5], v[28:29], v[66:67]
	v_pk_fma_f32 v[28:29], v[2:3], v[56:57], v[64:65]
	v_bfe_u32 v4, v26, 16, 1
	v_bfe_u32 v5, v27, 16, 1
	v_add3_u32 v4, v26, v4, s73
	v_add3_u32 v5, v27, v5, s73
	v_lshrrev_b32_e32 v4, 16, v4
	v_cvt_pk_bf16_f32 v2, v28, v29
	v_and_or_b32 v3, v5, s33, v4
	global_store_dwordx2 v[52:53], v[2:3], off offset:2048
.LBB0_1768:
	s_nop 0
	v_add_co_u32_e32 v2, vcc, 0x1000, v50
	v_pk_mul_f32 v[42:43], v[42:43], v[30:31]
	s_nop 0
	v_addc_co_u32_e32 v3, vcc, 0, v51, vcc
	v_add_co_u32_e32 v56, vcc, 0x1000, v48
	global_load_dwordx4 v[2:5], v[2:3], off offset:1024
	s_nop 0
	v_addc_co_u32_e32 v57, vcc, 0, v49, vcc
	global_load_dwordx4 v[64:67], v[56:57], off offset:1024
	v_pk_mul_f32 v[56:57], v[46:47], v[32:33]
	s_waitcnt vmcnt(0)
	v_pk_fma_f32 v[4:5], v[4:5], v[42:43], v[66:67]
	v_add_co_u32_e32 v42, vcc, 0x1000, v54
	v_pk_fma_f32 v[2:3], v[2:3], v[56:57], v[64:65]
	s_nop 0
	v_addc_co_u32_e32 v43, vcc, 0, v55, vcc
	s_and_b64 vcc, exec, s[8:9]
	global_store_dwordx4 v[42:43], v[2:5], off offset:1024
	s_cbranch_vccnz .LBB0_1770
	v_mov_b64_e32 v[30:31], 0x1400
	v_lshl_add_u64 v[42:43], v[40:41], 2, v[30:31]
	v_lshl_add_u64 v[30:31], v[6:7], 0, v[42:43]
	global_load_dwordx4 v[30:33], v[30:31], off
	v_lshl_add_u64 v[42:43], v[38:39], 0, v[42:43]
	global_load_dwordx4 v[64:67], v[42:43], off
	s_waitcnt vmcnt(1)
	v_pk_add_f32 v[32:33], v[32:33], 1.0 op_sel_hi:[1,0]
	v_pk_add_f32 v[42:43], v[30:31], 1.0 op_sel_hi:[1,0]
	s_waitcnt vmcnt(0)
	v_pk_fma_f32 v[30:31], v[4:5], v[32:33], v[66:67]
	v_pk_fma_f32 v[32:33], v[2:3], v[42:43], v[64:65]
	v_bfe_u32 v4, v30, 16, 1
	v_bfe_u32 v5, v31, 16, 1
	v_add3_u32 v4, v30, v4, s73
	v_add3_u32 v5, v31, v5, s73
	v_lshrrev_b32_e32 v4, 16, v4
	v_cvt_pk_bf16_f32 v2, v32, v33
	v_and_or_b32 v3, v5, s33, v4
	global_store_dwordx2 v[52:53], v[2:3], off offset:2560
.LBB0_1770:
	s_nop 0
	v_add_co_u32_e32 v2, vcc, 0x1000, v50
	v_pk_mul_f32 v[68:69], v[46:47], v[36:37]
	s_nop 0
	v_addc_co_u32_e32 v3, vcc, 0, v51, vcc
	v_add_co_u32_e32 v42, vcc, 0x1000, v48
	global_load_dwordx4 v[2:5], v[2:3], off offset:2048
	s_nop 0
	v_addc_co_u32_e32 v43, vcc, 0, v49, vcc
	global_load_dwordx4 v[64:67], v[42:43], off offset:2048
	v_mov_b32_e32 v42, v46
	v_mov_b32_e32 v43, v46
	v_pk_mul_f32 v[56:57], v[42:43], v[34:35]
	s_waitcnt vmcnt(0)
	v_pk_fma_f32 v[2:3], v[2:3], v[68:69], v[64:65]
	v_pk_fma_f32 v[4:5], v[4:5], v[56:57], v[66:67]
	v_add_co_u32_e32 v56, vcc, 0x1000, v54
	s_nop 1
	v_addc_co_u32_e32 v57, vcc, 0, v55, vcc
	s_and_b64 vcc, exec, s[8:9]
	global_store_dwordx4 v[56:57], v[2:5], off offset:2048
	s_cbranch_vccnz .LBB0_1772
	v_mov_b64_e32 v[34:35], 0x1800
	v_lshl_add_u64 v[56:57], v[40:41], 2, v[34:35]
	v_lshl_add_u64 v[34:35], v[6:7], 0, v[56:57]
	global_load_dwordx4 v[34:37], v[34:35], off
	v_lshl_add_u64 v[56:57], v[38:39], 0, v[56:57]
	global_load_dwordx4 v[64:67], v[56:57], off
	s_waitcnt vmcnt(1)
	v_pk_add_f32 v[36:37], v[36:37], 1.0 op_sel_hi:[1,0]
	v_pk_add_f32 v[56:57], v[34:35], 1.0 op_sel_hi:[1,0]
	s_waitcnt vmcnt(0)
	v_pk_fma_f32 v[34:35], v[4:5], v[36:37], v[66:67]
	v_pk_fma_f32 v[36:37], v[2:3], v[56:57], v[64:65]
	v_bfe_u32 v4, v34, 16, 1
	v_bfe_u32 v5, v35, 16, 1
	v_add3_u32 v4, v34, v4, s73
	v_add3_u32 v5, v35, v5, s73
	v_lshrrev_b32_e32 v4, 16, v4
	v_cvt_pk_bf16_f32 v2, v36, v37
	v_and_or_b32 v3, v5, s33, v4
	global_store_dwordx2 v[52:53], v[2:3], off offset:3072
.LBB0_1772:
	s_nop 0
	v_add_co_u32_e32 v2, vcc, 0x1000, v50
	v_pk_mul_f32 v[42:43], v[42:43], v[44:45]
	s_nop 0
	v_addc_co_u32_e32 v3, vcc, 0, v51, vcc
	v_add_co_u32_e32 v48, vcc, 0x1000, v48
	global_load_dwordx4 v[2:5], v[2:3], off offset:3072
	s_nop 0
	v_addc_co_u32_e32 v49, vcc, 0, v49, vcc
	global_load_dwordx4 v[48:51], v[48:49], off offset:3072
	v_add_co_u32_e32 v44, vcc, 0x1000, v54
	v_pk_mul_f32 v[8:9], v[46:47], v[8:9]
	s_nop 0
	v_addc_co_u32_e32 v45, vcc, 0, v55, vcc
	s_and_b64 vcc, exec, s[8:9]
	s_waitcnt vmcnt(0)
	v_pk_fma_f32 v[4:5], v[4:5], v[42:43], v[50:51]
	v_pk_fma_f32 v[2:3], v[2:3], v[8:9], v[48:49]
	global_store_dwordx4 v[44:45], v[2:5], off offset:3072
	s_cbranch_vccnz .LBB0_1756
	v_mov_b64_e32 v[8:9], 0x1c00
	v_lshl_add_u64 v[40:41], v[40:41], 2, v[8:9]
	v_lshl_add_u64 v[6:7], v[6:7], 0, v[40:41]
	global_load_dwordx4 v[6:9], v[6:7], off
	v_lshl_add_u64 v[38:39], v[38:39], 0, v[40:41]
	global_load_dwordx4 v[38:41], v[38:39], off
	s_waitcnt vmcnt(1)
	v_pk_add_f32 v[6:7], v[6:7], 1.0 op_sel_hi:[1,0]
	v_pk_add_f32 v[8:9], v[8:9], 1.0 op_sel_hi:[1,0]
	s_waitcnt vmcnt(0)
	v_pk_fma_f32 v[2:3], v[2:3], v[6:7], v[38:39]
	v_pk_fma_f32 v[4:5], v[4:5], v[8:9], v[40:41]
	v_cvt_pk_bf16_f32 v6, v2, v3
	v_cvt_pk_bf16_f32 v7, v4, v5
	global_store_dwordx2 v[52:53], v[6:7], off offset:3584
	v_lshl_add_u32 v6, v1, 4, 0
	ds_read_b128 v[38:41], v6
	s_waitcnt lgkmcnt(0)
	v_pk_fma_f32 v[8:9], v[12:13], v[38:39], 0 op_sel_hi:[1,1,0]
	s_nop 0
	v_pk_fma_f32 v[8:9], v[10:11], v[40:41], v[8:9]
	ds_read_b128 v[38:41], v6 offset:1024
	s_waitcnt lgkmcnt(0)
	v_pk_fma_f32 v[8:9], v[16:17], v[38:39], v[8:9]
	s_nop 0
	v_pk_fma_f32 v[8:9], v[14:15], v[40:41], v[8:9]
	ds_read_b128 v[38:41], v6 offset:2048
	s_waitcnt lgkmcnt(0)
	v_pk_fma_f32 v[8:9], v[20:21], v[38:39], v[8:9]
	s_nop 0
	v_pk_fma_f32 v[8:9], v[18:19], v[40:41], v[8:9]
	ds_read_b128 v[38:41], v6 offset:3072
	s_waitcnt lgkmcnt(0)
	v_pk_fma_f32 v[8:9], v[24:25], v[38:39], v[8:9]
	s_nop 0
	v_pk_fma_f32 v[8:9], v[22:23], v[40:41], v[8:9]
	ds_read_b128 v[38:41], v6 offset:4096
	s_waitcnt lgkmcnt(0)
	v_pk_fma_f32 v[8:9], v[28:29], v[38:39], v[8:9]
	s_nop 0
	v_pk_fma_f32 v[8:9], v[26:27], v[40:41], v[8:9]
	ds_read_b128 v[38:41], v6 offset:5120
	s_waitcnt lgkmcnt(0)
	v_pk_fma_f32 v[8:9], v[32:33], v[38:39], v[8:9]
	s_nop 0
	v_pk_fma_f32 v[8:9], v[30:31], v[40:41], v[8:9]
	ds_read_b128 v[38:41], v6 offset:6144
	s_waitcnt lgkmcnt(0)
	v_pk_fma_f32 v[8:9], v[36:37], v[38:39], v[8:9]
	s_nop 0
	v_pk_fma_f32 v[8:9], v[34:35], v[40:41], v[8:9]
	ds_read_b128 v[38:41], v6 offset:7168
	s_waitcnt lgkmcnt(0)
	v_pk_fma_f32 v[8:9], v[2:3], v[38:39], v[8:9]
	s_nop 0
	v_pk_fma_f32 v[8:9], v[4:5], v[40:41], v[8:9]
	ds_read_b128 v[38:41], v6 offset:8192
	v_add_f32_e32 v7, v8, v9
	s_waitcnt lgkmcnt(0)
	v_pk_fma_f32 v[8:9], v[12:13], v[38:39], 0 op_sel_hi:[1,1,0]
	s_nop 0
	v_pk_fma_f32 v[8:9], v[10:11], v[40:41], v[8:9]
	ds_read_b128 v[38:41], v6 offset:9216
	s_waitcnt lgkmcnt(0)
	v_pk_fma_f32 v[8:9], v[16:17], v[38:39], v[8:9]
	s_nop 0
	v_pk_fma_f32 v[8:9], v[14:15], v[40:41], v[8:9]
	ds_read_b128 v[38:41], v6 offset:10240
	s_waitcnt lgkmcnt(0)
	v_pk_fma_f32 v[8:9], v[20:21], v[38:39], v[8:9]
	s_nop 0
	v_pk_fma_f32 v[8:9], v[18:19], v[40:41], v[8:9]
	ds_read_b128 v[38:41], v6 offset:11264
	s_waitcnt lgkmcnt(0)
	v_pk_fma_f32 v[8:9], v[24:25], v[38:39], v[8:9]
	s_nop 0
	v_pk_fma_f32 v[8:9], v[22:23], v[40:41], v[8:9]
	ds_read_b128 v[38:41], v6 offset:12288
	s_waitcnt lgkmcnt(0)
	v_pk_fma_f32 v[8:9], v[28:29], v[38:39], v[8:9]
	s_nop 0
	v_pk_fma_f32 v[8:9], v[26:27], v[40:41], v[8:9]
	ds_read_b128 v[38:41], v6 offset:13312
	s_waitcnt lgkmcnt(0)
	v_pk_fma_f32 v[8:9], v[32:33], v[38:39], v[8:9]
	s_nop 0
	v_pk_fma_f32 v[8:9], v[30:31], v[40:41], v[8:9]
	ds_read_b128 v[38:41], v6 offset:14336
	s_waitcnt lgkmcnt(0)
	v_pk_fma_f32 v[8:9], v[36:37], v[38:39], v[8:9]
	s_nop 0
	v_pk_fma_f32 v[8:9], v[34:35], v[40:41], v[8:9]
	ds_read_b128 v[38:41], v6 offset:15360
	s_waitcnt lgkmcnt(0)
	v_pk_fma_f32 v[8:9], v[2:3], v[38:39], v[8:9]
	s_nop 0
	v_pk_fma_f32 v[8:9], v[4:5], v[40:41], v[8:9]
	ds_read_b128 v[38:41], v6 offset:16384
	v_add_f32_e32 v8, v8, v9
	s_waitcnt lgkmcnt(0)
	v_pk_fma_f32 v[38:39], v[12:13], v[38:39], 0 op_sel_hi:[1,1,0]
	s_nop 0
	v_pk_fma_f32 v[42:43], v[10:11], v[40:41], v[38:39]
	ds_read_b128 v[38:41], v6 offset:17408
	s_waitcnt lgkmcnt(0)
	v_pk_fma_f32 v[38:39], v[16:17], v[38:39], v[42:43]
	s_nop 0
	v_pk_fma_f32 v[42:43], v[14:15], v[40:41], v[38:39]
	ds_read_b128 v[38:41], v6 offset:18432
	s_waitcnt lgkmcnt(0)
	v_pk_fma_f32 v[38:39], v[20:21], v[38:39], v[42:43]
	s_nop 0
	v_pk_fma_f32 v[42:43], v[18:19], v[40:41], v[38:39]
	ds_read_b128 v[38:41], v6 offset:19456
	s_waitcnt lgkmcnt(0)
	v_pk_fma_f32 v[38:39], v[24:25], v[38:39], v[42:43]
	s_nop 0
	v_pk_fma_f32 v[42:43], v[22:23], v[40:41], v[38:39]
	ds_read_b128 v[38:41], v6 offset:20480
	s_waitcnt lgkmcnt(0)
	v_pk_fma_f32 v[38:39], v[28:29], v[38:39], v[42:43]
	s_nop 0
	v_pk_fma_f32 v[42:43], v[26:27], v[40:41], v[38:39]
	ds_read_b128 v[38:41], v6 offset:21504
	s_waitcnt lgkmcnt(0)
	v_pk_fma_f32 v[38:39], v[32:33], v[38:39], v[42:43]
	s_nop 0
	v_pk_fma_f32 v[42:43], v[30:31], v[40:41], v[38:39]
	ds_read_b128 v[38:41], v6 offset:22528
	s_waitcnt lgkmcnt(0)
	v_pk_fma_f32 v[38:39], v[36:37], v[38:39], v[42:43]
	s_nop 0
	v_pk_fma_f32 v[42:43], v[34:35], v[40:41], v[38:39]
	ds_read_b128 v[38:41], v6 offset:23552
	s_waitcnt lgkmcnt(0)
	v_pk_fma_f32 v[38:39], v[2:3], v[38:39], v[42:43]
	s_nop 0
	v_pk_fma_f32 v[38:39], v[4:5], v[40:41], v[38:39]
	s_nop 0
	v_add_f32_e32 v9, v38, v39
	ds_read_b128 v[38:41], v6 offset:24576
	s_waitcnt lgkmcnt(0)
	v_pk_fma_f32 v[38:39], v[12:13], v[38:39], 0 op_sel_hi:[1,1,0]
	s_nop 0
	v_pk_fma_f32 v[42:43], v[10:11], v[40:41], v[38:39]
	ds_read_b128 v[38:41], v6 offset:25600
	s_waitcnt lgkmcnt(0)
	v_pk_fma_f32 v[38:39], v[16:17], v[38:39], v[42:43]
	s_nop 0
	v_pk_fma_f32 v[42:43], v[14:15], v[40:41], v[38:39]
	ds_read_b128 v[38:41], v6 offset:26624
	s_waitcnt lgkmcnt(0)
	v_pk_fma_f32 v[38:39], v[20:21], v[38:39], v[42:43]
	s_nop 0
	v_pk_fma_f32 v[42:43], v[18:19], v[40:41], v[38:39]
	ds_read_b128 v[38:41], v6 offset:27648
	s_waitcnt lgkmcnt(0)
	v_pk_fma_f32 v[38:39], v[24:25], v[38:39], v[42:43]
	s_nop 0
	v_pk_fma_f32 v[42:43], v[22:23], v[40:41], v[38:39]
	ds_read_b128 v[38:41], v6 offset:28672
	s_waitcnt lgkmcnt(0)
	v_pk_fma_f32 v[38:39], v[28:29], v[38:39], v[42:43]
	s_nop 0
	v_pk_fma_f32 v[42:43], v[26:27], v[40:41], v[38:39]
	ds_read_b128 v[38:41], v6 offset:29696
	s_waitcnt lgkmcnt(0)
	v_pk_fma_f32 v[38:39], v[32:33], v[38:39], v[42:43]
	s_nop 0
	v_pk_fma_f32 v[42:43], v[30:31], v[40:41], v[38:39]
	ds_read_b128 v[38:41], v6 offset:30720
	s_waitcnt lgkmcnt(0)
	v_pk_fma_f32 v[38:39], v[36:37], v[38:39], v[42:43]
	s_nop 0
	v_pk_fma_f32 v[42:43], v[34:35], v[40:41], v[38:39]
	ds_read_b128 v[38:41], v6 offset:31744
	s_waitcnt lgkmcnt(0)
	v_pk_fma_f32 v[38:39], v[2:3], v[38:39], v[42:43]
	s_nop 0
	v_pk_fma_f32 v[38:39], v[4:5], v[40:41], v[38:39]
	ds_read_b128 v[40:43], v6 offset:32768
	v_add_f32_e32 v38, v38, v39
	s_waitcnt lgkmcnt(0)
	v_pk_fma_f32 v[40:41], v[12:13], v[40:41], 0 op_sel_hi:[1,1,0]
	s_nop 0
	v_pk_fma_f32 v[44:45], v[10:11], v[42:43], v[40:41]
	ds_read_b128 v[40:43], v6 offset:33792
	s_waitcnt lgkmcnt(0)
	v_pk_fma_f32 v[40:41], v[16:17], v[40:41], v[44:45]
	s_nop 0
	v_pk_fma_f32 v[44:45], v[14:15], v[42:43], v[40:41]
	ds_read_b128 v[40:43], v6 offset:34816
	s_waitcnt lgkmcnt(0)
	v_pk_fma_f32 v[40:41], v[20:21], v[40:41], v[44:45]
	s_nop 0
	v_pk_fma_f32 v[44:45], v[18:19], v[42:43], v[40:41]
	ds_read_b128 v[40:43], v6 offset:35840
	s_waitcnt lgkmcnt(0)
	v_pk_fma_f32 v[40:41], v[24:25], v[40:41], v[44:45]
	s_nop 0
	v_pk_fma_f32 v[44:45], v[22:23], v[42:43], v[40:41]
	ds_read_b128 v[40:43], v6 offset:36864
	s_waitcnt lgkmcnt(0)
	v_pk_fma_f32 v[40:41], v[28:29], v[40:41], v[44:45]
	s_nop 0
	v_pk_fma_f32 v[44:45], v[26:27], v[42:43], v[40:41]
	ds_read_b128 v[40:43], v6 offset:37888
	s_waitcnt lgkmcnt(0)
	v_pk_fma_f32 v[40:41], v[32:33], v[40:41], v[44:45]
	s_nop 0
	v_pk_fma_f32 v[44:45], v[30:31], v[42:43], v[40:41]
	ds_read_b128 v[40:43], v6 offset:38912
	s_waitcnt lgkmcnt(0)
	v_pk_fma_f32 v[40:41], v[36:37], v[40:41], v[44:45]
	s_nop 0
	v_pk_fma_f32 v[44:45], v[34:35], v[42:43], v[40:41]
	ds_read_b128 v[40:43], v6 offset:39936
	s_waitcnt lgkmcnt(0)
	v_pk_fma_f32 v[40:41], v[2:3], v[40:41], v[44:45]
	s_nop 0
	v_pk_fma_f32 v[40:41], v[4:5], v[42:43], v[40:41]
	s_nop 0
	v_add_f32_e32 v39, v40, v41
	ds_read_b128 v[40:43], v6 offset:40960
	s_waitcnt lgkmcnt(0)
	v_pk_fma_f32 v[40:41], v[12:13], v[40:41], 0 op_sel_hi:[1,1,0]
	s_nop 0
	v_pk_fma_f32 v[44:45], v[10:11], v[42:43], v[40:41]
	ds_read_b128 v[40:43], v6 offset:41984
	s_waitcnt lgkmcnt(0)
	v_pk_fma_f32 v[40:41], v[16:17], v[40:41], v[44:45]
	s_nop 0
	v_pk_fma_f32 v[44:45], v[14:15], v[42:43], v[40:41]
	ds_read_b128 v[40:43], v6 offset:43008
	s_waitcnt lgkmcnt(0)
	v_pk_fma_f32 v[40:41], v[20:21], v[40:41], v[44:45]
	s_nop 0
	v_pk_fma_f32 v[44:45], v[18:19], v[42:43], v[40:41]
	ds_read_b128 v[40:43], v6 offset:44032
	s_waitcnt lgkmcnt(0)
	v_pk_fma_f32 v[40:41], v[24:25], v[40:41], v[44:45]
	s_nop 0
	v_pk_fma_f32 v[44:45], v[22:23], v[42:43], v[40:41]
	ds_read_b128 v[40:43], v6 offset:45056
	s_waitcnt lgkmcnt(0)
	v_pk_fma_f32 v[40:41], v[28:29], v[40:41], v[44:45]
	s_nop 0
	v_pk_fma_f32 v[44:45], v[26:27], v[42:43], v[40:41]
	ds_read_b128 v[40:43], v6 offset:46080
	s_waitcnt lgkmcnt(0)
	v_pk_fma_f32 v[40:41], v[32:33], v[40:41], v[44:45]
	s_nop 0
	v_pk_fma_f32 v[44:45], v[30:31], v[42:43], v[40:41]
	ds_read_b128 v[40:43], v6 offset:47104
	s_waitcnt lgkmcnt(0)
	v_pk_fma_f32 v[40:41], v[36:37], v[40:41], v[44:45]
	s_nop 0
	v_pk_fma_f32 v[44:45], v[34:35], v[42:43], v[40:41]
	ds_read_b128 v[40:43], v6 offset:48128
	s_waitcnt lgkmcnt(0)
	v_pk_fma_f32 v[40:41], v[2:3], v[40:41], v[44:45]
	s_nop 0
	v_pk_fma_f32 v[40:41], v[4:5], v[42:43], v[40:41]
	ds_read_b128 v[42:45], v6 offset:49152
	v_add_f32_e32 v40, v40, v41
	s_waitcnt lgkmcnt(0)
	v_pk_fma_f32 v[42:43], v[12:13], v[42:43], 0 op_sel_hi:[1,1,0]
	s_nop 0
	v_pk_fma_f32 v[46:47], v[10:11], v[44:45], v[42:43]
	ds_read_b128 v[42:45], v6 offset:50176
	s_waitcnt lgkmcnt(0)
	v_pk_fma_f32 v[42:43], v[16:17], v[42:43], v[46:47]
	s_nop 0
	v_pk_fma_f32 v[46:47], v[14:15], v[44:45], v[42:43]
	ds_read_b128 v[42:45], v6 offset:51200
	s_waitcnt lgkmcnt(0)
	v_pk_fma_f32 v[42:43], v[20:21], v[42:43], v[46:47]
	s_nop 0
	v_pk_fma_f32 v[46:47], v[18:19], v[44:45], v[42:43]
	ds_read_b128 v[42:45], v6 offset:52224
	s_waitcnt lgkmcnt(0)
	v_pk_fma_f32 v[42:43], v[24:25], v[42:43], v[46:47]
	s_nop 0
	v_pk_fma_f32 v[46:47], v[22:23], v[44:45], v[42:43]
	ds_read_b128 v[42:45], v6 offset:53248
	s_waitcnt lgkmcnt(0)
	v_pk_fma_f32 v[42:43], v[28:29], v[42:43], v[46:47]
	s_nop 0
	v_pk_fma_f32 v[46:47], v[26:27], v[44:45], v[42:43]
	ds_read_b128 v[42:45], v6 offset:54272
	s_waitcnt lgkmcnt(0)
	v_pk_fma_f32 v[42:43], v[32:33], v[42:43], v[46:47]
	s_nop 0
	v_pk_fma_f32 v[46:47], v[30:31], v[44:45], v[42:43]
	ds_read_b128 v[42:45], v6 offset:55296
	s_waitcnt lgkmcnt(0)
	v_pk_fma_f32 v[42:43], v[36:37], v[42:43], v[46:47]
	s_nop 0
	v_pk_fma_f32 v[46:47], v[34:35], v[44:45], v[42:43]
	ds_read_b128 v[42:45], v6 offset:56320
	s_waitcnt lgkmcnt(0)
	v_pk_fma_f32 v[42:43], v[2:3], v[42:43], v[46:47]
	s_nop 0
	v_pk_fma_f32 v[42:43], v[4:5], v[44:45], v[42:43]
	s_nop 0
	v_add_f32_e32 v41, v42, v43
	ds_read_b128 v[42:45], v6 offset:57344
	s_waitcnt lgkmcnt(0)
	v_pk_fma_f32 v[42:43], v[12:13], v[42:43], 0 op_sel_hi:[1,1,0]
	s_nop 0
	v_pk_fma_f32 v[46:47], v[10:11], v[44:45], v[42:43]
	ds_read_b128 v[42:45], v6 offset:58368
	s_waitcnt lgkmcnt(0)
	v_pk_fma_f32 v[42:43], v[16:17], v[42:43], v[46:47]
	s_nop 0
	v_pk_fma_f32 v[46:47], v[14:15], v[44:45], v[42:43]
	ds_read_b128 v[42:45], v6 offset:59392
	s_waitcnt lgkmcnt(0)
	v_pk_fma_f32 v[42:43], v[20:21], v[42:43], v[46:47]
	s_nop 0
	v_pk_fma_f32 v[46:47], v[18:19], v[44:45], v[42:43]
	ds_read_b128 v[42:45], v6 offset:60416
	s_waitcnt lgkmcnt(0)
	v_pk_fma_f32 v[42:43], v[24:25], v[42:43], v[46:47]
	s_nop 0
	v_pk_fma_f32 v[46:47], v[22:23], v[44:45], v[42:43]
	ds_read_b128 v[42:45], v6 offset:61440
	s_waitcnt lgkmcnt(0)
	v_pk_fma_f32 v[42:43], v[28:29], v[42:43], v[46:47]
	s_nop 0
	v_pk_fma_f32 v[46:47], v[26:27], v[44:45], v[42:43]
	ds_read_b128 v[42:45], v6 offset:62464
	s_waitcnt lgkmcnt(0)
	v_pk_fma_f32 v[42:43], v[32:33], v[42:43], v[46:47]
	s_nop 0
	v_pk_fma_f32 v[46:47], v[30:31], v[44:45], v[42:43]
	ds_read_b128 v[42:45], v6 offset:63488
	s_waitcnt lgkmcnt(0)
	v_pk_fma_f32 v[42:43], v[36:37], v[42:43], v[46:47]
	s_nop 0
	v_pk_fma_f32 v[46:47], v[34:35], v[44:45], v[42:43]
	ds_read_b128 v[42:45], v6 offset:64512
	s_waitcnt lgkmcnt(0)
	v_pk_fma_f32 v[42:43], v[2:3], v[42:43], v[46:47]
	s_nop 0
	v_pk_fma_f32 v[42:43], v[4:5], v[44:45], v[42:43]
	s_nop 0
	v_add_f32_e32 v42, v42, v43
	v_add_u32_e32 v43, 0x10000, v6
	ds_read_b128 v[44:47], v43
	v_add_u32_e32 v43, 0x10400, v6
	s_waitcnt lgkmcnt(0)
	v_pk_fma_f32 v[44:45], v[12:13], v[44:45], 0 op_sel_hi:[1,1,0]
	s_nop 0
	v_pk_fma_f32 v[48:49], v[10:11], v[46:47], v[44:45]
	ds_read_b128 v[44:47], v43
	v_add_u32_e32 v43, 0x10800, v6
	s_waitcnt lgkmcnt(0)
	v_pk_fma_f32 v[44:45], v[16:17], v[44:45], v[48:49]
	s_nop 0
	v_pk_fma_f32 v[48:49], v[14:15], v[46:47], v[44:45]
	ds_read_b128 v[44:47], v43
	v_add_u32_e32 v43, 0x10c00, v6
	s_waitcnt lgkmcnt(0)
	v_pk_fma_f32 v[44:45], v[20:21], v[44:45], v[48:49]
	s_nop 0
	v_pk_fma_f32 v[48:49], v[18:19], v[46:47], v[44:45]
	ds_read_b128 v[44:47], v43
	v_add_u32_e32 v43, 0x11000, v6
	s_waitcnt lgkmcnt(0)
	v_pk_fma_f32 v[44:45], v[24:25], v[44:45], v[48:49]
	s_nop 0
	v_pk_fma_f32 v[48:49], v[22:23], v[46:47], v[44:45]
	ds_read_b128 v[44:47], v43
	v_add_u32_e32 v43, 0x11400, v6
	s_waitcnt lgkmcnt(0)
	v_pk_fma_f32 v[44:45], v[28:29], v[44:45], v[48:49]
	s_nop 0
	v_pk_fma_f32 v[48:49], v[26:27], v[46:47], v[44:45]
	ds_read_b128 v[44:47], v43
	v_add_u32_e32 v43, 0x11800, v6
	s_waitcnt lgkmcnt(0)
	v_pk_fma_f32 v[44:45], v[32:33], v[44:45], v[48:49]
	s_nop 0
	v_pk_fma_f32 v[48:49], v[30:31], v[46:47], v[44:45]
	ds_read_b128 v[44:47], v43
	v_add_u32_e32 v43, 0x11c00, v6
	s_waitcnt lgkmcnt(0)
	v_pk_fma_f32 v[44:45], v[36:37], v[44:45], v[48:49]
	s_nop 0
	v_pk_fma_f32 v[48:49], v[34:35], v[46:47], v[44:45]
	ds_read_b128 v[44:47], v43
	s_waitcnt lgkmcnt(0)
	v_pk_fma_f32 v[44:45], v[2:3], v[44:45], v[48:49]
	s_nop 0
	v_pk_fma_f32 v[44:45], v[4:5], v[46:47], v[44:45]
	s_nop 0
	v_add_f32_e32 v43, v44, v45
	v_add_u32_e32 v44, 0x12000, v6
	ds_read_b128 v[44:47], v44
	s_waitcnt lgkmcnt(0)
	v_pk_fma_f32 v[44:45], v[12:13], v[44:45], 0 op_sel_hi:[1,1,0]
	s_nop 0
	v_pk_fma_f32 v[48:49], v[10:11], v[46:47], v[44:45]
	v_add_u32_e32 v44, 0x12400, v6
	ds_read_b128 v[44:47], v44
	s_waitcnt lgkmcnt(0)
	v_pk_fma_f32 v[44:45], v[16:17], v[44:45], v[48:49]
	s_nop 0
	v_pk_fma_f32 v[48:49], v[14:15], v[46:47], v[44:45]
	v_add_u32_e32 v44, 0x12800, v6
	ds_read_b128 v[44:47], v44
	s_waitcnt lgkmcnt(0)
	v_pk_fma_f32 v[44:45], v[20:21], v[44:45], v[48:49]
	s_nop 0
	v_pk_fma_f32 v[48:49], v[18:19], v[46:47], v[44:45]
	v_add_u32_e32 v44, 0x12c00, v6
	ds_read_b128 v[44:47], v44
	s_waitcnt lgkmcnt(0)
	v_pk_fma_f32 v[44:45], v[24:25], v[44:45], v[48:49]
	s_nop 0
	v_pk_fma_f32 v[48:49], v[22:23], v[46:47], v[44:45]
	v_add_u32_e32 v44, 0x13000, v6
	ds_read_b128 v[44:47], v44
	s_waitcnt lgkmcnt(0)
	v_pk_fma_f32 v[44:45], v[28:29], v[44:45], v[48:49]
	s_nop 0
	v_pk_fma_f32 v[48:49], v[26:27], v[46:47], v[44:45]
	v_add_u32_e32 v44, 0x13400, v6
	ds_read_b128 v[44:47], v44
	s_waitcnt lgkmcnt(0)
	v_pk_fma_f32 v[44:45], v[32:33], v[44:45], v[48:49]
	s_nop 0
	v_pk_fma_f32 v[48:49], v[30:31], v[46:47], v[44:45]
	v_add_u32_e32 v44, 0x13800, v6
	ds_read_b128 v[44:47], v44
	s_waitcnt lgkmcnt(0)
	v_pk_fma_f32 v[44:45], v[36:37], v[44:45], v[48:49]
	s_nop 0
	v_pk_fma_f32 v[48:49], v[34:35], v[46:47], v[44:45]
	v_add_u32_e32 v44, 0x13c00, v6
	ds_read_b128 v[44:47], v44
	s_waitcnt lgkmcnt(0)
	v_pk_fma_f32 v[44:45], v[2:3], v[44:45], v[48:49]
	s_nop 0
	v_pk_fma_f32 v[44:45], v[4:5], v[46:47], v[44:45]
	s_nop 0
	v_add_f32_e32 v44, v44, v45
	v_add_u32_e32 v45, 0x14000, v6
	ds_read_b128 v[46:49], v45
	v_add_u32_e32 v45, 0x14400, v6
	s_waitcnt lgkmcnt(0)
	v_pk_fma_f32 v[46:47], v[12:13], v[46:47], 0 op_sel_hi:[1,1,0]
	s_nop 0
	v_pk_fma_f32 v[50:51], v[10:11], v[48:49], v[46:47]
	ds_read_b128 v[46:49], v45
	v_add_u32_e32 v45, 0x14800, v6
	s_waitcnt lgkmcnt(0)
	v_pk_fma_f32 v[46:47], v[16:17], v[46:47], v[50:51]
	s_nop 0
	v_pk_fma_f32 v[50:51], v[14:15], v[48:49], v[46:47]
	ds_read_b128 v[46:49], v45
	v_add_u32_e32 v45, 0x14c00, v6
	s_waitcnt lgkmcnt(0)
	v_pk_fma_f32 v[46:47], v[20:21], v[46:47], v[50:51]
	s_nop 0
	v_pk_fma_f32 v[50:51], v[18:19], v[48:49], v[46:47]
	ds_read_b128 v[46:49], v45
	v_add_u32_e32 v45, 0x15000, v6
	s_waitcnt lgkmcnt(0)
	v_pk_fma_f32 v[46:47], v[24:25], v[46:47], v[50:51]
	s_nop 0
	v_pk_fma_f32 v[50:51], v[22:23], v[48:49], v[46:47]
	ds_read_b128 v[46:49], v45
	v_add_u32_e32 v45, 0x15400, v6
	s_waitcnt lgkmcnt(0)
	v_pk_fma_f32 v[46:47], v[28:29], v[46:47], v[50:51]
	s_nop 0
	v_pk_fma_f32 v[50:51], v[26:27], v[48:49], v[46:47]
	ds_read_b128 v[46:49], v45
	v_add_u32_e32 v45, 0x15800, v6
	s_waitcnt lgkmcnt(0)
	v_pk_fma_f32 v[46:47], v[32:33], v[46:47], v[50:51]
	s_nop 0
	v_pk_fma_f32 v[50:51], v[30:31], v[48:49], v[46:47]
	ds_read_b128 v[46:49], v45
	v_add_u32_e32 v45, 0x15c00, v6
	s_waitcnt lgkmcnt(0)
	v_pk_fma_f32 v[46:47], v[36:37], v[46:47], v[50:51]
	s_nop 0
	v_pk_fma_f32 v[50:51], v[34:35], v[48:49], v[46:47]
	ds_read_b128 v[46:49], v45
	s_waitcnt lgkmcnt(0)
	v_pk_fma_f32 v[46:47], v[2:3], v[46:47], v[50:51]
	s_nop 0
	v_pk_fma_f32 v[46:47], v[4:5], v[48:49], v[46:47]
	s_nop 0
	v_add_f32_e32 v45, v46, v47
	v_add_u32_e32 v46, 0x16000, v6
	ds_read_b128 v[46:49], v46
	s_waitcnt lgkmcnt(0)
	v_pk_fma_f32 v[46:47], v[12:13], v[46:47], 0 op_sel_hi:[1,1,0]
	s_nop 0
	v_pk_fma_f32 v[50:51], v[10:11], v[48:49], v[46:47]
	v_add_u32_e32 v46, 0x16400, v6
	ds_read_b128 v[46:49], v46
	s_waitcnt lgkmcnt(0)
	v_pk_fma_f32 v[46:47], v[16:17], v[46:47], v[50:51]
	s_nop 0
	v_pk_fma_f32 v[50:51], v[14:15], v[48:49], v[46:47]
	v_add_u32_e32 v46, 0x16800, v6
	ds_read_b128 v[46:49], v46
	s_waitcnt lgkmcnt(0)
	v_pk_fma_f32 v[46:47], v[20:21], v[46:47], v[50:51]
	s_nop 0
	v_pk_fma_f32 v[50:51], v[18:19], v[48:49], v[46:47]
	v_add_u32_e32 v46, 0x16c00, v6
	ds_read_b128 v[46:49], v46
	s_waitcnt lgkmcnt(0)
	v_pk_fma_f32 v[46:47], v[24:25], v[46:47], v[50:51]
	s_nop 0
	v_pk_fma_f32 v[50:51], v[22:23], v[48:49], v[46:47]
	v_add_u32_e32 v46, 0x17000, v6
	ds_read_b128 v[46:49], v46
	s_waitcnt lgkmcnt(0)
	v_pk_fma_f32 v[46:47], v[28:29], v[46:47], v[50:51]
	s_nop 0
	v_pk_fma_f32 v[50:51], v[26:27], v[48:49], v[46:47]
	v_add_u32_e32 v46, 0x17400, v6
	ds_read_b128 v[46:49], v46
	s_waitcnt lgkmcnt(0)
	v_pk_fma_f32 v[46:47], v[32:33], v[46:47], v[50:51]
	s_nop 0
	v_pk_fma_f32 v[50:51], v[30:31], v[48:49], v[46:47]
	v_add_u32_e32 v46, 0x17800, v6
	ds_read_b128 v[46:49], v46
	s_waitcnt lgkmcnt(0)
	v_pk_fma_f32 v[46:47], v[36:37], v[46:47], v[50:51]
	s_nop 0
	v_pk_fma_f32 v[50:51], v[34:35], v[48:49], v[46:47]
	v_add_u32_e32 v46, 0x17c00, v6
	ds_read_b128 v[46:49], v46
	s_waitcnt lgkmcnt(0)
	v_pk_fma_f32 v[46:47], v[2:3], v[46:47], v[50:51]
	s_nop 0
	v_pk_fma_f32 v[46:47], v[4:5], v[48:49], v[46:47]
	s_nop 0
	v_add_f32_e32 v46, v46, v47
	v_add_u32_e32 v47, 0x18000, v6
	ds_read_b128 v[48:51], v47
	v_add_u32_e32 v47, 0x18400, v6
	s_waitcnt lgkmcnt(0)
	v_pk_fma_f32 v[48:49], v[12:13], v[48:49], 0 op_sel_hi:[1,1,0]
	s_nop 0
	v_pk_fma_f32 v[52:53], v[10:11], v[50:51], v[48:49]
	ds_read_b128 v[48:51], v47
	v_add_u32_e32 v47, 0x18800, v6
	s_waitcnt lgkmcnt(0)
	v_pk_fma_f32 v[48:49], v[16:17], v[48:49], v[52:53]
	s_nop 0
	v_pk_fma_f32 v[52:53], v[14:15], v[50:51], v[48:49]
	ds_read_b128 v[48:51], v47
	v_add_u32_e32 v47, 0x18c00, v6
	s_waitcnt lgkmcnt(0)
	v_pk_fma_f32 v[48:49], v[20:21], v[48:49], v[52:53]
	s_nop 0
	v_pk_fma_f32 v[52:53], v[18:19], v[50:51], v[48:49]
	ds_read_b128 v[48:51], v47
	v_add_u32_e32 v47, 0x19000, v6
	s_waitcnt lgkmcnt(0)
	v_pk_fma_f32 v[48:49], v[24:25], v[48:49], v[52:53]
	s_nop 0
	v_pk_fma_f32 v[52:53], v[22:23], v[50:51], v[48:49]
	ds_read_b128 v[48:51], v47
	v_add_u32_e32 v47, 0x19400, v6
	s_waitcnt lgkmcnt(0)
	v_pk_fma_f32 v[48:49], v[28:29], v[48:49], v[52:53]
	s_nop 0
	v_pk_fma_f32 v[52:53], v[26:27], v[50:51], v[48:49]
	ds_read_b128 v[48:51], v47
	v_add_u32_e32 v47, 0x19800, v6
	s_waitcnt lgkmcnt(0)
	v_pk_fma_f32 v[48:49], v[32:33], v[48:49], v[52:53]
	s_nop 0
	v_pk_fma_f32 v[52:53], v[30:31], v[50:51], v[48:49]
	ds_read_b128 v[48:51], v47
	v_add_u32_e32 v47, 0x19c00, v6
	s_waitcnt lgkmcnt(0)
	v_pk_fma_f32 v[48:49], v[36:37], v[48:49], v[52:53]
	s_nop 0
	v_pk_fma_f32 v[52:53], v[34:35], v[50:51], v[48:49]
	ds_read_b128 v[48:51], v47
	s_waitcnt lgkmcnt(0)
	v_pk_fma_f32 v[48:49], v[2:3], v[48:49], v[52:53]
	s_nop 0
	v_pk_fma_f32 v[48:49], v[4:5], v[50:51], v[48:49]
	s_nop 0
	v_add_f32_e32 v47, v48, v49
	v_add_u32_e32 v48, 0x1a000, v6
	ds_read_b128 v[48:51], v48
	s_waitcnt lgkmcnt(0)
	v_pk_fma_f32 v[48:49], v[12:13], v[48:49], 0 op_sel_hi:[1,1,0]
	s_nop 0
	v_pk_fma_f32 v[52:53], v[10:11], v[50:51], v[48:49]
	v_add_u32_e32 v48, 0x1a400, v6
	ds_read_b128 v[48:51], v48
	s_waitcnt lgkmcnt(0)
	v_pk_fma_f32 v[48:49], v[16:17], v[48:49], v[52:53]
	s_nop 0
	v_pk_fma_f32 v[52:53], v[14:15], v[50:51], v[48:49]
	v_add_u32_e32 v48, 0x1a800, v6
	ds_read_b128 v[48:51], v48
	s_waitcnt lgkmcnt(0)
	v_pk_fma_f32 v[48:49], v[20:21], v[48:49], v[52:53]
	s_nop 0
	v_pk_fma_f32 v[52:53], v[18:19], v[50:51], v[48:49]
	v_add_u32_e32 v48, 0x1ac00, v6
	ds_read_b128 v[48:51], v48
	s_waitcnt lgkmcnt(0)
	v_pk_fma_f32 v[48:49], v[24:25], v[48:49], v[52:53]
	s_nop 0
	v_pk_fma_f32 v[52:53], v[22:23], v[50:51], v[48:49]
	v_add_u32_e32 v48, 0x1b000, v6
	ds_read_b128 v[48:51], v48
	s_waitcnt lgkmcnt(0)
	v_pk_fma_f32 v[48:49], v[28:29], v[48:49], v[52:53]
	s_nop 0
	v_pk_fma_f32 v[52:53], v[26:27], v[50:51], v[48:49]
	v_add_u32_e32 v48, 0x1b400, v6
	ds_read_b128 v[48:51], v48
	s_waitcnt lgkmcnt(0)
	v_pk_fma_f32 v[48:49], v[32:33], v[48:49], v[52:53]
	s_nop 0
	v_pk_fma_f32 v[52:53], v[30:31], v[50:51], v[48:49]
	v_add_u32_e32 v48, 0x1b800, v6
	ds_read_b128 v[48:51], v48
	s_waitcnt lgkmcnt(0)
	v_pk_fma_f32 v[48:49], v[36:37], v[48:49], v[52:53]
	s_nop 0
	v_pk_fma_f32 v[52:53], v[34:35], v[50:51], v[48:49]
	v_add_u32_e32 v48, 0x1bc00, v6
	ds_read_b128 v[48:51], v48
	s_waitcnt lgkmcnt(0)
	v_pk_fma_f32 v[48:49], v[2:3], v[48:49], v[52:53]
	s_nop 0
	v_pk_fma_f32 v[48:49], v[4:5], v[50:51], v[48:49]
	s_nop 0
	v_add_f32_e32 v54, v48, v49
	v_add_u32_e32 v48, 0x1c000, v6
	ds_read_b128 v[48:51], v48
	s_waitcnt lgkmcnt(0)
	v_pk_fma_f32 v[48:49], v[12:13], v[48:49], 0 op_sel_hi:[1,1,0]
	s_nop 0
	v_pk_fma_f32 v[52:53], v[10:11], v[50:51], v[48:49]
	v_add_u32_e32 v48, 0x1c400, v6
	ds_read_b128 v[48:51], v48
	s_waitcnt lgkmcnt(0)
	v_pk_fma_f32 v[48:49], v[16:17], v[48:49], v[52:53]
	s_nop 0
	v_pk_fma_f32 v[52:53], v[14:15], v[50:51], v[48:49]
	v_add_u32_e32 v48, 0x1c800, v6
	ds_read_b128 v[48:51], v48
	s_waitcnt lgkmcnt(0)
	v_pk_fma_f32 v[48:49], v[20:21], v[48:49], v[52:53]
	s_nop 0
	v_pk_fma_f32 v[52:53], v[18:19], v[50:51], v[48:49]
	v_add_u32_e32 v48, 0x1cc00, v6
	ds_read_b128 v[48:51], v48
	s_waitcnt lgkmcnt(0)
	v_pk_fma_f32 v[48:49], v[24:25], v[48:49], v[52:53]
	s_nop 0
	v_pk_fma_f32 v[52:53], v[22:23], v[50:51], v[48:49]
	v_add_u32_e32 v48, 0x1d000, v6
	ds_read_b128 v[48:51], v48
	s_waitcnt lgkmcnt(0)
	v_pk_fma_f32 v[48:49], v[28:29], v[48:49], v[52:53]
	s_nop 0
	v_pk_fma_f32 v[52:53], v[26:27], v[50:51], v[48:49]
	v_add_u32_e32 v48, 0x1d400, v6
	ds_read_b128 v[48:51], v48
	s_waitcnt lgkmcnt(0)
	v_pk_fma_f32 v[48:49], v[32:33], v[48:49], v[52:53]
	s_nop 0
	v_pk_fma_f32 v[52:53], v[30:31], v[50:51], v[48:49]
	v_add_u32_e32 v48, 0x1d800, v6
	ds_read_b128 v[48:51], v48
	s_waitcnt lgkmcnt(0)
	v_pk_fma_f32 v[48:49], v[36:37], v[48:49], v[52:53]
	s_nop 0
	v_pk_fma_f32 v[52:53], v[34:35], v[50:51], v[48:49]
	v_add_u32_e32 v48, 0x1dc00, v6
	ds_read_b128 v[48:51], v48
	s_waitcnt lgkmcnt(0)
	v_pk_fma_f32 v[48:49], v[2:3], v[48:49], v[52:53]
	s_nop 0
	v_pk_fma_f32 v[48:49], v[4:5], v[50:51], v[48:49]
	s_nop 0
	v_add_f32_e32 v52, v48, v49
	v_add_u32_e32 v48, 0x1e000, v6
	ds_read_b128 v[48:51], v48
	s_waitcnt lgkmcnt(0)
	v_pk_fma_f32 v[12:13], v[12:13], v[48:49], 0 op_sel_hi:[1,1,0]
	s_nop 0
	v_pk_fma_f32 v[48:49], v[10:11], v[50:51], v[12:13]
	v_add_u32_e32 v10, 0x1e400, v6
	ds_read_b128 v[10:13], v10
	s_waitcnt lgkmcnt(0)
	v_pk_fma_f32 v[10:11], v[16:17], v[10:11], v[48:49]
	s_nop 0
	v_pk_fma_f32 v[14:15], v[14:15], v[12:13], v[10:11]
	v_add_u32_e32 v10, 0x1e800, v6
	ds_read_b128 v[10:13], v10
	s_waitcnt lgkmcnt(0)
	v_pk_fma_f32 v[10:11], v[20:21], v[10:11], v[14:15]
	s_nop 0
	v_pk_fma_f32 v[14:15], v[18:19], v[12:13], v[10:11]
	v_add_u32_e32 v10, 0x1ec00, v6
	ds_read_b128 v[10:13], v10
	s_waitcnt lgkmcnt(0)
	v_pk_fma_f32 v[10:11], v[24:25], v[10:11], v[14:15]
	s_nop 0
	v_pk_fma_f32 v[14:15], v[22:23], v[12:13], v[10:11]
	v_add_u32_e32 v10, 0x1f000, v6
	ds_read_b128 v[10:13], v10
	s_waitcnt lgkmcnt(0)
	v_pk_fma_f32 v[10:11], v[28:29], v[10:11], v[14:15]
	s_nop 0
	v_pk_fma_f32 v[14:15], v[26:27], v[12:13], v[10:11]
	v_add_u32_e32 v10, 0x1f400, v6
	ds_read_b128 v[10:13], v10
	s_waitcnt lgkmcnt(0)
	v_pk_fma_f32 v[10:11], v[32:33], v[10:11], v[14:15]
	s_nop 0
	v_pk_fma_f32 v[14:15], v[30:31], v[12:13], v[10:11]
	v_add_u32_e32 v10, 0x1f800, v6
	ds_read_b128 v[10:13], v10
	v_add_u32_e32 v6, 0x1fc00, v6
	s_waitcnt lgkmcnt(0)
	v_pk_fma_f32 v[10:11], v[36:37], v[10:11], v[14:15]
	s_nop 0
	v_pk_fma_f32 v[14:15], v[34:35], v[12:13], v[10:11]
	ds_read_b128 v[10:13], v6
	s_waitcnt lgkmcnt(0)
	v_pk_fma_f32 v[2:3], v[2:3], v[10:11], v[14:15]
	s_nop 0
	v_pk_fma_f32 v[2:3], v[4:5], v[12:13], v[2:3]
	s_nop 0
	v_add_f32_e32 v2, v2, v3
	v_and_b32_e32 v3, 32, v1
	v_cmp_eq_u32_e32 vcc, 0, v3
	s_nop 1
	v_cndmask_b32_e32 v4, v7, v43, vcc
	ds_bpermute_b32 v4, v63, v4
	v_cndmask_b32_e32 v5, v8, v44, vcc
	ds_bpermute_b32 v5, v63, v5
	v_cndmask_b32_e32 v6, v9, v45, vcc
	v_cndmask_b32_e32 v3, v43, v7, vcc
	ds_bpermute_b32 v6, v63, v6
	v_cndmask_b32_e32 v7, v38, v46, vcc
	s_waitcnt lgkmcnt(2)
	v_add_f32_e32 v3, v3, v4
	v_cndmask_b32_e32 v4, v44, v8, vcc
	ds_bpermute_b32 v7, v63, v7
	v_cndmask_b32_e32 v8, v39, v47, vcc
	s_waitcnt lgkmcnt(2)
	v_add_f32_e32 v4, v4, v5
	v_cndmask_b32_e32 v5, v45, v9, vcc
	ds_bpermute_b32 v8, v63, v8
	v_cndmask_b32_e32 v9, v40, v54, vcc
	ds_bpermute_b32 v9, v63, v9
	v_cndmask_b32_e32 v10, v41, v52, vcc
	ds_bpermute_b32 v10, v63, v10
	s_waitcnt lgkmcnt(4)
	v_add_f32_e32 v5, v5, v6
	v_cndmask_b32_e32 v6, v46, v38, vcc
	s_waitcnt lgkmcnt(3)
	v_add_f32_e32 v6, v6, v7
	v_cndmask_b32_e32 v7, v47, v39, vcc
	s_waitcnt lgkmcnt(2)
	v_add_f32_e32 v7, v7, v8
	v_cndmask_b32_e32 v8, v54, v40, vcc
	s_waitcnt lgkmcnt(1)
	v_add_f32_e32 v8, v8, v9
	v_cndmask_b32_e32 v9, v52, v41, vcc
	s_waitcnt lgkmcnt(0)
	v_add_f32_e32 v9, v9, v10
	v_cndmask_b32_e32 v10, v2, v42, vcc
	v_cndmask_b32_e32 v2, v42, v2, vcc
	ds_bpermute_b32 v2, v63, v2
	s_waitcnt lgkmcnt(0)
	v_add_f32_e32 v2, v10, v2
	v_and_b32_e32 v10, 16, v1
	v_cmp_eq_u32_e32 vcc, 0, v10
	s_nop 1
	v_cndmask_b32_e32 v10, v7, v3, vcc
	v_cndmask_b32_e32 v3, v3, v7, vcc
	v_cndmask_b32_e32 v7, v8, v4, vcc
	v_cndmask_b32_e32 v4, v4, v8, vcc
	ds_bpermute_b32 v4, v62, v4
	ds_bpermute_b32 v3, v62, v3
	s_waitcnt lgkmcnt(1)
	v_add_f32_e32 v4, v7, v4
	v_cndmask_b32_e32 v7, v9, v5, vcc
	v_cndmask_b32_e32 v5, v5, v9, vcc
	ds_bpermute_b32 v5, v62, v5
	s_waitcnt lgkmcnt(1)
	v_add_f32_e32 v3, v10, v3
	s_waitcnt lgkmcnt(0)
	v_add_f32_e32 v5, v7, v5
	v_cndmask_b32_e32 v7, v2, v6, vcc
	v_cndmask_b32_e32 v2, v6, v2, vcc
	ds_bpermute_b32 v2, v62, v2
	v_and_b32_e32 v6, 8, v1
	v_cmp_eq_u32_e32 vcc, 0, v6
	s_waitcnt lgkmcnt(0)
	v_add_f32_e32 v2, v7, v2
	v_cndmask_b32_e32 v6, v5, v3, vcc
	v_cndmask_b32_e32 v3, v3, v5, vcc
	v_cndmask_b32_e32 v5, v2, v4, vcc
	v_cndmask_b32_e32 v2, v4, v2, vcc
	ds_bpermute_b32 v3, v61, v3
	ds_bpermute_b32 v2, v61, v2
	v_and_b32_e32 v4, 4, v1
	v_cmp_eq_u32_e32 vcc, 0, v4
	s_waitcnt lgkmcnt(1)
	v_add_f32_e32 v3, v6, v3
	s_waitcnt lgkmcnt(0)
	v_add_f32_e32 v2, v5, v2
	v_cndmask_b32_e32 v4, v2, v3, vcc
	v_cndmask_b32_e32 v2, v3, v2, vcc
	ds_bpermute_b32 v2, v60, v2
	s_waitcnt lgkmcnt(0)
	v_add_f32_e32 v2, v4, v2
	ds_bpermute_b32 v3, v59, v2
	v_and_b32_e32 v4, 3, v1
	v_cmp_eq_u32_e32 vcc, 0, v4
	s_waitcnt lgkmcnt(0)
	v_add_f32_e32 v2, v2, v3
	ds_bpermute_b32 v3, v58, v2
	s_and_saveexec_b64 s[18:19], vcc
	s_cbranch_execz .LBB0_1755
	s_waitcnt lgkmcnt(0)
	v_add_f32_e32 v2, v2, v3
	v_bfe_u32 v3, v1, 2, 4
	v_lshlrev_b32_e32 v82, 2, v3
	global_load_dword v1, v82, s[16:17] offset:64
	v_cmp_lt_u32_e32 vcc, 7, v3
	s_lshl_b64 s[14:15], s[14:15], 5
	s_waitcnt vmcnt(0)
	v_add_f32_e32 v1, v2, v1
	s_and_saveexec_b64 s[8:9], vcc
	s_xor_b64 s[16:17], exec, s[8:9]
	s_cbranch_execz .LBB0_1776
	s_mov_b32 s8, 0xbfb8aa3b
	v_mul_f32_e64 v2, |v1|, s8
	v_exp_f32_e32 v4, v2
	s_add_u32 s8, s12, s14
	s_addc_u32 s9, s13, s15
	v_lshl_add_u64 v[2:3], s[8:9], 0, v[82:83]
	v_add_f32_e32 v4, 1.0, v4
	s_mov_b32 s8, 0x800000
	v_cmp_gt_f32_e32 vcc, s8, v4
	s_mov_b64 s[8:9], 0x1515afe0
	v_lshl_add_u64 v[2:3], v[2:3], 0, s[8:9]
	v_cndmask_b32_e64 v5, 0, 32, vcc
	v_ldexp_f32 v4, v4, v5
	v_log_f32_e32 v4, v4
	s_mov_b32 s8, 0x3f317217
	v_max_f32_e32 v1, v1, v1
	v_min_f32_e32 v1, 0, v1
	v_mul_f32_e32 v5, 0x3f317217, v4
	v_fma_f32 v5, v4, s8, -v5
	v_fmac_f32_e32 v5, 0x3377d1cf, v4
	s_mov_b32 s8, 0x7f800000
	v_fmac_f32_e32 v5, 0x3f317217, v4
	v_cmp_lt_f32_e64 s[8:9], |v4|, s8
	s_nop 1
	v_cndmask_b32_e64 v4, v4, v5, s[8:9]
	v_mov_b32_e32 v5, 0x41b17218
	v_cndmask_b32_e32 v5, 0, v5, vcc
	v_sub_f32_e32 v4, v4, v5
	v_sub_f32_e32 v1, v1, v4
